# all 16-byte global stores write-through (sc1) so the grid barriers have less to write back
# baseline (speedup 1.0000x reference)
.LBB0_49:
	s_waitcnt vmcnt(1)
	v_add_u32_e32 v10, 0x1400, v33
	ds_write2_b32 v10, v14, v15 offset0:40 offset1:106
	ds_write2_b32 v10, v16, v17 offset0:172 offset1:238
	s_waitcnt lgkmcnt(0)
	s_sub_i32 s24, 0, s29
	ds_read2_b32 v[14:15], v5 offset0:33 offset1:41
	ds_read2_b32 v[16:17], v5 offset1:8
	ds_read2_b32 v[18:19], v5 offset0:66 offset1:74
	ds_read2_b32 v[20:21], v5 offset0:99 offset1:107
	ds_read2_b32 v[22:23], v5 offset0:132 offset1:140
	ds_read2_b32 v[24:25], v5 offset0:165 offset1:173
	ds_read2_b32 v[26:27], v5 offset0:198 offset1:206
	ds_read2_b32 v[28:29], v5 offset0:231 offset1:239
	s_add_i32 s24, s24, s3
	v_add_u32_e32 v36, s24, v1
	v_ashrrev_i32_e32 v37, 31, v36
	v_lshl_add_u64 v[34:35], s[22:23], 1, v[8:9]
	v_lshlrev_b64 v[38:39], 11, v[36:37]
	s_waitcnt lgkmcnt(6)
	v_cvt_pk_bf16_f32 v10, v16, v14
	s_waitcnt vmcnt(0) lgkmcnt(4)
	v_cvt_pk_bf16_f32 v11, v18, v20
	s_waitcnt lgkmcnt(2)
	v_cvt_pk_bf16_f32 v12, v22, v24
	s_waitcnt lgkmcnt(0)
	v_cvt_pk_bf16_f32 v13, v26, v28
	v_lshl_add_u64 v[38:39], v[34:35], 0, v[38:39]
	v_add_u32_e32 v14, 8, v36
	global_store_dwordx4 v[38:39], v[10:13], off sc1
	s_add_i32 s28, s28, s78
	s_add_i32 s3, s3, s26
	v_cvt_pk_bf16_f32 v10, v17, v15
	v_ashrrev_i32_e32 v15, 31, v14
	v_cvt_pk_bf16_f32 v11, v19, v21
	v_cvt_pk_bf16_f32 v12, v23, v25
	v_cvt_pk_bf16_f32 v13, v27, v29
	v_lshlrev_b64 v[14:15], 11, v[14:15]
	ds_read2_b32 v[16:17], v5 offset0:49 offset1:57
	ds_read2_b32 v[18:19], v5 offset0:16 offset1:24
	ds_read2_b32 v[20:21], v5 offset0:82 offset1:90
	ds_read2_b32 v[22:23], v5 offset0:115 offset1:123
	ds_read2_b32 v[24:25], v5 offset0:148 offset1:156
	ds_read2_b32 v[26:27], v5 offset0:181 offset1:189
	ds_read2_b32 v[28:29], v5 offset0:214 offset1:222
	ds_read2_b32 v[38:39], v5 offset0:247 offset1:255
	v_lshl_add_u64 v[14:15], v[34:35], 0, v[14:15]
	global_store_dwordx4 v[14:15], v[10:13], off sc1
	v_add_u32_e32 v14, 16, v36
	v_ashrrev_i32_e32 v15, 31, v14
	v_lshlrev_b64 v[14:15], 11, v[14:15]
	s_waitcnt lgkmcnt(6)
	v_cvt_pk_bf16_f32 v10, v18, v16
	s_waitcnt lgkmcnt(4)
	v_cvt_pk_bf16_f32 v11, v20, v22
	s_waitcnt lgkmcnt(2)
	v_cvt_pk_bf16_f32 v12, v24, v26
	s_waitcnt lgkmcnt(0)
	v_cvt_pk_bf16_f32 v13, v28, v38
	v_lshl_add_u64 v[14:15], v[34:35], 0, v[14:15]
	global_store_dwordx4 v[14:15], v[10:13], off sc1
	v_add_u32_e32 v14, 24, v36
	v_ashrrev_i32_e32 v15, 31, v14
	v_lshlrev_b64 v[14:15], 11, v[14:15]
	v_cvt_pk_bf16_f32 v10, v19, v17
	v_cvt_pk_bf16_f32 v11, v21, v23
	v_cvt_pk_bf16_f32 v12, v25, v27
	v_cvt_pk_bf16_f32 v13, v29, v39
	v_lshl_add_u64 v[14:15], v[34:35], 0, v[14:15]
	global_store_dwordx4 v[14:15], v[10:13], off sc1
	s_waitcnt lgkmcnt(0)
	s_cmpk_lt_i32 s28, 0x200
	s_cbranch_scc0 .LBB0_65

.LBB0_68:
	s_waitcnt vmcnt(1)
	v_add_u32_e32 v10, 0x1400, v33
	ds_write2_b32 v10, v14, v15 offset0:40 offset1:106
	ds_write2_b32 v10, v16, v17 offset0:172 offset1:238
	s_waitcnt lgkmcnt(0)
	ds_read2_b32 v[14:15], v5 offset0:33 offset1:41
	ds_read2_b32 v[16:17], v5 offset1:8
	ds_read2_b32 v[18:19], v5 offset0:66 offset1:74
	ds_read2_b32 v[20:21], v5 offset0:99 offset1:107
	ds_read2_b32 v[22:23], v5 offset0:132 offset1:140
	ds_read2_b32 v[24:25], v5 offset0:165 offset1:173
	ds_read2_b32 v[26:27], v5 offset0:198 offset1:206
	ds_read2_b32 v[28:29], v5 offset0:231 offset1:239
	v_add_u32_e32 v38, s20, v1
	v_add_u32_e32 v36, 0x400, v38
	v_ashrrev_i32_e32 v37, 31, v36
	v_lshl_add_u64 v[34:35], s[22:23], 1, v[8:9]
	v_lshlrev_b64 v[36:37], 11, v[36:37]
	s_waitcnt lgkmcnt(6)
	v_cvt_pk_bf16_f32 v10, v16, v14
	s_waitcnt vmcnt(0) lgkmcnt(4)
	v_cvt_pk_bf16_f32 v11, v18, v20
	s_waitcnt lgkmcnt(2)
	v_cvt_pk_bf16_f32 v12, v22, v24
	s_waitcnt lgkmcnt(0)
	v_cvt_pk_bf16_f32 v13, v26, v28
	v_lshl_add_u64 v[36:37], v[34:35], 0, v[36:37]
	v_add_u32_e32 v14, 0x408, v38
	global_store_dwordx4 v[36:37], v[10:13], off sc1
	s_add_i32 s28, s28, s78
	s_add_i32 s3, s3, s26
	v_cvt_pk_bf16_f32 v10, v17, v15
	v_ashrrev_i32_e32 v15, 31, v14
	v_cvt_pk_bf16_f32 v11, v19, v21
	v_cvt_pk_bf16_f32 v12, v23, v25
	v_cvt_pk_bf16_f32 v13, v27, v29
	v_lshlrev_b64 v[14:15], 11, v[14:15]
	ds_read2_b32 v[16:17], v5 offset0:49 offset1:57
	ds_read2_b32 v[18:19], v5 offset0:16 offset1:24
	ds_read2_b32 v[20:21], v5 offset0:82 offset1:90
	ds_read2_b32 v[22:23], v5 offset0:115 offset1:123
	ds_read2_b32 v[24:25], v5 offset0:148 offset1:156
	ds_read2_b32 v[26:27], v5 offset0:181 offset1:189
	ds_read2_b32 v[28:29], v5 offset0:214 offset1:222
	ds_read2_b32 v[36:37], v5 offset0:247 offset1:255
	v_lshl_add_u64 v[14:15], v[34:35], 0, v[14:15]
	global_store_dwordx4 v[14:15], v[10:13], off sc1
	v_add_u32_e32 v14, 0x410, v38
	v_ashrrev_i32_e32 v15, 31, v14
	v_lshlrev_b64 v[14:15], 11, v[14:15]
	s_waitcnt lgkmcnt(6)
	v_cvt_pk_bf16_f32 v10, v18, v16
	s_waitcnt lgkmcnt(4)
	v_cvt_pk_bf16_f32 v11, v20, v22
	s_waitcnt lgkmcnt(2)
	v_cvt_pk_bf16_f32 v12, v24, v26
	s_waitcnt lgkmcnt(0)
	v_cvt_pk_bf16_f32 v13, v28, v36
	v_lshl_add_u64 v[14:15], v[34:35], 0, v[14:15]
	global_store_dwordx4 v[14:15], v[10:13], off sc1
	v_add_u32_e32 v14, 0x418, v38
	v_ashrrev_i32_e32 v15, 31, v14
	v_lshlrev_b64 v[14:15], 11, v[14:15]
	v_cvt_pk_bf16_f32 v10, v19, v17
	v_cvt_pk_bf16_f32 v11, v21, v23
	v_cvt_pk_bf16_f32 v12, v25, v27
	v_cvt_pk_bf16_f32 v13, v29, v37
	v_lshl_add_u64 v[14:15], v[34:35], 0, v[14:15]
	global_store_dwordx4 v[14:15], v[10:13], off sc1
	s_waitcnt lgkmcnt(0)
	s_cmpk_lt_i32 s28, 0x390
	s_cbranch_scc0 .LBB0_84

.LBB0_86:
	v_lshl_add_u64 v[10:11], v[10:11], 0, s[44:45]
	v_cmp_lt_u64_e32 vcc, s[22:23], v[10:11]
	global_store_dwordx4 v[8:9], v[12:15], off sc1
	s_or_b64 s[6:7], vcc, s[6:7]
	v_lshl_add_u64 v[8:9], v[8:9], 0, s[20:21]
	s_andn2_b64 exec, exec, s[6:7]
	s_cbranch_execnz .LBB0_86
	s_or_b64 exec, exec, s[6:7]

.LBB0_91:
	s_waitcnt vmcnt(1)
	v_add_u32_e32 v12, 0x1400, v34
	ds_write2_b32 v12, v16, v17 offset0:40 offset1:106
	ds_write2_b32 v12, v18, v19 offset0:172 offset1:238
	s_waitcnt lgkmcnt(0)
	s_sub_i32 s24, 0, s29
	ds_read2_b32 v[16:17], v5 offset0:33 offset1:41
	ds_read2_b32 v[18:19], v5 offset1:8
	ds_read2_b32 v[20:21], v5 offset0:66 offset1:74
	ds_read2_b32 v[22:23], v5 offset0:99 offset1:107
	ds_read2_b32 v[24:25], v5 offset0:132 offset1:140
	ds_read2_b32 v[26:27], v5 offset0:165 offset1:173
	ds_read2_b32 v[28:29], v5 offset0:198 offset1:206
	ds_read2_b32 v[30:31], v5 offset0:231 offset1:239
	s_add_i32 s24, s24, s3
	v_add_u32_e32 v38, s24, v1
	v_ashrrev_i32_e32 v39, 31, v38
	v_lshl_add_u64 v[36:37], s[22:23], 1, v[10:11]
	v_lshlrev_b64 v[40:41], 11, v[38:39]
	s_waitcnt lgkmcnt(6)
	v_cvt_pk_bf16_f32 v12, v18, v16
	s_waitcnt vmcnt(0) lgkmcnt(4)
	v_cvt_pk_bf16_f32 v13, v20, v22
	s_waitcnt lgkmcnt(2)
	v_cvt_pk_bf16_f32 v14, v24, v26
	s_waitcnt lgkmcnt(0)
	v_cvt_pk_bf16_f32 v15, v28, v30
	v_lshl_add_u64 v[40:41], v[36:37], 0, v[40:41]
	v_add_u32_e32 v16, 8, v38
	global_store_dwordx4 v[40:41], v[12:15], off sc1
	s_add_i32 s28, s28, s78
	s_add_i32 s3, s3, s26
	v_cvt_pk_bf16_f32 v12, v19, v17
	v_ashrrev_i32_e32 v17, 31, v16
	v_cvt_pk_bf16_f32 v13, v21, v23
	v_cvt_pk_bf16_f32 v14, v25, v27
	v_cvt_pk_bf16_f32 v15, v29, v31
	v_lshlrev_b64 v[16:17], 11, v[16:17]
	ds_read2_b32 v[18:19], v5 offset0:49 offset1:57
	ds_read2_b32 v[20:21], v5 offset0:16 offset1:24
	ds_read2_b32 v[22:23], v5 offset0:82 offset1:90
	ds_read2_b32 v[24:25], v5 offset0:115 offset1:123
	ds_read2_b32 v[26:27], v5 offset0:148 offset1:156
	ds_read2_b32 v[28:29], v5 offset0:181 offset1:189
	ds_read2_b32 v[30:31], v5 offset0:214 offset1:222
	ds_read2_b32 v[40:41], v5 offset0:247 offset1:255
	v_lshl_add_u64 v[16:17], v[36:37], 0, v[16:17]
	global_store_dwordx4 v[16:17], v[12:15], off sc1
	v_add_u32_e32 v16, 16, v38
	v_ashrrev_i32_e32 v17, 31, v16
	v_lshlrev_b64 v[16:17], 11, v[16:17]
	s_waitcnt lgkmcnt(6)
	v_cvt_pk_bf16_f32 v12, v20, v18
	s_waitcnt lgkmcnt(4)
	v_cvt_pk_bf16_f32 v13, v22, v24
	s_waitcnt lgkmcnt(2)
	v_cvt_pk_bf16_f32 v14, v26, v28
	s_waitcnt lgkmcnt(0)
	v_cvt_pk_bf16_f32 v15, v30, v40
	v_lshl_add_u64 v[16:17], v[36:37], 0, v[16:17]
	global_store_dwordx4 v[16:17], v[12:15], off sc1
	v_add_u32_e32 v16, 24, v38
	v_ashrrev_i32_e32 v17, 31, v16
	v_lshlrev_b64 v[16:17], 11, v[16:17]
	v_cvt_pk_bf16_f32 v12, v21, v19
	v_cvt_pk_bf16_f32 v13, v23, v25
	v_cvt_pk_bf16_f32 v14, v27, v29
	v_cvt_pk_bf16_f32 v15, v31, v41
	v_lshl_add_u64 v[16:17], v[36:37], 0, v[16:17]
	global_store_dwordx4 v[16:17], v[12:15], off sc1
	s_waitcnt lgkmcnt(0)
	s_cmpk_lt_i32 s28, 0x100
	s_cbranch_scc0 .LBB0_107

.LBB0_110:
	s_waitcnt vmcnt(1)
	v_add_u32_e32 v12, 0x1400, v34
	ds_write2_b32 v12, v16, v17 offset0:40 offset1:106
	ds_write2_b32 v12, v18, v19 offset0:172 offset1:238
	s_waitcnt lgkmcnt(0)
	s_sub_i32 s22, 0, s27
	ds_read2_b32 v[16:17], v5 offset0:33 offset1:41
	ds_read2_b32 v[18:19], v5 offset1:8
	ds_read2_b32 v[20:21], v5 offset0:66 offset1:74
	ds_read2_b32 v[22:23], v5 offset0:99 offset1:107
	ds_read2_b32 v[24:25], v5 offset0:132 offset1:140
	ds_read2_b32 v[26:27], v5 offset0:165 offset1:173
	ds_read2_b32 v[28:29], v5 offset0:198 offset1:206
	ds_read2_b32 v[30:31], v5 offset0:231 offset1:239
	s_add_i32 s22, s22, s3
	v_add_u32_e32 v38, s22, v1
	v_ashrrev_i32_e32 v39, 31, v38
	v_lshl_add_u64 v[36:37], s[18:19], 1, v[10:11]
	v_lshlrev_b64 v[40:41], 11, v[38:39]
	s_waitcnt lgkmcnt(6)
	v_cvt_pk_bf16_f32 v12, v18, v16
	s_waitcnt vmcnt(0) lgkmcnt(4)
	v_cvt_pk_bf16_f32 v13, v20, v22
	s_waitcnt lgkmcnt(2)
	v_cvt_pk_bf16_f32 v14, v24, v26
	s_waitcnt lgkmcnt(0)
	v_cvt_pk_bf16_f32 v15, v28, v30
	v_lshl_add_u64 v[40:41], v[36:37], 0, v[40:41]
	v_add_u32_e32 v16, 8, v38
	global_store_dwordx4 v[40:41], v[12:15], off sc1
	s_add_i32 s26, s26, s78
	s_add_i32 s3, s3, s24
	v_cvt_pk_bf16_f32 v12, v19, v17
	v_ashrrev_i32_e32 v17, 31, v16
	v_cvt_pk_bf16_f32 v13, v21, v23
	v_cvt_pk_bf16_f32 v14, v25, v27
	v_cvt_pk_bf16_f32 v15, v29, v31
	v_lshlrev_b64 v[16:17], 11, v[16:17]
	ds_read2_b32 v[18:19], v5 offset0:49 offset1:57
	ds_read2_b32 v[20:21], v5 offset0:16 offset1:24
	ds_read2_b32 v[22:23], v5 offset0:82 offset1:90
	ds_read2_b32 v[24:25], v5 offset0:115 offset1:123
	ds_read2_b32 v[26:27], v5 offset0:148 offset1:156
	ds_read2_b32 v[28:29], v5 offset0:181 offset1:189
	ds_read2_b32 v[30:31], v5 offset0:214 offset1:222
	ds_read2_b32 v[40:41], v5 offset0:247 offset1:255
	v_lshl_add_u64 v[16:17], v[36:37], 0, v[16:17]
	global_store_dwordx4 v[16:17], v[12:15], off sc1
	v_add_u32_e32 v16, 16, v38
	v_ashrrev_i32_e32 v17, 31, v16
	v_lshlrev_b64 v[16:17], 11, v[16:17]
	s_waitcnt lgkmcnt(6)
	v_cvt_pk_bf16_f32 v12, v20, v18
	s_waitcnt lgkmcnt(4)
	v_cvt_pk_bf16_f32 v13, v22, v24
	s_waitcnt lgkmcnt(2)
	v_cvt_pk_bf16_f32 v14, v26, v28
	s_waitcnt lgkmcnt(0)
	v_cvt_pk_bf16_f32 v15, v30, v40
	v_lshl_add_u64 v[16:17], v[36:37], 0, v[16:17]
	global_store_dwordx4 v[16:17], v[12:15], off sc1
	v_add_u32_e32 v16, 24, v38
	v_ashrrev_i32_e32 v17, 31, v16
	v_lshlrev_b64 v[16:17], 11, v[16:17]
	v_cvt_pk_bf16_f32 v12, v21, v19
	v_cvt_pk_bf16_f32 v13, v23, v25
	v_cvt_pk_bf16_f32 v14, v27, v29
	v_cvt_pk_bf16_f32 v15, v31, v41
	v_lshl_add_u64 v[16:17], v[36:37], 0, v[16:17]
	global_store_dwordx4 v[16:17], v[12:15], off sc1
	s_waitcnt lgkmcnt(0)
	s_cmpk_lt_i32 s26, 0x400
	s_cbranch_scc0 .LBB0_126

.LBB0_128:
	s_ashr_i32 s6, s20, 31
	s_lshr_b32 s6, s6, 27
	s_add_i32 s6, s20, s6
	s_ashr_i32 s7, s6, 5
	s_lshl_b32 s6, s7, 6
	s_lshl_b32 s7, s7, 10
	v_or_b32_e32 v20, s6, v2
	s_sub_i32 s10, s19, s7
	v_or_b32_e32 v30, 10, v20
	v_or_b32_e32 v34, 12, v20
	v_or_b32_e32 v36, 14, v20
	v_or_b32_e32 v46, 24, v20
	v_or_b32_e32 v48, 26, v20
	v_or_b32_e32 v50, 28, v20
	v_or_b32_e32 v52, 30, v20
	s_ashr_i32 s11, s10, 31
	v_ashrrev_i32_e32 v21, 31, v20
	v_or_b32_e32 v22, 2, v20
	v_or_b32_e32 v24, 4, v20
	v_or_b32_e32 v26, 6, v20
	v_or_b32_e32 v28, 8, v20
	v_or_b32_e32 v38, 16, v20
	v_or_b32_e32 v40, 18, v20
	v_or_b32_e32 v42, 20, v20
	v_or_b32_e32 v44, 22, v20
	v_or_b32_e32 v54, 32, v20
	v_or_b32_e32 v56, 34, v20
	v_or_b32_e32 v58, 36, v20
	v_or_b32_e32 v60, 38, v20
	v_or_b32_e32 v62, 40, v20
	v_or_b32_e32 v64, 42, v20
	v_or_b32_e32 v66, 44, v20
	v_or_b32_e32 v68, 46, v20
	v_or_b32_e32 v70, 48, v20
	v_or_b32_e32 v72, 50, v20
	v_or_b32_e32 v74, 52, v20
	v_or_b32_e32 v76, 54, v20
	v_or_b32_e32 v78, 56, v20
	v_or_b32_e32 v80, 58, v20
	v_or_b32_e32 v82, 60, v20
	v_or_b32_e32 v84, 62, v20
	v_ashrrev_i32_e32 v31, 31, v30
	v_ashrrev_i32_e32 v35, 31, v34
	v_ashrrev_i32_e32 v37, 31, v36
	v_ashrrev_i32_e32 v47, 31, v46
	v_ashrrev_i32_e32 v49, 31, v48
	v_ashrrev_i32_e32 v51, 31, v50
	v_ashrrev_i32_e32 v53, 31, v52
	v_lshl_add_u64 v[86:87], s[10:11], 2, v[10:11]
	v_lshlrev_b64 v[20:21], 12, v[20:21]
	v_ashrrev_i32_e32 v23, 31, v22
	v_ashrrev_i32_e32 v25, 31, v24
	v_ashrrev_i32_e32 v27, 31, v26
	v_ashrrev_i32_e32 v29, 31, v28
	v_ashrrev_i32_e32 v39, 31, v38
	v_ashrrev_i32_e32 v41, 31, v40
	v_ashrrev_i32_e32 v43, 31, v42
	v_ashrrev_i32_e32 v45, 31, v44
	v_ashrrev_i32_e32 v55, 31, v54
	v_ashrrev_i32_e32 v57, 31, v56
	v_ashrrev_i32_e32 v59, 31, v58
	v_ashrrev_i32_e32 v61, 31, v60
	v_ashrrev_i32_e32 v63, 31, v62
	v_ashrrev_i32_e32 v65, 31, v64
	v_ashrrev_i32_e32 v67, 31, v66
	v_ashrrev_i32_e32 v69, 31, v68
	v_ashrrev_i32_e32 v71, 31, v70
	v_ashrrev_i32_e32 v73, 31, v72
	v_ashrrev_i32_e32 v75, 31, v74
	v_ashrrev_i32_e32 v77, 31, v76
	v_ashrrev_i32_e32 v79, 31, v78
	v_ashrrev_i32_e32 v81, 31, v80
	v_ashrrev_i32_e32 v83, 31, v82
	v_ashrrev_i32_e32 v85, 31, v84
	v_lshlrev_b64 v[30:31], 12, v[30:31]
	v_lshlrev_b64 v[34:35], 12, v[34:35]
	v_lshlrev_b64 v[36:37], 12, v[36:37]
	v_lshlrev_b64 v[46:47], 12, v[46:47]
	v_lshlrev_b64 v[48:49], 12, v[48:49]
	v_lshlrev_b64 v[50:51], 12, v[50:51]
	v_lshlrev_b64 v[52:53], 12, v[52:53]
	v_lshl_add_u64 v[20:21], v[86:87], 0, v[20:21]
	v_lshlrev_b64 v[22:23], 12, v[22:23]
	v_lshlrev_b64 v[24:25], 12, v[24:25]
	v_lshlrev_b64 v[26:27], 12, v[26:27]
	v_lshlrev_b64 v[28:29], 12, v[28:29]
	v_lshlrev_b64 v[38:39], 12, v[38:39]
	v_lshlrev_b64 v[40:41], 12, v[40:41]
	v_lshlrev_b64 v[42:43], 12, v[42:43]
	v_lshlrev_b64 v[44:45], 12, v[44:45]
	v_lshlrev_b64 v[54:55], 12, v[54:55]
	v_lshlrev_b64 v[56:57], 12, v[56:57]
	v_lshlrev_b64 v[58:59], 12, v[58:59]
	v_lshlrev_b64 v[60:61], 12, v[60:61]
	v_lshlrev_b64 v[62:63], 12, v[62:63]
	v_lshlrev_b64 v[64:65], 12, v[64:65]
	v_lshlrev_b64 v[66:67], 12, v[66:67]
	v_lshlrev_b64 v[68:69], 12, v[68:69]
	v_lshlrev_b64 v[70:71], 12, v[70:71]
	v_lshlrev_b64 v[72:73], 12, v[72:73]
	v_lshlrev_b64 v[74:75], 12, v[74:75]
	v_lshlrev_b64 v[76:77], 12, v[76:77]
	v_lshlrev_b64 v[78:79], 12, v[78:79]
	v_lshlrev_b64 v[80:81], 12, v[80:81]
	v_lshlrev_b64 v[82:83], 12, v[82:83]
	v_lshlrev_b64 v[84:85], 12, v[84:85]
	v_lshl_add_u64 v[30:31], v[86:87], 0, v[30:31]
	v_lshl_add_u64 v[34:35], v[86:87], 0, v[34:35]
	v_lshl_add_u64 v[36:37], v[86:87], 0, v[36:37]
	v_lshl_add_u64 v[46:47], v[86:87], 0, v[46:47]
	v_lshl_add_u64 v[48:49], v[86:87], 0, v[48:49]
	v_lshl_add_u64 v[50:51], v[86:87], 0, v[50:51]
	v_lshl_add_u64 v[52:53], v[86:87], 0, v[52:53]
	v_lshl_add_u64 v[22:23], v[86:87], 0, v[22:23]
	v_lshl_add_u64 v[24:25], v[86:87], 0, v[24:25]
	v_lshl_add_u64 v[26:27], v[86:87], 0, v[26:27]
	v_lshl_add_u64 v[28:29], v[86:87], 0, v[28:29]
	v_lshl_add_u64 v[38:39], v[86:87], 0, v[38:39]
	v_lshl_add_u64 v[40:41], v[86:87], 0, v[40:41]
	v_lshl_add_u64 v[42:43], v[86:87], 0, v[42:43]
	v_lshl_add_u64 v[44:45], v[86:87], 0, v[44:45]
	v_lshl_add_u64 v[54:55], v[86:87], 0, v[54:55]
	v_lshl_add_u64 v[56:57], v[86:87], 0, v[56:57]
	v_lshl_add_u64 v[58:59], v[86:87], 0, v[58:59]
	v_lshl_add_u64 v[60:61], v[86:87], 0, v[60:61]
	v_lshl_add_u64 v[62:63], v[86:87], 0, v[62:63]
	v_lshl_add_u64 v[64:65], v[86:87], 0, v[64:65]
	v_lshl_add_u64 v[66:67], v[86:87], 0, v[66:67]
	v_lshl_add_u64 v[68:69], v[86:87], 0, v[68:69]
	v_lshl_add_u64 v[70:71], v[86:87], 0, v[70:71]
	v_lshl_add_u64 v[72:73], v[86:87], 0, v[72:73]
	v_lshl_add_u64 v[74:75], v[86:87], 0, v[74:75]
	v_lshl_add_u64 v[76:77], v[86:87], 0, v[76:77]
	v_lshl_add_u64 v[78:79], v[86:87], 0, v[78:79]
	v_lshl_add_u64 v[80:81], v[86:87], 0, v[80:81]
	v_lshl_add_u64 v[82:83], v[86:87], 0, v[82:83]
	v_lshl_add_u64 v[84:85], v[86:87], 0, v[84:85]
	global_load_dword v19, v[20:21], off
	global_load_dword v33, v[22:23], off
	global_load_dword v86, v[24:25], off
	global_load_dword v87, v[26:27], off
	global_load_dword v88, v[28:29], off
	global_load_dword v89, v[30:31], off
	global_load_dword v90, v[34:35], off
	global_load_dword v91, v[36:37], off
	global_load_dword v92, v[38:39], off
	global_load_dword v93, v[40:41], off
	global_load_dword v94, v[42:43], off
	global_load_dword v95, v[44:45], off
	global_load_dword v96, v[46:47], off
	global_load_dword v97, v[48:49], off
	global_load_dword v98, v[50:51], off
	global_load_dword v30, v[52:53], off
	global_load_dword v31, v[54:55], off
	global_load_dword v34, v[56:57], off
	global_load_dword v35, v[58:59], off
	global_load_dword v36, v[60:61], off
	global_load_dword v37, v[62:63], off
	global_load_dword v46, v[64:65], off
	global_load_dword v47, v[66:67], off
	global_load_dword v48, v[68:69], off
	global_load_dword v49, v[70:71], off
	global_load_dword v50, v[72:73], off
	global_load_dword v51, v[74:75], off
	global_load_dword v99, v[76:77], off
	global_load_dword v100, v[78:79], off
	global_load_dword v101, v[80:81], off
	global_load_dword v52, v[82:83], off
	global_load_dword v53, v[84:85], off
	v_add_u32_e32 v22, s10, v1
	s_ashr_i32 s7, s6, 31
	v_ashrrev_i32_e32 v23, 31, v22
	v_add_u32_e32 v24, 8, v22
	v_add_u32_e32 v26, 16, v22
	v_add_u32_e32 v28, 24, v22
	v_lshl_add_u64 v[20:21], s[6:7], 1, v[12:13]
	v_lshlrev_b64 v[22:23], 10, v[22:23]
	v_ashrrev_i32_e32 v25, 31, v24
	v_ashrrev_i32_e32 v27, 31, v26
	v_ashrrev_i32_e32 v29, 31, v28
	s_waitcnt vmcnt(30)
	ds_write2_b32 v5, v19, v33 offset1:66
	s_waitcnt vmcnt(28)
	ds_write2_b32 v5, v86, v87 offset0:132 offset1:198
	s_waitcnt vmcnt(26)
	ds_write2_b32 v7, v88, v89 offset0:8 offset1:74
	s_waitcnt vmcnt(24)
	ds_write2_b32 v7, v90, v91 offset0:140 offset1:206
	s_waitcnt vmcnt(22)
	ds_write2_b32 v9, v92, v93 offset0:16 offset1:82
	s_waitcnt vmcnt(20)
	ds_write2_b32 v9, v94, v95 offset0:148 offset1:214
	s_waitcnt vmcnt(18)
	ds_write2_b32 v14, v96, v97 offset0:24 offset1:90
	s_waitcnt vmcnt(16)
	ds_write2_b32 v14, v98, v30 offset0:156 offset1:222
	s_waitcnt vmcnt(14)
	ds_write2_b32 v15, v31, v34 offset0:32 offset1:98
	s_waitcnt vmcnt(12)
	ds_write2_b32 v15, v35, v36 offset0:164 offset1:230
	s_waitcnt vmcnt(10)
	ds_write2_b32 v16, v37, v46 offset0:40 offset1:106
	s_waitcnt vmcnt(8)
	ds_write2_b32 v16, v47, v48 offset0:172 offset1:238
	s_waitcnt vmcnt(6)
	ds_write2_b32 v17, v49, v50 offset0:48 offset1:114
	s_waitcnt vmcnt(4)
	ds_write2_b32 v17, v51, v99 offset0:180 offset1:246
	s_waitcnt vmcnt(2)
	ds_write2_b32 v18, v100, v101 offset0:56 offset1:122
	s_waitcnt vmcnt(0)
	ds_write2_b32 v18, v52, v53 offset0:188 offset1:254
	v_lshl_add_u64 v[38:39], v[20:21], 0, v[22:23]
	v_lshlrev_b64 v[22:23], 10, v[24:25]
	v_lshlrev_b64 v[24:25], 10, v[26:27]
	v_lshlrev_b64 v[26:27], 10, v[28:29]
	s_waitcnt lgkmcnt(0)
	v_lshl_add_u64 v[42:43], v[20:21], 0, v[24:25]
	v_lshl_add_u64 v[44:45], v[20:21], 0, v[26:27]
	ds_read2_b32 v[24:25], v3 offset0:33 offset1:41
	ds_read2_b32 v[26:27], v3 offset1:8
	ds_read2_b32 v[28:29], v3 offset0:66 offset1:74
	ds_read2_b32 v[30:31], v3 offset0:99 offset1:107
	ds_read2_b32 v[34:35], v3 offset0:132 offset1:140
	ds_read2_b32 v[36:37], v3 offset0:165 offset1:173
	ds_read2_b32 v[46:47], v3 offset0:198 offset1:206
	ds_read2_b32 v[48:49], v3 offset0:231 offset1:239
	ds_read2_b32 v[50:51], v3 offset0:49 offset1:57
	ds_read2_b32 v[52:53], v3 offset0:16 offset1:24
	ds_read2_b32 v[54:55], v3 offset0:82 offset1:90
	ds_read2_b32 v[56:57], v3 offset0:115 offset1:123
	ds_read2_b32 v[58:59], v3 offset0:148 offset1:156
	ds_read2_b32 v[60:61], v3 offset0:181 offset1:189
	ds_read2_b32 v[62:63], v3 offset0:214 offset1:222
	ds_read2_b32 v[64:65], v3 offset0:247 offset1:255
	v_lshl_add_u64 v[40:41], v[20:21], 0, v[22:23]
	s_waitcnt lgkmcnt(14)
	v_cvt_pk_bf16_f32 v20, v26, v24
	s_waitcnt lgkmcnt(12)
	v_cvt_pk_bf16_f32 v21, v28, v30
	s_waitcnt lgkmcnt(10)
	v_cvt_pk_bf16_f32 v22, v34, v36
	s_waitcnt lgkmcnt(8)
	v_cvt_pk_bf16_f32 v23, v46, v48
	v_cvt_pk_bf16_f32 v24, v27, v25
	v_cvt_pk_bf16_f32 v25, v29, v31
	v_cvt_pk_bf16_f32 v26, v35, v37
	v_cvt_pk_bf16_f32 v27, v47, v49
	s_waitcnt lgkmcnt(6)
	v_cvt_pk_bf16_f32 v28, v52, v50
	s_waitcnt lgkmcnt(4)
	v_cvt_pk_bf16_f32 v29, v54, v56
	s_waitcnt lgkmcnt(2)
	v_cvt_pk_bf16_f32 v30, v58, v60
	s_waitcnt lgkmcnt(0)
	v_cvt_pk_bf16_f32 v31, v62, v64
	v_cvt_pk_bf16_f32 v34, v53, v51
	v_cvt_pk_bf16_f32 v35, v55, v57
	v_cvt_pk_bf16_f32 v36, v59, v61
	v_cvt_pk_bf16_f32 v37, v63, v65
	global_store_dwordx4 v[38:39], v[20:23], off sc1
	global_store_dwordx4 v[40:41], v[24:27], off sc1
	global_store_dwordx4 v[42:43], v[28:31], off sc1
	global_store_dwordx4 v[44:45], v[34:37], off sc1
	s_waitcnt lgkmcnt(0)
	s_add_i32 s20, s20, s78
	s_add_i32 s19, s19, s18
	s_cmpk_lt_i32 s20, 0x100
	s_cbranch_scc1 .LBB0_128
	s_load_dwordx2 s[6:7], s[16:17], 0xb0
	v_lshlrev_b32_e32 v12, 2, v4
	v_mov_b32_e32 v13, 0
	s_mov_b32 s19, s88
	s_waitcnt lgkmcnt(0)
	v_lshl_add_u64 v[10:11], s[6:7], 0, v[12:13]
	v_lshlrev_b32_e32 v12, 1, v8
	v_lshl_add_u64 v[8:9], s[14:15], 0, v[12:13]
	s_mov_b64 s[6:7], 0x1008800
	v_lshl_add_u64 v[8:9], v[8:9], 0, s[6:7]
.LBB0_130:
	s_ashr_i32 s6, s19, 31
	s_lshr_b32 s6, s6, 27
	s_add_i32 s6, s19, s6
	s_ashr_i32 s7, s6, 5
	s_lshl_b32 s6, s7, 6
	s_lshl_b32 s7, s7, 10
	v_or_b32_e32 v12, s6, v2
	s_sub_i32 s10, s3, s7
	v_or_b32_e32 v22, 10, v12
	v_or_b32_e32 v24, 12, v12
	v_or_b32_e32 v26, 14, v12
	v_or_b32_e32 v38, 24, v12
	v_or_b32_e32 v40, 26, v12
	v_or_b32_e32 v42, 28, v12
	v_or_b32_e32 v44, 30, v12
	s_ashr_i32 s11, s10, 31
	v_ashrrev_i32_e32 v13, 31, v12
	v_or_b32_e32 v14, 2, v12
	v_or_b32_e32 v16, 4, v12
	v_or_b32_e32 v18, 6, v12
	v_or_b32_e32 v20, 8, v12
	v_or_b32_e32 v28, 16, v12
	v_or_b32_e32 v30, 18, v12
	v_or_b32_e32 v34, 20, v12
	v_or_b32_e32 v36, 22, v12
	v_or_b32_e32 v46, 32, v12
	v_or_b32_e32 v48, 34, v12
	v_or_b32_e32 v50, 36, v12
	v_or_b32_e32 v52, 38, v12
	v_or_b32_e32 v54, 40, v12
	v_or_b32_e32 v56, 42, v12
	v_or_b32_e32 v58, 44, v12
	v_or_b32_e32 v60, 46, v12
	v_or_b32_e32 v62, 48, v12
	v_or_b32_e32 v64, 50, v12
	v_or_b32_e32 v66, 52, v12
	v_or_b32_e32 v68, 54, v12
	v_or_b32_e32 v70, 56, v12
	v_or_b32_e32 v72, 58, v12
	v_or_b32_e32 v74, 60, v12
	v_or_b32_e32 v76, 62, v12
	v_ashrrev_i32_e32 v23, 31, v22
	v_ashrrev_i32_e32 v25, 31, v24
	v_ashrrev_i32_e32 v27, 31, v26
	v_ashrrev_i32_e32 v39, 31, v38
	v_ashrrev_i32_e32 v41, 31, v40
	v_ashrrev_i32_e32 v43, 31, v42
	v_ashrrev_i32_e32 v45, 31, v44
	v_lshl_add_u64 v[78:79], s[10:11], 2, v[10:11]
	v_lshlrev_b64 v[12:13], 12, v[12:13]
	v_ashrrev_i32_e32 v15, 31, v14
	v_ashrrev_i32_e32 v17, 31, v16
	v_ashrrev_i32_e32 v19, 31, v18
	v_ashrrev_i32_e32 v21, 31, v20
	v_ashrrev_i32_e32 v29, 31, v28
	v_ashrrev_i32_e32 v31, 31, v30
	v_ashrrev_i32_e32 v35, 31, v34
	v_ashrrev_i32_e32 v37, 31, v36
	v_ashrrev_i32_e32 v47, 31, v46
	v_ashrrev_i32_e32 v49, 31, v48
	v_ashrrev_i32_e32 v51, 31, v50
	v_ashrrev_i32_e32 v53, 31, v52
	v_ashrrev_i32_e32 v55, 31, v54
	v_ashrrev_i32_e32 v57, 31, v56
	v_ashrrev_i32_e32 v59, 31, v58
	v_ashrrev_i32_e32 v61, 31, v60
	v_ashrrev_i32_e32 v63, 31, v62
	v_ashrrev_i32_e32 v65, 31, v64
	v_ashrrev_i32_e32 v67, 31, v66
	v_ashrrev_i32_e32 v69, 31, v68
	v_ashrrev_i32_e32 v71, 31, v70
	v_ashrrev_i32_e32 v73, 31, v72
	v_ashrrev_i32_e32 v75, 31, v74
	v_ashrrev_i32_e32 v77, 31, v76
	v_lshlrev_b64 v[22:23], 12, v[22:23]
	v_lshlrev_b64 v[24:25], 12, v[24:25]
	v_lshlrev_b64 v[26:27], 12, v[26:27]
	v_lshlrev_b64 v[38:39], 12, v[38:39]
	v_lshlrev_b64 v[40:41], 12, v[40:41]
	v_lshlrev_b64 v[42:43], 12, v[42:43]
	v_lshlrev_b64 v[44:45], 12, v[44:45]
	v_lshl_add_u64 v[12:13], v[78:79], 0, v[12:13]
	v_lshlrev_b64 v[14:15], 12, v[14:15]
	v_lshlrev_b64 v[16:17], 12, v[16:17]
	v_lshlrev_b64 v[18:19], 12, v[18:19]
	v_lshlrev_b64 v[20:21], 12, v[20:21]
	v_lshlrev_b64 v[28:29], 12, v[28:29]
	v_lshlrev_b64 v[30:31], 12, v[30:31]
	v_lshlrev_b64 v[34:35], 12, v[34:35]
	v_lshlrev_b64 v[36:37], 12, v[36:37]
	v_lshlrev_b64 v[46:47], 12, v[46:47]
	v_lshlrev_b64 v[48:49], 12, v[48:49]
	v_lshlrev_b64 v[50:51], 12, v[50:51]
	v_lshlrev_b64 v[52:53], 12, v[52:53]
	v_lshlrev_b64 v[54:55], 12, v[54:55]
	v_lshlrev_b64 v[56:57], 12, v[56:57]
	v_lshlrev_b64 v[58:59], 12, v[58:59]
	v_lshlrev_b64 v[60:61], 12, v[60:61]
	v_lshlrev_b64 v[62:63], 12, v[62:63]
	v_lshlrev_b64 v[64:65], 12, v[64:65]
	v_lshlrev_b64 v[66:67], 12, v[66:67]
	v_lshlrev_b64 v[68:69], 12, v[68:69]
	v_lshlrev_b64 v[70:71], 12, v[70:71]
	v_lshlrev_b64 v[72:73], 12, v[72:73]
	v_lshlrev_b64 v[74:75], 12, v[74:75]
	v_lshlrev_b64 v[76:77], 12, v[76:77]
	v_lshl_add_u64 v[22:23], v[78:79], 0, v[22:23]
	v_lshl_add_u64 v[24:25], v[78:79], 0, v[24:25]
	v_lshl_add_u64 v[26:27], v[78:79], 0, v[26:27]
	v_lshl_add_u64 v[38:39], v[78:79], 0, v[38:39]
	v_lshl_add_u64 v[40:41], v[78:79], 0, v[40:41]
	v_lshl_add_u64 v[42:43], v[78:79], 0, v[42:43]
	v_lshl_add_u64 v[44:45], v[78:79], 0, v[44:45]
	v_lshl_add_u64 v[14:15], v[78:79], 0, v[14:15]
	v_lshl_add_u64 v[16:17], v[78:79], 0, v[16:17]
	v_lshl_add_u64 v[18:19], v[78:79], 0, v[18:19]
	v_lshl_add_u64 v[20:21], v[78:79], 0, v[20:21]
	v_lshl_add_u64 v[28:29], v[78:79], 0, v[28:29]
	v_lshl_add_u64 v[30:31], v[78:79], 0, v[30:31]
	v_lshl_add_u64 v[34:35], v[78:79], 0, v[34:35]
	v_lshl_add_u64 v[36:37], v[78:79], 0, v[36:37]
	v_lshl_add_u64 v[46:47], v[78:79], 0, v[46:47]
	v_lshl_add_u64 v[48:49], v[78:79], 0, v[48:49]
	v_lshl_add_u64 v[50:51], v[78:79], 0, v[50:51]
	v_lshl_add_u64 v[52:53], v[78:79], 0, v[52:53]
	v_lshl_add_u64 v[54:55], v[78:79], 0, v[54:55]
	v_lshl_add_u64 v[56:57], v[78:79], 0, v[56:57]
	v_lshl_add_u64 v[58:59], v[78:79], 0, v[58:59]
	v_lshl_add_u64 v[60:61], v[78:79], 0, v[60:61]
	v_lshl_add_u64 v[62:63], v[78:79], 0, v[62:63]
	v_lshl_add_u64 v[64:65], v[78:79], 0, v[64:65]
	v_lshl_add_u64 v[66:67], v[78:79], 0, v[66:67]
	v_lshl_add_u64 v[68:69], v[78:79], 0, v[68:69]
	v_lshl_add_u64 v[70:71], v[78:79], 0, v[70:71]
	v_lshl_add_u64 v[72:73], v[78:79], 0, v[72:73]
	v_lshl_add_u64 v[74:75], v[78:79], 0, v[74:75]
	v_lshl_add_u64 v[76:77], v[78:79], 0, v[76:77]
	global_load_dword v7, v[12:13], off
	global_load_dword v33, v[14:15], off
	global_load_dword v78, v[16:17], off
	global_load_dword v79, v[18:19], off
	global_load_dword v80, v[20:21], off
	global_load_dword v81, v[22:23], off
	global_load_dword v82, v[24:25], off
	global_load_dword v83, v[26:27], off
	global_load_dword v84, v[28:29], off
	global_load_dword v85, v[30:31], off
	global_load_dword v86, v[34:35], off
	global_load_dword v87, v[36:37], off
	global_load_dword v88, v[38:39], off
	global_load_dword v89, v[40:41], off
	global_load_dword v90, v[42:43], off
	global_load_dword v22, v[44:45], off
	global_load_dword v23, v[46:47], off
	global_load_dword v24, v[48:49], off
	global_load_dword v25, v[50:51], off
	global_load_dword v26, v[52:53], off
	global_load_dword v27, v[54:55], off
	global_load_dword v38, v[56:57], off
	global_load_dword v39, v[58:59], off
	global_load_dword v40, v[60:61], off
	global_load_dword v41, v[62:63], off
	global_load_dword v42, v[64:65], off
	global_load_dword v43, v[66:67], off
	global_load_dword v91, v[68:69], off
	global_load_dword v92, v[70:71], off
	global_load_dword v93, v[72:73], off
	global_load_dword v44, v[74:75], off
	global_load_dword v45, v[76:77], off
	v_add_u32_e32 v14, s10, v1
	s_ashr_i32 s7, s6, 31
	v_ashrrev_i32_e32 v15, 31, v14
	v_add_u32_e32 v16, 8, v14
	v_add_u32_e32 v18, 16, v14
	v_add_u32_e32 v20, 24, v14
	v_add_u32_e32 v46, 0x400, v5
	v_add_u32_e32 v47, 0x800, v5
	v_add_u32_e32 v48, 0xc00, v5
	v_add_u32_e32 v49, 0x1000, v5
	v_add_u32_e32 v50, 0x1400, v5
	v_add_u32_e32 v51, 0x1800, v5
	v_add_u32_e32 v52, 0x1c00, v5
	v_lshl_add_u64 v[12:13], s[6:7], 1, v[8:9]
	v_lshlrev_b64 v[14:15], 10, v[14:15]
	v_ashrrev_i32_e32 v17, 31, v16
	v_ashrrev_i32_e32 v19, 31, v18
	v_ashrrev_i32_e32 v21, 31, v20
	s_waitcnt vmcnt(30)
	ds_write2_b32 v5, v7, v33 offset1:66
	s_waitcnt vmcnt(28)
	ds_write2_b32 v5, v78, v79 offset0:132 offset1:198
	s_waitcnt vmcnt(26)
	ds_write2_b32 v46, v80, v81 offset0:8 offset1:74
	s_waitcnt vmcnt(24)
	ds_write2_b32 v46, v82, v83 offset0:140 offset1:206
	s_waitcnt vmcnt(22)
	ds_write2_b32 v47, v84, v85 offset0:16 offset1:82
	s_waitcnt vmcnt(20)
	ds_write2_b32 v47, v86, v87 offset0:148 offset1:214
	s_waitcnt vmcnt(18)
	ds_write2_b32 v48, v88, v89 offset0:24 offset1:90
	s_waitcnt vmcnt(16)
	ds_write2_b32 v48, v90, v22 offset0:156 offset1:222
	s_waitcnt vmcnt(14)
	ds_write2_b32 v49, v23, v24 offset0:32 offset1:98
	s_waitcnt vmcnt(12)
	ds_write2_b32 v49, v25, v26 offset0:164 offset1:230
	s_waitcnt vmcnt(10)
	ds_write2_b32 v50, v27, v38 offset0:40 offset1:106
	s_waitcnt vmcnt(8)
	ds_write2_b32 v50, v39, v40 offset0:172 offset1:238
	s_waitcnt vmcnt(6)
	ds_write2_b32 v51, v41, v42 offset0:48 offset1:114
	s_waitcnt vmcnt(4)
	ds_write2_b32 v51, v43, v91 offset0:180 offset1:246
	s_waitcnt vmcnt(2)
	ds_write2_b32 v52, v92, v93 offset0:56 offset1:122
	s_waitcnt vmcnt(0)
	ds_write2_b32 v52, v44, v45 offset0:188 offset1:254
	v_lshl_add_u64 v[28:29], v[12:13], 0, v[14:15]
	v_lshlrev_b64 v[14:15], 10, v[16:17]
	v_lshlrev_b64 v[16:17], 10, v[18:19]
	v_lshlrev_b64 v[18:19], 10, v[20:21]
	s_waitcnt lgkmcnt(0)
	v_lshl_add_u64 v[34:35], v[12:13], 0, v[16:17]
	v_lshl_add_u64 v[36:37], v[12:13], 0, v[18:19]
	ds_read2_b32 v[16:17], v3 offset0:33 offset1:41
	ds_read2_b32 v[18:19], v3 offset1:8
	ds_read2_b32 v[20:21], v3 offset0:66 offset1:74
	ds_read2_b32 v[22:23], v3 offset0:99 offset1:107
	ds_read2_b32 v[24:25], v3 offset0:132 offset1:140
	ds_read2_b32 v[26:27], v3 offset0:165 offset1:173
	ds_read2_b32 v[38:39], v3 offset0:198 offset1:206
	ds_read2_b32 v[40:41], v3 offset0:231 offset1:239
	ds_read2_b32 v[42:43], v3 offset0:49 offset1:57
	ds_read2_b32 v[44:45], v3 offset0:16 offset1:24
	ds_read2_b32 v[46:47], v3 offset0:82 offset1:90
	ds_read2_b32 v[48:49], v3 offset0:115 offset1:123
	ds_read2_b32 v[50:51], v3 offset0:148 offset1:156
	ds_read2_b32 v[52:53], v3 offset0:181 offset1:189
	ds_read2_b32 v[54:55], v3 offset0:214 offset1:222
	ds_read2_b32 v[56:57], v3 offset0:247 offset1:255
	v_lshl_add_u64 v[30:31], v[12:13], 0, v[14:15]
	s_waitcnt lgkmcnt(14)
	v_cvt_pk_bf16_f32 v12, v18, v16
	s_waitcnt lgkmcnt(12)
	v_cvt_pk_bf16_f32 v13, v20, v22
	s_waitcnt lgkmcnt(10)
	v_cvt_pk_bf16_f32 v14, v24, v26
	s_waitcnt lgkmcnt(8)
	v_cvt_pk_bf16_f32 v15, v38, v40
	v_cvt_pk_bf16_f32 v16, v19, v17
	v_cvt_pk_bf16_f32 v17, v21, v23
	v_cvt_pk_bf16_f32 v18, v25, v27
	v_cvt_pk_bf16_f32 v19, v39, v41
	s_waitcnt lgkmcnt(6)
	v_cvt_pk_bf16_f32 v20, v44, v42
	s_waitcnt lgkmcnt(4)
	v_cvt_pk_bf16_f32 v21, v46, v48
	s_waitcnt lgkmcnt(2)
	v_cvt_pk_bf16_f32 v22, v50, v52
	s_waitcnt lgkmcnt(0)
	v_cvt_pk_bf16_f32 v23, v54, v56
	v_cvt_pk_bf16_f32 v24, v45, v43
	v_cvt_pk_bf16_f32 v25, v47, v49
	v_cvt_pk_bf16_f32 v26, v51, v53
	v_cvt_pk_bf16_f32 v27, v55, v57
	global_store_dwordx4 v[28:29], v[12:15], off sc1
	global_store_dwordx4 v[30:31], v[16:19], off sc1
	global_store_dwordx4 v[34:35], v[20:23], off sc1
	global_store_dwordx4 v[36:37], v[24:27], off sc1
	s_waitcnt lgkmcnt(0)
	s_add_i32 s19, s19, s78
	s_add_i32 s3, s3, s18
	s_cmpk_lt_i32 s19, 0x100
	s_cbranch_scc1 .LBB0_130

.LBB0_133:
	s_ashr_i32 s6, s11, 31
	s_lshr_b32 s6, s6, 27
	s_add_i32 s6, s11, s6
	s_ashr_i32 s7, s6, 5
	s_lshl_b32 s6, s7, 6
	s_lshl_b32 s7, s7, 10
	v_or_b32_e32 v18, s6, v2
	s_sub_i32 s8, s3, s7
	v_or_b32_e32 v28, 10, v18
	v_or_b32_e32 v30, 12, v18
	v_or_b32_e32 v32, 14, v18
	v_or_b32_e32 v42, 24, v18
	v_or_b32_e32 v44, 26, v18
	v_or_b32_e32 v46, 28, v18
	v_or_b32_e32 v48, 30, v18
	s_ashr_i32 s9, s8, 31
	v_ashrrev_i32_e32 v19, 31, v18
	v_or_b32_e32 v20, 2, v18
	v_or_b32_e32 v22, 4, v18
	v_or_b32_e32 v24, 6, v18
	v_or_b32_e32 v26, 8, v18
	v_or_b32_e32 v34, 16, v18
	v_or_b32_e32 v36, 18, v18
	v_or_b32_e32 v38, 20, v18
	v_or_b32_e32 v40, 22, v18
	v_or_b32_e32 v50, 32, v18
	v_or_b32_e32 v52, 34, v18
	v_or_b32_e32 v54, 36, v18
	v_or_b32_e32 v56, 38, v18
	v_or_b32_e32 v58, 40, v18
	v_or_b32_e32 v60, 42, v18
	v_or_b32_e32 v62, 44, v18
	v_or_b32_e32 v64, 46, v18
	v_or_b32_e32 v66, 48, v18
	v_or_b32_e32 v68, 50, v18
	v_or_b32_e32 v70, 52, v18
	v_or_b32_e32 v72, 54, v18
	v_or_b32_e32 v74, 56, v18
	v_or_b32_e32 v76, 58, v18
	v_or_b32_e32 v78, 60, v18
	v_or_b32_e32 v80, 62, v18
	v_ashrrev_i32_e32 v29, 31, v28
	v_ashrrev_i32_e32 v31, 31, v30
	v_ashrrev_i32_e32 v33, 31, v32
	v_ashrrev_i32_e32 v43, 31, v42
	v_ashrrev_i32_e32 v45, 31, v44
	v_ashrrev_i32_e32 v47, 31, v46
	v_ashrrev_i32_e32 v49, 31, v48
	v_lshl_add_u64 v[82:83], s[8:9], 2, v[4:5]
	v_lshlrev_b64 v[18:19], 12, v[18:19]
	v_ashrrev_i32_e32 v21, 31, v20
	v_ashrrev_i32_e32 v23, 31, v22
	v_ashrrev_i32_e32 v25, 31, v24
	v_ashrrev_i32_e32 v27, 31, v26
	v_ashrrev_i32_e32 v35, 31, v34
	v_ashrrev_i32_e32 v37, 31, v36
	v_ashrrev_i32_e32 v39, 31, v38
	v_ashrrev_i32_e32 v41, 31, v40
	v_ashrrev_i32_e32 v51, 31, v50
	v_ashrrev_i32_e32 v53, 31, v52
	v_ashrrev_i32_e32 v55, 31, v54
	v_ashrrev_i32_e32 v57, 31, v56
	v_ashrrev_i32_e32 v59, 31, v58
	v_ashrrev_i32_e32 v61, 31, v60
	v_ashrrev_i32_e32 v63, 31, v62
	v_ashrrev_i32_e32 v65, 31, v64
	v_ashrrev_i32_e32 v67, 31, v66
	v_ashrrev_i32_e32 v69, 31, v68
	v_ashrrev_i32_e32 v71, 31, v70
	v_ashrrev_i32_e32 v73, 31, v72
	v_ashrrev_i32_e32 v75, 31, v74
	v_ashrrev_i32_e32 v77, 31, v76
	v_ashrrev_i32_e32 v79, 31, v78
	v_ashrrev_i32_e32 v81, 31, v80
	v_lshlrev_b64 v[28:29], 12, v[28:29]
	v_lshlrev_b64 v[30:31], 12, v[30:31]
	v_lshlrev_b64 v[32:33], 12, v[32:33]
	v_lshlrev_b64 v[42:43], 12, v[42:43]
	v_lshlrev_b64 v[44:45], 12, v[44:45]
	v_lshlrev_b64 v[46:47], 12, v[46:47]
	v_lshlrev_b64 v[48:49], 12, v[48:49]
	v_lshl_add_u64 v[18:19], v[82:83], 0, v[18:19]
	v_lshlrev_b64 v[20:21], 12, v[20:21]
	v_lshlrev_b64 v[22:23], 12, v[22:23]
	v_lshlrev_b64 v[24:25], 12, v[24:25]
	v_lshlrev_b64 v[26:27], 12, v[26:27]
	v_lshlrev_b64 v[34:35], 12, v[34:35]
	v_lshlrev_b64 v[36:37], 12, v[36:37]
	v_lshlrev_b64 v[38:39], 12, v[38:39]
	v_lshlrev_b64 v[40:41], 12, v[40:41]
	v_lshlrev_b64 v[50:51], 12, v[50:51]
	v_lshlrev_b64 v[52:53], 12, v[52:53]
	v_lshlrev_b64 v[54:55], 12, v[54:55]
	v_lshlrev_b64 v[56:57], 12, v[56:57]
	v_lshlrev_b64 v[58:59], 12, v[58:59]
	v_lshlrev_b64 v[60:61], 12, v[60:61]
	v_lshlrev_b64 v[62:63], 12, v[62:63]
	v_lshlrev_b64 v[64:65], 12, v[64:65]
	v_lshlrev_b64 v[66:67], 12, v[66:67]
	v_lshlrev_b64 v[68:69], 12, v[68:69]
	v_lshlrev_b64 v[70:71], 12, v[70:71]
	v_lshlrev_b64 v[72:73], 12, v[72:73]
	v_lshlrev_b64 v[74:75], 12, v[74:75]
	v_lshlrev_b64 v[76:77], 12, v[76:77]
	v_lshlrev_b64 v[78:79], 12, v[78:79]
	v_lshlrev_b64 v[80:81], 12, v[80:81]
	v_lshl_add_u64 v[28:29], v[82:83], 0, v[28:29]
	v_lshl_add_u64 v[30:31], v[82:83], 0, v[30:31]
	v_lshl_add_u64 v[32:33], v[82:83], 0, v[32:33]
	v_lshl_add_u64 v[42:43], v[82:83], 0, v[42:43]
	v_lshl_add_u64 v[44:45], v[82:83], 0, v[44:45]
	v_lshl_add_u64 v[46:47], v[82:83], 0, v[46:47]
	v_lshl_add_u64 v[48:49], v[82:83], 0, v[48:49]
	v_lshl_add_u64 v[20:21], v[82:83], 0, v[20:21]
	v_lshl_add_u64 v[22:23], v[82:83], 0, v[22:23]
	v_lshl_add_u64 v[24:25], v[82:83], 0, v[24:25]
	v_lshl_add_u64 v[26:27], v[82:83], 0, v[26:27]
	v_lshl_add_u64 v[34:35], v[82:83], 0, v[34:35]
	v_lshl_add_u64 v[36:37], v[82:83], 0, v[36:37]
	v_lshl_add_u64 v[38:39], v[82:83], 0, v[38:39]
	v_lshl_add_u64 v[40:41], v[82:83], 0, v[40:41]
	v_lshl_add_u64 v[50:51], v[82:83], 0, v[50:51]
	v_lshl_add_u64 v[52:53], v[82:83], 0, v[52:53]
	v_lshl_add_u64 v[54:55], v[82:83], 0, v[54:55]
	v_lshl_add_u64 v[56:57], v[82:83], 0, v[56:57]
	v_lshl_add_u64 v[58:59], v[82:83], 0, v[58:59]
	v_lshl_add_u64 v[60:61], v[82:83], 0, v[60:61]
	v_lshl_add_u64 v[62:63], v[82:83], 0, v[62:63]
	v_lshl_add_u64 v[64:65], v[82:83], 0, v[64:65]
	v_lshl_add_u64 v[66:67], v[82:83], 0, v[66:67]
	v_lshl_add_u64 v[68:69], v[82:83], 0, v[68:69]
	v_lshl_add_u64 v[70:71], v[82:83], 0, v[70:71]
	v_lshl_add_u64 v[72:73], v[82:83], 0, v[72:73]
	v_lshl_add_u64 v[74:75], v[82:83], 0, v[74:75]
	v_lshl_add_u64 v[76:77], v[82:83], 0, v[76:77]
	v_lshl_add_u64 v[78:79], v[82:83], 0, v[78:79]
	v_lshl_add_u64 v[80:81], v[82:83], 0, v[80:81]
	global_load_dword v17, v[18:19], off
	global_load_dword v82, v[20:21], off
	global_load_dword v83, v[22:23], off
	global_load_dword v84, v[24:25], off
	global_load_dword v85, v[26:27], off
	global_load_dword v86, v[28:29], off
	global_load_dword v87, v[30:31], off
	global_load_dword v88, v[32:33], off
	global_load_dword v89, v[34:35], off
	global_load_dword v90, v[36:37], off
	global_load_dword v91, v[38:39], off
	global_load_dword v92, v[40:41], off
	global_load_dword v93, v[42:43], off
	global_load_dword v94, v[44:45], off
	global_load_dword v95, v[46:47], off
	global_load_dword v28, v[48:49], off
	global_load_dword v29, v[50:51], off
	global_load_dword v30, v[52:53], off
	global_load_dword v31, v[54:55], off
	global_load_dword v32, v[56:57], off
	global_load_dword v33, v[58:59], off
	global_load_dword v42, v[60:61], off
	global_load_dword v43, v[62:63], off
	global_load_dword v44, v[64:65], off
	global_load_dword v45, v[66:67], off
	global_load_dword v46, v[68:69], off
	global_load_dword v47, v[70:71], off
	global_load_dword v96, v[72:73], off
	global_load_dword v97, v[74:75], off
	global_load_dword v98, v[76:77], off
	global_load_dword v48, v[78:79], off
	global_load_dword v49, v[80:81], off
	v_add_u32_e32 v20, s8, v1
	s_ashr_i32 s7, s6, 31
	v_ashrrev_i32_e32 v21, 31, v20
	v_add_u32_e32 v22, 8, v20
	v_add_u32_e32 v24, 16, v20
	v_add_u32_e32 v26, 24, v20
	v_lshl_add_u64 v[18:19], s[6:7], 1, v[8:9]
	v_lshlrev_b64 v[20:21], 11, v[20:21]
	v_ashrrev_i32_e32 v23, 31, v22
	v_ashrrev_i32_e32 v25, 31, v24
	v_ashrrev_i32_e32 v27, 31, v26
	s_waitcnt vmcnt(30)
	ds_write2_b32 v7, v17, v82 offset1:66
	s_waitcnt vmcnt(28)
	ds_write2_b32 v7, v83, v84 offset0:132 offset1:198
	s_waitcnt vmcnt(26)
	ds_write2_b32 v10, v85, v86 offset0:8 offset1:74
	s_waitcnt vmcnt(24)
	ds_write2_b32 v10, v87, v88 offset0:140 offset1:206
	s_waitcnt vmcnt(22)
	ds_write2_b32 v11, v89, v90 offset0:16 offset1:82
	s_waitcnt vmcnt(20)
	ds_write2_b32 v11, v91, v92 offset0:148 offset1:214
	s_waitcnt vmcnt(18)
	ds_write2_b32 v12, v93, v94 offset0:24 offset1:90
	s_waitcnt vmcnt(16)
	ds_write2_b32 v12, v95, v28 offset0:156 offset1:222
	s_waitcnt vmcnt(14)
	ds_write2_b32 v13, v29, v30 offset0:32 offset1:98
	s_waitcnt vmcnt(12)
	ds_write2_b32 v13, v31, v32 offset0:164 offset1:230
	s_waitcnt vmcnt(10)
	ds_write2_b32 v14, v33, v42 offset0:40 offset1:106
	s_waitcnt vmcnt(8)
	ds_write2_b32 v14, v43, v44 offset0:172 offset1:238
	s_waitcnt vmcnt(6)
	ds_write2_b32 v15, v45, v46 offset0:48 offset1:114
	s_waitcnt vmcnt(4)
	ds_write2_b32 v15, v47, v96 offset0:180 offset1:246
	s_waitcnt vmcnt(2)
	ds_write2_b32 v16, v97, v98 offset0:56 offset1:122
	s_waitcnt vmcnt(0)
	ds_write2_b32 v16, v48, v49 offset0:188 offset1:254
	v_lshl_add_u64 v[34:35], v[18:19], 0, v[20:21]
	v_lshlrev_b64 v[20:21], 11, v[22:23]
	v_lshlrev_b64 v[22:23], 11, v[24:25]
	v_lshlrev_b64 v[24:25], 11, v[26:27]
	s_waitcnt lgkmcnt(0)
	v_lshl_add_u64 v[38:39], v[18:19], 0, v[22:23]
	v_lshl_add_u64 v[40:41], v[18:19], 0, v[24:25]
	ds_read2_b32 v[22:23], v3 offset0:33 offset1:41
	ds_read2_b32 v[24:25], v3 offset1:8
	ds_read2_b32 v[26:27], v3 offset0:66 offset1:74
	ds_read2_b32 v[28:29], v3 offset0:99 offset1:107
	ds_read2_b32 v[30:31], v3 offset0:132 offset1:140
	ds_read2_b32 v[32:33], v3 offset0:165 offset1:173
	ds_read2_b32 v[42:43], v3 offset0:198 offset1:206
	ds_read2_b32 v[44:45], v3 offset0:231 offset1:239
	ds_read2_b32 v[46:47], v3 offset0:49 offset1:57
	ds_read2_b32 v[48:49], v3 offset0:16 offset1:24
	ds_read2_b32 v[50:51], v3 offset0:82 offset1:90
	ds_read2_b32 v[52:53], v3 offset0:115 offset1:123
	ds_read2_b32 v[54:55], v3 offset0:148 offset1:156
	ds_read2_b32 v[56:57], v3 offset0:181 offset1:189
	ds_read2_b32 v[58:59], v3 offset0:214 offset1:222
	ds_read2_b32 v[60:61], v3 offset0:247 offset1:255
	v_lshl_add_u64 v[36:37], v[18:19], 0, v[20:21]
	s_waitcnt lgkmcnt(14)
	v_cvt_pk_bf16_f32 v18, v24, v22
	s_waitcnt lgkmcnt(12)
	v_cvt_pk_bf16_f32 v19, v26, v28
	s_waitcnt lgkmcnt(10)
	v_cvt_pk_bf16_f32 v20, v30, v32
	s_waitcnt lgkmcnt(8)
	v_cvt_pk_bf16_f32 v21, v42, v44
	v_cvt_pk_bf16_f32 v22, v25, v23
	v_cvt_pk_bf16_f32 v23, v27, v29
	v_cvt_pk_bf16_f32 v24, v31, v33
	v_cvt_pk_bf16_f32 v25, v43, v45
	s_waitcnt lgkmcnt(6)
	v_cvt_pk_bf16_f32 v26, v48, v46
	s_waitcnt lgkmcnt(4)
	v_cvt_pk_bf16_f32 v27, v50, v52
	s_waitcnt lgkmcnt(2)
	v_cvt_pk_bf16_f32 v28, v54, v56
	s_waitcnt lgkmcnt(0)
	v_cvt_pk_bf16_f32 v29, v58, v60
	v_cvt_pk_bf16_f32 v30, v49, v47
	v_cvt_pk_bf16_f32 v31, v51, v53
	v_cvt_pk_bf16_f32 v32, v55, v57
	v_cvt_pk_bf16_f32 v33, v59, v61
	global_store_dwordx4 v[34:35], v[18:21], off sc1
	global_store_dwordx4 v[36:37], v[22:25], off sc1
	global_store_dwordx4 v[38:39], v[26:29], off sc1
	global_store_dwordx4 v[40:41], v[30:33], off sc1
	s_waitcnt lgkmcnt(0)
	s_add_i32 s11, s11, s78
	s_add_i32 s3, s3, s10
	s_cmpk_lt_i32 s11, 0x200
	s_cbranch_scc1 .LBB0_133

.LBB0_182:
	s_cmp_lt_i32 s23, 4
	s_cselect_b32 s24, 0, -4
	s_mov_b32 s6, 0x8000
	s_cselect_b32 s25, 10, 11
	s_mov_b32 s7, 0x28000
	v_lshl_add_u32 v142, s22, 8, v144
	s_cselect_b32 s57, s70, s72
	s_cselect_b32 s56, s69, s71
	s_cselect_b32 s6, 0x4000, s6
	s_cselect_b32 s7, 0x14000, s7
	s_add_i32 s24, s24, s23
	v_lshl_or_b32 v140, v142, s25, v146
	v_ashrrev_i32_e32 v143, 31, v142
	v_lshl_add_u32 v162, s24, 8, v140
	v_lshlrev_b64 v[140:141], 6, v[142:143]
	v_lshl_add_u64 v[140:141], s[42:43], 0, v[140:141]
	global_load_dwordx4 v[150:153], v[140:141], off offset:16
	global_load_dwordx4 v[154:157], v[140:141], off offset:48
	global_load_dwordx4 v[178:181], v[140:141], off
	global_load_dwordx4 v[182:185], v[140:141], off offset:32
	s_cmp_lt_i32 s23, 2
	s_cselect_b64 vcc, -1, 0
	v_cndmask_b32_e32 v148, 1.0, v210, vcc
	s_mov_b64 s[22:23], 0x2000
	s_mov_b64 s[30:31], s[34:35]
	s_waitcnt vmcnt(0)
	v_mov_b32_e32 v158, v178
	v_mov_b32_e32 v159, v182
	v_mov_b32_e32 v182, v179
	v_mov_b32_e32 v174, v180
	v_mov_b32_e32 v175, v184
	v_mov_b32_e32 v184, v181
	v_pk_add_f32 v[158:159], v[158:159], v[182:183]
	v_pk_add_f32 v[174:175], v[174:175], v[184:185]
	s_nop 0
	v_pk_add_f32 v[158:159], v[158:159], v[174:175]
	v_mov_b32_e32 v174, v150
	v_mov_b32_e32 v175, v154
	v_mov_b32_e32 v154, v151
	v_pk_add_f32 v[150:151], v[174:175], v[154:155]
	v_mov_b32_e32 v154, v152
	v_mov_b32_e32 v155, v156
	v_mov_b32_e32 v156, v153
	v_pk_add_f32 v[152:153], v[154:155], v[156:157]
	s_nop 0
	v_pk_add_f32 v[150:151], v[150:151], v[152:153]
	v_lshl_add_u64 v[152:153], v[162:163], 1, s[56:57]
	v_pk_add_f32 v[150:151], v[158:159], v[150:151]
	v_add_u32_e32 v162, s6, v162
	v_add_f32_e32 v143, v150, v151
	v_fmamk_f32 v143, v143, 0x3a800000, v206
	v_cmp_gt_f32_e32 vcc, s11, v143
	v_mul_f32_e32 v149, 0x4b800000, v143
	s_nop 0
	v_cndmask_b32_e32 v143, v143, v149, vcc
	v_rsq_f32_e32 v143, v143
	s_nop 0
	v_mul_f32_e32 v149, 0x45800000, v143
	v_cndmask_b32_e32 v143, v143, v149, vcc
	v_mul_f32_e32 v150, v148, v143
	v_pk_mul_f32 v[126:127], v[126:127], v[150:151] op_sel_hi:[1,0]
	v_pk_mul_f32 v[124:125], v[124:125], v[150:151] op_sel_hi:[1,0]
	v_pk_mul_f32 v[154:155], v[122:123], v[150:151] op_sel_hi:[1,0]
	v_pk_mul_f32 v[122:123], v[120:121], v[150:151] op_sel_hi:[1,0]
	v_cvt_pk_bf16_f32 v120, v124, v125
	v_cvt_pk_bf16_f32 v121, v126, v127
	v_cvt_pk_bf16_f32 v122, v122, v123
	v_cvt_pk_bf16_f32 v123, v154, v155
	global_store_dwordx4 v[152:153], v[120:123], off sc1
	v_pk_mul_f32 v[118:119], v[118:119], v[150:151] op_sel_hi:[1,0]
	v_pk_mul_f32 v[116:117], v[116:117], v[150:151] op_sel_hi:[1,0]
	v_pk_mul_f32 v[120:121], v[114:115], v[150:151] op_sel_hi:[1,0]
	v_pk_mul_f32 v[114:115], v[112:113], v[150:151] op_sel_hi:[1,0]
	v_cvt_pk_bf16_f32 v112, v116, v117
	v_cvt_pk_bf16_f32 v113, v118, v119
	v_cvt_pk_bf16_f32 v114, v114, v115
	v_cvt_pk_bf16_f32 v115, v120, v121
	global_store_dwordx4 v[152:153], v[112:115], off offset:256 sc1
	s_nop 1
	v_or_b32_e32 v112, 16, v142
	v_ashrrev_i32_e32 v113, 31, v112
	v_lshlrev_b64 v[112:113], 6, v[112:113]
	v_lshl_add_u64 v[124:125], s[42:43], 0, v[112:113]
	global_load_dwordx4 v[112:115], v[124:125], off offset:16
	global_load_dwordx4 v[116:119], v[124:125], off offset:48
	global_load_dwordx4 v[120:123], v[124:125], off
	s_nop 0
	global_load_dwordx4 v[124:127], v[124:125], off offset:32
	s_waitcnt vmcnt(1)
	v_mov_b32_e32 v150, v120
	s_waitcnt vmcnt(0)
	v_mov_b32_e32 v151, v124
	v_mov_b32_e32 v124, v121
	v_pk_add_f32 v[120:121], v[150:151], v[124:125]
	v_mov_b32_e32 v124, v122
	v_mov_b32_e32 v125, v126
	v_mov_b32_e32 v126, v123
	v_pk_add_f32 v[122:123], v[124:125], v[126:127]
	s_nop 0
	v_pk_add_f32 v[120:121], v[120:121], v[122:123]
	v_mov_b32_e32 v122, v112
	v_mov_b32_e32 v123, v116
	v_mov_b32_e32 v116, v113
	v_pk_add_f32 v[112:113], v[122:123], v[116:117]
	v_mov_b32_e32 v116, v114
	v_mov_b32_e32 v117, v118
	v_mov_b32_e32 v118, v115
	v_pk_add_f32 v[114:115], v[116:117], v[118:119]
	s_nop 0
	v_pk_add_f32 v[112:113], v[112:113], v[114:115]
	v_lshl_add_u64 v[114:115], v[162:163], 1, s[56:57]
	v_pk_add_f32 v[112:113], v[120:121], v[112:113]
	v_add_u32_e32 v162, s6, v162
	v_add_f32_e32 v112, v112, v113
	v_fmamk_f32 v112, v112, 0x3a800000, v206
	v_cmp_gt_f32_e32 vcc, s11, v112
	v_mul_f32_e32 v113, 0x4b800000, v112
	s_nop 0
	v_cndmask_b32_e32 v112, v112, v113, vcc
	v_rsq_f32_e32 v112, v112
	s_nop 0
	v_mul_f32_e32 v113, 0x45800000, v112
	v_cndmask_b32_e32 v112, v112, v113, vcc
	v_mul_f32_e32 v112, v148, v112
	v_pk_mul_f32 v[110:111], v[110:111], v[112:113] op_sel_hi:[1,0]
	v_pk_mul_f32 v[108:109], v[108:109], v[112:113] op_sel_hi:[1,0]
	v_pk_mul_f32 v[116:117], v[106:107], v[112:113] op_sel_hi:[1,0]
	v_pk_mul_f32 v[106:107], v[104:105], v[112:113] op_sel_hi:[1,0]
	v_cvt_pk_bf16_f32 v104, v108, v109
	v_cvt_pk_bf16_f32 v105, v110, v111
	v_cvt_pk_bf16_f32 v106, v106, v107
	v_cvt_pk_bf16_f32 v107, v116, v117
	global_store_dwordx4 v[114:115], v[104:107], off sc1
	v_pk_mul_f32 v[102:103], v[102:103], v[112:113] op_sel_hi:[1,0]
	v_pk_mul_f32 v[100:101], v[100:101], v[112:113] op_sel_hi:[1,0]
	v_pk_mul_f32 v[104:105], v[98:99], v[112:113] op_sel_hi:[1,0]
	v_pk_mul_f32 v[98:99], v[96:97], v[112:113] op_sel_hi:[1,0]
	v_cvt_pk_bf16_f32 v96, v100, v101
	v_cvt_pk_bf16_f32 v97, v102, v103
	v_cvt_pk_bf16_f32 v98, v98, v99
	v_cvt_pk_bf16_f32 v99, v104, v105
	global_store_dwordx4 v[114:115], v[96:99], off offset:256 sc1
	s_nop 1
	v_or_b32_e32 v96, 32, v142
	v_ashrrev_i32_e32 v97, 31, v96
	v_lshlrev_b64 v[96:97], 6, v[96:97]
	v_lshl_add_u64 v[108:109], s[42:43], 0, v[96:97]
	global_load_dwordx4 v[96:99], v[108:109], off offset:16
	global_load_dwordx4 v[100:103], v[108:109], off offset:48
	global_load_dwordx4 v[104:107], v[108:109], off
	s_nop 0
	global_load_dwordx4 v[108:111], v[108:109], off offset:32
	s_waitcnt vmcnt(1)
	v_mov_b32_e32 v112, v104
	s_waitcnt vmcnt(0)
	v_mov_b32_e32 v113, v108
	v_mov_b32_e32 v108, v105
	v_pk_add_f32 v[104:105], v[112:113], v[108:109]
	v_mov_b32_e32 v108, v106
	v_mov_b32_e32 v109, v110
	v_mov_b32_e32 v110, v107
	v_pk_add_f32 v[106:107], v[108:109], v[110:111]
	s_nop 0
	v_pk_add_f32 v[104:105], v[104:105], v[106:107]
	v_mov_b32_e32 v106, v96
	v_mov_b32_e32 v107, v100
	v_mov_b32_e32 v100, v97
	v_pk_add_f32 v[96:97], v[106:107], v[100:101]
	v_mov_b32_e32 v100, v98
	v_mov_b32_e32 v101, v102
	v_mov_b32_e32 v102, v99
	v_pk_add_f32 v[98:99], v[100:101], v[102:103]
	s_nop 0
	v_pk_add_f32 v[96:97], v[96:97], v[98:99]
	v_lshl_add_u64 v[98:99], v[162:163], 1, s[56:57]
	v_pk_add_f32 v[96:97], v[104:105], v[96:97]
	v_add_u32_e32 v162, s6, v162
	v_add_f32_e32 v96, v96, v97
	v_fmamk_f32 v96, v96, 0x3a800000, v206
	v_cmp_gt_f32_e32 vcc, s11, v96
	v_mul_f32_e32 v97, 0x4b800000, v96
	s_nop 0
	v_cndmask_b32_e32 v96, v96, v97, vcc
	v_rsq_f32_e32 v96, v96
	s_nop 0
	v_mul_f32_e32 v97, 0x45800000, v96
	v_cndmask_b32_e32 v96, v96, v97, vcc
	v_mul_f32_e32 v96, v148, v96
	v_pk_mul_f32 v[94:95], v[94:95], v[96:97] op_sel_hi:[1,0]
	v_pk_mul_f32 v[92:93], v[92:93], v[96:97] op_sel_hi:[1,0]
	v_pk_mul_f32 v[100:101], v[90:91], v[96:97] op_sel_hi:[1,0]
	v_pk_mul_f32 v[90:91], v[88:89], v[96:97] op_sel_hi:[1,0]
	v_cvt_pk_bf16_f32 v88, v92, v93
	v_cvt_pk_bf16_f32 v89, v94, v95
	v_cvt_pk_bf16_f32 v90, v90, v91
	v_cvt_pk_bf16_f32 v91, v100, v101
	global_store_dwordx4 v[98:99], v[88:91], off sc1
	v_pk_mul_f32 v[86:87], v[86:87], v[96:97] op_sel_hi:[1,0]
	v_pk_mul_f32 v[84:85], v[84:85], v[96:97] op_sel_hi:[1,0]
	v_pk_mul_f32 v[88:89], v[82:83], v[96:97] op_sel_hi:[1,0]
	v_pk_mul_f32 v[82:83], v[80:81], v[96:97] op_sel_hi:[1,0]
	v_cvt_pk_bf16_f32 v80, v84, v85
	v_cvt_pk_bf16_f32 v81, v86, v87
	v_cvt_pk_bf16_f32 v82, v82, v83
	v_cvt_pk_bf16_f32 v83, v88, v89
	global_store_dwordx4 v[98:99], v[80:83], off offset:256 sc1
	s_nop 1
	v_or_b32_e32 v80, 48, v142
	v_ashrrev_i32_e32 v81, 31, v80
	v_lshlrev_b64 v[80:81], 6, v[80:81]
	v_lshl_add_u64 v[92:93], s[42:43], 0, v[80:81]
	global_load_dwordx4 v[80:83], v[92:93], off offset:16
	global_load_dwordx4 v[84:87], v[92:93], off offset:48
	global_load_dwordx4 v[88:91], v[92:93], off
	s_nop 0
	global_load_dwordx4 v[92:95], v[92:93], off offset:32
	s_waitcnt vmcnt(1)
	v_mov_b32_e32 v96, v88
	s_waitcnt vmcnt(0)
	v_mov_b32_e32 v97, v92
	v_mov_b32_e32 v92, v89
	v_pk_add_f32 v[88:89], v[96:97], v[92:93]
	v_mov_b32_e32 v92, v90
	v_mov_b32_e32 v93, v94
	v_mov_b32_e32 v94, v91
	v_pk_add_f32 v[90:91], v[92:93], v[94:95]
	s_nop 0
	v_pk_add_f32 v[88:89], v[88:89], v[90:91]
	v_mov_b32_e32 v90, v80
	v_mov_b32_e32 v91, v84
	v_mov_b32_e32 v84, v81
	v_pk_add_f32 v[80:81], v[90:91], v[84:85]
	v_mov_b32_e32 v84, v82
	v_mov_b32_e32 v85, v86
	v_mov_b32_e32 v86, v83
	v_pk_add_f32 v[82:83], v[84:85], v[86:87]
	s_nop 0
	v_pk_add_f32 v[80:81], v[80:81], v[82:83]
	v_lshl_add_u64 v[82:83], v[162:163], 1, s[56:57]
	v_pk_add_f32 v[80:81], v[88:89], v[80:81]
	v_add_u32_e32 v162, s7, v162
	v_add_f32_e32 v80, v80, v81
	v_fmamk_f32 v80, v80, 0x3a800000, v206
	v_cmp_gt_f32_e32 vcc, s11, v80
	v_mul_f32_e32 v81, 0x4b800000, v80
	s_movk_i32 s7, 0x2000
	v_cndmask_b32_e32 v80, v80, v81, vcc
	v_rsq_f32_e32 v80, v80
	s_nop 0
	v_mul_f32_e32 v81, 0x45800000, v80
	v_cndmask_b32_e32 v80, v80, v81, vcc
	v_mul_f32_e32 v80, v148, v80
	v_pk_mul_f32 v[78:79], v[78:79], v[80:81] op_sel_hi:[1,0]
	v_pk_mul_f32 v[76:77], v[76:77], v[80:81] op_sel_hi:[1,0]
	v_pk_mul_f32 v[84:85], v[74:75], v[80:81] op_sel_hi:[1,0]
	v_pk_mul_f32 v[74:75], v[72:73], v[80:81] op_sel_hi:[1,0]
	v_cvt_pk_bf16_f32 v72, v76, v77
	v_cvt_pk_bf16_f32 v73, v78, v79
	v_cvt_pk_bf16_f32 v74, v74, v75
	v_cvt_pk_bf16_f32 v75, v84, v85
	global_store_dwordx4 v[82:83], v[72:75], off sc1
	v_pk_mul_f32 v[70:71], v[70:71], v[80:81] op_sel_hi:[1,0]
	v_pk_mul_f32 v[68:69], v[68:69], v[80:81] op_sel_hi:[1,0]
	v_pk_mul_f32 v[72:73], v[66:67], v[80:81] op_sel_hi:[1,0]
	v_pk_mul_f32 v[66:67], v[64:65], v[80:81] op_sel_hi:[1,0]
	v_cvt_pk_bf16_f32 v64, v68, v69
	v_cvt_pk_bf16_f32 v65, v70, v71
	v_cvt_pk_bf16_f32 v66, v66, v67
	v_cvt_pk_bf16_f32 v67, v72, v73
	global_store_dwordx4 v[82:83], v[64:67], off offset:256 sc1
	v_lshl_add_u64 v[78:79], v[140:141], 0, s[22:23]
	s_mov_b64 s[22:23], 0x2400
	v_add_co_u32_e32 v64, vcc, s7, v140
	s_nop 1
	v_addc_co_u32_e32 v65, vcc, 0, v141, vcc
	global_load_dwordx4 v[66:69], v[64:65], off
	global_load_dwordx4 v[70:73], v[78:79], off offset:16
	global_load_dwordx4 v[74:77], v[78:79], off offset:48
	s_nop 0
	global_load_dwordx4 v[78:81], v[78:79], off offset:32
	s_waitcnt vmcnt(3)
	v_mov_b32_e32 v82, v66
	s_waitcnt vmcnt(0)
	v_mov_b32_e32 v83, v78
	v_mov_b32_e32 v78, v67
	v_pk_add_f32 v[66:67], v[82:83], v[78:79]
	v_mov_b32_e32 v78, v68
	v_mov_b32_e32 v79, v80
	v_mov_b32_e32 v80, v69
	v_pk_add_f32 v[68:69], v[78:79], v[80:81]
	s_nop 0
	v_pk_add_f32 v[66:67], v[66:67], v[68:69]
	v_mov_b32_e32 v68, v70
	v_mov_b32_e32 v69, v74
	v_mov_b32_e32 v74, v71
	v_mov_b32_e32 v70, v72
	v_mov_b32_e32 v71, v76
	v_mov_b32_e32 v76, v73
	v_pk_add_f32 v[68:69], v[68:69], v[74:75]
	v_pk_add_f32 v[70:71], v[70:71], v[76:77]
	s_nop 0
	v_pk_add_f32 v[68:69], v[68:69], v[70:71]
	s_nop 0
	v_pk_add_f32 v[66:67], v[66:67], v[68:69]
	v_lshl_add_u64 v[68:69], v[162:163], 1, s[56:57]
	v_add_f32_e32 v66, v66, v67
	v_fmamk_f32 v66, v66, 0x3a800000, v206
	v_cmp_gt_f32_e32 vcc, s11, v66
	v_mul_f32_e32 v67, 0x4b800000, v66
	v_add_u32_e32 v162, s6, v162
	v_cndmask_b32_e32 v66, v66, v67, vcc
	v_rsq_f32_e32 v66, v66
	s_nop 0
	v_mul_f32_e32 v67, 0x45800000, v66
	v_cndmask_b32_e32 v66, v66, v67, vcc
	v_mul_f32_e32 v66, v148, v66
	v_pk_mul_f32 v[62:63], v[62:63], v[66:67] op_sel_hi:[1,0]
	v_pk_mul_f32 v[60:61], v[60:61], v[66:67] op_sel_hi:[1,0]
	v_pk_mul_f32 v[70:71], v[58:59], v[66:67] op_sel_hi:[1,0]
	v_pk_mul_f32 v[58:59], v[56:57], v[66:67] op_sel_hi:[1,0]
	v_cvt_pk_bf16_f32 v56, v60, v61
	v_cvt_pk_bf16_f32 v57, v62, v63
	v_cvt_pk_bf16_f32 v58, v58, v59
	v_cvt_pk_bf16_f32 v59, v70, v71
	global_store_dwordx4 v[68:69], v[56:59], off sc1
	v_pk_mul_f32 v[54:55], v[54:55], v[66:67] op_sel_hi:[1,0]
	v_pk_mul_f32 v[52:53], v[52:53], v[66:67] op_sel_hi:[1,0]
	v_pk_mul_f32 v[56:57], v[50:51], v[66:67] op_sel_hi:[1,0]
	v_pk_mul_f32 v[50:51], v[48:49], v[66:67] op_sel_hi:[1,0]
	v_cvt_pk_bf16_f32 v48, v52, v53
	v_cvt_pk_bf16_f32 v49, v54, v55
	v_cvt_pk_bf16_f32 v50, v50, v51
	v_cvt_pk_bf16_f32 v51, v56, v57
	global_store_dwordx4 v[68:69], v[48:51], off offset:256 sc1
	v_lshl_add_u64 v[60:61], v[140:141], 0, s[22:23]
	global_load_dwordx4 v[48:51], v[64:65], off offset:1024
	global_load_dwordx4 v[52:55], v[60:61], off offset:16
	global_load_dwordx4 v[56:59], v[60:61], off offset:48
	s_nop 0
	global_load_dwordx4 v[60:63], v[60:61], off offset:32
	s_mov_b64 s[22:23], 0x2800
	s_waitcnt vmcnt(3)
	v_mov_b32_e32 v66, v48
	s_waitcnt vmcnt(0)
	v_mov_b32_e32 v67, v60
	v_mov_b32_e32 v60, v49
	v_pk_add_f32 v[48:49], v[66:67], v[60:61]
	v_mov_b32_e32 v60, v50
	v_mov_b32_e32 v61, v62
	v_mov_b32_e32 v62, v51
	v_pk_add_f32 v[50:51], v[60:61], v[62:63]
	s_nop 0
	v_pk_add_f32 v[48:49], v[48:49], v[50:51]
	v_mov_b32_e32 v50, v52
	v_mov_b32_e32 v51, v56
	v_mov_b32_e32 v56, v53
	v_mov_b32_e32 v52, v54
	v_mov_b32_e32 v53, v58
	v_mov_b32_e32 v58, v55
	v_pk_add_f32 v[50:51], v[50:51], v[56:57]
	v_pk_add_f32 v[52:53], v[52:53], v[58:59]
	s_nop 0
	v_pk_add_f32 v[50:51], v[50:51], v[52:53]
	s_nop 0
	v_pk_add_f32 v[48:49], v[48:49], v[50:51]
	v_lshl_add_u64 v[50:51], v[162:163], 1, s[56:57]
	v_add_f32_e32 v48, v48, v49
	v_fmamk_f32 v48, v48, 0x3a800000, v206
	v_cmp_gt_f32_e32 vcc, s11, v48
	v_mul_f32_e32 v49, 0x4b800000, v48
	v_add_u32_e32 v162, s6, v162
	v_cndmask_b32_e32 v48, v48, v49, vcc
	v_rsq_f32_e32 v48, v48
	s_nop 0
	v_mul_f32_e32 v49, 0x45800000, v48
	v_cndmask_b32_e32 v48, v48, v49, vcc
	v_mul_f32_e32 v48, v148, v48
	v_pk_mul_f32 v[46:47], v[46:47], v[48:49] op_sel_hi:[1,0]
	v_pk_mul_f32 v[44:45], v[44:45], v[48:49] op_sel_hi:[1,0]
	v_pk_mul_f32 v[52:53], v[42:43], v[48:49] op_sel_hi:[1,0]
	v_pk_mul_f32 v[42:43], v[40:41], v[48:49] op_sel_hi:[1,0]
	v_cvt_pk_bf16_f32 v40, v44, v45
	v_cvt_pk_bf16_f32 v41, v46, v47
	v_cvt_pk_bf16_f32 v42, v42, v43
	v_cvt_pk_bf16_f32 v43, v52, v53
	global_store_dwordx4 v[50:51], v[40:43], off sc1
	v_pk_mul_f32 v[38:39], v[38:39], v[48:49] op_sel_hi:[1,0]
	v_pk_mul_f32 v[36:37], v[36:37], v[48:49] op_sel_hi:[1,0]
	v_pk_mul_f32 v[40:41], v[34:35], v[48:49] op_sel_hi:[1,0]
	v_pk_mul_f32 v[34:35], v[32:33], v[48:49] op_sel_hi:[1,0]
	v_cvt_pk_bf16_f32 v32, v36, v37
	v_cvt_pk_bf16_f32 v33, v38, v39
	v_cvt_pk_bf16_f32 v34, v34, v35
	v_cvt_pk_bf16_f32 v35, v40, v41
	global_store_dwordx4 v[50:51], v[32:35], off offset:256 sc1
	v_lshl_add_u64 v[44:45], v[140:141], 0, s[22:23]
	global_load_dwordx4 v[32:35], v[64:65], off offset:2048
	global_load_dwordx4 v[36:39], v[44:45], off offset:16
	global_load_dwordx4 v[40:43], v[44:45], off offset:48
	s_nop 0
	global_load_dwordx4 v[44:47], v[44:45], off offset:32
	s_waitcnt vmcnt(3)
	v_mov_b32_e32 v48, v32
	s_waitcnt vmcnt(0)
	v_mov_b32_e32 v49, v44
	v_mov_b32_e32 v44, v33
	v_pk_add_f32 v[32:33], v[48:49], v[44:45]
	v_mov_b32_e32 v44, v34
	v_mov_b32_e32 v45, v46
	v_mov_b32_e32 v46, v35
	v_pk_add_f32 v[34:35], v[44:45], v[46:47]
	s_nop 0
	v_pk_add_f32 v[32:33], v[32:33], v[34:35]
	v_mov_b32_e32 v34, v36
	v_mov_b32_e32 v35, v40
	v_mov_b32_e32 v40, v37
	v_mov_b32_e32 v36, v38
	v_mov_b32_e32 v37, v42
	v_mov_b32_e32 v42, v39
	v_pk_add_f32 v[34:35], v[34:35], v[40:41]
	v_pk_add_f32 v[36:37], v[36:37], v[42:43]
	s_nop 0
	v_pk_add_f32 v[34:35], v[34:35], v[36:37]
	s_nop 0
	v_pk_add_f32 v[32:33], v[32:33], v[34:35]
	v_lshl_add_u64 v[34:35], v[162:163], 1, s[56:57]
	v_add_f32_e32 v32, v32, v33
	v_fmamk_f32 v32, v32, 0x3a800000, v206
	v_cmp_gt_f32_e32 vcc, s11, v32
	v_mul_f32_e32 v33, 0x4b800000, v32
	v_add_u32_e32 v162, s6, v162
	v_cndmask_b32_e32 v32, v32, v33, vcc
	v_rsq_f32_e32 v32, v32
	s_mov_b64 s[6:7], 0x2c00
	v_mul_f32_e32 v33, 0x45800000, v32
	v_cndmask_b32_e32 v32, v32, v33, vcc
	v_mul_f32_e32 v32, v148, v32
	v_pk_mul_f32 v[30:31], v[30:31], v[32:33] op_sel_hi:[1,0]
	v_pk_mul_f32 v[28:29], v[28:29], v[32:33] op_sel_hi:[1,0]
	v_pk_mul_f32 v[36:37], v[26:27], v[32:33] op_sel_hi:[1,0]
	v_pk_mul_f32 v[26:27], v[24:25], v[32:33] op_sel_hi:[1,0]
	v_cvt_pk_bf16_f32 v24, v28, v29
	v_cvt_pk_bf16_f32 v25, v30, v31
	v_cvt_pk_bf16_f32 v26, v26, v27
	v_cvt_pk_bf16_f32 v27, v36, v37
	global_store_dwordx4 v[34:35], v[24:27], off sc1
	v_pk_mul_f32 v[22:23], v[22:23], v[32:33] op_sel_hi:[1,0]
	v_pk_mul_f32 v[20:21], v[20:21], v[32:33] op_sel_hi:[1,0]
	v_pk_mul_f32 v[24:25], v[18:19], v[32:33] op_sel_hi:[1,0]
	v_pk_mul_f32 v[18:19], v[16:17], v[32:33] op_sel_hi:[1,0]
	v_cvt_pk_bf16_f32 v16, v20, v21
	v_cvt_pk_bf16_f32 v17, v22, v23
	v_cvt_pk_bf16_f32 v18, v18, v19
	v_cvt_pk_bf16_f32 v19, v24, v25
	global_store_dwordx4 v[34:35], v[16:19], off offset:256 sc1
	v_lshl_add_u64 v[28:29], v[140:141], 0, s[6:7]
	global_load_dwordx4 v[16:19], v[64:65], off offset:3072
	global_load_dwordx4 v[20:23], v[28:29], off offset:16
	global_load_dwordx4 v[24:27], v[28:29], off offset:48
	s_nop 0
	global_load_dwordx4 v[28:31], v[28:29], off offset:32
	s_mov_b64 s[6:7], -1
	s_waitcnt vmcnt(3)
	v_mov_b32_e32 v32, v16
	s_waitcnt vmcnt(0)
	v_mov_b32_e32 v33, v28
	v_mov_b32_e32 v28, v17
	v_pk_add_f32 v[16:17], v[32:33], v[28:29]
	v_mov_b32_e32 v28, v18
	v_mov_b32_e32 v29, v30
	v_mov_b32_e32 v30, v19
	v_pk_add_f32 v[18:19], v[28:29], v[30:31]
	s_nop 0
	v_pk_add_f32 v[16:17], v[16:17], v[18:19]
	v_mov_b32_e32 v18, v20
	v_mov_b32_e32 v19, v24
	v_mov_b32_e32 v24, v21
	v_mov_b32_e32 v20, v22
	v_mov_b32_e32 v21, v26
	v_mov_b32_e32 v26, v23
	v_pk_add_f32 v[18:19], v[18:19], v[24:25]
	v_pk_add_f32 v[20:21], v[20:21], v[26:27]
	s_nop 0
	v_pk_add_f32 v[18:19], v[18:19], v[20:21]
	s_nop 0
	v_pk_add_f32 v[16:17], v[16:17], v[18:19]
	v_lshl_add_u64 v[18:19], v[162:163], 1, s[56:57]
	v_add_f32_e32 v16, v16, v17
	v_fmamk_f32 v16, v16, 0x3a800000, v206
	v_cmp_gt_f32_e32 vcc, s11, v16
	v_mul_f32_e32 v17, 0x4b800000, v16
	s_nop 0
	v_cndmask_b32_e32 v16, v16, v17, vcc
	v_rsq_f32_e32 v16, v16
	s_nop 0
	v_mul_f32_e32 v17, 0x45800000, v16
	v_cndmask_b32_e32 v16, v16, v17, vcc
	v_mul_f32_e32 v16, v148, v16
	v_pk_mul_f32 v[14:15], v[14:15], v[16:17] op_sel_hi:[1,0]
	v_pk_mul_f32 v[12:13], v[12:13], v[16:17] op_sel_hi:[1,0]
	v_pk_mul_f32 v[20:21], v[10:11], v[16:17] op_sel_hi:[1,0]
	v_pk_mul_f32 v[10:11], v[8:9], v[16:17] op_sel_hi:[1,0]
	v_cvt_pk_bf16_f32 v8, v12, v13
	v_cvt_pk_bf16_f32 v9, v14, v15
	v_cvt_pk_bf16_f32 v10, v10, v11
	v_cvt_pk_bf16_f32 v11, v20, v21
	global_store_dwordx4 v[18:19], v[8:11], off sc1
	v_pk_mul_f32 v[6:7], v[6:7], v[16:17] op_sel_hi:[1,0]
	v_pk_mul_f32 v[4:5], v[4:5], v[16:17] op_sel_hi:[1,0]
	v_pk_mul_f32 v[8:9], v[2:3], v[16:17] op_sel_hi:[1,0]
	v_pk_mul_f32 v[2:3], v[0:1], v[16:17] op_sel_hi:[1,0]
	v_cvt_pk_bf16_f32 v0, v4, v5
	v_cvt_pk_bf16_f32 v1, v6, v7
	v_cvt_pk_bf16_f32 v2, v2, v3
	v_cvt_pk_bf16_f32 v3, v8, v9
	global_store_dwordx4 v[18:19], v[0:3], off offset:256 sc1
	s_andn2_b64 vcc, exec, s[40:41]
	s_cbranch_vccnz .LBB0_175
	s_andn2_b64 vcc, exec, s[44:45]
	s_cbranch_vccnz .LBB0_174
	s_barrier
	s_branch .LBB0_174

.LBB0_189:
	v_lshl_add_u64 v[90:91], v[76:77], 0, s[80:81]
	v_add_co_u32_e32 v118, vcc, s12, v90
	v_lshl_add_u64 v[92:93], v[74:75], 0, s[80:81]
	s_nop 0
	v_addc_co_u32_e32 v119, vcc, 0, v91, vcc
	v_add_co_u32_e32 v120, vcc, s13, v90
	s_mov_b32 s24, 0x288000
	s_nop 0
	v_addc_co_u32_e32 v121, vcc, 0, v91, vcc
	v_add_co_u32_e32 v122, vcc, s24, v92
	s_mov_b32 s24, 0x298000
	s_nop 0
	v_addc_co_u32_e32 v123, vcc, 0, v93, vcc
	v_add_co_u32_e32 v124, vcc, s24, v92
	s_add_i32 s23, s23, 64
	s_nop 0
	v_addc_co_u32_e32 v125, vcc, 0, v93, vcc
	global_load_dwordx4 v[90:93], v[118:119], off offset:2048
	global_load_dwordx4 v[94:97], v[122:123], off offset:2048
	global_load_dwordx4 v[98:101], v[124:125], off offset:2048
	global_load_dwordx4 v[102:105], v[118:119], off offset:2080
	global_load_dwordx4 v[106:109], v[122:123], off offset:2080
	global_load_dwordx4 v[110:113], v[120:121], off offset:2048
	global_load_dwordx4 v[114:117], v[124:125], off offset:2080
	v_lshl_add_u64 v[74:75], v[74:75], 0, s[4:5]
	s_cmpk_gt_u32 s23, 0x6f
	v_lshl_add_u64 v[76:77], v[76:77], 0, s[4:5]
	s_waitcnt vmcnt(5)
	v_mfma_f32_32x32x16_bf16 v[0:15], v[90:93], v[94:97], v[0:15]
	s_waitcnt vmcnt(4)
	v_mfma_f32_32x32x16_bf16 v[32:47], v[90:93], v[98:101], v[32:47]
	global_load_dwordx4 v[90:93], v[120:121], off offset:2080
	s_waitcnt vmcnt(2)
	v_mfma_f32_32x32x16_bf16 v[16:31], v[110:113], v[94:97], v[16:31]
	global_load_dwordx4 v[94:97], v[118:119], off offset:2112
	v_mfma_f32_32x32x16_bf16 v[48:63], v[110:113], v[98:101], v[48:63]
	global_load_dwordx4 v[98:101], v[122:123], off offset:2112
	v_mfma_f32_32x32x16_bf16 v[0:15], v[102:105], v[106:109], v[0:15]
	s_waitcnt vmcnt(3)
	v_mfma_f32_32x32x16_bf16 v[32:47], v[102:105], v[114:117], v[32:47]
	s_waitcnt vmcnt(2)
	v_mfma_f32_32x32x16_bf16 v[16:31], v[90:93], v[106:109], v[16:31]
	v_mfma_f32_32x32x16_bf16 v[48:63], v[90:93], v[114:117], v[48:63]
	global_load_dwordx4 v[90:93], v[124:125], off offset:2112
	global_load_dwordx4 v[102:105], v[118:119], off offset:2144
	global_load_dwordx4 v[106:109], v[122:123], off offset:2144
	global_load_dwordx4 v[110:113], v[120:121], off offset:2112
	global_load_dwordx4 v[114:117], v[124:125], off offset:2144
	s_waitcnt vmcnt(5)
	v_mfma_f32_32x32x16_bf16 v[0:15], v[94:97], v[98:101], v[0:15]
	s_waitcnt vmcnt(4)
	v_mfma_f32_32x32x16_bf16 v[32:47], v[94:97], v[90:93], v[32:47]
	global_load_dwordx4 v[94:97], v[120:121], off offset:2144
	s_waitcnt vmcnt(2)
	v_mfma_f32_32x32x16_bf16 v[16:31], v[110:113], v[98:101], v[16:31]
	v_mfma_f32_32x32x16_bf16 v[48:63], v[110:113], v[90:93], v[48:63]
	v_mfma_f32_32x32x16_bf16 v[0:15], v[102:105], v[106:109], v[0:15]
	s_waitcnt vmcnt(1)
	v_mfma_f32_32x32x16_bf16 v[32:47], v[102:105], v[114:117], v[32:47]
	s_waitcnt vmcnt(0)
	v_mfma_f32_32x32x16_bf16 v[16:31], v[94:97], v[106:109], v[16:31]
	v_mfma_f32_32x32x16_bf16 v[48:63], v[94:97], v[114:117], v[48:63]
	s_cbranch_scc0 .LBB0_189
	s_nop 7
	ds_write2_b32 v80, v0, v32 offset1:32
	ds_write2_b32 v80, v1, v33 offset0:64 offset1:96
	ds_write2_b32 v80, v2, v34 offset0:128 offset1:160
	ds_write2_b32 v80, v3, v35 offset0:192 offset1:224
	v_add_u32_e32 v0, 0x800, v80
	ds_write2_b32 v0, v4, v36 offset1:32
	ds_write2_b32 v0, v5, v37 offset0:64 offset1:96
	ds_write2_b32 v0, v6, v38 offset0:128 offset1:160
	ds_write2_b32 v0, v7, v39 offset0:192 offset1:224
	v_add_u32_e32 v0, 0x1000, v80
	ds_write2_b32 v0, v8, v40 offset1:32
	ds_write2_b32 v0, v9, v41 offset0:64 offset1:96
	ds_write2_b32 v0, v10, v42 offset0:128 offset1:160
	ds_write2_b32 v0, v11, v43 offset0:192 offset1:224
	v_add_u32_e32 v0, 0x1800, v80
	ds_write2_b32 v0, v12, v44 offset1:32
	ds_write2_b32 v0, v13, v45 offset0:64 offset1:96
	ds_write2_b32 v0, v14, v46 offset0:128 offset1:160
	ds_write2_b32 v0, v15, v47 offset0:192 offset1:224
	v_add_u32_e32 v0, 0x2000, v80
	ds_write2_b32 v0, v16, v48 offset1:32
	ds_write2_b32 v0, v17, v49 offset0:64 offset1:96
	ds_write2_b32 v0, v18, v50 offset0:128 offset1:160
	ds_write2_b32 v0, v19, v51 offset0:192 offset1:224
	v_add_u32_e32 v0, 0x2800, v80
	ds_write2_b32 v0, v20, v52 offset1:32
	ds_write2_b32 v0, v21, v53 offset0:64 offset1:96
	ds_write2_b32 v0, v22, v54 offset0:128 offset1:160
	ds_write2_b32 v0, v23, v55 offset0:192 offset1:224
	v_add_u32_e32 v0, 0x3000, v80
	ds_write2_b32 v0, v24, v56 offset1:32
	ds_write2_b32 v0, v25, v57 offset0:64 offset1:96
	ds_write2_b32 v0, v26, v58 offset0:128 offset1:160
	ds_write2_b32 v0, v27, v59 offset0:192 offset1:224
	v_add_u32_e32 v0, 0x3800, v80
	ds_write2_b32 v0, v28, v60 offset1:32
	ds_write2_b32 v0, v29, v61 offset0:64 offset1:96
	ds_write2_b32 v0, v30, v62 offset0:128 offset1:160
	ds_write2_b32 v0, v31, v63 offset0:192 offset1:224
	s_waitcnt lgkmcnt(0)
	s_barrier
	global_load_dwordx4 v[0:3], v[66:67], off
	global_load_dwordx4 v[4:7], v[66:67], off offset:32
	global_load_dwordx4 v[8:11], v[66:67], off offset:16
	global_load_dwordx4 v[12:15], v[66:67], off offset:48
	ds_read_b128 v[16:19], v78
	ds_read_b128 v[20:23], v78 offset:16
	ds_read_b128 v[24:27], v78 offset:16384
	ds_read_b128 v[28:31], v78 offset:16400
	ds_read_b128 v[32:35], v78 offset:32768
	ds_read_b128 v[36:39], v78 offset:32784
	ds_read_b128 v[40:43], v78 offset:49152
	ds_read_b128 v[44:47], v78 offset:49168
	ds_read_b128 v[48:51], v81
	ds_read_b128 v[52:55], v82
	ds_read_b128 v[56:59], v83
	ds_read_b128 v[60:63], v84
	ds_read_b128 v[74:77], v85
	ds_read_b128 v[90:93], v86
	ds_read_b128 v[94:97], v87
	ds_read_b128 v[98:101], v88
	v_lshl_or_b32 v71, s22, 6, v79
	s_movk_i32 s23, 0x400
	v_cmp_gt_i32_e32 vcc, s23, v71
	s_movk_i32 s23, 0x200
	v_cmp_gt_i32_e64 s[42:43], s23, v71
	v_mov_b32_e32 v89, s9
	v_mov_b32_e32 v102, s7
	v_mov_b32_e32 v106, s8
	v_mov_b32_e32 v107, s6
	v_cndmask_b32_e32 v103, v89, v102, vcc
	v_cndmask_b32_e32 v102, v106, v107, vcc
	s_add_i32 s22, s22, s82
	s_cmp_gt_i32 s22, 47
	v_add_u32_e32 v70, s39, v70
	s_waitcnt vmcnt(3)
	v_mov_b32_e32 v104, v0
	s_waitcnt vmcnt(2)
	v_mov_b32_e32 v105, v4
	v_mov_b32_e32 v4, v1
	v_mov_b32_e32 v0, v2
	v_mov_b32_e32 v1, v6
	v_mov_b32_e32 v6, v3
	s_waitcnt vmcnt(1)
	v_mov_b32_e32 v2, v8
	s_waitcnt vmcnt(0)
	v_mov_b32_e32 v3, v12
	v_mov_b32_e32 v12, v9
	v_mov_b32_e32 v8, v10
	v_mov_b32_e32 v9, v14
	v_pk_add_f32 v[4:5], v[104:105], v[4:5]
	v_pk_add_f32 v[0:1], v[0:1], v[6:7]
	v_mov_b32_e32 v14, v11
	v_pk_add_f32 v[2:3], v[2:3], v[12:13]
	v_pk_add_f32 v[0:1], v[4:5], v[0:1]
	v_pk_add_f32 v[4:5], v[8:9], v[14:15]
	s_waitcnt lgkmcnt(14)
	v_pk_add_f32 v[6:7], v[20:21], 0 op_sel_hi:[1,0]
	v_pk_add_f32 v[2:3], v[2:3], v[4:5]
	v_pk_add_f32 v[4:5], v[18:19], 0 op_sel_hi:[1,0]
	v_pk_add_f32 v[0:1], v[0:1], v[2:3]
	v_pk_add_f32 v[8:9], v[22:23], 0 op_sel_hi:[1,0]
	v_add_f32_e32 v0, v0, v1
	v_fmamk_f32 v0, v0, 0x3a800000, v206
	v_mul_f32_e32 v1, 0x4b800000, v0
	v_cmp_gt_f32_e64 s[40:41], s11, v0
	s_waitcnt lgkmcnt(13)
	v_pk_add_f32 v[4:5], v[4:5], v[26:27]
	s_waitcnt lgkmcnt(12)
	v_pk_add_f32 v[6:7], v[6:7], v[28:29]
	v_cndmask_b32_e64 v0, v0, v1, s[40:41]
	v_rsq_f32_e32 v0, v0
	v_pk_add_f32 v[8:9], v[8:9], v[30:31]
	s_waitcnt lgkmcnt(11)
	v_pk_add_f32 v[4:5], v[4:5], v[34:35]
	s_waitcnt lgkmcnt(10)
	v_pk_add_f32 v[6:7], v[6:7], v[36:37]
	v_mul_f32_e32 v2, 0x45800000, v0
	v_cndmask_b32_e64 v0, v0, v2, s[40:41]
	v_pk_add_f32 v[2:3], v[16:17], 0 op_sel_hi:[1,0]
	v_pk_add_f32 v[8:9], v[8:9], v[38:39]
	v_pk_add_f32 v[2:3], v[2:3], v[24:25]
	s_waitcnt lgkmcnt(9)
	v_pk_add_f32 v[4:5], v[4:5], v[42:43]
	v_pk_add_f32 v[2:3], v[2:3], v[32:33]
	s_waitcnt lgkmcnt(8)
	v_pk_add_f32 v[6:7], v[6:7], v[44:45]
	v_pk_add_f32 v[2:3], v[2:3], v[40:41]
	v_pk_add_f32 v[8:9], v[8:9], v[46:47]
	s_waitcnt lgkmcnt(7)
	v_pk_add_f32 v[2:3], v[2:3], v[48:49]
	v_pk_add_f32 v[4:5], v[4:5], v[50:51]
	s_waitcnt lgkmcnt(6)
	v_pk_add_f32 v[6:7], v[6:7], v[52:53]
	v_pk_add_f32 v[8:9], v[8:9], v[54:55]
	s_waitcnt lgkmcnt(5)
	v_pk_add_f32 v[2:3], v[2:3], v[56:57]
	v_pk_add_f32 v[4:5], v[4:5], v[58:59]
	s_waitcnt lgkmcnt(4)
	v_pk_add_f32 v[6:7], v[6:7], v[60:61]
	v_pk_add_f32 v[8:9], v[8:9], v[62:63]
	v_cndmask_b32_e64 v1, 1.0, v210, s[42:43]
	s_waitcnt lgkmcnt(3)
	v_pk_add_f32 v[2:3], v[2:3], v[74:75]
	v_pk_add_f32 v[4:5], v[4:5], v[76:77]
	s_waitcnt lgkmcnt(2)
	v_pk_add_f32 v[6:7], v[6:7], v[90:91]
	v_pk_add_f32 v[8:9], v[8:9], v[92:93]
	v_mul_f32_e32 v0, v1, v0
	s_waitcnt lgkmcnt(1)
	v_pk_add_f32 v[2:3], v[2:3], v[94:95]
	v_pk_add_f32 v[4:5], v[4:5], v[96:97]
	s_waitcnt lgkmcnt(0)
	v_pk_add_f32 v[6:7], v[6:7], v[98:99]
	v_pk_add_f32 v[8:9], v[8:9], v[100:101]
	v_pk_mul_f32 v[2:3], v[2:3], v[0:1] op_sel_hi:[1,0]
	v_pk_mul_f32 v[4:5], v[4:5], v[0:1] op_sel_hi:[1,0]
	v_pk_mul_f32 v[6:7], v[6:7], v[0:1] op_sel_hi:[1,0]
	v_pk_mul_f32 v[8:9], v[8:9], v[0:1] op_sel_hi:[1,0]
	v_mov_b32_e32 v0, 0xfffffc00
	v_cndmask_b32_e64 v0, v0, 0, vcc
	v_cvt_pk_bf16_f32 v1, v4, v5
	v_cndmask_b32_e64 v4, 11, 10, vcc
	v_add_u32_e32 v10, v0, v71
	v_lshlrev_b64 v[4:5], v4, v[64:65]
	v_lshl_add_u64 v[4:5], v[4:5], 1, v[102:103]
	v_ashrrev_i32_e32 v11, 31, v10
	v_cvt_pk_bf16_f32 v0, v2, v3
	v_cvt_pk_bf16_f32 v2, v6, v7
	v_cvt_pk_bf16_f32 v3, v8, v9
	v_lshl_add_u64 v[4:5], v[10:11], 1, v[4:5]
	global_store_dwordx4 v[4:5], v[0:3], off sc1
	s_barrier
	s_cbranch_scc0 .LBB0_188

.LBB0_207:
	v_lshl_or_b32 v190, s22, 8, v222
	v_or_b32_e32 v144, 1, v190
	v_ashrrev_i32_e32 v191, 31, v190
	v_ashrrev_i32_e32 v145, 31, v144
	v_lshlrev_b64 v[128:129], 6, v[190:191]
	v_lshlrev_b64 v[144:145], 6, v[144:145]
	v_lshl_add_u64 v[140:141], s[44:45], 0, v[128:129]
	v_lshl_add_u64 v[156:157], s[44:45], 0, v[144:145]
	global_load_dwordx4 v[128:131], v[140:141], off offset:48
	global_load_dwordx4 v[132:135], v[140:141], off offset:32
	global_load_dwordx4 v[136:139], v[140:141], off offset:16
	s_nop 0
	global_load_dwordx4 v[140:143], v[140:141], off
	s_nop 0
	global_load_dwordx4 v[144:147], v[156:157], off offset:48
	global_load_dwordx4 v[148:151], v[156:157], off offset:32
	global_load_dwordx4 v[152:155], v[156:157], off offset:16
	s_nop 0
	global_load_dwordx4 v[156:159], v[156:157], off
	s_mov_b32 s6, 0x358637bd
	v_mov_b64_e32 v[192:193], s[6:7]
	s_mov_b32 s6, 0x3a800000
	s_mov_b32 s22, 0x45800000
	s_mov_b64 s[30:31], s[34:35]
	s_waitcnt vmcnt(0)
	v_mov_b32_e32 v174, v140
	v_mov_b32_e32 v175, v156
	v_mov_b32_e32 v156, v141
	v_pk_add_f32 v[140:141], v[174:175], v[156:157]
	v_mov_b32_e32 v156, v142
	v_mov_b32_e32 v157, v158
	v_mov_b32_e32 v158, v143
	v_pk_add_f32 v[142:143], v[156:157], v[158:159]
	s_nop 0
	v_pk_add_f32 v[140:141], v[140:141], v[142:143]
	v_mov_b32_e32 v142, v136
	v_mov_b32_e32 v143, v152
	v_mov_b32_e32 v152, v137
	v_pk_add_f32 v[136:137], v[142:143], v[152:153]
	v_mov_b32_e32 v142, v138
	v_mov_b32_e32 v143, v154
	v_mov_b32_e32 v154, v139
	v_pk_add_f32 v[138:139], v[142:143], v[154:155]
	s_nop 0
	v_pk_add_f32 v[136:137], v[136:137], v[138:139]
	v_mov_b32_e32 v138, v132
	v_mov_b32_e32 v139, v148
	v_mov_b32_e32 v148, v133
	v_pk_add_f32 v[132:133], v[138:139], v[148:149]
	v_mov_b32_e32 v138, v134
	v_mov_b32_e32 v139, v150
	v_mov_b32_e32 v150, v135
	v_pk_add_f32 v[134:135], v[138:139], v[150:151]
	v_pk_add_f32 v[136:137], v[140:141], v[136:137]
	v_pk_add_f32 v[132:133], v[132:133], v[134:135]
	v_mov_b32_e32 v134, v128
	v_mov_b32_e32 v135, v144
	v_mov_b32_e32 v144, v129
	v_pk_add_f32 v[128:129], v[134:135], v[144:145]
	v_mov_b32_e32 v134, v130
	v_mov_b32_e32 v135, v146
	v_mov_b32_e32 v146, v131
	v_pk_add_f32 v[130:131], v[134:135], v[146:147]
	v_or_b32_e32 v144, 3, v190
	v_pk_add_f32 v[128:129], v[128:129], v[130:131]
	v_ashrrev_i32_e32 v145, 31, v144
	v_pk_add_f32 v[128:129], v[132:133], v[128:129]
	v_lshlrev_b64 v[144:145], 6, v[144:145]
	v_pk_add_f32 v[128:129], v[136:137], v[128:129]
	v_lshl_add_u64 v[156:157], s[44:45], 0, v[144:145]
	v_pk_fma_f32 v[128:129], v[128:129], s[6:7], v[192:193] op_sel_hi:[1,0,0]
	s_nop 0
	v_mul_f32_e32 v130, 0x4b800000, v128
	v_cmp_gt_f32_e64 s[42:43], s11, v128
	v_cmp_gt_f32_e32 vcc, s11, v129
	s_nop 0
	v_cndmask_b32_e64 v128, v128, v130, s[42:43]
	v_mul_f32_e32 v130, 0x4b800000, v129
	v_cndmask_b32_e32 v129, v129, v130, vcc
	v_rsq_f32_e32 v128, v128
	v_rsq_f32_e32 v129, v129
	s_nop 0
	v_pk_mul_f32 v[130:131], v[128:129], s[22:23] op_sel_hi:[1,0]
	s_nop 0
	v_cndmask_b32_e64 v188, v128, v130, s[42:43]
	v_or_b32_e32 v128, 2, v190
	v_cndmask_b32_e32 v189, v129, v131, vcc
	v_ashrrev_i32_e32 v129, 31, v128
	v_lshlrev_b64 v[128:129], 6, v[128:129]
	v_lshl_add_u64 v[140:141], s[44:45], 0, v[128:129]
	global_load_dwordx4 v[128:131], v[140:141], off offset:48
	global_load_dwordx4 v[132:135], v[140:141], off offset:32
	global_load_dwordx4 v[136:139], v[140:141], off offset:16
	s_nop 0
	global_load_dwordx4 v[140:143], v[140:141], off
	s_nop 0
	global_load_dwordx4 v[144:147], v[156:157], off offset:48
	global_load_dwordx4 v[148:151], v[156:157], off offset:32
	global_load_dwordx4 v[152:155], v[156:157], off offset:16
	s_nop 0
	global_load_dwordx4 v[156:159], v[156:157], off
	v_pk_mul_f32 v[124:125], v[124:125], v[188:189]
	v_pk_mul_f32 v[60:61], v[60:61], v[188:189]
	s_waitcnt vmcnt(4)
	v_mov_b32_e32 v174, v140
	s_waitcnt vmcnt(0)
	v_mov_b32_e32 v175, v156
	v_mov_b32_e32 v156, v141
	v_pk_add_f32 v[140:141], v[174:175], v[156:157]
	v_mov_b32_e32 v156, v142
	v_mov_b32_e32 v157, v158
	v_mov_b32_e32 v158, v143
	v_pk_add_f32 v[142:143], v[156:157], v[158:159]
	s_nop 0
	v_pk_add_f32 v[140:141], v[140:141], v[142:143]
	v_mov_b32_e32 v142, v136
	v_mov_b32_e32 v143, v152
	v_mov_b32_e32 v152, v137
	v_pk_add_f32 v[136:137], v[142:143], v[152:153]
	v_mov_b32_e32 v142, v138
	v_mov_b32_e32 v143, v154
	v_mov_b32_e32 v154, v139
	v_pk_add_f32 v[138:139], v[142:143], v[154:155]
	s_nop 0
	v_pk_add_f32 v[136:137], v[136:137], v[138:139]
	v_mov_b32_e32 v138, v132
	v_mov_b32_e32 v139, v148
	v_mov_b32_e32 v148, v133
	v_pk_add_f32 v[132:133], v[138:139], v[148:149]
	v_mov_b32_e32 v138, v134
	v_mov_b32_e32 v139, v150
	v_mov_b32_e32 v150, v135
	v_pk_add_f32 v[134:135], v[138:139], v[150:151]
	v_pk_add_f32 v[136:137], v[140:141], v[136:137]
	v_pk_add_f32 v[132:133], v[132:133], v[134:135]
	v_mov_b32_e32 v134, v128
	v_mov_b32_e32 v135, v144
	v_mov_b32_e32 v144, v129
	v_pk_add_f32 v[128:129], v[134:135], v[144:145]
	v_mov_b32_e32 v134, v130
	v_mov_b32_e32 v135, v146
	v_mov_b32_e32 v146, v131
	v_pk_add_f32 v[130:131], v[134:135], v[146:147]
	v_or_b32_e32 v144, 5, v190
	v_pk_add_f32 v[128:129], v[128:129], v[130:131]
	v_ashrrev_i32_e32 v145, 31, v144
	v_pk_add_f32 v[128:129], v[132:133], v[128:129]
	v_lshlrev_b64 v[144:145], 6, v[144:145]
	v_pk_add_f32 v[128:129], v[136:137], v[128:129]
	v_lshl_add_u64 v[156:157], s[44:45], 0, v[144:145]
	v_pk_fma_f32 v[128:129], v[128:129], s[6:7], v[192:193] op_sel_hi:[1,0,0]
	s_nop 0
	v_mul_f32_e32 v130, 0x4b800000, v128
	v_cmp_gt_f32_e64 s[42:43], s11, v128
	v_cmp_gt_f32_e32 vcc, s11, v129
	s_nop 0
	v_cndmask_b32_e64 v128, v128, v130, s[42:43]
	v_mul_f32_e32 v130, 0x4b800000, v129
	v_cndmask_b32_e32 v129, v129, v130, vcc
	v_rsq_f32_e32 v128, v128
	v_rsq_f32_e32 v129, v129
	s_nop 0
	v_pk_mul_f32 v[130:131], v[128:129], s[22:23] op_sel_hi:[1,0]
	s_nop 0
	v_cndmask_b32_e64 v194, v128, v130, s[42:43]
	v_or_b32_e32 v128, 4, v190
	v_cndmask_b32_e32 v195, v129, v131, vcc
	v_ashrrev_i32_e32 v129, 31, v128
	v_lshlrev_b64 v[128:129], 6, v[128:129]
	v_lshl_add_u64 v[140:141], s[44:45], 0, v[128:129]
	global_load_dwordx4 v[128:131], v[140:141], off offset:48
	global_load_dwordx4 v[132:135], v[140:141], off offset:32
	global_load_dwordx4 v[136:139], v[140:141], off offset:16
	s_nop 0
	global_load_dwordx4 v[140:143], v[140:141], off
	s_nop 0
	global_load_dwordx4 v[144:147], v[156:157], off offset:48
	global_load_dwordx4 v[148:151], v[156:157], off offset:32
	global_load_dwordx4 v[152:155], v[156:157], off offset:16
	s_nop 0
	global_load_dwordx4 v[156:159], v[156:157], off
	v_pk_mul_f32 v[126:127], v[126:127], v[194:195]
	v_pk_mul_f32 v[62:63], v[62:63], v[194:195]
	s_waitcnt vmcnt(4)
	v_mov_b32_e32 v174, v140
	s_waitcnt vmcnt(0)
	v_mov_b32_e32 v175, v156
	v_mov_b32_e32 v156, v141
	v_pk_add_f32 v[140:141], v[174:175], v[156:157]
	v_mov_b32_e32 v156, v142
	v_mov_b32_e32 v157, v158
	v_mov_b32_e32 v158, v143
	v_pk_add_f32 v[142:143], v[156:157], v[158:159]
	s_nop 0
	v_pk_add_f32 v[140:141], v[140:141], v[142:143]
	v_mov_b32_e32 v142, v136
	v_mov_b32_e32 v143, v152
	v_mov_b32_e32 v152, v137
	v_pk_add_f32 v[136:137], v[142:143], v[152:153]
	v_mov_b32_e32 v142, v138
	v_mov_b32_e32 v143, v154
	v_mov_b32_e32 v154, v139
	v_pk_add_f32 v[138:139], v[142:143], v[154:155]
	s_nop 0
	v_pk_add_f32 v[136:137], v[136:137], v[138:139]
	v_mov_b32_e32 v138, v132
	v_mov_b32_e32 v139, v148
	v_mov_b32_e32 v148, v133
	v_pk_add_f32 v[132:133], v[138:139], v[148:149]
	v_mov_b32_e32 v138, v134
	v_mov_b32_e32 v139, v150
	v_mov_b32_e32 v150, v135
	v_pk_add_f32 v[134:135], v[138:139], v[150:151]
	v_pk_add_f32 v[136:137], v[140:141], v[136:137]
	v_pk_add_f32 v[132:133], v[132:133], v[134:135]
	v_mov_b32_e32 v134, v128
	v_mov_b32_e32 v135, v144
	v_mov_b32_e32 v144, v129
	v_pk_add_f32 v[128:129], v[134:135], v[144:145]
	v_mov_b32_e32 v134, v130
	v_mov_b32_e32 v135, v146
	v_mov_b32_e32 v146, v131
	v_pk_add_f32 v[130:131], v[134:135], v[146:147]
	v_or_b32_e32 v144, 7, v190
	v_pk_add_f32 v[128:129], v[128:129], v[130:131]
	v_ashrrev_i32_e32 v145, 31, v144
	v_pk_add_f32 v[128:129], v[132:133], v[128:129]
	v_lshlrev_b64 v[144:145], 6, v[144:145]
	v_pk_add_f32 v[128:129], v[136:137], v[128:129]
	v_lshl_add_u64 v[156:157], s[44:45], 0, v[144:145]
	v_pk_fma_f32 v[128:129], v[128:129], s[6:7], v[192:193] op_sel_hi:[1,0,0]
	s_nop 0
	v_mul_f32_e32 v130, 0x4b800000, v128
	v_cmp_gt_f32_e64 s[42:43], s11, v128
	v_cmp_gt_f32_e32 vcc, s11, v129
	s_nop 0
	v_cndmask_b32_e64 v128, v128, v130, s[42:43]
	v_mul_f32_e32 v130, 0x4b800000, v129
	v_cndmask_b32_e32 v129, v129, v130, vcc
	v_rsq_f32_e32 v128, v128
	v_rsq_f32_e32 v129, v129
	s_nop 0
	v_pk_mul_f32 v[130:131], v[128:129], s[22:23] op_sel_hi:[1,0]
	s_nop 0
	v_cndmask_b32_e64 v196, v128, v130, s[42:43]
	v_or_b32_e32 v128, 6, v190
	v_cndmask_b32_e32 v197, v129, v131, vcc
	v_ashrrev_i32_e32 v129, 31, v128
	v_lshlrev_b64 v[128:129], 6, v[128:129]
	v_lshl_add_u64 v[140:141], s[44:45], 0, v[128:129]
	global_load_dwordx4 v[128:131], v[140:141], off offset:48
	global_load_dwordx4 v[132:135], v[140:141], off offset:32
	global_load_dwordx4 v[136:139], v[140:141], off offset:16
	s_nop 0
	global_load_dwordx4 v[140:143], v[140:141], off
	s_nop 0
	global_load_dwordx4 v[144:147], v[156:157], off offset:48
	global_load_dwordx4 v[148:151], v[156:157], off offset:32
	global_load_dwordx4 v[152:155], v[156:157], off offset:16
	s_nop 0
	global_load_dwordx4 v[156:159], v[156:157], off
	v_pk_mul_f32 v[108:109], v[108:109], v[196:197]
	v_pk_mul_f32 v[92:93], v[92:93], v[196:197]
	v_pk_mul_f32 v[76:77], v[76:77], v[196:197]
	v_pk_mul_f32 v[44:45], v[44:45], v[196:197]
	v_pk_mul_f32 v[28:29], v[28:29], v[196:197]
	v_pk_mul_f32 v[12:13], v[12:13], v[196:197]
	s_waitcnt vmcnt(4)
	v_mov_b32_e32 v174, v140
	s_waitcnt vmcnt(0)
	v_mov_b32_e32 v175, v156
	v_mov_b32_e32 v156, v141
	v_pk_add_f32 v[140:141], v[174:175], v[156:157]
	v_mov_b32_e32 v156, v142
	v_mov_b32_e32 v157, v158
	v_mov_b32_e32 v158, v143
	v_pk_add_f32 v[142:143], v[156:157], v[158:159]
	s_nop 0
	v_pk_add_f32 v[140:141], v[140:141], v[142:143]
	v_mov_b32_e32 v142, v136
	v_mov_b32_e32 v143, v152
	v_mov_b32_e32 v152, v137
	v_pk_add_f32 v[136:137], v[142:143], v[152:153]
	v_mov_b32_e32 v142, v138
	v_mov_b32_e32 v143, v154
	v_mov_b32_e32 v154, v139
	v_pk_add_f32 v[138:139], v[142:143], v[154:155]
	s_nop 0
	v_pk_add_f32 v[136:137], v[136:137], v[138:139]
	v_mov_b32_e32 v138, v132
	v_mov_b32_e32 v139, v148
	v_mov_b32_e32 v148, v133
	v_pk_add_f32 v[132:133], v[138:139], v[148:149]
	v_mov_b32_e32 v138, v134
	v_mov_b32_e32 v139, v150
	v_mov_b32_e32 v150, v135
	v_pk_add_f32 v[134:135], v[138:139], v[150:151]
	v_pk_add_f32 v[136:137], v[140:141], v[136:137]
	v_pk_add_f32 v[132:133], v[132:133], v[134:135]
	v_mov_b32_e32 v134, v128
	v_mov_b32_e32 v135, v144
	v_mov_b32_e32 v144, v129
	v_pk_add_f32 v[128:129], v[134:135], v[144:145]
	v_mov_b32_e32 v134, v130
	v_mov_b32_e32 v135, v146
	v_mov_b32_e32 v146, v131
	v_pk_add_f32 v[130:131], v[134:135], v[146:147]
	v_or_b32_e32 v144, 0x81, v190
	v_pk_add_f32 v[128:129], v[128:129], v[130:131]
	v_ashrrev_i32_e32 v145, 31, v144
	v_pk_add_f32 v[128:129], v[132:133], v[128:129]
	v_lshlrev_b64 v[144:145], 6, v[144:145]
	v_pk_add_f32 v[128:129], v[136:137], v[128:129]
	v_lshl_add_u64 v[156:157], s[44:45], 0, v[144:145]
	v_pk_fma_f32 v[128:129], v[128:129], s[6:7], v[192:193] op_sel_hi:[1,0,0]
	s_nop 0
	v_mul_f32_e32 v130, 0x4b800000, v128
	v_cmp_gt_f32_e64 s[42:43], s11, v128
	v_cmp_gt_f32_e32 vcc, s11, v129
	s_nop 0
	v_cndmask_b32_e64 v128, v128, v130, s[42:43]
	v_mul_f32_e32 v130, 0x4b800000, v129
	v_cndmask_b32_e32 v129, v129, v130, vcc
	v_rsq_f32_e32 v128, v128
	v_rsq_f32_e32 v129, v129
	s_nop 0
	v_pk_mul_f32 v[130:131], v[128:129], s[22:23] op_sel_hi:[1,0]
	s_nop 0
	v_cndmask_b32_e64 v198, v128, v130, s[42:43]
	v_or_b32_e32 v128, 0x80, v190
	v_cndmask_b32_e32 v199, v129, v131, vcc
	v_ashrrev_i32_e32 v129, 31, v128
	v_lshlrev_b64 v[128:129], 6, v[128:129]
	v_lshl_add_u64 v[140:141], s[44:45], 0, v[128:129]
	global_load_dwordx4 v[128:131], v[140:141], off offset:48
	global_load_dwordx4 v[132:135], v[140:141], off offset:32
	global_load_dwordx4 v[136:139], v[140:141], off offset:16
	s_nop 0
	global_load_dwordx4 v[140:143], v[140:141], off
	s_nop 0
	global_load_dwordx4 v[144:147], v[156:157], off offset:48
	global_load_dwordx4 v[148:151], v[156:157], off offset:32
	global_load_dwordx4 v[152:155], v[156:157], off offset:16
	s_nop 0
	global_load_dwordx4 v[156:159], v[156:157], off
	v_pk_mul_f32 v[110:111], v[110:111], v[198:199]
	v_pk_mul_f32 v[94:95], v[94:95], v[198:199]
	v_pk_mul_f32 v[78:79], v[78:79], v[198:199]
	v_pk_mul_f32 v[46:47], v[46:47], v[198:199]
	v_pk_mul_f32 v[30:31], v[30:31], v[198:199]
	v_pk_mul_f32 v[14:15], v[14:15], v[198:199]
	s_waitcnt vmcnt(4)
	v_mov_b32_e32 v174, v140
	s_waitcnt vmcnt(0)
	v_mov_b32_e32 v175, v156
	v_mov_b32_e32 v156, v141
	v_pk_add_f32 v[140:141], v[174:175], v[156:157]
	v_mov_b32_e32 v156, v142
	v_mov_b32_e32 v157, v158
	v_mov_b32_e32 v158, v143
	v_pk_add_f32 v[142:143], v[156:157], v[158:159]
	s_nop 0
	v_pk_add_f32 v[140:141], v[140:141], v[142:143]
	v_mov_b32_e32 v142, v136
	v_mov_b32_e32 v143, v152
	v_mov_b32_e32 v152, v137
	v_pk_add_f32 v[136:137], v[142:143], v[152:153]
	v_mov_b32_e32 v142, v138
	v_mov_b32_e32 v143, v154
	v_mov_b32_e32 v154, v139
	v_pk_add_f32 v[138:139], v[142:143], v[154:155]
	s_nop 0
	v_pk_add_f32 v[136:137], v[136:137], v[138:139]
	v_mov_b32_e32 v138, v132
	v_mov_b32_e32 v139, v148
	v_mov_b32_e32 v148, v133
	v_pk_add_f32 v[132:133], v[138:139], v[148:149]
	v_mov_b32_e32 v138, v134
	v_mov_b32_e32 v139, v150
	v_mov_b32_e32 v150, v135
	v_pk_add_f32 v[134:135], v[138:139], v[150:151]
	v_pk_add_f32 v[136:137], v[140:141], v[136:137]
	v_pk_add_f32 v[132:133], v[132:133], v[134:135]
	v_mov_b32_e32 v134, v128
	v_mov_b32_e32 v135, v144
	v_mov_b32_e32 v144, v129
	v_pk_add_f32 v[128:129], v[134:135], v[144:145]
	v_mov_b32_e32 v134, v130
	v_mov_b32_e32 v135, v146
	v_mov_b32_e32 v146, v131
	v_pk_add_f32 v[130:131], v[134:135], v[146:147]
	v_or_b32_e32 v144, 0x83, v190
	v_pk_add_f32 v[128:129], v[128:129], v[130:131]
	v_ashrrev_i32_e32 v145, 31, v144
	v_pk_add_f32 v[128:129], v[132:133], v[128:129]
	v_lshlrev_b64 v[144:145], 6, v[144:145]
	v_pk_add_f32 v[128:129], v[136:137], v[128:129]
	v_lshl_add_u64 v[156:157], s[44:45], 0, v[144:145]
	v_pk_fma_f32 v[128:129], v[128:129], s[6:7], v[192:193] op_sel_hi:[1,0,0]
	s_nop 0
	v_mul_f32_e32 v130, 0x4b800000, v128
	v_cmp_gt_f32_e64 s[42:43], s11, v128
	v_cmp_gt_f32_e32 vcc, s11, v129
	s_nop 0
	v_cndmask_b32_e64 v128, v128, v130, s[42:43]
	v_mul_f32_e32 v130, 0x4b800000, v129
	v_cndmask_b32_e32 v129, v129, v130, vcc
	v_rsq_f32_e32 v128, v128
	v_rsq_f32_e32 v129, v129
	s_nop 0
	v_pk_mul_f32 v[130:131], v[128:129], s[22:23] op_sel_hi:[1,0]
	s_nop 0
	v_cndmask_b32_e64 v200, v128, v130, s[42:43]
	v_or_b32_e32 v128, 0x82, v190
	v_cndmask_b32_e32 v201, v129, v131, vcc
	v_ashrrev_i32_e32 v129, 31, v128
	v_lshlrev_b64 v[128:129], 6, v[128:129]
	v_lshl_add_u64 v[140:141], s[44:45], 0, v[128:129]
	global_load_dwordx4 v[128:131], v[140:141], off offset:48
	global_load_dwordx4 v[132:135], v[140:141], off offset:32
	global_load_dwordx4 v[136:139], v[140:141], off offset:16
	s_nop 0
	global_load_dwordx4 v[140:143], v[140:141], off
	s_nop 0
	global_load_dwordx4 v[144:147], v[156:157], off offset:48
	global_load_dwordx4 v[148:151], v[156:157], off offset:32
	global_load_dwordx4 v[152:155], v[156:157], off offset:16
	s_nop 0
	global_load_dwordx4 v[156:159], v[156:157], off
	v_pk_mul_f32 v[112:113], v[112:113], v[200:201]
	v_pk_mul_f32 v[96:97], v[96:97], v[200:201]
	v_pk_mul_f32 v[80:81], v[80:81], v[200:201]
	v_pk_mul_f32 v[68:69], v[68:69], v[200:201]
	v_pk_mul_f32 v[48:49], v[48:49], v[200:201]
	v_pk_mul_f32 v[32:33], v[32:33], v[200:201]
	v_pk_mul_f32 v[16:17], v[16:17], v[200:201]
	v_pk_mul_f32 v[4:5], v[4:5], v[200:201]
	s_waitcnt vmcnt(4)
	v_mov_b32_e32 v174, v140
	s_waitcnt vmcnt(0)
	v_mov_b32_e32 v175, v156
	v_mov_b32_e32 v156, v141
	v_pk_add_f32 v[140:141], v[174:175], v[156:157]
	v_mov_b32_e32 v156, v142
	v_mov_b32_e32 v157, v158
	v_mov_b32_e32 v158, v143
	v_pk_add_f32 v[142:143], v[156:157], v[158:159]
	s_nop 0
	v_pk_add_f32 v[140:141], v[140:141], v[142:143]
	v_mov_b32_e32 v142, v136
	v_mov_b32_e32 v143, v152
	v_mov_b32_e32 v152, v137
	v_pk_add_f32 v[136:137], v[142:143], v[152:153]
	v_mov_b32_e32 v142, v138
	v_mov_b32_e32 v143, v154
	v_mov_b32_e32 v154, v139
	v_pk_add_f32 v[138:139], v[142:143], v[154:155]
	s_nop 0
	v_pk_add_f32 v[136:137], v[136:137], v[138:139]
	v_mov_b32_e32 v138, v132
	v_mov_b32_e32 v139, v148
	v_mov_b32_e32 v148, v133
	v_pk_add_f32 v[132:133], v[138:139], v[148:149]
	v_mov_b32_e32 v138, v134
	v_mov_b32_e32 v139, v150
	v_mov_b32_e32 v150, v135
	v_pk_add_f32 v[134:135], v[138:139], v[150:151]
	v_pk_add_f32 v[136:137], v[140:141], v[136:137]
	v_pk_add_f32 v[132:133], v[132:133], v[134:135]
	v_mov_b32_e32 v134, v128
	v_mov_b32_e32 v135, v144
	v_mov_b32_e32 v144, v129
	v_pk_add_f32 v[128:129], v[134:135], v[144:145]
	v_mov_b32_e32 v134, v130
	v_mov_b32_e32 v135, v146
	v_mov_b32_e32 v146, v131
	v_pk_add_f32 v[130:131], v[134:135], v[146:147]
	v_or_b32_e32 v144, 0x85, v190
	v_pk_add_f32 v[128:129], v[128:129], v[130:131]
	v_ashrrev_i32_e32 v145, 31, v144
	v_pk_add_f32 v[128:129], v[132:133], v[128:129]
	v_lshlrev_b64 v[144:145], 6, v[144:145]
	v_pk_add_f32 v[128:129], v[136:137], v[128:129]
	v_lshl_add_u64 v[156:157], s[44:45], 0, v[144:145]
	v_pk_fma_f32 v[128:129], v[128:129], s[6:7], v[192:193] op_sel_hi:[1,0,0]
	s_nop 0
	v_mul_f32_e32 v130, 0x4b800000, v128
	v_cmp_gt_f32_e64 s[42:43], s11, v128
	v_cmp_gt_f32_e32 vcc, s11, v129
	s_nop 0
	v_cndmask_b32_e64 v128, v128, v130, s[42:43]
	v_mul_f32_e32 v130, 0x4b800000, v129
	v_cndmask_b32_e32 v129, v129, v130, vcc
	v_rsq_f32_e32 v128, v128
	v_rsq_f32_e32 v129, v129
	s_nop 0
	v_pk_mul_f32 v[130:131], v[128:129], s[22:23] op_sel_hi:[1,0]
	s_nop 0
	v_cndmask_b32_e64 v202, v128, v130, s[42:43]
	v_or_b32_e32 v128, 0x84, v190
	v_cndmask_b32_e32 v203, v129, v131, vcc
	v_ashrrev_i32_e32 v129, 31, v128
	v_lshlrev_b64 v[128:129], 6, v[128:129]
	v_lshl_add_u64 v[140:141], s[44:45], 0, v[128:129]
	global_load_dwordx4 v[128:131], v[140:141], off offset:48
	global_load_dwordx4 v[132:135], v[140:141], off offset:32
	global_load_dwordx4 v[136:139], v[140:141], off offset:16
	s_nop 0
	global_load_dwordx4 v[140:143], v[140:141], off
	s_nop 0
	global_load_dwordx4 v[144:147], v[156:157], off offset:48
	global_load_dwordx4 v[148:151], v[156:157], off offset:32
	global_load_dwordx4 v[152:155], v[156:157], off offset:16
	s_nop 0
	global_load_dwordx4 v[156:159], v[156:157], off
	v_pk_mul_f32 v[114:115], v[114:115], v[202:203]
	v_pk_mul_f32 v[98:99], v[98:99], v[202:203]
	v_pk_mul_f32 v[82:83], v[82:83], v[202:203]
	v_pk_mul_f32 v[70:71], v[70:71], v[202:203]
	v_pk_mul_f32 v[50:51], v[50:51], v[202:203]
	v_pk_mul_f32 v[34:35], v[34:35], v[202:203]
	v_pk_mul_f32 v[18:19], v[18:19], v[202:203]
	v_pk_mul_f32 v[6:7], v[6:7], v[202:203]
	s_waitcnt vmcnt(4)
	v_mov_b32_e32 v174, v140
	s_waitcnt vmcnt(0)
	v_mov_b32_e32 v175, v156
	v_mov_b32_e32 v156, v141
	v_pk_add_f32 v[140:141], v[174:175], v[156:157]
	v_mov_b32_e32 v156, v142
	v_mov_b32_e32 v157, v158
	v_mov_b32_e32 v158, v143
	v_pk_add_f32 v[142:143], v[156:157], v[158:159]
	s_nop 0
	v_pk_add_f32 v[140:141], v[140:141], v[142:143]
	v_mov_b32_e32 v142, v136
	v_mov_b32_e32 v143, v152
	v_mov_b32_e32 v152, v137
	v_pk_add_f32 v[136:137], v[142:143], v[152:153]
	v_mov_b32_e32 v142, v138
	v_mov_b32_e32 v143, v154
	v_mov_b32_e32 v154, v139
	v_pk_add_f32 v[138:139], v[142:143], v[154:155]
	s_nop 0
	v_pk_add_f32 v[136:137], v[136:137], v[138:139]
	v_mov_b32_e32 v138, v132
	v_mov_b32_e32 v139, v148
	v_mov_b32_e32 v148, v133
	v_pk_add_f32 v[132:133], v[138:139], v[148:149]
	v_mov_b32_e32 v138, v134
	v_mov_b32_e32 v139, v150
	v_mov_b32_e32 v150, v135
	v_pk_add_f32 v[134:135], v[138:139], v[150:151]
	v_pk_add_f32 v[136:137], v[140:141], v[136:137]
	v_pk_add_f32 v[132:133], v[132:133], v[134:135]
	v_mov_b32_e32 v134, v128
	v_mov_b32_e32 v135, v144
	v_mov_b32_e32 v144, v129
	v_pk_add_f32 v[128:129], v[134:135], v[144:145]
	v_mov_b32_e32 v134, v130
	v_mov_b32_e32 v135, v146
	v_mov_b32_e32 v146, v131
	v_pk_add_f32 v[130:131], v[134:135], v[146:147]
	s_nop 0
	v_pk_add_f32 v[128:129], v[128:129], v[130:131]
	s_nop 0
	v_pk_add_f32 v[128:129], v[132:133], v[128:129]
	s_nop 0
	v_pk_add_f32 v[128:129], v[136:137], v[128:129]
	s_nop 0
	v_pk_fma_f32 v[128:129], v[128:129], s[6:7], v[192:193] op_sel_hi:[1,0,0]
	s_nop 0
	v_mul_f32_e32 v130, 0x4b800000, v128
	v_cmp_gt_f32_e64 s[42:43], s11, v128
	v_cmp_gt_f32_e32 vcc, s11, v129
	s_nop 0
	v_cndmask_b32_e64 v128, v128, v130, s[42:43]
	v_mul_f32_e32 v130, 0x4b800000, v129
	v_cndmask_b32_e32 v129, v129, v130, vcc
	v_rsq_f32_e32 v128, v128
	v_rsq_f32_e32 v129, v129
	s_nop 0
	v_pk_mul_f32 v[130:131], v[128:129], s[22:23] op_sel_hi:[1,0]
	s_nop 0
	v_cndmask_b32_e64 v204, v128, v130, s[42:43]
	v_or_b32_e32 v128, 0x86, v190
	v_cndmask_b32_e32 v205, v129, v131, vcc
	v_ashrrev_i32_e32 v129, 31, v128
	v_lshlrev_b64 v[128:129], 6, v[128:129]
	v_lshl_add_u64 v[136:137], s[44:45], 0, v[128:129]
	global_load_dwordx4 v[128:131], v[136:137], off offset:48
	global_load_dwordx4 v[132:135], v[136:137], off offset:32
	global_load_dwordx4 v[144:147], v[136:137], off offset:16
	global_load_dwordx4 v[152:155], v[136:137], off
	v_or_b32_e32 v136, 0x87, v190
	v_ashrrev_i32_e32 v137, 31, v136
	v_lshlrev_b64 v[136:137], 6, v[136:137]
	v_lshl_add_u64 v[156:157], s[44:45], 0, v[136:137]
	global_load_dwordx4 v[136:139], v[156:157], off offset:48
	global_load_dwordx4 v[140:143], v[156:157], off offset:32
	global_load_dwordx4 v[148:151], v[156:157], off offset:16
	s_nop 0
	global_load_dwordx4 v[156:159], v[156:157], off
	s_waitcnt vmcnt(4)
	v_mov_b32_e32 v174, v152
	s_waitcnt vmcnt(0)
	v_mov_b32_e32 v175, v156
	v_mov_b32_e32 v156, v153
	v_pk_add_f32 v[152:153], v[174:175], v[156:157]
	v_mov_b32_e32 v156, v154
	v_mov_b32_e32 v157, v158
	v_mov_b32_e32 v158, v155
	v_pk_add_f32 v[154:155], v[156:157], v[158:159]
	s_nop 0
	v_pk_add_f32 v[152:153], v[152:153], v[154:155]
	v_mov_b32_e32 v154, v144
	v_mov_b32_e32 v155, v148
	v_mov_b32_e32 v148, v145
	v_pk_add_f32 v[144:145], v[154:155], v[148:149]
	v_mov_b32_e32 v148, v146
	v_mov_b32_e32 v149, v150
	v_mov_b32_e32 v150, v147
	v_pk_add_f32 v[146:147], v[148:149], v[150:151]
	s_nop 0
	v_pk_add_f32 v[144:145], v[144:145], v[146:147]
	v_mov_b32_e32 v146, v132
	v_mov_b32_e32 v147, v140
	v_mov_b32_e32 v140, v133
	v_pk_add_f32 v[132:133], v[146:147], v[140:141]
	v_mov_b32_e32 v140, v134
	v_mov_b32_e32 v141, v142
	v_mov_b32_e32 v142, v135
	v_pk_add_f32 v[134:135], v[140:141], v[142:143]
	v_pk_add_f32 v[144:145], v[152:153], v[144:145]
	v_pk_add_f32 v[132:133], v[132:133], v[134:135]
	v_mov_b32_e32 v134, v128
	v_mov_b32_e32 v135, v136
	v_mov_b32_e32 v136, v129
	v_pk_add_f32 v[128:129], v[134:135], v[136:137]
	v_mov_b32_e32 v134, v130
	v_mov_b32_e32 v135, v138
	v_mov_b32_e32 v138, v131
	v_pk_add_f32 v[130:131], v[134:135], v[138:139]
	v_lshl_add_u32 v138, s74, 8, v220
	v_pk_add_f32 v[128:129], v[128:129], v[130:131]
	v_pk_mul_f32 v[136:137], v[122:123], v[198:199]
	v_pk_add_f32 v[128:129], v[132:133], v[128:129]
	v_lshlrev_b64 v[132:133], 1, v[190:191]
	v_pk_add_f32 v[128:129], v[144:145], v[128:129]
	v_pk_mul_f32 v[122:123], v[120:121], v[196:197]
	v_pk_fma_f32 v[128:129], v[128:129], s[6:7], v[192:193] op_sel_hi:[1,0,0]
	v_cvt_pk_bf16_f32 v120, v124, v125
	v_mul_f32_e32 v130, 0x4b800000, v128
	v_cmp_gt_f32_e64 s[42:43], s11, v128
	v_cmp_gt_f32_e32 vcc, s11, v129
	v_cvt_pk_bf16_f32 v121, v126, v127
	v_cndmask_b32_e64 v128, v128, v130, s[42:43]
	v_mul_f32_e32 v130, 0x4b800000, v129
	v_cndmask_b32_e32 v129, v129, v130, vcc
	v_rsq_f32_e32 v128, v128
	v_rsq_f32_e32 v129, v129
	v_cvt_pk_bf16_f32 v122, v122, v123
	v_cvt_pk_bf16_f32 v123, v136, v137
	v_pk_mul_f32 v[130:131], v[128:129], s[22:23] op_sel_hi:[1,0]
	s_nop 0
	v_cndmask_b32_e32 v129, v129, v131, vcc
	v_cndmask_b32_e64 v128, v128, v130, s[42:43]
	v_mov_b64_e32 v[130:131], s[48:49]
	v_mad_i64_i32 v[134:135], s[6:7], v138, s14, v[130:131]
	v_lshl_add_u64 v[134:135], v[134:135], 0, v[132:133]
	global_store_dwordx4 v[134:135], v[120:123], off sc1
	s_andn2_b64 vcc, exec, s[40:41]
	s_nop 0
	v_pk_mul_f32 v[120:121], v[106:107], v[128:129]
	v_pk_mul_f32 v[106:107], v[104:105], v[204:205]
	v_cvt_pk_bf16_f32 v104, v112, v113
	v_cvt_pk_bf16_f32 v105, v114, v115
	v_cvt_pk_bf16_f32 v106, v106, v107
	v_cvt_pk_bf16_f32 v107, v120, v121
	global_store_dwordx4 v[134:135], v[104:107], off offset:256 sc1
	s_nop 1
	v_or_b32_e32 v104, 16, v138
	v_mad_i64_i32 v[104:105], s[6:7], v104, s14, v[130:131]
	v_lshl_add_u64 v[112:113], v[104:105], 0, v[132:133]
	v_pk_mul_f32 v[106:107], v[118:119], v[194:195]
	v_pk_mul_f32 v[104:105], v[116:117], v[188:189]
	s_nop 0
	v_cvt_pk_bf16_f32 v104, v104, v105
	v_cvt_pk_bf16_f32 v105, v106, v107
	v_cvt_pk_bf16_f32 v106, v108, v109
	v_cvt_pk_bf16_f32 v107, v110, v111
	global_store_dwordx4 v[112:113], v[104:107], off sc1
	s_nop 1
	v_pk_mul_f32 v[104:105], v[90:91], v[128:129]
	v_pk_mul_f32 v[90:91], v[88:89], v[204:205]
	v_cvt_pk_bf16_f32 v88, v96, v97
	v_cvt_pk_bf16_f32 v89, v98, v99
	v_cvt_pk_bf16_f32 v90, v90, v91
	v_cvt_pk_bf16_f32 v91, v104, v105
	global_store_dwordx4 v[112:113], v[88:91], off offset:256 sc1
	s_nop 1
	v_or_b32_e32 v88, 32, v138
	v_mad_i64_i32 v[88:89], s[6:7], v88, s14, v[130:131]
	v_lshl_add_u64 v[96:97], v[88:89], 0, v[132:133]
	v_pk_mul_f32 v[90:91], v[102:103], v[194:195]
	v_pk_mul_f32 v[88:89], v[100:101], v[188:189]
	s_nop 0
	v_cvt_pk_bf16_f32 v88, v88, v89
	v_cvt_pk_bf16_f32 v89, v90, v91
	v_cvt_pk_bf16_f32 v90, v92, v93
	v_cvt_pk_bf16_f32 v91, v94, v95
	global_store_dwordx4 v[96:97], v[88:91], off sc1
	s_nop 1
	v_pk_mul_f32 v[88:89], v[74:75], v[128:129]
	v_pk_mul_f32 v[74:75], v[72:73], v[204:205]
	v_cvt_pk_bf16_f32 v72, v80, v81
	v_cvt_pk_bf16_f32 v73, v82, v83
	v_cvt_pk_bf16_f32 v74, v74, v75
	v_cvt_pk_bf16_f32 v75, v88, v89
	global_store_dwordx4 v[96:97], v[72:75], off offset:256 sc1
	s_nop 1
	v_or_b32_e32 v72, 48, v138
	v_mad_i64_i32 v[72:73], s[6:7], v72, s14, v[130:131]
	v_lshl_add_u64 v[80:81], v[72:73], 0, v[132:133]
	v_pk_mul_f32 v[74:75], v[86:87], v[194:195]
	v_pk_mul_f32 v[72:73], v[84:85], v[188:189]
	s_nop 0
	v_cvt_pk_bf16_f32 v72, v72, v73
	v_cvt_pk_bf16_f32 v73, v74, v75
	v_cvt_pk_bf16_f32 v74, v76, v77
	v_cvt_pk_bf16_f32 v75, v78, v79
	global_store_dwordx4 v[80:81], v[72:75], off sc1
	s_nop 1
	v_pk_mul_f32 v[72:73], v[66:67], v[128:129]
	v_pk_mul_f32 v[66:67], v[64:65], v[204:205]
	v_cvt_pk_bf16_f32 v64, v68, v69
	v_cvt_pk_bf16_f32 v65, v70, v71
	v_cvt_pk_bf16_f32 v66, v66, v67
	v_cvt_pk_bf16_f32 v67, v72, v73
	global_store_dwordx4 v[80:81], v[64:67], off offset:256 sc1
	s_nop 1
	v_add_u32_e32 v64, 0x80, v138
	v_mad_i64_i32 v[64:65], s[6:7], v64, s14, v[130:131]
	v_pk_mul_f32 v[66:67], v[58:59], v[198:199]
	v_pk_mul_f32 v[58:59], v[56:57], v[196:197]
	v_lshl_add_u64 v[64:65], v[64:65], 0, v[132:133]
	v_cvt_pk_bf16_f32 v56, v60, v61
	v_cvt_pk_bf16_f32 v57, v62, v63
	v_cvt_pk_bf16_f32 v58, v58, v59
	v_cvt_pk_bf16_f32 v59, v66, v67
	global_store_dwordx4 v[64:65], v[56:59], off sc1
	s_nop 1
	v_pk_mul_f32 v[56:57], v[42:43], v[128:129]
	v_pk_mul_f32 v[42:43], v[40:41], v[204:205]
	v_cvt_pk_bf16_f32 v40, v48, v49
	v_cvt_pk_bf16_f32 v41, v50, v51
	v_cvt_pk_bf16_f32 v42, v42, v43
	v_cvt_pk_bf16_f32 v43, v56, v57
	global_store_dwordx4 v[64:65], v[40:43], off offset:256 sc1
	s_nop 1
	v_add_u32_e32 v40, 0x90, v138
	v_mad_i64_i32 v[40:41], s[6:7], v40, s14, v[130:131]
	v_lshl_add_u64 v[48:49], v[40:41], 0, v[132:133]
	v_pk_mul_f32 v[42:43], v[54:55], v[194:195]
	v_pk_mul_f32 v[40:41], v[52:53], v[188:189]
	s_nop 0
	v_cvt_pk_bf16_f32 v40, v40, v41
	v_cvt_pk_bf16_f32 v41, v42, v43
	v_cvt_pk_bf16_f32 v42, v44, v45
	v_cvt_pk_bf16_f32 v43, v46, v47
	global_store_dwordx4 v[48:49], v[40:43], off sc1
	s_nop 1
	v_pk_mul_f32 v[40:41], v[26:27], v[128:129]
	v_pk_mul_f32 v[26:27], v[24:25], v[204:205]
	v_cvt_pk_bf16_f32 v24, v32, v33
	v_cvt_pk_bf16_f32 v25, v34, v35
	v_cvt_pk_bf16_f32 v26, v26, v27
	v_cvt_pk_bf16_f32 v27, v40, v41
	global_store_dwordx4 v[48:49], v[24:27], off offset:256 sc1
	s_nop 1
	v_add_u32_e32 v24, 0xa0, v138
	v_mad_i64_i32 v[24:25], s[6:7], v24, s14, v[130:131]
	v_lshl_add_u64 v[32:33], v[24:25], 0, v[132:133]
	v_pk_mul_f32 v[26:27], v[38:39], v[194:195]
	v_pk_mul_f32 v[24:25], v[36:37], v[188:189]
	s_nop 0
	v_cvt_pk_bf16_f32 v24, v24, v25
	v_cvt_pk_bf16_f32 v25, v26, v27
	v_cvt_pk_bf16_f32 v26, v28, v29
	v_cvt_pk_bf16_f32 v27, v30, v31
	global_store_dwordx4 v[32:33], v[24:27], off sc1
	s_nop 1
	v_pk_mul_f32 v[24:25], v[10:11], v[128:129]
	v_pk_mul_f32 v[10:11], v[8:9], v[204:205]
	v_cvt_pk_bf16_f32 v8, v16, v17
	v_cvt_pk_bf16_f32 v9, v18, v19
	v_cvt_pk_bf16_f32 v10, v10, v11
	v_cvt_pk_bf16_f32 v11, v24, v25
	global_store_dwordx4 v[32:33], v[8:11], off offset:256 sc1
	s_nop 1
	v_add_u32_e32 v8, 0xb0, v138
	v_mad_i64_i32 v[8:9], s[6:7], v8, s14, v[130:131]
	v_lshl_add_u64 v[16:17], v[8:9], 0, v[132:133]
	v_pk_mul_f32 v[10:11], v[22:23], v[194:195]
	v_pk_mul_f32 v[8:9], v[20:21], v[188:189]
	s_mov_b64 s[6:7], -1
	v_cvt_pk_bf16_f32 v8, v8, v9
	v_cvt_pk_bf16_f32 v9, v10, v11
	v_cvt_pk_bf16_f32 v10, v12, v13
	v_cvt_pk_bf16_f32 v11, v14, v15
	global_store_dwordx4 v[16:17], v[8:11], off sc1
	s_nop 1
	v_pk_mul_f32 v[8:9], v[2:3], v[128:129]
	v_pk_mul_f32 v[2:3], v[0:1], v[204:205]
	v_cvt_pk_bf16_f32 v0, v4, v5
	v_cvt_pk_bf16_f32 v1, v6, v7
	v_cvt_pk_bf16_f32 v2, v2, v3
	v_cvt_pk_bf16_f32 v3, v8, v9
	global_store_dwordx4 v[16:17], v[0:3], off offset:256 sc1
	s_cbranch_vccnz .LBB0_196
	s_andn2_b64 vcc, exec, s[46:47]
	s_cbranch_vccnz .LBB0_195
	s_barrier
	s_branch .LBB0_195

.LBB0_220:
	s_waitcnt vmcnt(3)
	v_add_u32_e32 v4, 0x1400, v35
	ds_write2_b32 v4, v8, v9 offset0:40 offset1:106
	ds_write2_b32 v4, v10, v11 offset0:172 offset1:238
	s_waitcnt lgkmcnt(0)
	ds_read2_b32 v[10:11], v33 offset0:33 offset1:41
	ds_read2_b32 v[12:13], v33 offset1:8
	v_add_u32_e32 v38, s8, v27
	v_add_u32_e32 v39, s24, v38
	s_movk_i32 s6, 0xaff
	v_cmp_lt_i32_e32 vcc, s6, v39
	s_waitcnt lgkmcnt(0)
	v_cvt_pk_bf16_f32 v4, v12, v10
	s_mulk_i32 s23, 0x1600
	v_cndmask_b32_e32 v10, 0, v211, vcc
	v_subrev_u32_e32 v10, s23, v10
	v_add_lshl_u32 v10, v38, v10, 1
	v_and_b32_e32 v10, -8, v10
	v_cndmask_b32_e64 v12, 0, 4, vcc
	ds_read2_b32 v[14:15], v33 offset0:66 offset1:74
	ds_read2_b32 v[16:17], v33 offset0:99 offset1:107
	ds_read2_b32 v[18:19], v33 offset0:132 offset1:140
	ds_read2_b32 v[20:21], v33 offset0:165 offset1:173
	ds_read2_b32 v[22:23], v33 offset0:198 offset1:206
	ds_read2_b32 v[24:25], v33 offset0:231 offset1:239
	v_or3_b32 v36, v12, v10, v32
	v_add_u32_e32 v10, 8, v39
	v_cmp_lt_i32_e32 vcc, s6, v10
	s_ashr_i32 s51, s50, 31
	v_ashrrev_i32_e32 v37, 31, v36
	v_cndmask_b32_e32 v10, 0, v211, vcc
	v_subrev_u32_e32 v10, s23, v10
	v_lshl_add_u64 v[8:9], s[50:51], 1, v[2:3]
	v_lshlrev_b64 v[36:37], 11, v[36:37]
	v_add_u32_e32 v10, v38, v10
	s_waitcnt vmcnt(2) lgkmcnt(4)
	v_cvt_pk_bf16_f32 v5, v14, v16
	s_waitcnt vmcnt(1) lgkmcnt(2)
	v_cvt_pk_bf16_f32 v6, v18, v20
	s_waitcnt vmcnt(0) lgkmcnt(0)
	v_cvt_pk_bf16_f32 v7, v22, v24
	v_lshl_add_u64 v[36:37], v[8:9], 0, v[36:37]
	v_lshl_add_u32 v10, v10, 1, 16
	global_store_dwordx4 v[36:37], v[4:7], off sc1
	v_and_b32_e32 v10, -8, v10
	s_add_i32 s22, s22, s38
	v_cvt_pk_bf16_f32 v4, v13, v11
	v_cndmask_b32_e64 v11, 0, 4, vcc
	v_or3_b32 v10, v11, v10, v32
	v_ashrrev_i32_e32 v11, 31, v10
	v_lshlrev_b64 v[10:11], 11, v[10:11]
	v_cvt_pk_bf16_f32 v5, v15, v17
	v_cvt_pk_bf16_f32 v6, v19, v21
	v_cvt_pk_bf16_f32 v7, v23, v25
	v_lshl_add_u64 v[10:11], v[8:9], 0, v[10:11]
	global_store_dwordx4 v[10:11], v[4:7], off sc1
	ds_read2_b32 v[10:11], v33 offset0:16 offset1:24
	ds_read2_b32 v[12:13], v33 offset0:49 offset1:57
	ds_read2_b32 v[14:15], v33 offset0:82 offset1:90
	ds_read2_b32 v[16:17], v33 offset0:115 offset1:123
	ds_read2_b32 v[18:19], v33 offset0:148 offset1:156
	ds_read2_b32 v[20:21], v33 offset0:181 offset1:189
	ds_read2_b32 v[22:23], v33 offset0:214 offset1:222
	ds_read2_b32 v[24:25], v33 offset0:247 offset1:255
	s_add_i32 s8, s8, s9
	s_waitcnt lgkmcnt(6)
	v_cvt_pk_bf16_f32 v4, v10, v12
	v_add_u32_e32 v10, 16, v39
	v_cmp_lt_i32_e32 vcc, s6, v10
	s_waitcnt lgkmcnt(4)
	v_cvt_pk_bf16_f32 v5, v14, v16
	s_waitcnt lgkmcnt(2)
	v_cvt_pk_bf16_f32 v6, v18, v20
	v_cndmask_b32_e32 v10, 0, v211, vcc
	v_subrev_u32_e32 v10, s23, v10
	v_add_u32_e32 v10, v38, v10
	v_lshl_add_u32 v10, v10, 1, 32
	v_and_b32_e32 v10, -8, v10
	v_cndmask_b32_e64 v12, 0, 4, vcc
	v_or3_b32 v36, v12, v10, v32
	v_ashrrev_i32_e32 v37, 31, v36
	v_lshlrev_b64 v[36:37], 11, v[36:37]
	s_waitcnt lgkmcnt(0)
	v_cvt_pk_bf16_f32 v7, v22, v24
	v_lshl_add_u64 v[36:37], v[8:9], 0, v[36:37]
	global_store_dwordx4 v[36:37], v[4:7], off sc1
	s_cmpk_lt_i32 s22, 0xb00
	s_nop 0
	v_add_u32_e32 v4, 24, v39
	v_cmp_lt_i32_e32 vcc, s6, v4
	v_cvt_pk_bf16_f32 v6, v19, v21
	v_cvt_pk_bf16_f32 v7, v23, v25
	v_cndmask_b32_e32 v4, 0, v211, vcc
	v_subrev_u32_e32 v4, s23, v4
	v_add_u32_e32 v4, v38, v4
	v_lshl_add_u32 v4, v4, 1, 48
	v_and_b32_e32 v4, -8, v4
	v_cndmask_b32_e64 v5, 0, 4, vcc
	v_or3_b32 v10, v5, v4, v32
	v_cvt_pk_bf16_f32 v4, v11, v13
	v_ashrrev_i32_e32 v11, 31, v10
	v_lshlrev_b64 v[10:11], 11, v[10:11]
	v_cvt_pk_bf16_f32 v5, v15, v17
	v_lshl_add_u64 v[8:9], v[8:9], 0, v[10:11]
	global_store_dwordx4 v[8:9], v[4:7], off sc1
	s_waitcnt lgkmcnt(0)
	s_cbranch_scc0 .LBB0_236

.LBB0_238:
	s_ashr_i32 s9, s8, 31
	s_lshr_b32 s9, s9, 27
	s_add_i32 s9, s8, s9
	s_ashr_i32 s9, s9, 5
	s_lshl_b32 s42, s9, 6
	s_lshl_b32 s9, s9, 10
	v_add_u32_e32 v6, s42, v26
	s_sub_i32 s40, s6, s9
	v_add_u32_e32 v12, 2, v6
	s_ashr_i32 s41, s40, 31
	v_ashrrev_i32_e32 v7, 31, v6
	v_ashrrev_i32_e32 v13, 31, v12
	v_lshl_add_u64 v[4:5], s[40:41], 2, v[0:1]
	v_lshlrev_b64 v[10:11], 12, v[6:7]
	v_lshlrev_b64 v[12:13], 12, v[12:13]
	v_lshl_add_u64 v[10:11], v[4:5], 0, v[10:11]
	v_lshl_add_u64 v[12:13], v[4:5], 0, v[12:13]
	global_load_dword v10, v[10:11], off
	v_add_u32_e32 v14, 6, v6
	global_load_dword v11, v[12:13], off
	v_add_u32_e32 v12, 4, v6
	v_ashrrev_i32_e32 v13, 31, v12
	v_ashrrev_i32_e32 v15, 31, v14
	v_lshlrev_b64 v[12:13], 12, v[12:13]
	v_lshlrev_b64 v[14:15], 12, v[14:15]
	v_lshl_add_u64 v[12:13], v[4:5], 0, v[12:13]
	v_lshl_add_u64 v[14:15], v[4:5], 0, v[14:15]
	global_load_dword v12, v[12:13], off
	v_add_u32_e32 v16, 10, v6
	global_load_dword v13, v[14:15], off
	v_add_u32_e32 v14, 8, v6
	v_ashrrev_i32_e32 v15, 31, v14
	v_ashrrev_i32_e32 v17, 31, v16
	v_lshlrev_b64 v[14:15], 12, v[14:15]
	v_lshlrev_b64 v[16:17], 12, v[16:17]
	v_lshl_add_u64 v[14:15], v[4:5], 0, v[14:15]
	v_lshl_add_u64 v[16:17], v[4:5], 0, v[16:17]
	global_load_dword v14, v[14:15], off
	v_add_u32_e32 v18, 14, v6
	global_load_dword v15, v[16:17], off
	v_add_u32_e32 v16, 12, v6
	v_ashrrev_i32_e32 v17, 31, v16
	v_ashrrev_i32_e32 v19, 31, v18
	v_lshlrev_b64 v[16:17], 12, v[16:17]
	v_lshlrev_b64 v[18:19], 12, v[18:19]
	v_lshl_add_u64 v[16:17], v[4:5], 0, v[16:17]
	v_lshl_add_u64 v[18:19], v[4:5], 0, v[18:19]
	global_load_dword v16, v[16:17], off
	v_add_u32_e32 v20, 18, v6
	global_load_dword v17, v[18:19], off
	v_add_u32_e32 v18, 16, v6
	v_ashrrev_i32_e32 v19, 31, v18
	v_ashrrev_i32_e32 v21, 31, v20
	v_lshlrev_b64 v[18:19], 12, v[18:19]
	v_lshlrev_b64 v[20:21], 12, v[20:21]
	v_lshl_add_u64 v[18:19], v[4:5], 0, v[18:19]
	v_lshl_add_u64 v[20:21], v[4:5], 0, v[20:21]
	global_load_dword v18, v[18:19], off
	v_add_u32_e32 v22, 22, v6
	global_load_dword v19, v[20:21], off
	v_add_u32_e32 v20, 20, v6
	v_ashrrev_i32_e32 v21, 31, v20
	v_ashrrev_i32_e32 v23, 31, v22
	v_lshlrev_b64 v[20:21], 12, v[20:21]
	v_lshlrev_b64 v[22:23], 12, v[22:23]
	v_lshl_add_u64 v[20:21], v[4:5], 0, v[20:21]
	v_lshl_add_u64 v[22:23], v[4:5], 0, v[22:23]
	global_load_dword v20, v[20:21], off
	v_add_u32_e32 v24, 26, v6
	global_load_dword v21, v[22:23], off
	v_add_u32_e32 v22, 24, v6
	v_ashrrev_i32_e32 v23, 31, v22
	v_ashrrev_i32_e32 v25, 31, v24
	v_lshlrev_b64 v[22:23], 12, v[22:23]
	v_lshlrev_b64 v[24:25], 12, v[24:25]
	v_lshl_add_u64 v[22:23], v[4:5], 0, v[22:23]
	v_lshl_add_u64 v[24:25], v[4:5], 0, v[24:25]
	global_load_dword v22, v[22:23], off
	v_add_u32_e32 v28, 30, v6
	global_load_dword v23, v[24:25], off
	v_add_u32_e32 v24, 28, v6
	v_ashrrev_i32_e32 v25, 31, v24
	v_ashrrev_i32_e32 v29, 31, v28
	v_lshlrev_b64 v[24:25], 12, v[24:25]
	v_lshlrev_b64 v[28:29], 12, v[28:29]
	v_lshl_add_u64 v[24:25], v[4:5], 0, v[24:25]
	v_lshl_add_u64 v[28:29], v[4:5], 0, v[28:29]
	global_load_dword v24, v[24:25], off
	v_add_u32_e32 v30, 34, v6
	global_load_dword v25, v[28:29], off
	v_add_u32_e32 v28, 32, v6
	v_ashrrev_i32_e32 v29, 31, v28
	v_ashrrev_i32_e32 v31, 31, v30
	v_lshlrev_b64 v[28:29], 12, v[28:29]
	v_lshlrev_b64 v[30:31], 12, v[30:31]
	v_lshl_add_u64 v[28:29], v[4:5], 0, v[28:29]
	v_lshl_add_u64 v[30:31], v[4:5], 0, v[30:31]
	global_load_dword v28, v[28:29], off
	v_add_u32_e32 v32, 38, v6
	global_load_dword v29, v[30:31], off
	v_add_u32_e32 v30, 36, v6
	v_ashrrev_i32_e32 v31, 31, v30
	v_ashrrev_i32_e32 v33, 31, v32
	v_lshlrev_b64 v[30:31], 12, v[30:31]
	v_lshlrev_b64 v[32:33], 12, v[32:33]
	v_lshl_add_u64 v[30:31], v[4:5], 0, v[30:31]
	v_lshl_add_u64 v[32:33], v[4:5], 0, v[32:33]
	global_load_dword v30, v[30:31], off
	v_add_u32_e32 v34, 42, v6
	global_load_dword v31, v[32:33], off
	v_add_u32_e32 v32, 40, v6
	v_ashrrev_i32_e32 v33, 31, v32
	v_ashrrev_i32_e32 v35, 31, v34
	v_lshlrev_b64 v[32:33], 12, v[32:33]
	v_lshlrev_b64 v[34:35], 12, v[34:35]
	v_lshl_add_u64 v[32:33], v[4:5], 0, v[32:33]
	v_lshl_add_u64 v[34:35], v[4:5], 0, v[34:35]
	global_load_dword v32, v[32:33], off
	v_add_u32_e32 v36, 46, v6
	global_load_dword v33, v[34:35], off
	v_add_u32_e32 v34, 44, v6
	v_ashrrev_i32_e32 v35, 31, v34
	v_ashrrev_i32_e32 v37, 31, v36
	v_lshlrev_b64 v[34:35], 12, v[34:35]
	v_lshlrev_b64 v[36:37], 12, v[36:37]
	v_lshl_add_u64 v[34:35], v[4:5], 0, v[34:35]
	v_lshl_add_u64 v[36:37], v[4:5], 0, v[36:37]
	global_load_dword v34, v[34:35], off
	v_add_u32_e32 v38, 50, v6
	global_load_dword v35, v[36:37], off
	v_add_u32_e32 v36, 48, v6
	v_ashrrev_i32_e32 v37, 31, v36
	v_ashrrev_i32_e32 v39, 31, v38
	v_lshlrev_b64 v[36:37], 12, v[36:37]
	v_lshlrev_b64 v[38:39], 12, v[38:39]
	v_lshl_add_u64 v[36:37], v[4:5], 0, v[36:37]
	v_lshl_add_u64 v[38:39], v[4:5], 0, v[38:39]
	global_load_dword v36, v[36:37], off
	v_add_u32_e32 v40, 54, v6
	global_load_dword v37, v[38:39], off
	v_add_u32_e32 v38, 52, v6
	v_ashrrev_i32_e32 v39, 31, v38
	v_ashrrev_i32_e32 v41, 31, v40
	v_lshlrev_b64 v[38:39], 12, v[38:39]
	v_lshlrev_b64 v[40:41], 12, v[40:41]
	v_lshl_add_u64 v[38:39], v[4:5], 0, v[38:39]
	v_lshl_add_u64 v[40:41], v[4:5], 0, v[40:41]
	global_load_dword v38, v[38:39], off
	v_add_u32_e32 v42, 58, v6
	global_load_dword v39, v[40:41], off
	v_add_u32_e32 v40, 56, v6
	v_ashrrev_i32_e32 v41, 31, v40
	v_ashrrev_i32_e32 v43, 31, v42
	v_lshlrev_b64 v[40:41], 12, v[40:41]
	v_lshlrev_b64 v[42:43], 12, v[42:43]
	v_lshl_add_u64 v[40:41], v[4:5], 0, v[40:41]
	v_lshl_add_u64 v[42:43], v[4:5], 0, v[42:43]
	global_load_dword v40, v[40:41], off
	s_ashr_i32 s43, s42, 31
	global_load_dword v41, v[42:43], off
	v_add_u32_e32 v42, 60, v6
	v_add_u32_e32 v6, 62, v6
	v_ashrrev_i32_e32 v43, 31, v42
	v_ashrrev_i32_e32 v7, 31, v6
	v_lshlrev_b64 v[42:43], 12, v[42:43]
	v_lshlrev_b64 v[6:7], 12, v[6:7]
	v_lshl_add_u64 v[42:43], v[4:5], 0, v[42:43]
	v_lshl_add_u64 v[4:5], v[4:5], 0, v[6:7]
	global_load_dword v42, v[42:43], off
	s_add_i32 s8, s8, s38
	global_load_dword v4, v[4:5], off
	v_add_u32_e32 v5, 0x400, v9
	s_waitcnt vmcnt(30)
	ds_write2_b32 v9, v10, v11 offset1:66
	s_waitcnt vmcnt(28)
	ds_write2_b32 v9, v12, v13 offset0:132 offset1:198
	s_waitcnt vmcnt(26)
	ds_write2_b32 v5, v14, v15 offset0:8 offset1:74
	s_waitcnt vmcnt(24)
	ds_write2_b32 v5, v16, v17 offset0:140 offset1:206
	v_add_u32_e32 v5, 0x800, v9
	s_waitcnt vmcnt(22)
	ds_write2_b32 v5, v18, v19 offset0:16 offset1:82
	s_waitcnt vmcnt(20)
	ds_write2_b32 v5, v20, v21 offset0:148 offset1:214
	v_add_u32_e32 v5, 0xc00, v9
	s_waitcnt vmcnt(18)
	ds_write2_b32 v5, v22, v23 offset0:24 offset1:90
	s_waitcnt vmcnt(16)
	ds_write2_b32 v5, v24, v25 offset0:156 offset1:222
	v_add_u32_e32 v5, 0x1000, v9
	s_waitcnt vmcnt(14)
	ds_write2_b32 v5, v28, v29 offset0:32 offset1:98
	s_waitcnt vmcnt(12)
	ds_write2_b32 v5, v30, v31 offset0:164 offset1:230
	v_add_u32_e32 v5, 0x1400, v9
	s_waitcnt vmcnt(10)
	ds_write2_b32 v5, v32, v33 offset0:40 offset1:106
	s_waitcnt vmcnt(8)
	ds_write2_b32 v5, v34, v35 offset0:172 offset1:238
	v_add_u32_e32 v5, 0x1800, v9
	s_waitcnt vmcnt(6)
	ds_write2_b32 v5, v36, v37 offset0:48 offset1:114
	s_waitcnt vmcnt(4)
	ds_write2_b32 v5, v38, v39 offset0:180 offset1:246
	v_add_u32_e32 v5, 0x1c00, v9
	s_waitcnt vmcnt(2)
	ds_write2_b32 v5, v40, v41 offset0:56 offset1:122
	s_waitcnt vmcnt(0)
	ds_write2_b32 v5, v42, v4 offset0:188 offset1:254
	s_waitcnt lgkmcnt(0)
	ds_read2_b32 v[12:13], v8 offset0:33 offset1:41
	ds_read2_b32 v[14:15], v8 offset1:8
	ds_read2_b32 v[16:17], v8 offset0:66 offset1:74
	ds_read2_b32 v[18:19], v8 offset0:99 offset1:107
	ds_read2_b32 v[20:21], v8 offset0:132 offset1:140
	ds_read2_b32 v[22:23], v8 offset0:165 offset1:173
	ds_read2_b32 v[24:25], v8 offset0:198 offset1:206
	ds_read2_b32 v[28:29], v8 offset0:231 offset1:239
	v_lshl_add_u64 v[10:11], s[42:43], 1, v[2:3]
	v_add_u32_e32 v32, s40, v27
	s_waitcnt lgkmcnt(6)
	v_cvt_pk_bf16_f32 v4, v14, v12
	s_waitcnt lgkmcnt(4)
	v_cvt_pk_bf16_f32 v5, v16, v18
	s_waitcnt lgkmcnt(2)
	v_cvt_pk_bf16_f32 v6, v20, v22
	s_waitcnt lgkmcnt(0)
	v_cvt_pk_bf16_f32 v7, v24, v28
	v_mad_i64_i32 v[30:31], s[22:23], v32, s16, v[10:11]
	v_add_u32_e32 v12, 8, v32
	global_store_dwordx4 v[30:31], v[4:7], off sc1
	s_add_i32 s6, s6, s7
	s_cmpk_lt_i32 s8, 0x580
	v_cvt_pk_bf16_f32 v4, v15, v13
	v_cvt_pk_bf16_f32 v5, v17, v19
	v_cvt_pk_bf16_f32 v6, v21, v23
	v_cvt_pk_bf16_f32 v7, v25, v29
	v_mad_i64_i32 v[12:13], s[22:23], v12, s16, v[10:11]
	global_store_dwordx4 v[12:13], v[4:7], off sc1
	ds_read2_b32 v[12:13], v8 offset0:49 offset1:57
	ds_read2_b32 v[14:15], v8 offset0:16 offset1:24
	ds_read2_b32 v[16:17], v8 offset0:82 offset1:90
	ds_read2_b32 v[18:19], v8 offset0:115 offset1:123
	ds_read2_b32 v[20:21], v8 offset0:148 offset1:156
	ds_read2_b32 v[22:23], v8 offset0:181 offset1:189
	ds_read2_b32 v[24:25], v8 offset0:214 offset1:222
	ds_read2_b32 v[28:29], v8 offset0:247 offset1:255
	s_waitcnt lgkmcnt(6)
	v_cvt_pk_bf16_f32 v4, v14, v12
	v_add_u32_e32 v12, 16, v32
	s_waitcnt lgkmcnt(4)
	v_cvt_pk_bf16_f32 v5, v16, v18
	s_waitcnt lgkmcnt(2)
	v_cvt_pk_bf16_f32 v6, v20, v22
	s_waitcnt lgkmcnt(0)
	v_cvt_pk_bf16_f32 v7, v24, v28
	v_mad_i64_i32 v[30:31], s[22:23], v12, s16, v[10:11]
	v_add_u32_e32 v12, 24, v32
	global_store_dwordx4 v[30:31], v[4:7], off sc1
	v_mad_i64_i32 v[10:11], s[22:23], v12, s16, v[10:11]
	s_nop 0
	v_cvt_pk_bf16_f32 v4, v15, v13
	v_cvt_pk_bf16_f32 v5, v17, v19
	v_cvt_pk_bf16_f32 v6, v21, v23
	v_cvt_pk_bf16_f32 v7, v25, v29
	global_store_dwordx4 v[10:11], v[4:7], off sc1
	s_waitcnt lgkmcnt(0)
	s_cbranch_scc1 .LBB0_238

.LBB0_502:
	s_add_i32 s62, 0, 0x10000
	s_add_i32 s61, 0, 0x14000
	v_add_u32_e32 v19, s62, v16
	v_add_u32_e32 v20, s61, v16
	ds_read_b128 v[22:25], v19
	ds_read_b128 v[26:29], v19 offset:1024
	ds_read_b128 v[30:33], v19 offset:2048
	ds_read_b128 v[34:37], v19 offset:3072
	ds_read_b128 v[38:41], v20
	ds_read_b128 v[42:45], v20 offset:1024
	ds_read_b128 v[46:49], v20 offset:2048
	ds_read_b128 v[50:53], v20 offset:3072
	s_add_u32 s58, s50, 0x18080
	s_addc_u32 s59, s51, 0
	s_add_i32 s65, s26, 0xc000
	v_lshl_add_u64 v[78:79], s[58:59], 0, v[6:7]
	s_mov_b32 m0, s65
	s_add_i32 s57, s26, 0xe000
	ds_read_b128 v[8:11], v17
	ds_read_b128 v[12:15], v17 offset:1024
	ds_read_b128 v[54:57], v17 offset:2048
	ds_read_b128 v[58:61], v17 offset:3072
	ds_read_b128 v[62:65], v17 offset:4096
	ds_read_b128 v[66:69], v17 offset:5120
	ds_read_b128 v[70:73], v17 offset:6144
	ds_read_b128 v[74:77], v17 offset:7168
	global_load_lds_dwordx4 v[78:79], off
	v_lshl_add_u64 v[78:79], s[58:59], 0, v[2:3]
	s_mov_b32 m0, s57
	s_nop 0
	global_load_lds_dwordx4 v[78:79], off
	s_waitcnt vmcnt(8)
	s_waitcnt lgkmcnt(0)
	s_barrier
	s_setprio 1
	s_waitcnt lgkmcnt(0)
	v_mfma_f32_16x16x32_bf16 v[78:81], v[22:25], v[8:11], 0
	v_mfma_f32_16x16x32_bf16 v[82:85], v[30:33], v[8:11], 0
	v_mfma_f32_16x16x32_bf16 v[86:89], v[22:25], v[54:57], 0
	v_mfma_f32_16x16x32_bf16 v[90:93], v[30:33], v[54:57], 0
	v_mfma_f32_16x16x32_bf16 v[94:97], v[22:25], v[62:65], 0
	v_mfma_f32_16x16x32_bf16 v[98:101], v[30:33], v[62:65], 0
	v_mfma_f32_16x16x32_bf16 v[102:105], v[22:25], v[70:73], 0
	v_mfma_f32_16x16x32_bf16 v[106:109], v[30:33], v[70:73], 0
	v_mfma_f32_16x16x32_bf16 v[78:81], v[26:29], v[12:15], v[78:81]
	v_mfma_f32_16x16x32_bf16 v[82:85], v[34:37], v[12:15], v[82:85]
	v_mfma_f32_16x16x32_bf16 v[86:89], v[26:29], v[58:61], v[86:89]
	v_mfma_f32_16x16x32_bf16 v[90:93], v[34:37], v[58:61], v[90:93]
	v_mfma_f32_16x16x32_bf16 v[94:97], v[26:29], v[66:69], v[94:97]
	v_mfma_f32_16x16x32_bf16 v[98:101], v[34:37], v[66:69], v[98:101]
	v_mfma_f32_16x16x32_bf16 v[102:105], v[26:29], v[74:77], v[102:105]
	v_mfma_f32_16x16x32_bf16 v[106:109], v[34:37], v[74:77], v[106:109]
	s_setprio 0
	s_setprio 1
	v_mfma_f32_16x16x32_bf16 v[110:113], v[38:41], v[8:11], 0
	v_mfma_f32_16x16x32_bf16 v[8:11], v[46:49], v[8:11], 0
	v_mfma_f32_16x16x32_bf16 v[114:117], v[50:53], v[12:15], v[8:11]
	v_mfma_f32_16x16x32_bf16 v[8:11], v[38:41], v[54:57], 0
	v_mfma_f32_16x16x32_bf16 v[118:121], v[42:45], v[58:61], v[8:11]
	v_mfma_f32_16x16x32_bf16 v[8:11], v[46:49], v[54:57], 0
	v_mfma_f32_16x16x32_bf16 v[54:57], v[50:53], v[58:61], v[8:11]
	v_mfma_f32_16x16x32_bf16 v[8:11], v[38:41], v[62:65], 0
	v_mfma_f32_16x16x32_bf16 v[58:61], v[42:45], v[66:69], v[8:11]
	v_mfma_f32_16x16x32_bf16 v[8:11], v[46:49], v[62:65], 0
	v_mfma_f32_16x16x32_bf16 v[62:65], v[50:53], v[66:69], v[8:11]
	v_mfma_f32_16x16x32_bf16 v[8:11], v[38:41], v[70:73], 0
	v_mfma_f32_16x16x32_bf16 v[66:69], v[42:45], v[74:77], v[8:11]
	v_mfma_f32_16x16x32_bf16 v[8:11], v[46:49], v[70:73], 0
	v_mfma_f32_16x16x32_bf16 v[110:113], v[42:45], v[12:15], v[110:113]
	v_mfma_f32_16x16x32_bf16 v[70:73], v[50:53], v[74:77], v[8:11]
	s_setprio 0
	s_barrier
	s_nop 3
	v_lshl_add_u64 v[8:9], s[52:53], 0, v[4:5]
	s_mov_b64 s[68:69], 0x100
	s_add_i32 s62, s62, s25
	v_lshl_add_u64 v[10:11], v[8:9], 0, s[68:69]
	s_mov_b32 m0, s62
	s_add_i32 s58, s62, 0x2000
	ds_read_b128 v[74:77], v17 offset:16384
	ds_read_b128 v[122:125], v17 offset:17408
	ds_read_b128 v[126:129], v17 offset:18432
	ds_read_b128 v[130:133], v17 offset:19456
	ds_read_b128 v[134:137], v17 offset:20480
	ds_read_b128 v[138:141], v17 offset:21504
	ds_read_b128 v[142:145], v17 offset:22528
	ds_read_b128 v[146:149], v17 offset:23552
	global_load_lds_dwordx4 v[10:11], off
	v_lshl_add_u64 v[10:11], s[52:53], 0, v[0:1]
	s_add_u32 s66, s52, 0x18100
	v_lshl_add_u64 v[12:13], v[10:11], 0, s[68:69]
	s_mov_b32 m0, s58
	s_addc_u32 s67, s53, 0
	s_add_i32 s59, s61, s25
	global_load_lds_dwordx4 v[12:13], off
	v_lshl_add_u64 v[12:13], s[66:67], 0, v[4:5]
	s_mov_b32 m0, s59
	s_add_i32 s61, s59, 0x2000
	global_load_lds_dwordx4 v[12:13], off
	v_lshl_add_u64 v[12:13], s[66:67], 0, v[0:1]
	s_mov_b32 m0, s61
	s_nop 0
	global_load_lds_dwordx4 v[12:13], off
	v_lshl_add_u64 v[12:13], s[50:51], 0, v[6:7]
	v_lshl_add_u64 v[14:15], v[12:13], 0, s[68:69]
	s_mov_b32 m0, s26
	s_nop 0
	global_load_lds_dwordx4 v[14:15], off
	v_lshl_add_u64 v[14:15], s[50:51], 0, v[2:3]
	v_lshl_add_u64 v[150:151], v[14:15], 0, s[68:69]
	s_mov_b32 m0, s27
	s_nop 0
	global_load_lds_dwordx4 v[150:151], off
	s_waitcnt vmcnt(8)
	s_waitcnt lgkmcnt(0)
	s_barrier
	s_setprio 1
	s_waitcnt lgkmcnt(0)
	v_mfma_f32_16x16x32_bf16 v[150:153], v[22:25], v[74:77], 0
	v_mfma_f32_16x16x32_bf16 v[178:181], v[22:25], v[126:129], 0
	v_mfma_f32_16x16x32_bf16 v[186:189], v[22:25], v[134:137], 0
	v_mfma_f32_16x16x32_bf16 v[22:25], v[22:25], v[142:145], 0
	v_mfma_f32_16x16x32_bf16 v[150:153], v[26:29], v[122:125], v[150:153]
	v_mfma_f32_16x16x32_bf16 v[154:157], v[30:33], v[74:77], 0
	v_mfma_f32_16x16x32_bf16 v[178:181], v[26:29], v[130:133], v[178:181]
	v_mfma_f32_16x16x32_bf16 v[182:185], v[30:33], v[126:129], 0
	v_mfma_f32_16x16x32_bf16 v[186:189], v[26:29], v[138:141], v[186:189]
	v_mfma_f32_16x16x32_bf16 v[190:193], v[30:33], v[134:137], 0
	v_mfma_f32_16x16x32_bf16 v[24:27], v[26:29], v[146:149], v[22:25]
	v_mfma_f32_16x16x32_bf16 v[28:31], v[30:33], v[142:145], 0
	v_mfma_f32_16x16x32_bf16 v[154:157], v[34:37], v[122:125], v[154:157]
	v_mfma_f32_16x16x32_bf16 v[182:185], v[34:37], v[130:133], v[182:185]
	v_mfma_f32_16x16x32_bf16 v[190:193], v[34:37], v[138:141], v[190:193]
	v_mfma_f32_16x16x32_bf16 v[28:31], v[34:37], v[146:149], v[28:31]
	s_setprio 0
	s_setprio 1
	v_mfma_f32_16x16x32_bf16 v[32:35], v[38:41], v[74:77], 0
	v_mfma_f32_16x16x32_bf16 v[74:77], v[46:49], v[74:77], 0
	v_mfma_f32_16x16x32_bf16 v[32:35], v[42:45], v[122:125], v[32:35]
	v_mfma_f32_16x16x32_bf16 v[74:77], v[50:53], v[122:125], v[74:77]
	v_mfma_f32_16x16x32_bf16 v[122:125], v[38:41], v[126:129], 0
	v_mfma_f32_16x16x32_bf16 v[126:129], v[46:49], v[126:129], 0
	v_mfma_f32_16x16x32_bf16 v[122:125], v[42:45], v[130:133], v[122:125]
	v_mfma_f32_16x16x32_bf16 v[126:129], v[50:53], v[130:133], v[126:129]
	v_mfma_f32_16x16x32_bf16 v[130:133], v[38:41], v[134:137], 0
	v_mfma_f32_16x16x32_bf16 v[36:39], v[38:41], v[142:145], 0
	v_mfma_f32_16x16x32_bf16 v[130:133], v[42:45], v[138:141], v[130:133]
	v_mfma_f32_16x16x32_bf16 v[134:137], v[46:49], v[134:137], 0
	v_mfma_f32_16x16x32_bf16 v[36:39], v[42:45], v[146:149], v[36:39]
	v_mfma_f32_16x16x32_bf16 v[40:43], v[46:49], v[142:145], 0
	v_mfma_f32_16x16x32_bf16 v[134:137], v[50:53], v[138:141], v[134:137]
	v_mfma_f32_16x16x32_bf16 v[40:43], v[50:53], v[146:149], v[40:43]
	s_setprio 0
	s_barrier
	s_add_i32 s63, 0, 0x18000
	s_add_i32 s64, 0, 0x1c000
	v_add_u32_e32 v21, s63, v16
	v_add_u32_e32 v22, s64, v16
	ds_read_b128 v[44:47], v21
	ds_read_b128 v[48:51], v21 offset:1024
	ds_read_b128 v[138:141], v21 offset:2048
	ds_read_b128 v[142:145], v21 offset:3072
	ds_read_b128 v[146:149], v22
	ds_read_b128 v[194:197], v22 offset:1024
	ds_read_b128 v[198:201], v22 offset:2048
	ds_read_b128 v[202:205], v22 offset:3072
	s_add_u32 s66, s50, 0x18100
	s_addc_u32 s67, s51, 0
	s_mov_b32 m0, s28
	v_lshl_add_u64 v[52:53], s[66:67], 0, v[6:7]
	ds_read_b128 v[220:223], v17 offset:32768
	ds_read_b128 v[228:231], v17 offset:33792
	ds_read_b128 v[232:235], v17 offset:34816
	ds_read_b128 v[236:239], v17 offset:35840
	ds_read_b128 v[240:243], v17 offset:36864
	ds_read_b128 v[244:247], v17 offset:37888
	ds_read_b128 v[248:251], v17 offset:38912
	ds_read_b128 v[174:177], v17 offset:39936
	global_load_lds_dwordx4 v[52:53], off
	v_lshl_add_u64 v[52:53], s[66:67], 0, v[2:3]
	s_mov_b32 m0, s29
	s_nop 0
	global_load_lds_dwordx4 v[52:53], off
	s_waitcnt vmcnt(8)
	s_waitcnt lgkmcnt(0)
	s_barrier
	s_setprio 1
	s_waitcnt lgkmcnt(0)
	v_mfma_f32_16x16x32_bf16 v[78:81], v[44:47], v[220:223], v[78:81]
	v_mfma_f32_16x16x32_bf16 v[82:85], v[138:141], v[220:223], v[82:85]
	v_mfma_f32_16x16x32_bf16 v[86:89], v[44:47], v[232:235], v[86:89]
	v_mfma_f32_16x16x32_bf16 v[90:93], v[138:141], v[232:235], v[90:93]
	v_mfma_f32_16x16x32_bf16 v[94:97], v[44:47], v[240:243], v[94:97]
	v_mfma_f32_16x16x32_bf16 v[98:101], v[138:141], v[240:243], v[98:101]
	v_mfma_f32_16x16x32_bf16 v[102:105], v[44:47], v[248:251], v[102:105]
	v_mfma_f32_16x16x32_bf16 v[106:109], v[138:141], v[248:251], v[106:109]
	v_mfma_f32_16x16x32_bf16 v[78:81], v[48:51], v[228:231], v[78:81]
	v_mfma_f32_16x16x32_bf16 v[82:85], v[142:145], v[228:231], v[82:85]
	v_mfma_f32_16x16x32_bf16 v[86:89], v[48:51], v[236:239], v[86:89]
	v_mfma_f32_16x16x32_bf16 v[90:93], v[142:145], v[236:239], v[90:93]
	v_mfma_f32_16x16x32_bf16 v[94:97], v[48:51], v[244:247], v[94:97]
	v_mfma_f32_16x16x32_bf16 v[98:101], v[142:145], v[244:247], v[98:101]
	v_mfma_f32_16x16x32_bf16 v[102:105], v[48:51], v[174:177], v[102:105]
	v_mfma_f32_16x16x32_bf16 v[106:109], v[142:145], v[174:177], v[106:109]
	s_setprio 0
	s_setprio 1
	v_mfma_f32_16x16x32_bf16 v[110:113], v[146:149], v[220:223], v[110:113]
	v_mfma_f32_16x16x32_bf16 v[114:117], v[198:201], v[220:223], v[114:117]
	v_mfma_f32_16x16x32_bf16 v[118:121], v[146:149], v[232:235], v[118:121]
	v_mfma_f32_16x16x32_bf16 v[52:55], v[198:201], v[232:235], v[54:57]
	v_mfma_f32_16x16x32_bf16 v[56:59], v[146:149], v[240:243], v[58:61]
	v_mfma_f32_16x16x32_bf16 v[60:63], v[198:201], v[240:243], v[62:65]
	v_mfma_f32_16x16x32_bf16 v[64:67], v[146:149], v[248:251], v[66:69]
	v_mfma_f32_16x16x32_bf16 v[68:71], v[198:201], v[248:251], v[70:73]
	v_mfma_f32_16x16x32_bf16 v[110:113], v[194:197], v[228:231], v[110:113]
	v_mfma_f32_16x16x32_bf16 v[114:117], v[202:205], v[228:231], v[114:117]
	v_mfma_f32_16x16x32_bf16 v[118:121], v[194:197], v[236:239], v[118:121]
	v_mfma_f32_16x16x32_bf16 v[52:55], v[202:205], v[236:239], v[52:55]
	v_mfma_f32_16x16x32_bf16 v[56:59], v[194:197], v[244:247], v[56:59]
	v_mfma_f32_16x16x32_bf16 v[60:63], v[202:205], v[244:247], v[60:63]
	v_mfma_f32_16x16x32_bf16 v[64:67], v[194:197], v[174:177], v[64:67]
	v_mfma_f32_16x16x32_bf16 v[68:71], v[202:205], v[174:177], v[68:71]
	s_setprio 0
	s_barrier
	s_add_i32 s67, s63, s25
	s_mov_b64 s[70:71], 0x180
	s_add_i32 s63, s67, 0x2000
	v_lshl_add_u64 v[72:73], v[8:9], 0, s[70:71]
	s_mov_b32 m0, s67
	s_add_u32 s68, s52, 0x18180
	ds_read_b128 v[174:177], v17 offset:49152
	ds_read_b128 v[220:223], v17 offset:50176
	ds_read_b128 v[228:231], v17 offset:51200
	ds_read_b128 v[232:235], v17 offset:52224
	ds_read_b128 v[236:239], v17 offset:53248
	ds_read_b128 v[240:243], v17 offset:54272
	ds_read_b128 v[244:247], v17 offset:55296
	ds_read_b128 v[248:251], v17 offset:56320
	global_load_lds_dwordx4 v[72:73], off
	v_lshl_add_u64 v[72:73], v[10:11], 0, s[70:71]
	s_mov_b32 m0, s63
	s_addc_u32 s69, s53, 0
	s_add_i32 s64, s64, s25
	global_load_lds_dwordx4 v[72:73], off
	v_lshl_add_u64 v[72:73], s[68:69], 0, v[4:5]
	s_mov_b32 m0, s64
	s_add_i32 s66, s64, 0x2000
	global_load_lds_dwordx4 v[72:73], off
	v_lshl_add_u64 v[72:73], s[68:69], 0, v[0:1]
	s_mov_b32 m0, s66
	s_nop 0
	global_load_lds_dwordx4 v[72:73], off
	v_lshl_add_u64 v[72:73], v[12:13], 0, s[70:71]
	s_mov_b32 m0, s30
	s_nop 0
	global_load_lds_dwordx4 v[72:73], off
	v_lshl_add_u64 v[72:73], v[14:15], 0, s[70:71]
	s_mov_b32 m0, s31
	s_nop 0
	global_load_lds_dwordx4 v[72:73], off
	s_waitcnt vmcnt(8)
	s_waitcnt lgkmcnt(0)
	s_barrier
	s_setprio 1
	s_waitcnt lgkmcnt(0)
	v_mfma_f32_16x16x32_bf16 v[150:153], v[44:47], v[174:177], v[150:153]
	v_mfma_f32_16x16x32_bf16 v[154:157], v[138:141], v[174:177], v[154:157]
	v_mfma_f32_16x16x32_bf16 v[178:181], v[44:47], v[228:231], v[178:181]
	v_mfma_f32_16x16x32_bf16 v[182:185], v[138:141], v[228:231], v[182:185]
	v_mfma_f32_16x16x32_bf16 v[186:189], v[44:47], v[236:239], v[186:189]
	v_mfma_f32_16x16x32_bf16 v[190:193], v[138:141], v[236:239], v[190:193]
	v_mfma_f32_16x16x32_bf16 v[24:27], v[44:47], v[244:247], v[24:27]
	v_mfma_f32_16x16x32_bf16 v[28:31], v[138:141], v[244:247], v[28:31]
	v_mfma_f32_16x16x32_bf16 v[150:153], v[48:51], v[220:223], v[150:153]
	v_mfma_f32_16x16x32_bf16 v[154:157], v[142:145], v[220:223], v[154:157]
	v_mfma_f32_16x16x32_bf16 v[178:181], v[48:51], v[232:235], v[178:181]
	v_mfma_f32_16x16x32_bf16 v[182:185], v[142:145], v[232:235], v[182:185]
	v_mfma_f32_16x16x32_bf16 v[186:189], v[48:51], v[240:243], v[186:189]
	v_mfma_f32_16x16x32_bf16 v[190:193], v[142:145], v[240:243], v[190:193]
	v_mfma_f32_16x16x32_bf16 v[24:27], v[48:51], v[248:251], v[24:27]
	v_mfma_f32_16x16x32_bf16 v[28:31], v[142:145], v[248:251], v[28:31]
	s_setprio 0
	s_setprio 1
	v_mfma_f32_16x16x32_bf16 v[32:35], v[146:149], v[174:177], v[32:35]
	v_mfma_f32_16x16x32_bf16 v[44:47], v[198:201], v[174:177], v[74:77]
	v_mfma_f32_16x16x32_bf16 v[48:51], v[146:149], v[228:231], v[122:125]
	v_mfma_f32_16x16x32_bf16 v[72:75], v[198:201], v[228:231], v[126:129]
	v_mfma_f32_16x16x32_bf16 v[122:125], v[146:149], v[236:239], v[130:133]
	v_mfma_f32_16x16x32_bf16 v[126:129], v[198:201], v[236:239], v[134:137]
	v_mfma_f32_16x16x32_bf16 v[36:39], v[146:149], v[244:247], v[36:39]
	v_mfma_f32_16x16x32_bf16 v[40:43], v[198:201], v[244:247], v[40:43]
	v_mfma_f32_16x16x32_bf16 v[32:35], v[194:197], v[220:223], v[32:35]
	v_mfma_f32_16x16x32_bf16 v[44:47], v[202:205], v[220:223], v[44:47]
	v_mfma_f32_16x16x32_bf16 v[48:51], v[194:197], v[232:235], v[48:51]
	v_mfma_f32_16x16x32_bf16 v[72:75], v[202:205], v[232:235], v[72:75]
	v_mfma_f32_16x16x32_bf16 v[122:125], v[194:197], v[240:243], v[122:125]
	v_mfma_f32_16x16x32_bf16 v[126:129], v[202:205], v[240:243], v[126:129]
	v_mfma_f32_16x16x32_bf16 v[36:39], v[194:197], v[248:251], v[36:39]
	v_mfma_f32_16x16x32_bf16 v[40:43], v[202:205], v[248:251], v[40:43]
	s_setprio 0
	s_barrier
	ds_read_b128 v[130:133], v19
	ds_read_b128 v[134:137], v19 offset:1024
	ds_read_b128 v[138:141], v19 offset:2048
	ds_read_b128 v[142:145], v19 offset:3072
	ds_read_b128 v[146:149], v20
	ds_read_b128 v[174:177], v20 offset:1024
	ds_read_b128 v[194:197], v20 offset:2048
	ds_read_b128 v[198:201], v20 offset:3072
	s_add_u32 s68, s50, 0x18180
	s_addc_u32 s69, s51, 0
	s_mov_b32 m0, s65
	v_lshl_add_u64 v[76:77], s[68:69], 0, v[6:7]
	ds_read_b128 v[202:205], v17
	ds_read_b128 v[220:223], v17 offset:1024
	ds_read_b128 v[228:231], v17 offset:2048
	ds_read_b128 v[232:235], v17 offset:3072
	ds_read_b128 v[236:239], v17 offset:4096
	ds_read_b128 v[240:243], v17 offset:5120
	ds_read_b128 v[244:247], v17 offset:6144
	ds_read_b128 v[248:251], v17 offset:7168
	global_load_lds_dwordx4 v[76:77], off
	v_lshl_add_u64 v[76:77], s[68:69], 0, v[2:3]
	s_mov_b32 m0, s57
	s_nop 0
	global_load_lds_dwordx4 v[76:77], off
	s_waitcnt vmcnt(8)
	s_waitcnt lgkmcnt(0)
	s_barrier
	s_setprio 1
	s_waitcnt lgkmcnt(0)
	v_mfma_f32_16x16x32_bf16 v[76:79], v[130:133], v[202:205], v[78:81]
	v_mfma_f32_16x16x32_bf16 v[80:83], v[138:141], v[202:205], v[82:85]
	v_mfma_f32_16x16x32_bf16 v[84:87], v[130:133], v[228:231], v[86:89]
	v_mfma_f32_16x16x32_bf16 v[88:91], v[138:141], v[228:231], v[90:93]
	v_mfma_f32_16x16x32_bf16 v[92:95], v[130:133], v[236:239], v[94:97]
	v_mfma_f32_16x16x32_bf16 v[96:99], v[138:141], v[236:239], v[98:101]
	v_mfma_f32_16x16x32_bf16 v[100:103], v[130:133], v[244:247], v[102:105]
	v_mfma_f32_16x16x32_bf16 v[104:107], v[138:141], v[244:247], v[106:109]
	v_mfma_f32_16x16x32_bf16 v[76:79], v[134:137], v[220:223], v[76:79]
	v_mfma_f32_16x16x32_bf16 v[80:83], v[142:145], v[220:223], v[80:83]
	v_mfma_f32_16x16x32_bf16 v[84:87], v[134:137], v[232:235], v[84:87]
	v_mfma_f32_16x16x32_bf16 v[88:91], v[142:145], v[232:235], v[88:91]
	v_mfma_f32_16x16x32_bf16 v[92:95], v[134:137], v[240:243], v[92:95]
	v_mfma_f32_16x16x32_bf16 v[96:99], v[142:145], v[240:243], v[96:99]
	v_mfma_f32_16x16x32_bf16 v[100:103], v[134:137], v[248:251], v[100:103]
	v_mfma_f32_16x16x32_bf16 v[104:107], v[142:145], v[248:251], v[104:107]
	s_setprio 0
	s_setprio 1
	v_mfma_f32_16x16x32_bf16 v[108:111], v[146:149], v[202:205], v[110:113]
	v_mfma_f32_16x16x32_bf16 v[112:115], v[194:197], v[202:205], v[114:117]
	v_mfma_f32_16x16x32_bf16 v[116:119], v[146:149], v[228:231], v[118:121]
	v_mfma_f32_16x16x32_bf16 v[52:55], v[194:197], v[228:231], v[52:55]
	v_mfma_f32_16x16x32_bf16 v[56:59], v[146:149], v[236:239], v[56:59]
	v_mfma_f32_16x16x32_bf16 v[60:63], v[194:197], v[236:239], v[60:63]
	v_mfma_f32_16x16x32_bf16 v[64:67], v[146:149], v[244:247], v[64:67]
	v_mfma_f32_16x16x32_bf16 v[68:71], v[194:197], v[244:247], v[68:71]
	v_mfma_f32_16x16x32_bf16 v[108:111], v[174:177], v[220:223], v[108:111]
	v_mfma_f32_16x16x32_bf16 v[112:115], v[198:201], v[220:223], v[112:115]
	v_mfma_f32_16x16x32_bf16 v[116:119], v[174:177], v[232:235], v[116:119]
	v_mfma_f32_16x16x32_bf16 v[52:55], v[198:201], v[232:235], v[52:55]
	v_mfma_f32_16x16x32_bf16 v[56:59], v[174:177], v[240:243], v[56:59]
	v_mfma_f32_16x16x32_bf16 v[60:63], v[198:201], v[240:243], v[60:63]
	v_mfma_f32_16x16x32_bf16 v[64:67], v[174:177], v[248:251], v[64:67]
	v_mfma_f32_16x16x32_bf16 v[68:71], v[198:201], v[248:251], v[68:71]
	s_setprio 0
	s_barrier
	s_mov_b64 s[70:71], 0x200
	s_mov_b32 m0, s62
	v_lshl_add_u64 v[120:121], v[8:9], 0, s[70:71]
	s_add_u32 s68, s52, 0x18200
	ds_read_b128 v[202:205], v17 offset:16384
	ds_read_b128 v[220:223], v17 offset:17408
	ds_read_b128 v[228:231], v17 offset:18432
	ds_read_b128 v[232:235], v17 offset:19456
	ds_read_b128 v[236:239], v17 offset:20480
	ds_read_b128 v[240:243], v17 offset:21504
	ds_read_b128 v[244:247], v17 offset:22528
	ds_read_b128 v[248:251], v17 offset:23552
	global_load_lds_dwordx4 v[120:121], off
	v_lshl_add_u64 v[120:121], v[10:11], 0, s[70:71]
	s_mov_b32 m0, s58
	s_addc_u32 s69, s53, 0
	global_load_lds_dwordx4 v[120:121], off
	v_lshl_add_u64 v[120:121], s[68:69], 0, v[4:5]
	s_mov_b32 m0, s59
	s_nop 0
	global_load_lds_dwordx4 v[120:121], off
	v_lshl_add_u64 v[120:121], s[68:69], 0, v[0:1]
	s_mov_b32 m0, s61
	s_nop 0
	global_load_lds_dwordx4 v[120:121], off
	v_lshl_add_u64 v[120:121], v[12:13], 0, s[70:71]
	s_mov_b32 m0, s26
	s_nop 0
	global_load_lds_dwordx4 v[120:121], off
	v_lshl_add_u64 v[120:121], v[14:15], 0, s[70:71]
	s_mov_b32 m0, s27
	s_nop 0
	global_load_lds_dwordx4 v[120:121], off
	s_waitcnt vmcnt(8)
	s_waitcnt lgkmcnt(0)
	s_barrier
	s_setprio 1
	s_waitcnt lgkmcnt(0)
	v_mfma_f32_16x16x32_bf16 v[150:153], v[130:133], v[202:205], v[150:153]
	v_mfma_f32_16x16x32_bf16 v[154:157], v[138:141], v[202:205], v[154:157]
	v_mfma_f32_16x16x32_bf16 v[178:181], v[130:133], v[228:231], v[178:181]
	v_mfma_f32_16x16x32_bf16 v[182:185], v[138:141], v[228:231], v[182:185]
	v_mfma_f32_16x16x32_bf16 v[186:189], v[130:133], v[236:239], v[186:189]
	v_mfma_f32_16x16x32_bf16 v[190:193], v[138:141], v[236:239], v[190:193]
	v_mfma_f32_16x16x32_bf16 v[24:27], v[130:133], v[244:247], v[24:27]
	v_mfma_f32_16x16x32_bf16 v[28:31], v[138:141], v[244:247], v[28:31]
	v_mfma_f32_16x16x32_bf16 v[150:153], v[134:137], v[220:223], v[150:153]
	v_mfma_f32_16x16x32_bf16 v[154:157], v[142:145], v[220:223], v[154:157]
	v_mfma_f32_16x16x32_bf16 v[178:181], v[134:137], v[232:235], v[178:181]
	v_mfma_f32_16x16x32_bf16 v[182:185], v[142:145], v[232:235], v[182:185]
	v_mfma_f32_16x16x32_bf16 v[186:189], v[134:137], v[240:243], v[186:189]
	v_mfma_f32_16x16x32_bf16 v[190:193], v[142:145], v[240:243], v[190:193]
	v_mfma_f32_16x16x32_bf16 v[24:27], v[134:137], v[248:251], v[24:27]
	v_mfma_f32_16x16x32_bf16 v[28:31], v[142:145], v[248:251], v[28:31]
	s_setprio 0
	s_setprio 1
	v_mfma_f32_16x16x32_bf16 v[32:35], v[146:149], v[202:205], v[32:35]
	v_mfma_f32_16x16x32_bf16 v[44:47], v[194:197], v[202:205], v[44:47]
	v_mfma_f32_16x16x32_bf16 v[48:51], v[146:149], v[228:231], v[48:51]
	v_mfma_f32_16x16x32_bf16 v[72:75], v[194:197], v[228:231], v[72:75]
	v_mfma_f32_16x16x32_bf16 v[120:123], v[146:149], v[236:239], v[122:125]
	v_mfma_f32_16x16x32_bf16 v[124:127], v[194:197], v[236:239], v[126:129]
	v_mfma_f32_16x16x32_bf16 v[36:39], v[146:149], v[244:247], v[36:39]
	v_mfma_f32_16x16x32_bf16 v[40:43], v[194:197], v[244:247], v[40:43]
	v_mfma_f32_16x16x32_bf16 v[32:35], v[174:177], v[220:223], v[32:35]
	v_mfma_f32_16x16x32_bf16 v[44:47], v[198:201], v[220:223], v[44:47]
	v_mfma_f32_16x16x32_bf16 v[48:51], v[174:177], v[232:235], v[48:51]
	v_mfma_f32_16x16x32_bf16 v[72:75], v[198:201], v[232:235], v[72:75]
	v_mfma_f32_16x16x32_bf16 v[120:123], v[174:177], v[240:243], v[120:123]
	v_mfma_f32_16x16x32_bf16 v[124:127], v[198:201], v[240:243], v[124:127]
	v_mfma_f32_16x16x32_bf16 v[36:39], v[174:177], v[248:251], v[36:39]
	v_mfma_f32_16x16x32_bf16 v[40:43], v[198:201], v[248:251], v[40:43]
	s_setprio 0
	s_barrier
	ds_read_b128 v[128:131], v21
	ds_read_b128 v[132:135], v21 offset:1024
	ds_read_b128 v[136:139], v21 offset:2048
	ds_read_b128 v[140:143], v21 offset:3072
	ds_read_b128 v[144:147], v22
	ds_read_b128 v[174:177], v22 offset:1024
	ds_read_b128 v[194:197], v22 offset:2048
	ds_read_b128 v[198:201], v22 offset:3072
	s_add_u32 s68, s50, 0x18200
	s_addc_u32 s69, s51, 0
	s_mov_b32 m0, s28
	v_lshl_add_u64 v[148:149], s[68:69], 0, v[6:7]
	ds_read_b128 v[202:205], v17 offset:32768
	ds_read_b128 v[220:223], v17 offset:33792
	ds_read_b128 v[228:231], v17 offset:34816
	ds_read_b128 v[232:235], v17 offset:35840
	ds_read_b128 v[236:239], v17 offset:36864
	ds_read_b128 v[240:243], v17 offset:37888
	ds_read_b128 v[244:247], v17 offset:38912
	ds_read_b128 v[248:251], v17 offset:39936
	global_load_lds_dwordx4 v[148:149], off
	v_lshl_add_u64 v[148:149], s[68:69], 0, v[2:3]
	s_mov_b32 m0, s29
	s_nop 0
	global_load_lds_dwordx4 v[148:149], off
	s_waitcnt vmcnt(8)
	s_waitcnt lgkmcnt(0)
	s_barrier
	s_setprio 1
	s_waitcnt lgkmcnt(0)
	v_mfma_f32_16x16x32_bf16 v[76:79], v[128:131], v[202:205], v[76:79]
	v_mfma_f32_16x16x32_bf16 v[80:83], v[136:139], v[202:205], v[80:83]
	v_mfma_f32_16x16x32_bf16 v[84:87], v[128:131], v[228:231], v[84:87]
	v_mfma_f32_16x16x32_bf16 v[88:91], v[136:139], v[228:231], v[88:91]
	v_mfma_f32_16x16x32_bf16 v[92:95], v[128:131], v[236:239], v[92:95]
	v_mfma_f32_16x16x32_bf16 v[96:99], v[136:139], v[236:239], v[96:99]
	v_mfma_f32_16x16x32_bf16 v[100:103], v[128:131], v[244:247], v[100:103]
	v_mfma_f32_16x16x32_bf16 v[104:107], v[136:139], v[244:247], v[104:107]
	v_mfma_f32_16x16x32_bf16 v[76:79], v[132:135], v[220:223], v[76:79]
	v_mfma_f32_16x16x32_bf16 v[80:83], v[140:143], v[220:223], v[80:83]
	v_mfma_f32_16x16x32_bf16 v[84:87], v[132:135], v[232:235], v[84:87]
	v_mfma_f32_16x16x32_bf16 v[88:91], v[140:143], v[232:235], v[88:91]
	v_mfma_f32_16x16x32_bf16 v[92:95], v[132:135], v[240:243], v[92:95]
	v_mfma_f32_16x16x32_bf16 v[96:99], v[140:143], v[240:243], v[96:99]
	v_mfma_f32_16x16x32_bf16 v[100:103], v[132:135], v[248:251], v[100:103]
	v_mfma_f32_16x16x32_bf16 v[104:107], v[140:143], v[248:251], v[104:107]
	s_setprio 0
	s_setprio 1
	v_mfma_f32_16x16x32_bf16 v[108:111], v[144:147], v[202:205], v[108:111]
	v_mfma_f32_16x16x32_bf16 v[112:115], v[194:197], v[202:205], v[112:115]
	v_mfma_f32_16x16x32_bf16 v[116:119], v[144:147], v[228:231], v[116:119]
	v_mfma_f32_16x16x32_bf16 v[52:55], v[194:197], v[228:231], v[52:55]
	v_mfma_f32_16x16x32_bf16 v[56:59], v[144:147], v[236:239], v[56:59]
	v_mfma_f32_16x16x32_bf16 v[60:63], v[194:197], v[236:239], v[60:63]
	v_mfma_f32_16x16x32_bf16 v[64:67], v[144:147], v[244:247], v[64:67]
	v_mfma_f32_16x16x32_bf16 v[68:71], v[194:197], v[244:247], v[68:71]
	v_mfma_f32_16x16x32_bf16 v[108:111], v[174:177], v[220:223], v[108:111]
	v_mfma_f32_16x16x32_bf16 v[112:115], v[198:201], v[220:223], v[112:115]
	v_mfma_f32_16x16x32_bf16 v[116:119], v[174:177], v[232:235], v[116:119]
	v_mfma_f32_16x16x32_bf16 v[52:55], v[198:201], v[232:235], v[52:55]
	v_mfma_f32_16x16x32_bf16 v[56:59], v[174:177], v[240:243], v[56:59]
	v_mfma_f32_16x16x32_bf16 v[60:63], v[198:201], v[240:243], v[60:63]
	v_mfma_f32_16x16x32_bf16 v[64:67], v[174:177], v[248:251], v[64:67]
	v_mfma_f32_16x16x32_bf16 v[68:71], v[198:201], v[248:251], v[68:71]
	s_setprio 0
	s_barrier
	s_mov_b64 s[68:69], 0x280
	s_mov_b32 m0, s67
	v_lshl_add_u64 v[8:9], v[8:9], 0, s[68:69]
	s_add_u32 s52, s52, 0x18280
	ds_read_b128 v[202:205], v17 offset:49152
	ds_read_b128 v[220:223], v17 offset:50176
	ds_read_b128 v[228:231], v17 offset:51200
	ds_read_b128 v[232:235], v17 offset:52224
	ds_read_b128 v[236:239], v17 offset:53248
	ds_read_b128 v[240:243], v17 offset:54272
	ds_read_b128 v[244:247], v17 offset:55296
	ds_read_b128 v[248:251], v17 offset:56320
	global_load_lds_dwordx4 v[8:9], off
	v_lshl_add_u64 v[8:9], v[10:11], 0, s[68:69]
	s_mov_b32 m0, s63
	s_addc_u32 s53, s53, 0
	global_load_lds_dwordx4 v[8:9], off
	v_lshl_add_u64 v[8:9], s[52:53], 0, v[4:5]
	s_mov_b32 m0, s64
	s_nop 0
	global_load_lds_dwordx4 v[8:9], off
	v_lshl_add_u64 v[8:9], s[52:53], 0, v[0:1]
	s_mov_b32 m0, s66
	s_nop 0
	global_load_lds_dwordx4 v[8:9], off
	v_lshl_add_u64 v[8:9], v[12:13], 0, s[68:69]
	s_mov_b32 m0, s30
	s_nop 0
	global_load_lds_dwordx4 v[8:9], off
	v_lshl_add_u64 v[8:9], v[14:15], 0, s[68:69]
	s_mov_b32 m0, s31
	s_nop 0
	global_load_lds_dwordx4 v[8:9], off
	s_waitcnt vmcnt(8)
	s_waitcnt lgkmcnt(0)
	s_barrier
	s_setprio 1
	s_waitcnt lgkmcnt(0)
	v_mfma_f32_16x16x32_bf16 v[8:11], v[128:131], v[202:205], v[150:153]
	v_mfma_f32_16x16x32_bf16 v[12:15], v[136:139], v[202:205], v[154:157]
	v_mfma_f32_16x16x32_bf16 v[148:151], v[128:131], v[228:231], v[178:181]
	v_mfma_f32_16x16x32_bf16 v[152:155], v[136:139], v[228:231], v[182:185]
	v_mfma_f32_16x16x32_bf16 v[156:159], v[128:131], v[236:239], v[186:189]
	v_mfma_f32_16x16x32_bf16 v[178:181], v[136:139], v[236:239], v[190:193]
	v_mfma_f32_16x16x32_bf16 v[24:27], v[128:131], v[244:247], v[24:27]
	v_mfma_f32_16x16x32_bf16 v[28:31], v[136:139], v[244:247], v[28:31]
	v_mfma_f32_16x16x32_bf16 v[8:11], v[132:135], v[220:223], v[8:11]
	v_mfma_f32_16x16x32_bf16 v[12:15], v[140:143], v[220:223], v[12:15]
	v_mfma_f32_16x16x32_bf16 v[148:151], v[132:135], v[232:235], v[148:151]
	v_mfma_f32_16x16x32_bf16 v[152:155], v[140:143], v[232:235], v[152:155]
	v_mfma_f32_16x16x32_bf16 v[156:159], v[132:135], v[240:243], v[156:159]
	v_mfma_f32_16x16x32_bf16 v[178:181], v[140:143], v[240:243], v[178:181]
	v_mfma_f32_16x16x32_bf16 v[24:27], v[132:135], v[248:251], v[24:27]
	v_mfma_f32_16x16x32_bf16 v[28:31], v[140:143], v[248:251], v[28:31]
	s_setprio 0
	s_setprio 1
	v_mfma_f32_16x16x32_bf16 v[32:35], v[144:147], v[202:205], v[32:35]
	v_mfma_f32_16x16x32_bf16 v[44:47], v[194:197], v[202:205], v[44:47]
	v_mfma_f32_16x16x32_bf16 v[48:51], v[144:147], v[228:231], v[48:51]
	v_mfma_f32_16x16x32_bf16 v[72:75], v[194:197], v[228:231], v[72:75]
	v_mfma_f32_16x16x32_bf16 v[120:123], v[144:147], v[236:239], v[120:123]
	v_mfma_f32_16x16x32_bf16 v[124:127], v[194:197], v[236:239], v[124:127]
	v_mfma_f32_16x16x32_bf16 v[36:39], v[144:147], v[244:247], v[36:39]
	v_mfma_f32_16x16x32_bf16 v[40:43], v[194:197], v[244:247], v[40:43]
	v_mfma_f32_16x16x32_bf16 v[32:35], v[174:177], v[220:223], v[32:35]
	v_mfma_f32_16x16x32_bf16 v[44:47], v[198:201], v[220:223], v[44:47]
	v_mfma_f32_16x16x32_bf16 v[48:51], v[174:177], v[232:235], v[48:51]
	v_mfma_f32_16x16x32_bf16 v[72:75], v[198:201], v[232:235], v[72:75]
	v_mfma_f32_16x16x32_bf16 v[120:123], v[174:177], v[240:243], v[120:123]
	v_mfma_f32_16x16x32_bf16 v[124:127], v[198:201], v[240:243], v[124:127]
	v_mfma_f32_16x16x32_bf16 v[36:39], v[174:177], v[248:251], v[36:39]
	v_mfma_f32_16x16x32_bf16 v[40:43], v[198:201], v[248:251], v[40:43]
	s_setprio 0
	s_barrier
	ds_read_b128 v[128:131], v19
	ds_read_b128 v[132:135], v19 offset:1024
	ds_read_b128 v[136:139], v19 offset:2048
	ds_read_b128 v[140:143], v19 offset:3072
	ds_read_b128 v[144:147], v20
	ds_read_b128 v[174:177], v20 offset:1024
	ds_read_b128 v[182:185], v20 offset:2048
	ds_read_b128 v[186:189], v20 offset:3072
	s_add_u32 s50, s50, 0x18280
	s_addc_u32 s51, s51, 0
	s_mov_b32 m0, s65
	v_lshl_add_u64 v[240:241], s[50:51], 0, v[6:7]
	ds_read_b128 v[190:193], v17
	ds_read_b128 v[194:197], v17 offset:1024
	ds_read_b128 v[198:201], v17 offset:2048
	ds_read_b128 v[202:205], v17 offset:3072
	ds_read_b128 v[220:223], v17 offset:4096
	ds_read_b128 v[228:231], v17 offset:5120
	ds_read_b128 v[232:235], v17 offset:6144
	ds_read_b128 v[236:239], v17 offset:7168
	global_load_lds_dwordx4 v[240:241], off
	v_lshl_add_u64 v[240:241], s[50:51], 0, v[2:3]
	s_mov_b32 m0, s57
	s_nop 0
	global_load_lds_dwordx4 v[240:241], off
	s_waitcnt vmcnt(8)
	s_waitcnt lgkmcnt(0)
	s_barrier
	s_setprio 1
	s_waitcnt lgkmcnt(0)
	v_mfma_f32_16x16x32_bf16 v[76:79], v[128:131], v[190:193], v[76:79]
	v_mfma_f32_16x16x32_bf16 v[80:83], v[136:139], v[190:193], v[80:83]
	v_mfma_f32_16x16x32_bf16 v[84:87], v[128:131], v[198:201], v[84:87]
	v_mfma_f32_16x16x32_bf16 v[88:91], v[136:139], v[198:201], v[88:91]
	v_mfma_f32_16x16x32_bf16 v[92:95], v[128:131], v[220:223], v[92:95]
	v_mfma_f32_16x16x32_bf16 v[96:99], v[136:139], v[220:223], v[96:99]
	v_mfma_f32_16x16x32_bf16 v[100:103], v[128:131], v[232:235], v[100:103]
	v_mfma_f32_16x16x32_bf16 v[104:107], v[136:139], v[232:235], v[104:107]
	v_mfma_f32_16x16x32_bf16 v[76:79], v[132:135], v[194:197], v[76:79]
	v_mfma_f32_16x16x32_bf16 v[80:83], v[140:143], v[194:197], v[80:83]
	v_mfma_f32_16x16x32_bf16 v[84:87], v[132:135], v[202:205], v[84:87]
	v_mfma_f32_16x16x32_bf16 v[88:91], v[140:143], v[202:205], v[88:91]
	v_mfma_f32_16x16x32_bf16 v[92:95], v[132:135], v[228:231], v[92:95]
	v_mfma_f32_16x16x32_bf16 v[96:99], v[140:143], v[228:231], v[96:99]
	v_mfma_f32_16x16x32_bf16 v[100:103], v[132:135], v[236:239], v[100:103]
	v_mfma_f32_16x16x32_bf16 v[104:107], v[140:143], v[236:239], v[104:107]
	s_setprio 0
	s_setprio 1
	v_mfma_f32_16x16x32_bf16 v[108:111], v[144:147], v[190:193], v[108:111]
	v_mfma_f32_16x16x32_bf16 v[112:115], v[182:185], v[190:193], v[112:115]
	v_mfma_f32_16x16x32_bf16 v[116:119], v[144:147], v[198:201], v[116:119]
	v_mfma_f32_16x16x32_bf16 v[52:55], v[182:185], v[198:201], v[52:55]
	v_mfma_f32_16x16x32_bf16 v[56:59], v[144:147], v[220:223], v[56:59]
	v_mfma_f32_16x16x32_bf16 v[60:63], v[182:185], v[220:223], v[60:63]
	v_mfma_f32_16x16x32_bf16 v[64:67], v[144:147], v[232:235], v[64:67]
	v_mfma_f32_16x16x32_bf16 v[68:71], v[182:185], v[232:235], v[68:71]
	v_mfma_f32_16x16x32_bf16 v[108:111], v[174:177], v[194:197], v[108:111]
	v_mfma_f32_16x16x32_bf16 v[112:115], v[186:189], v[194:197], v[112:115]
	v_mfma_f32_16x16x32_bf16 v[116:119], v[174:177], v[202:205], v[116:119]
	v_mfma_f32_16x16x32_bf16 v[52:55], v[186:189], v[202:205], v[52:55]
	v_mfma_f32_16x16x32_bf16 v[56:59], v[174:177], v[228:231], v[56:59]
	v_mfma_f32_16x16x32_bf16 v[60:63], v[186:189], v[228:231], v[60:63]
	v_mfma_f32_16x16x32_bf16 v[64:67], v[174:177], v[236:239], v[64:67]
	v_mfma_f32_16x16x32_bf16 v[68:71], v[186:189], v[236:239], v[68:71]
	s_setprio 0
	s_barrier
	s_mov_b32 m0, s62
	v_lshl_add_u64 v[240:241], s[44:45], 0, v[4:5]
	s_add_u32 s50, s44, 0x18000
	ds_read_b128 v[190:193], v17 offset:16384
	ds_read_b128 v[194:197], v17 offset:17408
	ds_read_b128 v[198:201], v17 offset:18432
	ds_read_b128 v[202:205], v17 offset:19456
	ds_read_b128 v[220:223], v17 offset:20480
	ds_read_b128 v[228:231], v17 offset:21504
	ds_read_b128 v[232:235], v17 offset:22528
	ds_read_b128 v[236:239], v17 offset:23552
	global_load_lds_dwordx4 v[240:241], off
	v_lshl_add_u64 v[242:243], s[44:45], 0, v[0:1]
	s_mov_b32 m0, s58
	s_addc_u32 s51, s45, 0
	global_load_lds_dwordx4 v[242:243], off
	v_lshl_add_u64 v[244:245], s[50:51], 0, v[4:5]
	s_mov_b32 m0, s59
	v_lshl_add_u64 v[246:247], s[42:43], 0, v[2:3]
	global_load_lds_dwordx4 v[244:245], off
	v_lshl_add_u64 v[244:245], s[50:51], 0, v[0:1]
	s_mov_b32 m0, s61
	s_nop 0
	global_load_lds_dwordx4 v[244:245], off
	v_lshl_add_u64 v[244:245], s[42:43], 0, v[6:7]
	s_mov_b32 m0, s26
	s_nop 0
	global_load_lds_dwordx4 v[244:245], off
	s_mov_b32 m0, s27
	s_nop 0
	global_load_lds_dwordx4 v[246:247], off
	s_waitcnt vmcnt(8)
	s_waitcnt lgkmcnt(0)
	s_barrier
	s_setprio 1
	s_waitcnt lgkmcnt(0)
	v_mfma_f32_16x16x32_bf16 v[8:11], v[128:131], v[190:193], v[8:11]
	v_mfma_f32_16x16x32_bf16 v[12:15], v[136:139], v[190:193], v[12:15]
	v_mfma_f32_16x16x32_bf16 v[148:151], v[128:131], v[198:201], v[148:151]
	v_mfma_f32_16x16x32_bf16 v[152:155], v[136:139], v[198:201], v[152:155]
	v_mfma_f32_16x16x32_bf16 v[156:159], v[128:131], v[220:223], v[156:159]
	v_mfma_f32_16x16x32_bf16 v[178:181], v[136:139], v[220:223], v[178:181]
	v_mfma_f32_16x16x32_bf16 v[24:27], v[128:131], v[232:235], v[24:27]
	v_mfma_f32_16x16x32_bf16 v[28:31], v[136:139], v[232:235], v[28:31]
	v_mfma_f32_16x16x32_bf16 v[8:11], v[132:135], v[194:197], v[8:11]
	v_mfma_f32_16x16x32_bf16 v[12:15], v[140:143], v[194:197], v[12:15]
	v_mfma_f32_16x16x32_bf16 v[148:151], v[132:135], v[202:205], v[148:151]
	v_mfma_f32_16x16x32_bf16 v[152:155], v[140:143], v[202:205], v[152:155]
	v_mfma_f32_16x16x32_bf16 v[156:159], v[132:135], v[228:231], v[156:159]
	v_mfma_f32_16x16x32_bf16 v[178:181], v[140:143], v[228:231], v[178:181]
	v_mfma_f32_16x16x32_bf16 v[24:27], v[132:135], v[236:239], v[24:27]
	v_mfma_f32_16x16x32_bf16 v[28:31], v[140:143], v[236:239], v[28:31]
	s_setprio 0
	s_setprio 1
	v_mfma_f32_16x16x32_bf16 v[32:35], v[144:147], v[190:193], v[32:35]
	v_mfma_f32_16x16x32_bf16 v[44:47], v[182:185], v[190:193], v[44:47]
	v_mfma_f32_16x16x32_bf16 v[48:51], v[144:147], v[198:201], v[48:51]
	v_mfma_f32_16x16x32_bf16 v[72:75], v[182:185], v[198:201], v[72:75]
	v_mfma_f32_16x16x32_bf16 v[120:123], v[144:147], v[220:223], v[120:123]
	v_mfma_f32_16x16x32_bf16 v[124:127], v[182:185], v[220:223], v[124:127]
	v_mfma_f32_16x16x32_bf16 v[36:39], v[144:147], v[232:235], v[36:39]
	v_mfma_f32_16x16x32_bf16 v[40:43], v[182:185], v[232:235], v[40:43]
	v_mfma_f32_16x16x32_bf16 v[32:35], v[174:177], v[194:197], v[32:35]
	v_mfma_f32_16x16x32_bf16 v[44:47], v[186:189], v[194:197], v[44:47]
	v_mfma_f32_16x16x32_bf16 v[48:51], v[174:177], v[202:205], v[48:51]
	v_mfma_f32_16x16x32_bf16 v[72:75], v[186:189], v[202:205], v[72:75]
	v_mfma_f32_16x16x32_bf16 v[120:123], v[174:177], v[228:231], v[120:123]
	v_mfma_f32_16x16x32_bf16 v[124:127], v[186:189], v[228:231], v[124:127]
	v_mfma_f32_16x16x32_bf16 v[36:39], v[174:177], v[236:239], v[36:39]
	v_mfma_f32_16x16x32_bf16 v[40:43], v[186:189], v[236:239], v[40:43]
	s_setprio 0
	s_barrier
	ds_read_b128 v[128:131], v21
	ds_read_b128 v[132:135], v21 offset:1024
	ds_read_b128 v[136:139], v21 offset:2048
	ds_read_b128 v[140:143], v21 offset:3072
	ds_read_b128 v[144:147], v22
	ds_read_b128 v[174:177], v22 offset:1024
	ds_read_b128 v[182:185], v22 offset:2048
	ds_read_b128 v[20:23], v22 offset:3072
	s_add_u32 s50, s42, 0x18000
	s_addc_u32 s51, s43, 0
	s_mov_b32 m0, s28
	v_lshl_add_u64 v[236:237], s[50:51], 0, v[6:7]
	ds_read_b128 v[186:189], v17 offset:32768
	ds_read_b128 v[190:193], v17 offset:33792
	ds_read_b128 v[194:197], v17 offset:34816
	ds_read_b128 v[198:201], v17 offset:35840
	ds_read_b128 v[202:205], v17 offset:36864
	ds_read_b128 v[220:223], v17 offset:37888
	ds_read_b128 v[228:231], v17 offset:38912
	ds_read_b128 v[232:235], v17 offset:39936
	global_load_lds_dwordx4 v[236:237], off
	v_lshl_add_u64 v[236:237], s[50:51], 0, v[2:3]
	s_mov_b32 m0, s29
	s_nop 0
	global_load_lds_dwordx4 v[236:237], off
	s_waitcnt vmcnt(8)
	s_waitcnt lgkmcnt(0)
	s_barrier
	s_setprio 1
	s_waitcnt lgkmcnt(0)
	v_mfma_f32_16x16x32_bf16 v[76:79], v[128:131], v[186:189], v[76:79]
	v_mfma_f32_16x16x32_bf16 v[80:83], v[136:139], v[186:189], v[80:83]
	v_mfma_f32_16x16x32_bf16 v[84:87], v[128:131], v[194:197], v[84:87]
	v_mfma_f32_16x16x32_bf16 v[88:91], v[136:139], v[194:197], v[88:91]
	v_mfma_f32_16x16x32_bf16 v[92:95], v[128:131], v[202:205], v[92:95]
	v_mfma_f32_16x16x32_bf16 v[96:99], v[136:139], v[202:205], v[96:99]
	v_mfma_f32_16x16x32_bf16 v[100:103], v[128:131], v[228:231], v[100:103]
	v_mfma_f32_16x16x32_bf16 v[104:107], v[136:139], v[228:231], v[104:107]
	v_mfma_f32_16x16x32_bf16 v[76:79], v[132:135], v[190:193], v[76:79]
	v_mfma_f32_16x16x32_bf16 v[80:83], v[140:143], v[190:193], v[80:83]
	v_mfma_f32_16x16x32_bf16 v[84:87], v[132:135], v[198:201], v[84:87]
	v_mfma_f32_16x16x32_bf16 v[88:91], v[140:143], v[198:201], v[88:91]
	v_mfma_f32_16x16x32_bf16 v[92:95], v[132:135], v[220:223], v[92:95]
	v_mfma_f32_16x16x32_bf16 v[96:99], v[140:143], v[220:223], v[96:99]
	v_mfma_f32_16x16x32_bf16 v[100:103], v[132:135], v[232:235], v[100:103]
	v_mfma_f32_16x16x32_bf16 v[104:107], v[140:143], v[232:235], v[104:107]
	s_setprio 0
	s_setprio 1
	v_mfma_f32_16x16x32_bf16 v[108:111], v[144:147], v[186:189], v[108:111]
	v_mfma_f32_16x16x32_bf16 v[112:115], v[182:185], v[186:189], v[112:115]
	v_mfma_f32_16x16x32_bf16 v[116:119], v[144:147], v[194:197], v[116:119]
	v_mfma_f32_16x16x32_bf16 v[52:55], v[182:185], v[194:197], v[52:55]
	v_mfma_f32_16x16x32_bf16 v[56:59], v[144:147], v[202:205], v[56:59]
	v_mfma_f32_16x16x32_bf16 v[60:63], v[182:185], v[202:205], v[60:63]
	v_mfma_f32_16x16x32_bf16 v[64:67], v[144:147], v[228:231], v[64:67]
	v_mfma_f32_16x16x32_bf16 v[68:71], v[182:185], v[228:231], v[68:71]
	v_mfma_f32_16x16x32_bf16 v[108:111], v[174:177], v[190:193], v[108:111]
	v_mfma_f32_16x16x32_bf16 v[112:115], v[20:23], v[190:193], v[112:115]
	v_mfma_f32_16x16x32_bf16 v[116:119], v[174:177], v[198:201], v[116:119]
	v_mfma_f32_16x16x32_bf16 v[52:55], v[20:23], v[198:201], v[52:55]
	v_mfma_f32_16x16x32_bf16 v[56:59], v[174:177], v[220:223], v[56:59]
	v_mfma_f32_16x16x32_bf16 v[60:63], v[20:23], v[220:223], v[60:63]
	v_mfma_f32_16x16x32_bf16 v[64:67], v[174:177], v[232:235], v[64:67]
	v_mfma_f32_16x16x32_bf16 v[68:71], v[20:23], v[232:235], v[68:71]
	s_setprio 0
	s_barrier
	s_mov_b32 m0, s67
	v_lshl_add_u64 v[236:237], v[240:241], 0, s[4:5]
	s_add_u32 s50, s44, 0x18080
	ds_read_b128 v[186:189], v17 offset:49152
	ds_read_b128 v[190:193], v17 offset:50176
	ds_read_b128 v[194:197], v17 offset:51200
	ds_read_b128 v[198:201], v17 offset:52224
	ds_read_b128 v[202:205], v17 offset:53248
	ds_read_b128 v[220:223], v17 offset:54272
	ds_read_b128 v[228:231], v17 offset:55296
	ds_read_b128 v[232:235], v17 offset:56320
	global_load_lds_dwordx4 v[236:237], off
	v_lshl_add_u64 v[236:237], v[242:243], 0, s[4:5]
	s_mov_b32 m0, s63
	s_addc_u32 s51, s45, 0
	global_load_lds_dwordx4 v[236:237], off
	v_lshl_add_u64 v[236:237], s[50:51], 0, v[4:5]
	s_mov_b32 m0, s64
	s_nop 0
	global_load_lds_dwordx4 v[236:237], off
	v_lshl_add_u64 v[236:237], s[50:51], 0, v[0:1]
	s_mov_b32 m0, s66
	s_nop 0
	global_load_lds_dwordx4 v[236:237], off
	v_lshl_add_u64 v[236:237], v[244:245], 0, s[4:5]
	s_mov_b32 m0, s30
	s_nop 0
	global_load_lds_dwordx4 v[236:237], off
	v_lshl_add_u64 v[236:237], v[246:247], 0, s[4:5]
	s_mov_b32 m0, s31
	s_nop 0
	global_load_lds_dwordx4 v[236:237], off
	s_waitcnt vmcnt(8)
	s_waitcnt lgkmcnt(0)
	s_barrier
	s_setprio 1
	s_waitcnt lgkmcnt(0)
	v_mfma_f32_16x16x32_bf16 v[8:11], v[128:131], v[186:189], v[8:11]
	v_mfma_f32_16x16x32_bf16 v[12:15], v[136:139], v[186:189], v[12:15]
	v_mfma_f32_16x16x32_bf16 v[148:151], v[128:131], v[194:197], v[148:151]
	v_mfma_f32_16x16x32_bf16 v[152:155], v[136:139], v[194:197], v[152:155]
	v_mfma_f32_16x16x32_bf16 v[156:159], v[128:131], v[202:205], v[156:159]
	v_mfma_f32_16x16x32_bf16 v[178:181], v[136:139], v[202:205], v[178:181]
	v_mfma_f32_16x16x32_bf16 v[24:27], v[128:131], v[228:231], v[24:27]
	v_mfma_f32_16x16x32_bf16 v[28:31], v[136:139], v[228:231], v[28:31]
	v_mfma_f32_16x16x32_bf16 v[8:11], v[132:135], v[190:193], v[8:11]
	v_mfma_f32_16x16x32_bf16 v[12:15], v[140:143], v[190:193], v[12:15]
	v_mfma_f32_16x16x32_bf16 v[148:151], v[132:135], v[198:201], v[148:151]
	v_mfma_f32_16x16x32_bf16 v[152:155], v[140:143], v[198:201], v[152:155]
	v_mfma_f32_16x16x32_bf16 v[156:159], v[132:135], v[220:223], v[156:159]
	v_mfma_f32_16x16x32_bf16 v[178:181], v[140:143], v[220:223], v[178:181]
	v_mfma_f32_16x16x32_bf16 v[24:27], v[132:135], v[232:235], v[24:27]
	v_mfma_f32_16x16x32_bf16 v[28:31], v[140:143], v[232:235], v[28:31]
	s_setprio 0
	s_setprio 1
	v_mfma_f32_16x16x32_bf16 v[32:35], v[144:147], v[186:189], v[32:35]
	v_mfma_f32_16x16x32_bf16 v[44:47], v[182:185], v[186:189], v[44:47]
	v_mfma_f32_16x16x32_bf16 v[48:51], v[144:147], v[194:197], v[48:51]
	v_mfma_f32_16x16x32_bf16 v[72:75], v[182:185], v[194:197], v[72:75]
	v_mfma_f32_16x16x32_bf16 v[120:123], v[144:147], v[202:205], v[120:123]
	v_mfma_f32_16x16x32_bf16 v[124:127], v[182:185], v[202:205], v[124:127]
	v_mfma_f32_16x16x32_bf16 v[36:39], v[144:147], v[228:231], v[36:39]
	v_mfma_f32_16x16x32_bf16 v[40:43], v[182:185], v[228:231], v[40:43]
	v_mfma_f32_16x16x32_bf16 v[32:35], v[174:177], v[190:193], v[32:35]
	v_mfma_f32_16x16x32_bf16 v[44:47], v[20:23], v[190:193], v[44:47]
	v_mfma_f32_16x16x32_bf16 v[48:51], v[174:177], v[198:201], v[48:51]
	v_mfma_f32_16x16x32_bf16 v[72:75], v[20:23], v[198:201], v[72:75]
	v_mfma_f32_16x16x32_bf16 v[120:123], v[174:177], v[220:223], v[120:123]
	v_mfma_f32_16x16x32_bf16 v[124:127], v[20:23], v[220:223], v[124:127]
	v_mfma_f32_16x16x32_bf16 v[36:39], v[174:177], v[232:235], v[36:39]
	v_mfma_f32_16x16x32_bf16 v[20:23], v[20:23], v[232:235], v[40:43]
	s_setprio 0
	s_barrier
	s_lshl_b32 s50, s55, 8
	s_lshl_b32 s51, s56, 19
	s_add_i32 s50, s50, s51
	v_add_u32_e32 v162, s50, v18
	v_lshl_add_u64 v[128:129], v[162:163], 1, s[46:47]
	v_cvt_pk_bf16_f32 v40, v76, v77
	v_cvt_pk_bf16_f32 v41, v78, v79
	v_cvt_pk_bf16_f32 v42, v80, v81
	v_cvt_pk_bf16_f32 v43, v82, v83
	global_store_dwordx4 v[128:129], v[40:43], off sc1
	v_cvt_pk_bf16_f32 v8, v8, v9
	v_cvt_pk_bf16_f32 v9, v10, v11
	v_cvt_pk_bf16_f32 v40, v108, v109
	v_cvt_pk_bf16_f32 v41, v110, v111
	v_cvt_pk_bf16_f32 v42, v112, v113
	v_cvt_pk_bf16_f32 v43, v114, v115
	global_store_dwordx4 v[128:129], v[40:43], off offset:256 sc1
	v_cvt_pk_bf16_f32 v10, v12, v13
	v_cvt_pk_bf16_f32 v11, v14, v15
	v_add_u32_e32 v40, 0x8000, v162
	v_mov_b32_e32 v41, v163
	v_lshl_add_u64 v[76:77], v[40:41], 1, s[46:47]
	v_cvt_pk_bf16_f32 v40, v84, v85
	v_cvt_pk_bf16_f32 v41, v86, v87
	v_cvt_pk_bf16_f32 v42, v88, v89
	v_cvt_pk_bf16_f32 v43, v90, v91
	global_store_dwordx4 v[76:77], v[40:43], off sc1
	s_add_i32 s54, s54, s82
	s_andn2_b64 vcc, exec, s[40:41]
	v_cvt_pk_bf16_f32 v40, v116, v117
	v_cvt_pk_bf16_f32 v41, v118, v119
	v_cvt_pk_bf16_f32 v42, v52, v53
	v_cvt_pk_bf16_f32 v43, v54, v55
	global_store_dwordx4 v[76:77], v[40:43], off offset:256 sc1
	s_mov_b32 s55, s6
	s_mov_b32 s56, s7
	v_add_u32_e32 v40, 0x10000, v162
	v_mov_b32_e32 v41, v163
	v_lshl_add_u64 v[52:53], v[40:41], 1, s[46:47]
	v_cvt_pk_bf16_f32 v40, v92, v93
	v_cvt_pk_bf16_f32 v41, v94, v95
	v_cvt_pk_bf16_f32 v42, v96, v97
	v_cvt_pk_bf16_f32 v43, v98, v99
	global_store_dwordx4 v[52:53], v[40:43], off sc1
	s_mov_b64 s[52:53], s[44:45]
	s_mov_b64 s[50:51], s[42:43]
	v_cvt_pk_bf16_f32 v40, v56, v57
	v_cvt_pk_bf16_f32 v41, v58, v59
	v_cvt_pk_bf16_f32 v42, v60, v61
	v_cvt_pk_bf16_f32 v43, v62, v63
	global_store_dwordx4 v[52:53], v[40:43], off offset:256 sc1
	s_nop 1
	v_add_u32_e32 v40, 0x18000, v162
	v_mov_b32_e32 v41, v163
	v_lshl_add_u64 v[52:53], v[40:41], 1, s[46:47]
	v_cvt_pk_bf16_f32 v40, v100, v101
	v_cvt_pk_bf16_f32 v41, v102, v103
	v_cvt_pk_bf16_f32 v42, v104, v105
	v_cvt_pk_bf16_f32 v43, v106, v107
	global_store_dwordx4 v[52:53], v[40:43], off sc1
	s_nop 1
	v_cvt_pk_bf16_f32 v40, v64, v65
	v_cvt_pk_bf16_f32 v41, v66, v67
	v_cvt_pk_bf16_f32 v42, v68, v69
	v_cvt_pk_bf16_f32 v43, v70, v71
	global_store_dwordx4 v[52:53], v[40:43], off offset:256 sc1
	s_nop 1
	v_add_u32_e32 v40, 0x40000, v162
	v_mov_b32_e32 v41, v163
	v_lshl_add_u64 v[40:41], v[40:41], 1, s[46:47]
	global_store_dwordx4 v[40:41], v[8:11], off sc1
	s_nop 1
	v_cvt_pk_bf16_f32 v8, v32, v33
	v_cvt_pk_bf16_f32 v9, v34, v35
	v_cvt_pk_bf16_f32 v10, v44, v45
	v_cvt_pk_bf16_f32 v11, v46, v47
	global_store_dwordx4 v[40:41], v[8:11], off offset:256 sc1
	s_nop 1
	v_add_u32_e32 v8, 0x48000, v162
	v_mov_b32_e32 v9, v163
	v_lshl_add_u64 v[12:13], v[8:9], 1, s[46:47]
	v_cvt_pk_bf16_f32 v8, v148, v149
	v_cvt_pk_bf16_f32 v9, v150, v151
	v_cvt_pk_bf16_f32 v10, v152, v153
	v_cvt_pk_bf16_f32 v11, v154, v155
	global_store_dwordx4 v[12:13], v[8:11], off sc1
	s_nop 1
	v_cvt_pk_bf16_f32 v8, v48, v49
	v_cvt_pk_bf16_f32 v9, v50, v51
	v_cvt_pk_bf16_f32 v10, v72, v73
	v_cvt_pk_bf16_f32 v11, v74, v75
	global_store_dwordx4 v[12:13], v[8:11], off offset:256 sc1
	s_nop 1
	v_add_u32_e32 v8, 0x50000, v162
	v_mov_b32_e32 v9, v163
	v_lshl_add_u64 v[12:13], v[8:9], 1, s[46:47]
	v_cvt_pk_bf16_f32 v8, v156, v157
	v_cvt_pk_bf16_f32 v9, v158, v159
	v_cvt_pk_bf16_f32 v10, v178, v179
	v_cvt_pk_bf16_f32 v11, v180, v181
	global_store_dwordx4 v[12:13], v[8:11], off sc1
	v_add_u32_e32 v162, 0x58000, v162
	s_nop 0
	v_cvt_pk_bf16_f32 v8, v120, v121
	v_cvt_pk_bf16_f32 v9, v122, v123
	v_cvt_pk_bf16_f32 v10, v124, v125
	v_cvt_pk_bf16_f32 v11, v126, v127
	global_store_dwordx4 v[12:13], v[8:11], off offset:256 sc1
	v_lshl_add_u64 v[12:13], v[162:163], 1, s[46:47]
	s_nop 0
	v_cvt_pk_bf16_f32 v8, v24, v25
	v_cvt_pk_bf16_f32 v9, v26, v27
	v_cvt_pk_bf16_f32 v10, v28, v29
	v_cvt_pk_bf16_f32 v11, v30, v31
	global_store_dwordx4 v[12:13], v[8:11], off sc1
	s_nop 1
	v_cvt_pk_bf16_f32 v8, v36, v37
	v_cvt_pk_bf16_f32 v9, v38, v39
	v_cvt_pk_bf16_f32 v10, v20, v21
	v_cvt_pk_bf16_f32 v11, v22, v23
	global_store_dwordx4 v[12:13], v[8:11], off offset:256 sc1
	s_cbranch_vccz .LBB0_513

.LBB0_518:
	s_nop 0
	v_add_u32_e32 v0, s6, v76
	s_movk_i32 s8, 0x300
	v_mad_i64_i32 v[104:105], s[8:9], v0, s8, v[66:67]
	v_add_co_u32_e32 v106, vcc, 0x6000, v104
	global_load_dwordx4 v[0:3], v[64:65], off
	global_load_dwordx4 v[16:19], v[68:69], off
	global_load_dwordx4 v[4:7], v[104:105], off
	v_addc_co_u32_e32 v107, vcc, 0, v105, vcc
	global_load_dwordx4 v[20:23], v[106:107], off
	global_load_dwordx4 v[88:91], v[64:65], off offset:32
	global_load_dwordx4 v[92:95], v[72:73], off
	global_load_dwordx4 v[96:99], v[104:105], off offset:32
	global_load_dwordx4 v[100:103], v[106:107], off offset:32
	s_add_i32 s7, s7, s82
	s_waitcnt vmcnt(0)
	v_mfma_f32_32x32x16_bf16 v[32:47], v[0:3], v[4:7], 0
	v_mfma_f32_32x32x16_bf16 v[48:63], v[0:3], v[20:23], 0
	v_mfma_f32_32x32x16_bf16 v[0:15], v[16:19], v[4:7], 0
	v_mfma_f32_32x32x16_bf16 v[16:31], v[16:19], v[20:23], 0
	v_mfma_f32_32x32x16_bf16 v[32:47], v[88:91], v[96:99], v[32:47]
	v_mfma_f32_32x32x16_bf16 v[48:63], v[88:91], v[100:103], v[48:63]
	v_mfma_f32_32x32x16_bf16 v[0:15], v[92:95], v[96:99], v[0:15]
	v_mfma_f32_32x32x16_bf16 v[16:31], v[92:95], v[100:103], v[16:31]
	global_load_dwordx4 v[88:91], v[64:65], off offset:64
	global_load_dwordx4 v[92:95], v[74:75], off
	global_load_dwordx4 v[96:99], v[104:105], off offset:64
	global_load_dwordx4 v[100:103], v[106:107], off offset:64
	s_waitcnt vmcnt(1)
	v_mfma_f32_32x32x16_bf16 v[32:47], v[88:91], v[96:99], v[32:47]
	s_waitcnt vmcnt(0)
	v_mfma_f32_32x32x16_bf16 v[48:63], v[88:91], v[100:103], v[48:63]
	s_nop 11
	ds_write2_b32 v79, v32, v48 offset1:32
	ds_write2_b32 v79, v33, v49 offset0:64 offset1:96
	ds_write2_b32 v79, v34, v50 offset0:128 offset1:160
	ds_write2_b32 v79, v35, v51 offset0:192 offset1:224
	v_mfma_f32_32x32x16_bf16 v[0:15], v[92:95], v[96:99], v[0:15]
	v_add_u32_e32 v32, 0x800, v79
	ds_write2_b32 v32, v36, v52 offset1:32
	ds_write2_b32 v32, v37, v53 offset0:64 offset1:96
	ds_write2_b32 v32, v38, v54 offset0:128 offset1:160
	ds_write2_b32 v32, v39, v55 offset0:192 offset1:224
	v_add_u32_e32 v32, 0x1000, v79
	ds_write2_b32 v32, v40, v56 offset1:32
	ds_write2_b32 v32, v41, v57 offset0:64 offset1:96
	ds_write2_b32 v32, v42, v58 offset0:128 offset1:160
	ds_write2_b32 v32, v43, v59 offset0:192 offset1:224
	v_add_u32_e32 v32, 0x1800, v79
	ds_write2_b32 v32, v44, v60 offset1:32
	ds_write2_b32 v32, v45, v61 offset0:64 offset1:96
	ds_write2_b32 v32, v46, v62 offset0:128 offset1:160
	ds_write2_b32 v32, v47, v63 offset0:192 offset1:224
	v_add_u32_e32 v32, 0x2000, v79
	v_mfma_f32_32x32x16_bf16 v[16:31], v[92:95], v[100:103], v[16:31]
	s_nop 11
	ds_write2_b32 v32, v0, v16 offset1:32
	ds_write2_b32 v32, v1, v17 offset0:64 offset1:96
	ds_write2_b32 v32, v2, v18 offset0:128 offset1:160
	ds_write2_b32 v32, v3, v19 offset0:192 offset1:224
	v_add_u32_e32 v0, 0x2800, v79
	ds_write2_b32 v0, v4, v20 offset1:32
	ds_write2_b32 v0, v5, v21 offset0:64 offset1:96
	ds_write2_b32 v0, v6, v22 offset0:128 offset1:160
	ds_write2_b32 v0, v7, v23 offset0:192 offset1:224
	v_add_u32_e32 v0, 0x3000, v79
	ds_write2_b32 v0, v8, v24 offset1:32
	ds_write2_b32 v0, v9, v25 offset0:64 offset1:96
	ds_write2_b32 v0, v10, v26 offset0:128 offset1:160
	ds_write2_b32 v0, v11, v27 offset0:192 offset1:224
	v_add_u32_e32 v0, 0x3800, v79
	ds_write2_b32 v0, v12, v28 offset1:32
	ds_write2_b32 v0, v13, v29 offset0:64 offset1:96
	ds_write2_b32 v0, v14, v30 offset0:128 offset1:160
	ds_write2_b32 v0, v15, v31 offset0:192 offset1:224
	s_waitcnt lgkmcnt(0)
	s_barrier
	ds_read_b128 v[0:3], v77
	ds_read_b128 v[4:7], v77 offset:16
	ds_read_b128 v[8:11], v77 offset:16384
	ds_read_b128 v[12:15], v77 offset:16400
	ds_read_b128 v[16:19], v77 offset:32768
	ds_read_b128 v[20:23], v77 offset:32784
	ds_read_b128 v[24:27], v77 offset:49152
	ds_read_b128 v[28:31], v77 offset:49168
	ds_read_b128 v[32:35], v80
	ds_read_b128 v[36:39], v81
	ds_read_b128 v[40:43], v82
	ds_read_b128 v[44:47], v83
	ds_read_b128 v[48:51], v84
	ds_read_b128 v[52:55], v85
	ds_read_b128 v[56:59], v86
	ds_read_b128 v[60:63], v87
	s_waitcnt lgkmcnt(14)
	v_pk_add_f32 v[0:1], v[0:1], 0 op_sel_hi:[1,0]
	v_pk_add_f32 v[2:3], v[2:3], 0 op_sel_hi:[1,0]
	v_pk_add_f32 v[4:5], v[4:5], 0 op_sel_hi:[1,0]
	s_waitcnt lgkmcnt(13)
	v_pk_add_f32 v[0:1], v[0:1], v[8:9]
	v_pk_add_f32 v[2:3], v[2:3], v[10:11]
	s_waitcnt lgkmcnt(12)
	v_pk_add_f32 v[4:5], v[4:5], v[12:13]
	s_waitcnt lgkmcnt(11)
	v_pk_add_f32 v[0:1], v[0:1], v[16:17]
	v_pk_add_f32 v[2:3], v[2:3], v[18:19]
	s_waitcnt lgkmcnt(10)
	v_pk_add_f32 v[4:5], v[4:5], v[20:21]
	s_waitcnt lgkmcnt(9)
	v_pk_add_f32 v[0:1], v[0:1], v[24:25]
	v_pk_add_f32 v[2:3], v[2:3], v[26:27]
	s_waitcnt lgkmcnt(8)
	v_pk_add_f32 v[4:5], v[4:5], v[28:29]
	v_pk_add_f32 v[6:7], v[6:7], 0 op_sel_hi:[1,0]
	v_add_u32_e32 v10, s6, v78
	s_waitcnt lgkmcnt(7)
	v_pk_add_f32 v[0:1], v[0:1], v[32:33]
	v_pk_add_f32 v[2:3], v[2:3], v[34:35]
	s_waitcnt lgkmcnt(6)
	v_pk_add_f32 v[4:5], v[4:5], v[36:37]
	v_pk_add_f32 v[6:7], v[6:7], v[14:15]
	v_cmp_gt_i32_e32 vcc, 2.0, v10
	v_mov_b32_e32 v8, s43
	v_mov_b32_e32 v9, s41
	s_waitcnt lgkmcnt(5)
	v_pk_add_f32 v[0:1], v[0:1], v[40:41]
	v_pk_add_f32 v[2:3], v[2:3], v[42:43]
	s_waitcnt lgkmcnt(4)
	v_pk_add_f32 v[4:5], v[4:5], v[44:45]
	v_pk_add_f32 v[6:7], v[6:7], v[22:23]
	v_cndmask_b32_e32 v9, v8, v9, vcc
	v_mov_b32_e32 v8, s42
	v_mov_b32_e32 v11, s40
	s_waitcnt lgkmcnt(3)
	v_pk_add_f32 v[0:1], v[0:1], v[48:49]
	v_pk_add_f32 v[2:3], v[2:3], v[50:51]
	s_waitcnt lgkmcnt(2)
	v_pk_add_f32 v[4:5], v[4:5], v[52:53]
	v_pk_add_f32 v[6:7], v[6:7], v[30:31]
	v_cndmask_b32_e32 v8, v8, v11, vcc
	v_cndmask_b32_e64 v11, -2.0, 0, vcc
	s_waitcnt lgkmcnt(1)
	v_pk_add_f32 v[0:1], v[0:1], v[56:57]
	v_pk_add_f32 v[2:3], v[2:3], v[58:59]
	s_waitcnt lgkmcnt(0)
	v_pk_add_f32 v[4:5], v[4:5], v[60:61]
	v_pk_add_f32 v[6:7], v[6:7], v[38:39]
	v_add_u32_e32 v10, v10, v11
	v_pk_add_f32 v[6:7], v[6:7], v[46:47]
	v_cvt_pk_bf16_f32 v0, v0, v1
	v_cvt_pk_bf16_f32 v1, v2, v3
	v_cvt_pk_bf16_f32 v2, v4, v5
	v_lshl_add_u64 v[4:5], v[8:9], 0, v[70:71]
	v_ashrrev_i32_e32 v11, 31, v10
	v_pk_add_f32 v[6:7], v[6:7], v[54:55]
	v_lshl_add_u64 v[4:5], v[10:11], 1, v[4:5]
	v_pk_add_f32 v[6:7], v[6:7], v[62:63]
	v_add_co_u32_e32 v4, vcc, 0xc598000, v4
	s_add_i32 s6, s6, s39
	v_cvt_pk_bf16_f32 v3, v6, v7
	v_addc_co_u32_e32 v5, vcc, 0, v5, vcc
	s_cmp_lt_i32 s7, 32
	global_store_dwordx4 v[4:5], v[0:3], off offset:2048 sc1
	s_barrier
	s_cbranch_scc1 .LBB0_518

.LBB0_774:
	v_lshl_add_u32 v142, s27, 8, v144
	v_ashrrev_i32_e32 v143, 31, v142
	v_lshlrev_b64 v[140:141], 6, v[142:143]
	v_lshl_add_u64 v[140:141], s[44:45], 0, v[140:141]
	global_load_dwordx4 v[148:151], v[140:141], off
	global_load_dwordx4 v[152:155], v[140:141], off offset:32
	global_load_dwordx4 v[156:159], v[140:141], off offset:16
	global_load_dwordx4 v[174:177], v[140:141], off offset:48
	s_mov_b64 s[6:7], 0x2000
	s_waitcnt vmcnt(0)
	v_mov_b32_e32 v178, v148
	v_mov_b32_e32 v179, v152
	v_mov_b32_e32 v152, v149
	v_mov_b32_e32 v148, v150
	v_mov_b32_e32 v149, v154
	v_mov_b32_e32 v154, v151
	v_mov_b32_e32 v150, v156
	v_mov_b32_e32 v151, v174
	v_mov_b32_e32 v174, v157
	v_mov_b32_e32 v156, v158
	v_mov_b32_e32 v157, v176
	v_mov_b32_e32 v176, v159
	v_pk_add_f32 v[152:153], v[178:179], v[152:153]
	v_pk_add_f32 v[148:149], v[148:149], v[154:155]
	v_pk_add_f32 v[150:151], v[150:151], v[174:175]
	v_pk_add_f32 v[154:155], v[156:157], v[176:177]
	v_pk_add_f32 v[148:149], v[152:153], v[148:149]
	v_pk_add_f32 v[150:151], v[150:151], v[154:155]
	s_nop 0
	v_pk_add_f32 v[148:149], v[148:149], v[150:151]
	s_nop 0
	v_add_f32_e32 v143, v148, v149
	v_fmamk_f32 v143, v143, 0x3a800000, v206
	v_mul_f32_e32 v148, 0x4b800000, v143
	v_cmp_gt_f32_e32 vcc, s11, v143
	s_nop 1
	v_cndmask_b32_e32 v143, v143, v148, vcc
	v_rsq_f32_e32 v143, v143
	v_lshl_or_b32 v148, v142, 11, v146
	v_lshl_add_u32 v162, s26, 8, v148
	v_lshl_add_u64 v[148:149], v[162:163], 1, s[50:51]
	v_mul_f32_e32 v150, 0x45800000, v143
	v_cndmask_b32_e32 v150, v143, v150, vcc
	v_pk_mul_f32 v[126:127], v[126:127], v[150:151] op_sel_hi:[1,0]
	v_pk_mul_f32 v[124:125], v[124:125], v[150:151] op_sel_hi:[1,0]
	v_pk_mul_f32 v[122:123], v[122:123], v[150:151] op_sel_hi:[1,0]
	v_pk_mul_f32 v[120:121], v[120:121], v[150:151] op_sel_hi:[1,0]
	v_mul_f32_e32 v124, 0xbfb8aa3b, v124
	v_mul_f32_e32 v120, 0xbfb8aa3b, v120
	v_mul_f32_e32 v125, 0xbfb8aa3b, v125
	v_mul_f32_e32 v121, 0xbfb8aa3b, v121
	v_mul_f32_e32 v126, 0xbfb8aa3b, v126
	v_mul_f32_e32 v122, 0xbfb8aa3b, v122
	v_mul_f32_e32 v127, 0xbfb8aa3b, v127
	v_mul_f32_e32 v123, 0xbfb8aa3b, v123
	v_exp_f32_e32 v124, v124
	v_exp_f32_e32 v120, v120
	v_exp_f32_e32 v125, v125
	v_exp_f32_e32 v121, v121
	v_exp_f32_e32 v126, v126
	v_exp_f32_e32 v122, v122
	v_exp_f32_e32 v127, v127
	v_exp_f32_e32 v123, v123
	v_pk_mul_f32 v[114:115], v[114:115], v[150:151] op_sel_hi:[1,0]
	v_pk_mul_f32 v[112:113], v[112:113], v[150:151] op_sel_hi:[1,0]
	v_mul_f32_e32 v114, 0xbfb8aa3b, v114
	v_mul_f32_e32 v112, 0xbfb8aa3b, v112
	v_mul_f32_e32 v113, 0xbfb8aa3b, v113
	v_mul_f32_e32 v115, 0xbfb8aa3b, v115
	v_pk_mul_f32 v[118:119], v[118:119], v[150:151] op_sel_hi:[1,0]
	v_exp_f32_e32 v112, v112
	v_exp_f32_e32 v113, v113
	v_exp_f32_e32 v114, v114
	v_exp_f32_e32 v143, v115
	v_add_f32_e32 v115, 1.0, v124
	v_add_f32_e32 v120, 1.0, v120
	v_add_f32_e32 v124, 1.0, v125
	v_add_f32_e32 v121, 1.0, v121
	v_add_f32_e32 v125, 1.0, v126
	v_add_f32_e32 v122, 1.0, v122
	v_add_f32_e32 v126, 1.0, v127
	v_add_f32_e32 v123, 1.0, v123
	v_pk_mul_f32 v[116:117], v[116:117], v[150:151] op_sel_hi:[1,0]
	v_mul_f32_e32 v119, 0xbfb8aa3b, v119
	v_rcp_f32_e32 v115, v115
	v_rcp_f32_e32 v120, v120
	v_rcp_f32_e32 v124, v124
	v_rcp_f32_e32 v121, v121
	v_rcp_f32_e32 v125, v125
	v_rcp_f32_e32 v122, v122
	v_rcp_f32_e32 v126, v126
	v_rcp_f32_e32 v123, v123
	v_mul_f32_e32 v116, 0xbfb8aa3b, v116
	v_mul_f32_e32 v117, 0xbfb8aa3b, v117
	v_mul_f32_e32 v118, 0xbfb8aa3b, v118
	v_exp_f32_e32 v119, v119
	v_exp_f32_e32 v116, v116
	v_exp_f32_e32 v117, v117
	v_exp_f32_e32 v118, v118
	v_add_f32_e32 v112, 1.0, v112
	v_add_f32_e32 v113, 1.0, v113
	v_add_f32_e32 v114, 1.0, v114
	v_rcp_f32_e32 v127, v112
	v_rcp_f32_e32 v150, v113
	v_rcp_f32_e32 v151, v114
	v_cvt_pk_bf16_f32 v112, v115, v124
	v_cvt_pk_bf16_f32 v113, v125, v126
	v_cvt_pk_bf16_f32 v114, v120, v121
	v_cvt_pk_bf16_f32 v115, v122, v123
	global_store_dwordx4 v[148:149], v[112:115], off sc1
	v_add_f32_e32 v116, 1.0, v116
	v_add_f32_e32 v117, 1.0, v117
	v_add_f32_e32 v112, 1.0, v119
	v_add_f32_e32 v118, 1.0, v118
	v_rcp_f32_e32 v113, v112
	v_add_f32_e32 v112, 1.0, v143
	v_rcp_f32_e32 v116, v116
	v_rcp_f32_e32 v117, v117
	v_rcp_f32_e32 v118, v118
	v_rcp_f32_e32 v115, v112
	v_cvt_pk_bf16_f32 v114, v127, v150
	v_cvt_pk_bf16_f32 v112, v116, v117
	v_cvt_pk_bf16_f32 v113, v118, v113
	v_cvt_pk_bf16_f32 v115, v151, v115
	global_store_dwordx4 v[148:149], v[112:115], off offset:256 sc1
	s_nop 1
	v_or_b32_e32 v112, 16, v142
	v_ashrrev_i32_e32 v113, 31, v112
	v_lshlrev_b64 v[112:113], 6, v[112:113]
	v_lshl_add_u64 v[124:125], s[44:45], 0, v[112:113]
	global_load_dwordx4 v[112:115], v[124:125], off
	global_load_dwordx4 v[116:119], v[124:125], off offset:32
	global_load_dwordx4 v[120:123], v[124:125], off offset:16
	s_nop 0
	global_load_dwordx4 v[124:127], v[124:125], off offset:48
	s_waitcnt vmcnt(3)
	v_mov_b32_e32 v148, v112
	s_waitcnt vmcnt(2)
	v_mov_b32_e32 v149, v116
	v_mov_b32_e32 v116, v113
	v_mov_b32_e32 v112, v114
	v_mov_b32_e32 v113, v118
	v_mov_b32_e32 v118, v115
	s_waitcnt vmcnt(1)
	v_mov_b32_e32 v114, v120
	s_waitcnt vmcnt(0)
	v_mov_b32_e32 v115, v124
	v_mov_b32_e32 v124, v121
	v_mov_b32_e32 v120, v122
	v_mov_b32_e32 v121, v126
	v_mov_b32_e32 v126, v123
	v_pk_add_f32 v[116:117], v[148:149], v[116:117]
	v_pk_add_f32 v[112:113], v[112:113], v[118:119]
	v_pk_add_f32 v[114:115], v[114:115], v[124:125]
	v_pk_add_f32 v[118:119], v[120:121], v[126:127]
	v_pk_add_f32 v[112:113], v[116:117], v[112:113]
	v_pk_add_f32 v[114:115], v[114:115], v[118:119]
	s_nop 0
	v_pk_add_f32 v[112:113], v[112:113], v[114:115]
	s_nop 0
	v_add_f32_e32 v112, v112, v113
	v_fmamk_f32 v112, v112, 0x3a800000, v206
	v_mul_f32_e32 v113, 0x4b800000, v112
	v_cmp_gt_f32_e32 vcc, s11, v112
	s_nop 1
	v_cndmask_b32_e32 v112, v112, v113, vcc
	v_rsq_f32_e32 v114, v112
	v_mov_b32_e32 v113, v163
	v_add_u32_e32 v112, 0x8000, v162
	v_lshl_add_u64 v[112:113], v[112:113], 1, s[50:51]
	v_mul_f32_e32 v115, 0x45800000, v114
	v_cndmask_b32_e32 v114, v114, v115, vcc
	v_pk_mul_f32 v[110:111], v[110:111], v[114:115] op_sel_hi:[1,0]
	v_pk_mul_f32 v[108:109], v[108:109], v[114:115] op_sel_hi:[1,0]
	v_pk_mul_f32 v[106:107], v[106:107], v[114:115] op_sel_hi:[1,0]
	v_pk_mul_f32 v[104:105], v[104:105], v[114:115] op_sel_hi:[1,0]
	v_pk_mul_f32 v[116:117], v[98:99], v[114:115] op_sel_hi:[1,0]
	v_pk_mul_f32 v[96:97], v[96:97], v[114:115] op_sel_hi:[1,0]
	v_mul_f32_e32 v98, 0xbfb8aa3b, v108
	v_mul_f32_e32 v99, 0xbfb8aa3b, v104
	v_mul_f32_e32 v104, 0xbfb8aa3b, v109
	v_mul_f32_e32 v105, 0xbfb8aa3b, v105
	v_mul_f32_e32 v108, 0xbfb8aa3b, v110
	v_mul_f32_e32 v106, 0xbfb8aa3b, v106
	v_mul_f32_e32 v109, 0xbfb8aa3b, v111
	v_mul_f32_e32 v107, 0xbfb8aa3b, v107
	v_mul_f32_e32 v97, 0xbfb8aa3b, v97
	v_exp_f32_e32 v98, v98
	v_exp_f32_e32 v99, v99
	v_exp_f32_e32 v104, v104
	v_exp_f32_e32 v105, v105
	v_exp_f32_e32 v108, v108
	v_exp_f32_e32 v106, v106
	v_exp_f32_e32 v109, v109
	v_exp_f32_e32 v107, v107
	v_exp_f32_e32 v97, v97
	v_mul_f32_e32 v96, 0xbfb8aa3b, v96
	v_exp_f32_e32 v96, v96
	v_add_f32_e32 v98, 1.0, v98
	v_add_f32_e32 v99, 1.0, v99
	v_add_f32_e32 v104, 1.0, v104
	v_add_f32_e32 v105, 1.0, v105
	v_add_f32_e32 v108, 1.0, v108
	v_add_f32_e32 v106, 1.0, v106
	v_add_f32_e32 v109, 1.0, v109
	v_add_f32_e32 v107, 1.0, v107
	v_add_f32_e32 v110, 1.0, v97
	v_rcp_f32_e32 v97, v98
	v_rcp_f32_e32 v98, v99
	v_rcp_f32_e32 v99, v104
	v_rcp_f32_e32 v104, v105
	v_rcp_f32_e32 v105, v108
	v_rcp_f32_e32 v106, v106
	v_rcp_f32_e32 v108, v109
	v_rcp_f32_e32 v107, v107
	v_add_f32_e32 v96, 1.0, v96
	v_pk_mul_f32 v[102:103], v[102:103], v[114:115] op_sel_hi:[1,0]
	v_rcp_f32_e32 v109, v96
	v_cvt_pk_bf16_f32 v96, v97, v99
	v_cvt_pk_bf16_f32 v97, v105, v108
	v_cvt_pk_bf16_f32 v98, v98, v104
	v_cvt_pk_bf16_f32 v99, v106, v107
	global_store_dwordx4 v[112:113], v[96:99], off sc1
	v_pk_mul_f32 v[100:101], v[100:101], v[114:115] op_sel_hi:[1,0]
	s_nop 0
	v_mul_f32_e32 v96, 0xbfb8aa3b, v102
	v_exp_f32_e32 v96, v96
	v_mul_f32_e32 v97, 0xbfb8aa3b, v116
	v_exp_f32_e32 v97, v97
	v_mul_f32_e32 v100, 0xbfb8aa3b, v100
	v_add_f32_e32 v96, 1.0, v96
	v_rcp_f32_e32 v99, v96
	v_add_f32_e32 v96, 1.0, v97
	v_mul_f32_e32 v97, 0xbfb8aa3b, v103
	v_mul_f32_e32 v101, 0xbfb8aa3b, v101
	v_exp_f32_e32 v97, v97
	v_mul_f32_e32 v102, 0xbfb8aa3b, v117
	v_exp_f32_e32 v100, v100
	v_exp_f32_e32 v101, v101
	v_exp_f32_e32 v102, v102
	v_rcp_f32_e32 v103, v96
	v_add_f32_e32 v96, 1.0, v97
	v_add_f32_e32 v100, 1.0, v100
	v_add_f32_e32 v101, 1.0, v101
	v_rcp_f32_e32 v97, v96
	v_add_f32_e32 v96, 1.0, v102
	v_rcp_f32_e32 v100, v100
	v_rcp_f32_e32 v101, v101
	v_rcp_f32_e32 v98, v110
	v_rcp_f32_e32 v102, v96
	v_cvt_pk_bf16_f32 v97, v99, v97
	v_cvt_pk_bf16_f32 v96, v100, v101
	v_cvt_pk_bf16_f32 v98, v109, v98
	v_cvt_pk_bf16_f32 v99, v103, v102
	global_store_dwordx4 v[112:113], v[96:99], off offset:256 sc1
	s_nop 1
	v_or_b32_e32 v96, 32, v142
	v_ashrrev_i32_e32 v97, 31, v96
	v_lshlrev_b64 v[96:97], 6, v[96:97]
	v_lshl_add_u64 v[108:109], s[44:45], 0, v[96:97]
	global_load_dwordx4 v[96:99], v[108:109], off
	global_load_dwordx4 v[100:103], v[108:109], off offset:32
	global_load_dwordx4 v[104:107], v[108:109], off offset:16
	s_nop 0
	global_load_dwordx4 v[108:111], v[108:109], off offset:48
	s_waitcnt vmcnt(3)
	v_mov_b32_e32 v112, v96
	s_waitcnt vmcnt(2)
	v_mov_b32_e32 v113, v100
	v_mov_b32_e32 v100, v97
	v_mov_b32_e32 v96, v98
	v_mov_b32_e32 v97, v102
	v_mov_b32_e32 v102, v99
	s_waitcnt vmcnt(1)
	v_mov_b32_e32 v98, v104
	s_waitcnt vmcnt(0)
	v_mov_b32_e32 v99, v108
	v_mov_b32_e32 v108, v105
	v_mov_b32_e32 v104, v106
	v_mov_b32_e32 v105, v110
	v_mov_b32_e32 v110, v107
	v_pk_add_f32 v[100:101], v[112:113], v[100:101]
	v_pk_add_f32 v[96:97], v[96:97], v[102:103]
	v_pk_add_f32 v[98:99], v[98:99], v[108:109]
	v_pk_add_f32 v[102:103], v[104:105], v[110:111]
	v_pk_add_f32 v[96:97], v[100:101], v[96:97]
	v_pk_add_f32 v[98:99], v[98:99], v[102:103]
	s_nop 0
	v_pk_add_f32 v[96:97], v[96:97], v[98:99]
	s_nop 0
	v_add_f32_e32 v96, v96, v97
	v_fmamk_f32 v96, v96, 0x3a800000, v206
	v_mul_f32_e32 v97, 0x4b800000, v96
	v_cmp_gt_f32_e32 vcc, s11, v96
	s_nop 1
	v_cndmask_b32_e32 v96, v96, v97, vcc
	v_rsq_f32_e32 v98, v96
	v_mov_b32_e32 v97, v163
	v_add_u32_e32 v96, 0x10000, v162
	v_lshl_add_u64 v[96:97], v[96:97], 1, s[50:51]
	v_mul_f32_e32 v99, 0x45800000, v98
	v_cndmask_b32_e32 v98, v98, v99, vcc
	v_pk_mul_f32 v[94:95], v[94:95], v[98:99] op_sel_hi:[1,0]
	v_pk_mul_f32 v[92:93], v[92:93], v[98:99] op_sel_hi:[1,0]
	v_pk_mul_f32 v[90:91], v[90:91], v[98:99] op_sel_hi:[1,0]
	v_pk_mul_f32 v[88:89], v[88:89], v[98:99] op_sel_hi:[1,0]
	v_pk_mul_f32 v[100:101], v[86:87], v[98:99] op_sel_hi:[1,0]
	v_pk_mul_f32 v[102:103], v[84:85], v[98:99] op_sel_hi:[1,0]
	v_mul_f32_e32 v84, 0xbfb8aa3b, v92
	v_mul_f32_e32 v85, 0xbfb8aa3b, v88
	v_mul_f32_e32 v86, 0xbfb8aa3b, v93
	v_mul_f32_e32 v87, 0xbfb8aa3b, v89
	v_mul_f32_e32 v88, 0xbfb8aa3b, v94
	v_mul_f32_e32 v89, 0xbfb8aa3b, v90
	v_mul_f32_e32 v90, 0xbfb8aa3b, v95
	v_mul_f32_e32 v91, 0xbfb8aa3b, v91
	v_exp_f32_e32 v84, v84
	v_exp_f32_e32 v85, v85
	v_exp_f32_e32 v86, v86
	v_exp_f32_e32 v87, v87
	v_exp_f32_e32 v88, v88
	v_exp_f32_e32 v89, v89
	v_exp_f32_e32 v90, v90
	v_exp_f32_e32 v91, v91
	v_add_f32_e32 v84, 1.0, v84
	v_add_f32_e32 v85, 1.0, v85
	v_add_f32_e32 v86, 1.0, v86
	v_add_f32_e32 v87, 1.0, v87
	v_add_f32_e32 v88, 1.0, v88
	v_add_f32_e32 v89, 1.0, v89
	v_add_f32_e32 v90, 1.0, v90
	v_add_f32_e32 v91, 1.0, v91
	v_rcp_f32_e32 v84, v84
	v_rcp_f32_e32 v93, v85
	v_rcp_f32_e32 v85, v86
	v_rcp_f32_e32 v86, v87
	v_rcp_f32_e32 v87, v88
	v_rcp_f32_e32 v88, v90
	v_rcp_f32_e32 v89, v89
	v_rcp_f32_e32 v90, v91
	v_pk_mul_f32 v[80:81], v[80:81], v[98:99] op_sel_hi:[1,0]
	v_cvt_pk_bf16_f32 v84, v84, v85
	v_mul_f32_e32 v80, 0xbfb8aa3b, v80
	v_cvt_pk_bf16_f32 v85, v87, v88
	v_cvt_pk_bf16_f32 v86, v93, v86
	v_cvt_pk_bf16_f32 v87, v89, v90
	global_store_dwordx4 v[96:97], v[84:87], off sc1
	v_exp_f32_e32 v80, v80
	v_mul_f32_e32 v81, 0xbfb8aa3b, v81
	v_mul_f32_e32 v85, 0xbfb8aa3b, v103
	v_exp_f32_e32 v85, v85
	v_add_f32_e32 v80, 1.0, v80
	v_exp_f32_e32 v81, v81
	v_rcp_f32_e32 v86, v80
	v_add_f32_e32 v80, 1.0, v85
	v_mul_f32_e32 v85, 0xbfb8aa3b, v100
	v_exp_f32_e32 v85, v85
	v_pk_mul_f32 v[82:83], v[82:83], v[98:99] op_sel_hi:[1,0]
	v_add_f32_e32 v81, 1.0, v81
	v_mul_f32_e32 v82, 0xbfb8aa3b, v82
	v_mul_f32_e32 v92, 0xbfb8aa3b, v102
	v_exp_f32_e32 v82, v82
	v_rcp_f32_e32 v87, v81
	v_add_f32_e32 v81, 1.0, v85
	v_mul_f32_e32 v85, 0xbfb8aa3b, v101
	v_mul_f32_e32 v83, 0xbfb8aa3b, v83
	v_exp_f32_e32 v92, v92
	v_exp_f32_e32 v85, v85
	v_exp_f32_e32 v83, v83
	v_add_f32_e32 v82, 1.0, v82
	v_add_f32_e32 v84, 1.0, v92
	v_rcp_f32_e32 v88, v82
	v_add_f32_e32 v82, 1.0, v85
	v_add_f32_e32 v83, 1.0, v83
	v_rcp_f32_e32 v84, v84
	v_rcp_f32_e32 v80, v80
	v_rcp_f32_e32 v81, v81
	v_rcp_f32_e32 v82, v82
	v_rcp_f32_e32 v83, v83
	v_cvt_pk_bf16_f32 v80, v84, v80
	v_cvt_pk_bf16_f32 v81, v81, v82
	v_cvt_pk_bf16_f32 v82, v86, v87
	v_cvt_pk_bf16_f32 v83, v88, v83
	global_store_dwordx4 v[96:97], v[80:83], off offset:256 sc1
	s_nop 1
	v_or_b32_e32 v80, 48, v142
	v_ashrrev_i32_e32 v81, 31, v80
	v_lshlrev_b64 v[80:81], 6, v[80:81]
	v_lshl_add_u64 v[92:93], s[44:45], 0, v[80:81]
	global_load_dwordx4 v[80:83], v[92:93], off
	global_load_dwordx4 v[84:87], v[92:93], off offset:32
	global_load_dwordx4 v[88:91], v[92:93], off offset:16
	s_nop 0
	global_load_dwordx4 v[92:95], v[92:93], off offset:48
	s_waitcnt vmcnt(3)
	v_mov_b32_e32 v96, v80
	s_waitcnt vmcnt(2)
	v_mov_b32_e32 v97, v84
	v_mov_b32_e32 v84, v81
	v_mov_b32_e32 v80, v82
	v_mov_b32_e32 v81, v86
	v_mov_b32_e32 v86, v83
	s_waitcnt vmcnt(1)
	v_mov_b32_e32 v82, v88
	s_waitcnt vmcnt(0)
	v_mov_b32_e32 v83, v92
	v_mov_b32_e32 v92, v89
	v_mov_b32_e32 v88, v90
	v_mov_b32_e32 v89, v94
	v_mov_b32_e32 v94, v91
	v_pk_add_f32 v[84:85], v[96:97], v[84:85]
	v_pk_add_f32 v[80:81], v[80:81], v[86:87]
	v_pk_add_f32 v[82:83], v[82:83], v[92:93]
	v_pk_add_f32 v[86:87], v[88:89], v[94:95]
	v_pk_add_f32 v[80:81], v[84:85], v[80:81]
	v_pk_add_f32 v[82:83], v[82:83], v[86:87]
	s_nop 0
	v_pk_add_f32 v[80:81], v[80:81], v[82:83]
	s_nop 0
	v_add_f32_e32 v80, v80, v81
	v_fmamk_f32 v80, v80, 0x3a800000, v206
	v_mul_f32_e32 v81, 0x4b800000, v80
	v_cmp_gt_f32_e32 vcc, s11, v80
	s_nop 1
	v_cndmask_b32_e32 v80, v80, v81, vcc
	v_rsq_f32_e32 v82, v80
	v_mov_b32_e32 v81, v163
	v_add_u32_e32 v80, 0x18000, v162
	v_lshl_add_u64 v[80:81], v[80:81], 1, s[50:51]
	v_mul_f32_e32 v83, 0x45800000, v82
	v_cndmask_b32_e32 v82, v82, v83, vcc
	v_pk_mul_f32 v[72:73], v[72:73], v[82:83] op_sel_hi:[1,0]
	v_pk_mul_f32 v[78:79], v[78:79], v[82:83] op_sel_hi:[1,0]
	v_mul_f32_e32 v72, 0xbfb8aa3b, v72
	v_exp_f32_e32 v72, v72
	v_pk_mul_f32 v[76:77], v[76:77], v[82:83] op_sel_hi:[1,0]
	v_pk_mul_f32 v[74:75], v[74:75], v[82:83] op_sel_hi:[1,0]
	v_mul_f32_e32 v77, 0xbfb8aa3b, v77
	v_mul_f32_e32 v73, 0xbfb8aa3b, v73
	v_mul_f32_e32 v78, 0xbfb8aa3b, v78
	v_mul_f32_e32 v74, 0xbfb8aa3b, v74
	v_add_f32_e32 v72, 1.0, v72
	v_mul_f32_e32 v76, 0xbfb8aa3b, v76
	v_mul_f32_e32 v79, 0xbfb8aa3b, v79
	v_exp_f32_e32 v77, v77
	v_exp_f32_e32 v73, v73
	v_exp_f32_e32 v78, v78
	v_exp_f32_e32 v74, v74
	v_rcp_f32_e32 v83, v72
	v_mul_f32_e32 v75, 0xbfb8aa3b, v75
	v_exp_f32_e32 v76, v76
	v_exp_f32_e32 v79, v79
	v_exp_f32_e32 v75, v75
	v_add_f32_e32 v77, 1.0, v77
	v_add_f32_e32 v73, 1.0, v73
	v_add_f32_e32 v78, 1.0, v78
	v_add_f32_e32 v74, 1.0, v74
	v_pk_mul_f32 v[64:65], v[64:65], v[82:83] op_sel_hi:[1,0]
	v_add_f32_e32 v76, 1.0, v76
	v_rcp_f32_e32 v72, v77
	v_rcp_f32_e32 v77, v73
	v_rcp_f32_e32 v73, v78
	v_rcp_f32_e32 v78, v74
	v_add_f32_e32 v74, 1.0, v79
	v_add_f32_e32 v75, 1.0, v75
	v_pk_mul_f32 v[68:69], v[68:69], v[82:83] op_sel_hi:[1,0]
	v_mul_f32_e32 v64, 0xbfb8aa3b, v64
	v_rcp_f32_e32 v76, v76
	v_rcp_f32_e32 v74, v74
	v_rcp_f32_e32 v75, v75
	v_exp_f32_e32 v64, v64
	v_mul_f32_e32 v69, 0xbfb8aa3b, v69
	v_exp_f32_e32 v69, v69
	v_cvt_pk_bf16_f32 v72, v76, v72
	v_cvt_pk_bf16_f32 v73, v73, v74
	v_cvt_pk_bf16_f32 v74, v83, v77
	v_cvt_pk_bf16_f32 v75, v78, v75
	v_pk_mul_f32 v[70:71], v[70:71], v[82:83] op_sel_hi:[1,0]
	v_add_f32_e32 v64, 1.0, v64
	v_mul_f32_e32 v65, 0xbfb8aa3b, v65
	global_store_dwordx4 v[80:81], v[72:75], off sc1
	v_exp_f32_e32 v65, v65
	v_pk_mul_f32 v[66:67], v[66:67], v[82:83] op_sel_hi:[1,0]
	v_rcp_f32_e32 v72, v64
	v_add_f32_e32 v64, 1.0, v69
	v_mul_f32_e32 v69, 0xbfb8aa3b, v70
	v_exp_f32_e32 v69, v69
	v_add_f32_e32 v65, 1.0, v65
	v_mul_f32_e32 v66, 0xbfb8aa3b, v66
	v_mul_f32_e32 v68, 0xbfb8aa3b, v68
	v_exp_f32_e32 v66, v66
	v_rcp_f32_e32 v70, v65
	v_add_f32_e32 v65, 1.0, v69
	v_mul_f32_e32 v69, 0xbfb8aa3b, v71
	v_mul_f32_e32 v67, 0xbfb8aa3b, v67
	v_exp_f32_e32 v68, v68
	v_exp_f32_e32 v69, v69
	v_exp_f32_e32 v67, v67
	v_add_f32_e32 v66, 1.0, v66
	v_add_f32_e32 v68, 1.0, v68
	v_rcp_f32_e32 v71, v66
	v_add_f32_e32 v66, 1.0, v69
	v_add_f32_e32 v67, 1.0, v67
	v_rcp_f32_e32 v68, v68
	v_rcp_f32_e32 v64, v64
	v_rcp_f32_e32 v65, v65
	v_rcp_f32_e32 v66, v66
	v_rcp_f32_e32 v67, v67
	v_cvt_pk_bf16_f32 v64, v68, v64
	v_lshl_add_u64 v[78:79], v[140:141], 0, s[6:7]
	v_cvt_pk_bf16_f32 v65, v65, v66
	v_cvt_pk_bf16_f32 v66, v72, v70
	v_cvt_pk_bf16_f32 v67, v71, v67
	s_movk_i32 s6, 0x2000
	global_store_dwordx4 v[80:81], v[64:67], off offset:256 sc1
	s_nop 1
	v_add_co_u32_e32 v64, vcc, s6, v140
	s_mov_b64 s[6:7], 0x2400
	s_nop 0
	v_addc_co_u32_e32 v65, vcc, 0, v141, vcc
	global_load_dwordx4 v[66:69], v[64:65], off
	global_load_dwordx4 v[70:73], v[78:79], off offset:32
	global_load_dwordx4 v[74:77], v[78:79], off offset:16
	s_nop 0
	global_load_dwordx4 v[78:81], v[78:79], off offset:48
	s_waitcnt vmcnt(3)
	v_mov_b32_e32 v82, v66
	s_waitcnt vmcnt(2)
	v_mov_b32_e32 v83, v70
	v_mov_b32_e32 v70, v67
	v_mov_b32_e32 v66, v68
	v_mov_b32_e32 v67, v72
	v_mov_b32_e32 v72, v69
	s_waitcnt vmcnt(1)
	v_mov_b32_e32 v68, v74
	s_waitcnt vmcnt(0)
	v_mov_b32_e32 v69, v78
	v_mov_b32_e32 v78, v75
	v_mov_b32_e32 v74, v76
	v_mov_b32_e32 v75, v80
	v_mov_b32_e32 v80, v77
	v_pk_add_f32 v[70:71], v[82:83], v[70:71]
	v_pk_add_f32 v[66:67], v[66:67], v[72:73]
	v_pk_add_f32 v[68:69], v[68:69], v[78:79]
	v_pk_add_f32 v[72:73], v[74:75], v[80:81]
	v_pk_add_f32 v[66:67], v[70:71], v[66:67]
	v_pk_add_f32 v[68:69], v[68:69], v[72:73]
	s_nop 0
	v_pk_add_f32 v[66:67], v[66:67], v[68:69]
	s_nop 0
	v_add_f32_e32 v66, v66, v67
	v_fmamk_f32 v66, v66, 0x3a800000, v206
	v_mul_f32_e32 v67, 0x4b800000, v66
	v_cmp_gt_f32_e32 vcc, s11, v66
	s_nop 1
	v_cndmask_b32_e32 v66, v66, v67, vcc
	v_rsq_f32_e32 v68, v66
	v_mov_b32_e32 v67, v163
	v_add_u32_e32 v66, 0x40000, v162
	v_lshl_add_u64 v[66:67], v[66:67], 1, s[50:51]
	v_mul_f32_e32 v69, 0x45800000, v68
	v_cndmask_b32_e32 v68, v68, v69, vcc
	v_pk_mul_f32 v[56:57], v[56:57], v[68:69] op_sel_hi:[1,0]
	v_pk_mul_f32 v[60:61], v[60:61], v[68:69] op_sel_hi:[1,0]
	v_mul_f32_e32 v56, 0xbfb8aa3b, v56
	v_mul_f32_e32 v61, 0xbfb8aa3b, v61
	v_exp_f32_e32 v56, v56
	v_exp_f32_e32 v61, v61
	v_pk_mul_f32 v[62:63], v[62:63], v[68:69] op_sel_hi:[1,0]
	v_mul_f32_e32 v57, 0xbfb8aa3b, v57
	v_add_f32_e32 v56, 1.0, v56
	v_pk_mul_f32 v[58:59], v[58:59], v[68:69] op_sel_hi:[1,0]
	v_exp_f32_e32 v57, v57
	v_rcp_f32_e32 v69, v56
	v_add_f32_e32 v56, 1.0, v61
	v_mul_f32_e32 v61, 0xbfb8aa3b, v62
	v_exp_f32_e32 v61, v61
	v_add_f32_e32 v57, 1.0, v57
	v_mul_f32_e32 v58, 0xbfb8aa3b, v58
	v_mul_f32_e32 v60, 0xbfb8aa3b, v60
	v_exp_f32_e32 v58, v58
	v_rcp_f32_e32 v62, v57
	v_add_f32_e32 v57, 1.0, v61
	v_mul_f32_e32 v61, 0xbfb8aa3b, v63
	v_mul_f32_e32 v59, 0xbfb8aa3b, v59
	v_exp_f32_e32 v60, v60
	v_exp_f32_e32 v61, v61
	v_exp_f32_e32 v59, v59
	v_add_f32_e32 v58, 1.0, v58
	v_pk_mul_f32 v[48:49], v[48:49], v[68:69] op_sel_hi:[1,0]
	v_add_f32_e32 v60, 1.0, v60
	v_rcp_f32_e32 v63, v58
	v_add_f32_e32 v58, 1.0, v61
	v_add_f32_e32 v59, 1.0, v59
	v_pk_mul_f32 v[52:53], v[52:53], v[68:69] op_sel_hi:[1,0]
	v_mul_f32_e32 v48, 0xbfb8aa3b, v48
	v_rcp_f32_e32 v60, v60
	v_rcp_f32_e32 v56, v56
	v_rcp_f32_e32 v57, v57
	v_rcp_f32_e32 v58, v58
	v_rcp_f32_e32 v59, v59
	v_exp_f32_e32 v48, v48
	v_mul_f32_e32 v53, 0xbfb8aa3b, v53
	v_exp_f32_e32 v53, v53
	v_cvt_pk_bf16_f32 v56, v60, v56
	v_cvt_pk_bf16_f32 v57, v57, v58
	v_cvt_pk_bf16_f32 v58, v69, v62
	v_cvt_pk_bf16_f32 v59, v63, v59
	v_pk_mul_f32 v[54:55], v[54:55], v[68:69] op_sel_hi:[1,0]
	v_add_f32_e32 v48, 1.0, v48
	v_mul_f32_e32 v49, 0xbfb8aa3b, v49
	global_store_dwordx4 v[66:67], v[56:59], off sc1
	v_exp_f32_e32 v49, v49
	v_pk_mul_f32 v[50:51], v[50:51], v[68:69] op_sel_hi:[1,0]
	v_rcp_f32_e32 v56, v48
	v_add_f32_e32 v48, 1.0, v53
	v_mul_f32_e32 v53, 0xbfb8aa3b, v54
	v_exp_f32_e32 v53, v53
	v_add_f32_e32 v49, 1.0, v49
	v_mul_f32_e32 v50, 0xbfb8aa3b, v50
	v_mul_f32_e32 v52, 0xbfb8aa3b, v52
	v_exp_f32_e32 v50, v50
	v_rcp_f32_e32 v54, v49
	v_add_f32_e32 v49, 1.0, v53
	v_mul_f32_e32 v53, 0xbfb8aa3b, v55
	v_mul_f32_e32 v51, 0xbfb8aa3b, v51
	v_exp_f32_e32 v52, v52
	v_exp_f32_e32 v53, v53
	v_exp_f32_e32 v51, v51
	v_add_f32_e32 v50, 1.0, v50
	v_add_f32_e32 v52, 1.0, v52
	v_rcp_f32_e32 v55, v50
	v_add_f32_e32 v50, 1.0, v53
	v_add_f32_e32 v51, 1.0, v51
	v_rcp_f32_e32 v52, v52
	v_rcp_f32_e32 v48, v48
	v_rcp_f32_e32 v49, v49
	v_rcp_f32_e32 v50, v50
	v_rcp_f32_e32 v51, v51
	v_cvt_pk_bf16_f32 v48, v52, v48
	v_lshl_add_u64 v[60:61], v[140:141], 0, s[6:7]
	v_cvt_pk_bf16_f32 v49, v49, v50
	v_cvt_pk_bf16_f32 v50, v56, v54
	v_cvt_pk_bf16_f32 v51, v55, v51
	global_store_dwordx4 v[66:67], v[48:51], off offset:256 sc1
	global_load_dwordx4 v[48:51], v[64:65], off offset:1024
	global_load_dwordx4 v[52:55], v[60:61], off offset:32
	global_load_dwordx4 v[56:59], v[60:61], off offset:16
	s_nop 0
	global_load_dwordx4 v[60:63], v[60:61], off offset:48
	s_mov_b64 s[6:7], 0x2800
	s_waitcnt vmcnt(3)
	v_mov_b32_e32 v66, v48
	s_waitcnt vmcnt(2)
	v_mov_b32_e32 v67, v52
	v_mov_b32_e32 v52, v49
	v_mov_b32_e32 v48, v50
	v_mov_b32_e32 v49, v54
	v_mov_b32_e32 v54, v51
	s_waitcnt vmcnt(1)
	v_mov_b32_e32 v50, v56
	s_waitcnt vmcnt(0)
	v_mov_b32_e32 v51, v60
	v_mov_b32_e32 v60, v57
	v_mov_b32_e32 v56, v58
	v_mov_b32_e32 v57, v62
	v_mov_b32_e32 v62, v59
	v_pk_add_f32 v[52:53], v[66:67], v[52:53]
	v_pk_add_f32 v[48:49], v[48:49], v[54:55]
	v_pk_add_f32 v[50:51], v[50:51], v[60:61]
	v_pk_add_f32 v[48:49], v[52:53], v[48:49]
	v_pk_add_f32 v[52:53], v[56:57], v[62:63]
	s_nop 0
	v_pk_add_f32 v[50:51], v[50:51], v[52:53]
	s_nop 0
	v_pk_add_f32 v[48:49], v[48:49], v[50:51]
	s_nop 0
	v_add_f32_e32 v48, v48, v49
	v_fmamk_f32 v48, v48, 0x3a800000, v206
	v_mul_f32_e32 v49, 0x4b800000, v48
	v_cmp_gt_f32_e32 vcc, s11, v48
	s_nop 1
	v_cndmask_b32_e32 v48, v48, v49, vcc
	v_rsq_f32_e32 v49, v48
	v_add_u32_e32 v48, 0x48000, v162
	v_mul_f32_e32 v50, 0x45800000, v49
	v_cndmask_b32_e32 v50, v49, v50, vcc
	v_pk_mul_f32 v[40:41], v[40:41], v[50:51] op_sel_hi:[1,0]
	v_pk_mul_f32 v[44:45], v[44:45], v[50:51] op_sel_hi:[1,0]
	v_mul_f32_e32 v40, 0xbfb8aa3b, v40
	v_exp_f32_e32 v40, v40
	v_mul_f32_e32 v45, 0xbfb8aa3b, v45
	v_exp_f32_e32 v45, v45
	v_pk_mul_f32 v[46:47], v[46:47], v[50:51] op_sel_hi:[1,0]
	v_add_f32_e32 v40, 1.0, v40
	v_mul_f32_e32 v41, 0xbfb8aa3b, v41
	v_pk_mul_f32 v[42:43], v[42:43], v[50:51] op_sel_hi:[1,0]
	v_exp_f32_e32 v41, v41
	v_rcp_f32_e32 v51, v40
	v_add_f32_e32 v40, 1.0, v45
	v_mul_f32_e32 v45, 0xbfb8aa3b, v46
	v_exp_f32_e32 v45, v45
	v_add_f32_e32 v41, 1.0, v41
	v_mul_f32_e32 v42, 0xbfb8aa3b, v42
	v_mul_f32_e32 v44, 0xbfb8aa3b, v44
	v_exp_f32_e32 v42, v42
	v_rcp_f32_e32 v46, v41
	v_add_f32_e32 v41, 1.0, v45
	v_mul_f32_e32 v45, 0xbfb8aa3b, v47
	v_mul_f32_e32 v43, 0xbfb8aa3b, v43
	v_exp_f32_e32 v44, v44
	v_exp_f32_e32 v45, v45
	v_exp_f32_e32 v43, v43
	v_add_f32_e32 v42, 1.0, v42
	v_pk_mul_f32 v[32:33], v[32:33], v[50:51] op_sel_hi:[1,0]
	v_add_f32_e32 v44, 1.0, v44
	v_rcp_f32_e32 v47, v42
	v_add_f32_e32 v42, 1.0, v45
	v_add_f32_e32 v43, 1.0, v43
	v_pk_mul_f32 v[36:37], v[36:37], v[50:51] op_sel_hi:[1,0]
	v_mul_f32_e32 v32, 0xbfb8aa3b, v32
	v_rcp_f32_e32 v44, v44
	v_rcp_f32_e32 v40, v40
	v_rcp_f32_e32 v41, v41
	v_rcp_f32_e32 v42, v42
	v_rcp_f32_e32 v43, v43
	v_exp_f32_e32 v32, v32
	v_mul_f32_e32 v37, 0xbfb8aa3b, v37
	v_exp_f32_e32 v37, v37
	v_mov_b32_e32 v49, v163
	v_lshl_add_u64 v[48:49], v[48:49], 1, s[50:51]
	v_cvt_pk_bf16_f32 v40, v44, v40
	v_cvt_pk_bf16_f32 v41, v41, v42
	v_cvt_pk_bf16_f32 v42, v51, v46
	v_cvt_pk_bf16_f32 v43, v47, v43
	v_pk_mul_f32 v[38:39], v[38:39], v[50:51] op_sel_hi:[1,0]
	v_add_f32_e32 v32, 1.0, v32
	v_mul_f32_e32 v33, 0xbfb8aa3b, v33
	global_store_dwordx4 v[48:49], v[40:43], off sc1
	v_exp_f32_e32 v33, v33
	v_pk_mul_f32 v[34:35], v[34:35], v[50:51] op_sel_hi:[1,0]
	v_rcp_f32_e32 v40, v32
	v_add_f32_e32 v32, 1.0, v37
	v_mul_f32_e32 v37, 0xbfb8aa3b, v38
	v_exp_f32_e32 v37, v37
	v_add_f32_e32 v33, 1.0, v33
	v_mul_f32_e32 v34, 0xbfb8aa3b, v34
	v_mul_f32_e32 v36, 0xbfb8aa3b, v36
	v_exp_f32_e32 v34, v34
	v_rcp_f32_e32 v38, v33
	v_add_f32_e32 v33, 1.0, v37
	v_mul_f32_e32 v37, 0xbfb8aa3b, v39
	v_mul_f32_e32 v35, 0xbfb8aa3b, v35
	v_exp_f32_e32 v36, v36
	v_exp_f32_e32 v37, v37
	v_exp_f32_e32 v35, v35
	v_add_f32_e32 v34, 1.0, v34
	v_add_f32_e32 v36, 1.0, v36
	v_rcp_f32_e32 v39, v34
	v_add_f32_e32 v34, 1.0, v37
	v_add_f32_e32 v35, 1.0, v35
	v_rcp_f32_e32 v36, v36
	v_rcp_f32_e32 v32, v32
	v_rcp_f32_e32 v33, v33
	v_rcp_f32_e32 v34, v34
	v_rcp_f32_e32 v35, v35
	v_cvt_pk_bf16_f32 v32, v36, v32
	v_lshl_add_u64 v[44:45], v[140:141], 0, s[6:7]
	v_cvt_pk_bf16_f32 v33, v33, v34
	v_cvt_pk_bf16_f32 v34, v40, v38
	v_cvt_pk_bf16_f32 v35, v39, v35
	global_store_dwordx4 v[48:49], v[32:35], off offset:256 sc1
	global_load_dwordx4 v[32:35], v[64:65], off offset:2048
	global_load_dwordx4 v[36:39], v[44:45], off offset:32
	global_load_dwordx4 v[40:43], v[44:45], off offset:16
	s_nop 0
	global_load_dwordx4 v[44:47], v[44:45], off offset:48
	s_mov_b64 s[6:7], 0x2c00
	s_waitcnt vmcnt(3)
	v_mov_b32_e32 v48, v32
	s_waitcnt vmcnt(2)
	v_mov_b32_e32 v49, v36
	v_mov_b32_e32 v36, v33
	v_mov_b32_e32 v32, v34
	v_mov_b32_e32 v33, v38
	v_mov_b32_e32 v38, v35
	v_pk_add_f32 v[36:37], v[48:49], v[36:37]
	v_pk_add_f32 v[32:33], v[32:33], v[38:39]
	s_waitcnt vmcnt(1)
	v_mov_b32_e32 v34, v40
	v_pk_add_f32 v[32:33], v[36:37], v[32:33]
	s_waitcnt vmcnt(0)
	v_mov_b32_e32 v35, v44
	v_mov_b32_e32 v44, v41
	v_mov_b32_e32 v36, v42
	v_mov_b32_e32 v37, v46
	v_mov_b32_e32 v46, v43
	v_pk_add_f32 v[34:35], v[34:35], v[44:45]
	v_pk_add_f32 v[36:37], v[36:37], v[46:47]
	s_nop 0
	v_pk_add_f32 v[34:35], v[34:35], v[36:37]
	s_nop 0
	v_pk_add_f32 v[32:33], v[32:33], v[34:35]
	s_nop 0
	v_add_f32_e32 v32, v32, v33
	v_fmamk_f32 v32, v32, 0x3a800000, v206
	v_mul_f32_e32 v33, 0x4b800000, v32
	v_cmp_gt_f32_e32 vcc, s11, v32
	s_nop 1
	v_cndmask_b32_e32 v32, v32, v33, vcc
	v_rsq_f32_e32 v33, v32
	v_add_u32_e32 v32, 0x50000, v162
	v_add_u32_e32 v162, 0x58000, v162
	v_mul_f32_e32 v34, 0x45800000, v33
	v_cndmask_b32_e32 v34, v33, v34, vcc
	v_pk_mul_f32 v[24:25], v[24:25], v[34:35] op_sel_hi:[1,0]
	v_pk_mul_f32 v[28:29], v[28:29], v[34:35] op_sel_hi:[1,0]
	v_mul_f32_e32 v24, 0xbfb8aa3b, v24
	v_exp_f32_e32 v24, v24
	v_mul_f32_e32 v29, 0xbfb8aa3b, v29
	v_exp_f32_e32 v29, v29
	v_pk_mul_f32 v[30:31], v[30:31], v[34:35] op_sel_hi:[1,0]
	v_add_f32_e32 v24, 1.0, v24
	v_mul_f32_e32 v25, 0xbfb8aa3b, v25
	v_pk_mul_f32 v[26:27], v[26:27], v[34:35] op_sel_hi:[1,0]
	v_exp_f32_e32 v25, v25
	v_rcp_f32_e32 v35, v24
	v_add_f32_e32 v24, 1.0, v29
	v_mul_f32_e32 v29, 0xbfb8aa3b, v30
	v_exp_f32_e32 v29, v29
	v_add_f32_e32 v25, 1.0, v25
	v_mul_f32_e32 v26, 0xbfb8aa3b, v26
	v_mul_f32_e32 v28, 0xbfb8aa3b, v28
	v_exp_f32_e32 v26, v26
	v_rcp_f32_e32 v30, v25
	v_add_f32_e32 v25, 1.0, v29
	v_mul_f32_e32 v29, 0xbfb8aa3b, v31
	v_mul_f32_e32 v27, 0xbfb8aa3b, v27
	v_exp_f32_e32 v28, v28
	v_exp_f32_e32 v29, v29
	v_exp_f32_e32 v27, v27
	v_add_f32_e32 v26, 1.0, v26
	v_pk_mul_f32 v[16:17], v[16:17], v[34:35] op_sel_hi:[1,0]
	v_add_f32_e32 v28, 1.0, v28
	v_rcp_f32_e32 v31, v26
	v_add_f32_e32 v26, 1.0, v29
	v_add_f32_e32 v27, 1.0, v27
	v_pk_mul_f32 v[20:21], v[20:21], v[34:35] op_sel_hi:[1,0]
	v_mul_f32_e32 v16, 0xbfb8aa3b, v16
	v_rcp_f32_e32 v28, v28
	v_rcp_f32_e32 v24, v24
	v_rcp_f32_e32 v25, v25
	v_rcp_f32_e32 v26, v26
	v_rcp_f32_e32 v27, v27
	v_exp_f32_e32 v16, v16
	v_mul_f32_e32 v21, 0xbfb8aa3b, v21
	v_exp_f32_e32 v21, v21
	v_mov_b32_e32 v33, v163
	v_lshl_add_u64 v[32:33], v[32:33], 1, s[50:51]
	v_cvt_pk_bf16_f32 v24, v28, v24
	v_cvt_pk_bf16_f32 v25, v25, v26
	v_cvt_pk_bf16_f32 v26, v35, v30
	v_cvt_pk_bf16_f32 v27, v31, v27
	v_pk_mul_f32 v[22:23], v[22:23], v[34:35] op_sel_hi:[1,0]
	v_add_f32_e32 v16, 1.0, v16
	v_mul_f32_e32 v17, 0xbfb8aa3b, v17
	global_store_dwordx4 v[32:33], v[24:27], off sc1
	v_exp_f32_e32 v17, v17
	v_pk_mul_f32 v[18:19], v[18:19], v[34:35] op_sel_hi:[1,0]
	v_rcp_f32_e32 v24, v16
	v_add_f32_e32 v16, 1.0, v21
	v_mul_f32_e32 v21, 0xbfb8aa3b, v22
	v_exp_f32_e32 v21, v21
	v_add_f32_e32 v17, 1.0, v17
	v_mul_f32_e32 v18, 0xbfb8aa3b, v18
	v_mul_f32_e32 v20, 0xbfb8aa3b, v20
	v_exp_f32_e32 v18, v18
	v_rcp_f32_e32 v22, v17
	v_add_f32_e32 v17, 1.0, v21
	v_mul_f32_e32 v21, 0xbfb8aa3b, v23
	v_mul_f32_e32 v19, 0xbfb8aa3b, v19
	v_exp_f32_e32 v20, v20
	v_exp_f32_e32 v21, v21
	v_exp_f32_e32 v19, v19
	v_add_f32_e32 v18, 1.0, v18
	v_add_f32_e32 v20, 1.0, v20
	v_rcp_f32_e32 v23, v18
	v_add_f32_e32 v18, 1.0, v21
	v_add_f32_e32 v19, 1.0, v19
	v_rcp_f32_e32 v20, v20
	v_rcp_f32_e32 v16, v16
	v_rcp_f32_e32 v17, v17
	v_rcp_f32_e32 v18, v18
	v_rcp_f32_e32 v19, v19
	v_cvt_pk_bf16_f32 v16, v20, v16
	v_lshl_add_u64 v[28:29], v[140:141], 0, s[6:7]
	v_cvt_pk_bf16_f32 v17, v17, v18
	v_cvt_pk_bf16_f32 v18, v24, v22
	v_cvt_pk_bf16_f32 v19, v23, v19
	global_store_dwordx4 v[32:33], v[16:19], off offset:256 sc1
	global_load_dwordx4 v[16:19], v[64:65], off offset:3072
	global_load_dwordx4 v[20:23], v[28:29], off offset:32
	global_load_dwordx4 v[24:27], v[28:29], off offset:16
	s_nop 0
	global_load_dwordx4 v[28:31], v[28:29], off offset:48
	s_mov_b64 s[6:7], -1
	s_waitcnt vmcnt(3)
	v_mov_b32_e32 v32, v16
	s_waitcnt vmcnt(2)
	v_mov_b32_e32 v33, v20
	v_mov_b32_e32 v20, v17
	v_pk_add_f32 v[16:17], v[32:33], v[20:21]
	v_mov_b32_e32 v20, v18
	v_mov_b32_e32 v21, v22
	v_mov_b32_e32 v22, v19
	v_pk_add_f32 v[18:19], v[20:21], v[22:23]
	s_waitcnt vmcnt(1)
	v_mov_b32_e32 v20, v26
	v_pk_add_f32 v[16:17], v[16:17], v[18:19]
	v_mov_b32_e32 v18, v24
	s_waitcnt vmcnt(0)
	v_mov_b32_e32 v19, v28
	v_mov_b32_e32 v28, v25
	v_mov_b32_e32 v21, v30
	v_mov_b32_e32 v30, v27
	v_pk_add_f32 v[18:19], v[18:19], v[28:29]
	v_pk_add_f32 v[20:21], v[20:21], v[30:31]
	s_nop 0
	v_pk_add_f32 v[18:19], v[18:19], v[20:21]
	s_nop 0
	v_pk_add_f32 v[16:17], v[16:17], v[18:19]
	v_lshl_add_u64 v[18:19], v[162:163], 1, s[50:51]
	v_add_f32_e32 v16, v16, v17
	v_fmamk_f32 v16, v16, 0x3a800000, v206
	v_mul_f32_e32 v17, 0x4b800000, v16
	v_cmp_gt_f32_e32 vcc, s11, v16
	s_nop 1
	v_cndmask_b32_e32 v16, v16, v17, vcc
	v_rsq_f32_e32 v16, v16
	s_nop 0
	v_mul_f32_e32 v17, 0x45800000, v16
	v_cndmask_b32_e32 v16, v16, v17, vcc
	v_pk_mul_f32 v[8:9], v[8:9], v[16:17] op_sel_hi:[1,0]
	v_pk_mul_f32 v[12:13], v[12:13], v[16:17] op_sel_hi:[1,0]
	v_mul_f32_e32 v8, 0xbfb8aa3b, v8
	v_exp_f32_e32 v8, v8
	v_mul_f32_e32 v13, 0xbfb8aa3b, v13
	v_exp_f32_e32 v13, v13
	v_pk_mul_f32 v[14:15], v[14:15], v[16:17] op_sel_hi:[1,0]
	v_add_f32_e32 v8, 1.0, v8
	v_mul_f32_e32 v9, 0xbfb8aa3b, v9
	v_pk_mul_f32 v[10:11], v[10:11], v[16:17] op_sel_hi:[1,0]
	v_exp_f32_e32 v9, v9
	v_rcp_f32_e32 v17, v8
	v_add_f32_e32 v8, 1.0, v13
	v_mul_f32_e32 v13, 0xbfb8aa3b, v14
	v_exp_f32_e32 v13, v13
	v_add_f32_e32 v9, 1.0, v9
	v_mul_f32_e32 v10, 0xbfb8aa3b, v10
	v_mul_f32_e32 v12, 0xbfb8aa3b, v12
	v_exp_f32_e32 v10, v10
	v_rcp_f32_e32 v14, v9
	v_add_f32_e32 v9, 1.0, v13
	v_mul_f32_e32 v13, 0xbfb8aa3b, v15
	v_mul_f32_e32 v11, 0xbfb8aa3b, v11
	v_exp_f32_e32 v12, v12
	v_exp_f32_e32 v13, v13
	v_exp_f32_e32 v11, v11
	v_add_f32_e32 v10, 1.0, v10
	v_pk_mul_f32 v[0:1], v[0:1], v[16:17] op_sel_hi:[1,0]
	v_add_f32_e32 v12, 1.0, v12
	v_rcp_f32_e32 v15, v10
	v_add_f32_e32 v10, 1.0, v13
	v_add_f32_e32 v11, 1.0, v11
	v_pk_mul_f32 v[4:5], v[4:5], v[16:17] op_sel_hi:[1,0]
	v_mul_f32_e32 v0, 0xbfb8aa3b, v0
	v_rcp_f32_e32 v12, v12
	v_rcp_f32_e32 v8, v8
	v_rcp_f32_e32 v9, v9
	v_rcp_f32_e32 v10, v10
	v_rcp_f32_e32 v11, v11
	v_exp_f32_e32 v0, v0
	v_mul_f32_e32 v5, 0xbfb8aa3b, v5
	v_exp_f32_e32 v5, v5
	v_cvt_pk_bf16_f32 v8, v12, v8
	v_cvt_pk_bf16_f32 v9, v9, v10
	v_cvt_pk_bf16_f32 v10, v17, v14
	v_cvt_pk_bf16_f32 v11, v15, v11
	v_pk_mul_f32 v[6:7], v[6:7], v[16:17] op_sel_hi:[1,0]
	v_add_f32_e32 v0, 1.0, v0
	v_mul_f32_e32 v1, 0xbfb8aa3b, v1
	global_store_dwordx4 v[18:19], v[8:11], off sc1
	v_exp_f32_e32 v1, v1
	v_pk_mul_f32 v[2:3], v[2:3], v[16:17] op_sel_hi:[1,0]
	v_rcp_f32_e32 v8, v0
	v_add_f32_e32 v0, 1.0, v5
	v_mul_f32_e32 v5, 0xbfb8aa3b, v6
	v_exp_f32_e32 v5, v5
	v_add_f32_e32 v1, 1.0, v1
	v_mul_f32_e32 v2, 0xbfb8aa3b, v2
	v_mul_f32_e32 v4, 0xbfb8aa3b, v4
	v_exp_f32_e32 v2, v2
	v_rcp_f32_e32 v6, v1
	v_add_f32_e32 v1, 1.0, v5
	v_mul_f32_e32 v5, 0xbfb8aa3b, v7
	v_mul_f32_e32 v3, 0xbfb8aa3b, v3
	v_exp_f32_e32 v4, v4
	v_exp_f32_e32 v5, v5
	v_exp_f32_e32 v3, v3
	v_add_f32_e32 v2, 1.0, v2
	v_add_f32_e32 v4, 1.0, v4
	v_rcp_f32_e32 v7, v2
	v_add_f32_e32 v2, 1.0, v5
	v_add_f32_e32 v3, 1.0, v3
	v_rcp_f32_e32 v4, v4
	v_rcp_f32_e32 v0, v0
	v_rcp_f32_e32 v1, v1
	v_rcp_f32_e32 v2, v2
	v_rcp_f32_e32 v3, v3
	v_cvt_pk_bf16_f32 v0, v4, v0
	s_andn2_b64 vcc, exec, s[42:43]
	v_cvt_pk_bf16_f32 v1, v1, v2
	v_cvt_pk_bf16_f32 v2, v8, v6
	v_cvt_pk_bf16_f32 v3, v7, v3
	global_store_dwordx4 v[18:19], v[0:3], off offset:256 sc1
	s_cbranch_vccnz .LBB0_763
	s_andn2_b64 vcc, exec, s[46:47]
	s_cbranch_vccnz .LBB0_762
	s_barrier
	s_branch .LBB0_762

.LBB0_781:
	v_lshl_add_u64 v[94:95], v[76:77], 0, s[80:81]
	v_add_co_u32_e32 v106, vcc, s12, v94
	v_lshl_add_u64 v[102:103], v[74:75], 0, s[80:81]
	s_nop 0
	v_addc_co_u32_e32 v107, vcc, 0, v95, vcc
	v_add_co_u32_e32 v108, vcc, s13, v94
	s_mov_b32 s8, 0x988000
	s_nop 0
	v_addc_co_u32_e32 v109, vcc, 0, v95, vcc
	global_load_dwordx4 v[90:93], v[106:107], off offset:2048
	global_load_dwordx4 v[94:97], v[108:109], off offset:2048
	v_add_co_u32_e32 v110, vcc, s8, v102
	s_mov_b32 s8, 0x998000
	s_nop 0
	v_addc_co_u32_e32 v111, vcc, 0, v103, vcc
	s_waitcnt vmcnt(50)
	v_add_co_u32_e32 v112, vcc, s8, v102
	global_load_dwordx4 v[98:101], v[110:111], off offset:2048
	s_nop 0
	v_addc_co_u32_e32 v113, vcc, 0, v103, vcc
	global_load_dwordx4 v[102:105], v[112:113], off offset:2048
	s_add_i32 s7, s7, 64
	v_lshl_add_u64 v[74:75], v[74:75], 0, s[4:5]
	v_lshl_add_u64 v[76:77], v[76:77], 0, s[4:5]
	s_cmpk_gt_u32 s7, 0x6f
	s_waitcnt vmcnt(1)
	v_mfma_f32_32x32x16_bf16 v[0:15], v[90:93], v[98:101], v[0:15]
	s_waitcnt vmcnt(0)
	v_mfma_f32_32x32x16_bf16 v[32:47], v[90:93], v[102:105], v[32:47]
	v_mfma_f32_32x32x16_bf16 v[16:31], v[94:97], v[98:101], v[16:31]
	v_mfma_f32_32x32x16_bf16 v[48:63], v[94:97], v[102:105], v[48:63]
	global_load_dwordx4 v[90:93], v[106:107], off offset:2080
	global_load_dwordx4 v[94:97], v[108:109], off offset:2080
	global_load_dwordx4 v[98:101], v[110:111], off offset:2080
	global_load_dwordx4 v[102:105], v[112:113], off offset:2080
	s_waitcnt vmcnt(1)
	v_mfma_f32_32x32x16_bf16 v[0:15], v[90:93], v[98:101], v[0:15]
	s_waitcnt vmcnt(0)
	v_mfma_f32_32x32x16_bf16 v[32:47], v[90:93], v[102:105], v[32:47]
	v_mfma_f32_32x32x16_bf16 v[16:31], v[94:97], v[98:101], v[16:31]
	v_mfma_f32_32x32x16_bf16 v[48:63], v[94:97], v[102:105], v[48:63]
	global_load_dwordx4 v[90:93], v[106:107], off offset:2112
	global_load_dwordx4 v[94:97], v[108:109], off offset:2112
	global_load_dwordx4 v[98:101], v[110:111], off offset:2112
	global_load_dwordx4 v[102:105], v[112:113], off offset:2112
	s_waitcnt vmcnt(1)
	v_mfma_f32_32x32x16_bf16 v[0:15], v[90:93], v[98:101], v[0:15]
	s_waitcnt vmcnt(0)
	v_mfma_f32_32x32x16_bf16 v[32:47], v[90:93], v[102:105], v[32:47]
	v_mfma_f32_32x32x16_bf16 v[16:31], v[94:97], v[98:101], v[16:31]
	v_mfma_f32_32x32x16_bf16 v[48:63], v[94:97], v[102:105], v[48:63]
	global_load_dwordx4 v[90:93], v[106:107], off offset:2144
	global_load_dwordx4 v[94:97], v[108:109], off offset:2144
	global_load_dwordx4 v[98:101], v[110:111], off offset:2144
	global_load_dwordx4 v[102:105], v[112:113], off offset:2144
	s_waitcnt vmcnt(1)
	v_mfma_f32_32x32x16_bf16 v[0:15], v[90:93], v[98:101], v[0:15]
	s_waitcnt vmcnt(0)
	v_mfma_f32_32x32x16_bf16 v[32:47], v[90:93], v[102:105], v[32:47]
	v_mfma_f32_32x32x16_bf16 v[16:31], v[94:97], v[98:101], v[16:31]
	v_mfma_f32_32x32x16_bf16 v[48:63], v[94:97], v[102:105], v[48:63]
	s_cbranch_scc0 .LBB0_781
	s_nop 8
	ds_write2_b32 v80, v0, v32 offset1:32
	ds_write2_b32 v80, v1, v33 offset0:64 offset1:96
	ds_write2_b32 v80, v2, v34 offset0:128 offset1:160
	ds_write2_b32 v80, v3, v35 offset0:192 offset1:224
	v_add_u32_e32 v0, 0x800, v80
	ds_write2_b32 v0, v4, v36 offset1:32
	ds_write2_b32 v0, v5, v37 offset0:64 offset1:96
	ds_write2_b32 v0, v6, v38 offset0:128 offset1:160
	ds_write2_b32 v0, v7, v39 offset0:192 offset1:224
	v_add_u32_e32 v0, 0x1000, v80
	ds_write2_b32 v0, v8, v40 offset1:32
	ds_write2_b32 v0, v9, v41 offset0:64 offset1:96
	ds_write2_b32 v0, v10, v42 offset0:128 offset1:160
	ds_write2_b32 v0, v11, v43 offset0:192 offset1:224
	v_add_u32_e32 v0, 0x1800, v80
	ds_write2_b32 v0, v12, v44 offset1:32
	ds_write2_b32 v0, v13, v45 offset0:64 offset1:96
	ds_write2_b32 v0, v14, v46 offset0:128 offset1:160
	ds_write2_b32 v0, v15, v47 offset0:192 offset1:224
	v_add_u32_e32 v0, 0x2000, v80
	ds_write2_b32 v0, v16, v48 offset1:32
	ds_write2_b32 v0, v17, v49 offset0:64 offset1:96
	ds_write2_b32 v0, v18, v50 offset0:128 offset1:160
	ds_write2_b32 v0, v19, v51 offset0:192 offset1:224
	v_add_u32_e32 v0, 0x2800, v80
	ds_write2_b32 v0, v20, v52 offset1:32
	ds_write2_b32 v0, v21, v53 offset0:64 offset1:96
	ds_write2_b32 v0, v22, v54 offset0:128 offset1:160
	ds_write2_b32 v0, v23, v55 offset0:192 offset1:224
	v_add_u32_e32 v0, 0x3000, v80
	ds_write2_b32 v0, v24, v56 offset1:32
	ds_write2_b32 v0, v25, v57 offset0:64 offset1:96
	ds_write2_b32 v0, v26, v58 offset0:128 offset1:160
	ds_write2_b32 v0, v27, v59 offset0:192 offset1:224
	v_add_u32_e32 v0, 0x3800, v80
	ds_write2_b32 v0, v28, v60 offset1:32
	ds_write2_b32 v0, v29, v61 offset0:64 offset1:96
	ds_write2_b32 v0, v30, v62 offset0:128 offset1:160
	ds_write2_b32 v0, v31, v63 offset0:192 offset1:224
	s_waitcnt lgkmcnt(0)
	s_barrier
	ds_read_b128 v[0:3], v78
	ds_read_b128 v[4:7], v78 offset:16
	global_load_dwordx4 v[8:11], v[64:65], off offset:16
	global_load_dwordx4 v[12:15], v[64:65], off
	global_load_dwordx4 v[16:19], v[64:65], off offset:48
	global_load_dwordx4 v[20:23], v[64:65], off offset:32
	v_mov_b32_e32 v32, s45
	v_add_u32_e32 v70, s39, v70
	s_waitcnt lgkmcnt(1)
	v_add_f32_e32 v24, 0, v0
	v_add_f32_e32 v25, 0, v1
	v_add_f32_e32 v26, 0, v2
	v_add_f32_e32 v27, 0, v3
	ds_read_b128 v[0:3], v78 offset:16384
	s_waitcnt lgkmcnt(1)
	v_add_f32_e32 v28, 0, v4
	v_add_f32_e32 v29, 0, v5
	v_add_f32_e32 v30, 0, v6
	v_add_f32_e32 v31, 0, v7
	ds_read_b128 v[4:7], v78 offset:16400
	s_waitcnt lgkmcnt(1)
	v_add_f32_e32 v24, v24, v0
	v_add_f32_e32 v25, v25, v1
	v_add_f32_e32 v26, v26, v2
	v_add_f32_e32 v27, v27, v3
	ds_read_b128 v[0:3], v78 offset:32768
	s_waitcnt lgkmcnt(1)
	v_add_f32_e32 v28, v28, v4
	v_add_f32_e32 v29, v29, v5
	v_add_f32_e32 v30, v30, v6
	v_add_f32_e32 v31, v31, v7
	ds_read_b128 v[4:7], v78 offset:32784
	s_waitcnt lgkmcnt(1)
	v_add_f32_e32 v24, v24, v0
	v_add_f32_e32 v25, v25, v1
	v_add_f32_e32 v26, v26, v2
	v_add_f32_e32 v27, v27, v3
	ds_read_b128 v[0:3], v78 offset:49152
	s_waitcnt lgkmcnt(1)
	v_add_f32_e32 v28, v28, v4
	v_add_f32_e32 v29, v29, v5
	v_add_f32_e32 v30, v30, v6
	v_add_f32_e32 v31, v31, v7
	ds_read_b128 v[4:7], v78 offset:49168
	s_waitcnt lgkmcnt(1)
	v_add_f32_e32 v24, v24, v0
	v_add_f32_e32 v25, v25, v1
	v_add_f32_e32 v26, v26, v2
	v_add_f32_e32 v27, v27, v3
	ds_read_b128 v[0:3], v81
	s_waitcnt lgkmcnt(1)
	v_add_f32_e32 v28, v28, v4
	v_add_f32_e32 v29, v29, v5
	v_add_f32_e32 v30, v30, v6
	v_add_f32_e32 v31, v31, v7
	ds_read_b128 v[4:7], v82
	s_waitcnt lgkmcnt(1)
	v_add_f32_e32 v24, v24, v0
	v_add_f32_e32 v25, v25, v1
	v_add_f32_e32 v26, v26, v2
	v_add_f32_e32 v27, v27, v3
	ds_read_b128 v[0:3], v83
	s_waitcnt lgkmcnt(1)
	v_add_f32_e32 v28, v28, v4
	v_add_f32_e32 v29, v29, v5
	v_add_f32_e32 v30, v30, v6
	v_add_f32_e32 v31, v31, v7
	ds_read_b128 v[4:7], v84
	s_waitcnt lgkmcnt(1)
	v_add_f32_e32 v24, v24, v0
	v_add_f32_e32 v25, v25, v1
	v_add_f32_e32 v26, v26, v2
	v_add_f32_e32 v27, v27, v3
	ds_read_b128 v[0:3], v85
	s_waitcnt lgkmcnt(1)
	v_add_f32_e32 v28, v28, v4
	v_add_f32_e32 v29, v29, v5
	v_add_f32_e32 v30, v30, v6
	v_add_f32_e32 v31, v31, v7
	ds_read_b128 v[4:7], v86
	s_waitcnt lgkmcnt(1)
	v_add_f32_e32 v24, v24, v0
	v_add_f32_e32 v25, v25, v1
	v_add_f32_e32 v26, v26, v2
	v_add_f32_e32 v27, v27, v3
	ds_read_b128 v[0:3], v87
	s_waitcnt lgkmcnt(1)
	v_add_f32_e32 v28, v28, v4
	v_add_f32_e32 v29, v29, v5
	v_add_f32_e32 v30, v30, v6
	v_add_f32_e32 v31, v31, v7
	ds_read_b128 v[4:7], v88
	s_waitcnt lgkmcnt(1)
	v_add_f32_e32 v24, v24, v0
	v_add_f32_e32 v25, v25, v1
	v_add_f32_e32 v26, v26, v2
	v_add_f32_e32 v27, v27, v3
	s_waitcnt lgkmcnt(0)
	v_add_f32_e32 v28, v28, v4
	s_waitcnt vmcnt(2)
	v_mov_b32_e32 v0, v12
	v_mov_b32_e32 v2, v14
	s_waitcnt vmcnt(0)
	v_mov_b32_e32 v1, v20
	v_mov_b32_e32 v20, v13
	v_mov_b32_e32 v3, v22
	v_mov_b32_e32 v22, v15
	v_pk_add_f32 v[0:1], v[0:1], v[20:21]
	v_pk_add_f32 v[2:3], v[2:3], v[22:23]
	v_add_f32_e32 v29, v29, v5
	v_pk_add_f32 v[0:1], v[0:1], v[2:3]
	v_mov_b32_e32 v2, v8
	v_mov_b32_e32 v3, v16
	v_mov_b32_e32 v16, v9
	v_mov_b32_e32 v4, v10
	v_mov_b32_e32 v5, v18
	v_mov_b32_e32 v18, v11
	v_pk_add_f32 v[2:3], v[2:3], v[16:17]
	v_pk_add_f32 v[4:5], v[4:5], v[18:19]
	v_add_f32_e32 v6, v30, v6
	v_pk_add_f32 v[2:3], v[2:3], v[4:5]
	v_lshl_or_b32 v30, s6, 6, v79
	v_pk_add_f32 v[0:1], v[0:1], v[2:3]
	v_add_f32_e32 v7, v31, v7
	v_add_f32_e32 v0, v0, v1
	v_fmamk_f32 v0, v0, 0x3a800000, v206
	v_mul_f32_e32 v1, 0x4b800000, v0
	v_cmp_gt_f32_e32 vcc, s11, v0
	v_cmp_gt_i32_e64 s[42:43], 2.0, v30
	v_mov_b32_e32 v2, s44
	v_cndmask_b32_e32 v0, v0, v1, vcc
	v_rsq_f32_e32 v0, v0
	v_mov_b32_e32 v1, s46
	v_mov_b32_e32 v31, s47
	v_cndmask_b32_e64 v5, v31, v32, s[42:43]
	v_mul_f32_e32 v3, 0x45800000, v0
	v_cndmask_b32_e32 v0, v0, v3, vcc
	v_mul_f32_e32 v3, v24, v0
	v_mul_f32_e32 v4, v25, v0
	v_mul_f32_e32 v3, 0xbfb8aa3b, v3
	v_mul_f32_e32 v4, 0xbfb8aa3b, v4
	v_exp_f32_e32 v3, v3
	v_exp_f32_e32 v8, v4
	v_mul_f32_e32 v9, v28, v0
	v_mul_f32_e32 v10, v29, v0
	v_mul_f32_e32 v9, 0xbfb8aa3b, v9
	v_mul_f32_e32 v10, 0xbfb8aa3b, v10
	v_cndmask_b32_e64 v4, v1, v2, s[42:43]
	v_add_f32_e32 v1, 1.0, v3
	v_add_f32_e32 v2, 1.0, v8
	v_mul_f32_e32 v3, v26, v0
	v_mul_f32_e32 v8, v27, v0
	v_exp_f32_e32 v9, v9
	v_exp_f32_e32 v10, v10
	v_mul_f32_e32 v6, v6, v0
	v_mul_f32_e32 v0, v7, v0
	v_mul_f32_e32 v0, 0xbfb8aa3b, v0
	v_mul_f32_e32 v3, 0xbfb8aa3b, v3
	v_mul_f32_e32 v8, 0xbfb8aa3b, v8
	v_mul_f32_e32 v6, 0xbfb8aa3b, v6
	v_exp_f32_e32 v0, v0
	v_exp_f32_e32 v3, v3
	v_exp_f32_e32 v8, v8
	v_exp_f32_e32 v6, v6
	v_add_f32_e32 v9, 1.0, v9
	v_add_f32_e32 v10, 1.0, v10
	v_rcp_f32_e32 v1, v1
	v_rcp_f32_e32 v2, v2
	v_rcp_f32_e32 v9, v9
	v_rcp_f32_e32 v7, v10
	v_add_f32_e32 v0, 1.0, v0
	v_add_f32_e32 v3, 1.0, v3
	v_add_f32_e32 v8, 1.0, v8
	v_add_f32_e32 v6, 1.0, v6
	v_rcp_f32_e32 v11, v0
	v_cndmask_b32_e64 v0, -2.0, 0, s[42:43]
	v_rcp_f32_e32 v3, v3
	v_rcp_f32_e32 v8, v8
	v_rcp_f32_e32 v10, v6
	v_add_u32_e32 v6, v0, v30
	v_cvt_pk_bf16_f32 v0, v1, v2
	v_cvt_pk_bf16_f32 v2, v9, v7
	v_lshl_add_u64 v[4:5], v[4:5], 0, v[66:67]
	v_ashrrev_i32_e32 v7, 31, v6
	v_lshl_add_u64 v[4:5], v[6:7], 1, v[4:5]
	v_add_co_u32_e32 v4, vcc, 0x8498000, v4
	s_add_i32 s6, s6, s82
	v_cvt_pk_bf16_f32 v1, v3, v8
	v_cvt_pk_bf16_f32 v3, v10, v11
	v_addc_co_u32_e32 v5, vcc, 0, v5, vcc
	s_cmp_gt_i32 s6, 31
	global_store_dwordx4 v[4:5], v[0:3], off offset:2048 sc1
	s_barrier
	s_cbranch_scc0 .LBB0_780

.LBB0_863:
	s_waitcnt vmcnt(0)
	v_lshlrev_b32_e32 v174, 16, v130
	v_and_b32_e32 v175, 0xffff0000, v130
	v_lshlrev_b32_e32 v176, 16, v134
	v_and_b32_e32 v177, 0xffff0000, v134
	v_lshlrev_b32_e32 v130, 16, v131
	v_and_b32_e32 v131, 0xffff0000, v131
	v_lshlrev_b32_e32 v134, 16, v135
	v_and_b32_e32 v135, 0xffff0000, v135
	v_pk_fma_f32 v[124:125], v[124:125], v[174:175], v[176:177]
	v_pk_fma_f32 v[126:127], v[126:127], v[130:131], v[134:135]
	v_cvt_pk_bf16_f32 v124, v124, v125
	v_cvt_pk_bf16_f32 v125, v126, v127
	v_lshlrev_b32_e32 v126, 16, v132
	v_and_b32_e32 v127, 0xffff0000, v132
	v_lshlrev_b32_e32 v130, 16, v136
	v_and_b32_e32 v131, 0xffff0000, v136
	v_pk_fma_f32 v[120:121], v[120:121], v[126:127], v[130:131]
	v_lshlrev_b32_e32 v130, 16, v137
	v_cvt_pk_bf16_f32 v126, v120, v121
	v_lshlrev_b32_e32 v120, 16, v133
	v_and_b32_e32 v121, 0xffff0000, v133
	v_and_b32_e32 v131, 0xffff0000, v137
	v_pk_fma_f32 v[120:121], v[122:123], v[120:121], v[130:131]
	s_and_b64 vcc, exec, s[42:43]
	v_cvt_pk_bf16_f32 v127, v120, v121
	global_store_dwordx4 v[152:153], v[124:127], off sc1
	global_load_dwordx4 v[120:123], v[154:155], off offset:256
	v_mov_b32_e32 v129, 0
	v_mov_b32_e32 v130, 0
	v_mov_b32_e32 v131, 0
	s_cbranch_vccnz .LBB0_865
	global_load_dwordx4 v[128:131], v[152:153], off offset:256
.LBB0_865:
	s_waitcnt vmcnt(0)
	v_lshlrev_b32_e32 v124, 16, v120
	v_and_b32_e32 v125, 0xffff0000, v120
	v_lshlrev_b32_e32 v126, 16, v128
	v_and_b32_e32 v127, 0xffff0000, v128
	v_pk_fma_f32 v[116:117], v[116:117], v[124:125], v[126:127]
	v_lshlrev_b32_e32 v120, 16, v121
	v_and_b32_e32 v121, 0xffff0000, v121
	v_lshlrev_b32_e32 v124, 16, v129
	v_and_b32_e32 v125, 0xffff0000, v129
	v_pk_fma_f32 v[118:119], v[118:119], v[120:121], v[124:125]
	v_cvt_pk_bf16_f32 v116, v116, v117
	v_cvt_pk_bf16_f32 v117, v118, v119
	v_lshlrev_b32_e32 v118, 16, v122
	v_and_b32_e32 v119, 0xffff0000, v122
	v_lshlrev_b32_e32 v120, 16, v130
	v_and_b32_e32 v121, 0xffff0000, v130
	v_pk_fma_f32 v[112:113], v[112:113], v[118:119], v[120:121]
	v_lshlrev_b32_e32 v120, 16, v131
	v_cvt_pk_bf16_f32 v118, v112, v113
	v_lshlrev_b32_e32 v112, 16, v123
	v_and_b32_e32 v113, 0xffff0000, v123
	v_and_b32_e32 v121, 0xffff0000, v131
	v_pk_fma_f32 v[112:113], v[114:115], v[112:113], v[120:121]
	s_and_b64 vcc, exec, s[42:43]
	v_cvt_pk_bf16_f32 v119, v112, v113
	v_or_b32_e32 v112, 16, v148
	v_ashrrev_i32_e32 v113, 31, v112
	v_lshlrev_b64 v[114:115], 12, v[112:113]
	v_lshl_add_u64 v[114:115], s[54:55], 0, v[114:115]
	global_store_dwordx4 v[152:153], v[116:119], off offset:256 sc1
	v_lshl_add_u64 v[124:125], v[114:115], 0, v[150:151]
	global_load_dwordx4 v[114:117], v[124:125], off
	v_lshlrev_b64 v[112:113], 11, v[112:113]
	v_lshl_add_u64 v[112:113], s[52:53], 0, v[112:113]
	v_lshl_add_u64 v[122:123], v[112:113], 0, v[150:151]
	v_mov_b32_e32 v112, 0
	v_mov_b32_e32 v118, 0
	v_mov_b32_e32 v119, 0
	v_mov_b32_e32 v120, 0
	v_mov_b32_e32 v121, 0
	s_cbranch_vccnz .LBB0_867
	global_load_dwordx4 v[118:121], v[122:123], off
.LBB0_867:
	s_waitcnt vmcnt(0)
	v_lshlrev_b32_e32 v126, 16, v114
	v_and_b32_e32 v127, 0xffff0000, v114
	v_lshlrev_b32_e32 v128, 16, v118
	v_and_b32_e32 v129, 0xffff0000, v118
	v_lshlrev_b32_e32 v114, 16, v115
	v_and_b32_e32 v115, 0xffff0000, v115
	v_lshlrev_b32_e32 v118, 16, v119
	v_and_b32_e32 v119, 0xffff0000, v119
	v_pk_fma_f32 v[108:109], v[108:109], v[126:127], v[128:129]
	v_pk_fma_f32 v[110:111], v[110:111], v[114:115], v[118:119]
	v_cvt_pk_bf16_f32 v108, v108, v109
	v_cvt_pk_bf16_f32 v109, v110, v111
	v_lshlrev_b32_e32 v110, 16, v116
	v_and_b32_e32 v111, 0xffff0000, v116
	v_lshlrev_b32_e32 v114, 16, v120
	v_and_b32_e32 v115, 0xffff0000, v120
	v_pk_fma_f32 v[104:105], v[104:105], v[110:111], v[114:115]
	v_lshlrev_b32_e32 v114, 16, v121
	v_cvt_pk_bf16_f32 v110, v104, v105
	v_lshlrev_b32_e32 v104, 16, v117
	v_and_b32_e32 v105, 0xffff0000, v117
	v_and_b32_e32 v115, 0xffff0000, v121
	v_pk_fma_f32 v[104:105], v[106:107], v[104:105], v[114:115]
	s_and_b64 vcc, exec, s[42:43]
	v_cvt_pk_bf16_f32 v111, v104, v105
	global_store_dwordx4 v[122:123], v[108:111], off sc1
	global_load_dwordx4 v[104:107], v[124:125], off offset:256
	v_mov_b32_e32 v113, 0
	v_mov_b32_e32 v114, 0
	v_mov_b32_e32 v115, 0
	s_cbranch_vccnz .LBB0_869
	global_load_dwordx4 v[112:115], v[122:123], off offset:256
.LBB0_869:
	s_waitcnt vmcnt(0)
	v_lshlrev_b32_e32 v108, 16, v104
	v_and_b32_e32 v109, 0xffff0000, v104
	v_lshlrev_b32_e32 v110, 16, v112
	v_and_b32_e32 v111, 0xffff0000, v112
	v_pk_fma_f32 v[100:101], v[100:101], v[108:109], v[110:111]
	v_lshlrev_b32_e32 v104, 16, v105
	v_and_b32_e32 v105, 0xffff0000, v105
	v_lshlrev_b32_e32 v108, 16, v113
	v_and_b32_e32 v109, 0xffff0000, v113
	v_pk_fma_f32 v[102:103], v[102:103], v[104:105], v[108:109]
	v_cvt_pk_bf16_f32 v100, v100, v101
	v_cvt_pk_bf16_f32 v101, v102, v103
	v_lshlrev_b32_e32 v102, 16, v106
	v_and_b32_e32 v103, 0xffff0000, v106
	v_lshlrev_b32_e32 v104, 16, v114
	v_and_b32_e32 v105, 0xffff0000, v114
	v_pk_fma_f32 v[96:97], v[96:97], v[102:103], v[104:105]
	v_lshlrev_b32_e32 v104, 16, v115
	v_cvt_pk_bf16_f32 v102, v96, v97
	v_lshlrev_b32_e32 v96, 16, v107
	v_and_b32_e32 v97, 0xffff0000, v107
	v_and_b32_e32 v105, 0xffff0000, v115
	v_pk_fma_f32 v[96:97], v[98:99], v[96:97], v[104:105]
	s_and_b64 vcc, exec, s[42:43]
	v_cvt_pk_bf16_f32 v103, v96, v97
	v_or_b32_e32 v96, 32, v148
	v_ashrrev_i32_e32 v97, 31, v96
	v_lshlrev_b64 v[98:99], 12, v[96:97]
	v_lshl_add_u64 v[98:99], s[54:55], 0, v[98:99]
	global_store_dwordx4 v[122:123], v[100:103], off offset:256 sc1
	v_lshl_add_u64 v[108:109], v[98:99], 0, v[150:151]
	global_load_dwordx4 v[98:101], v[108:109], off
	v_lshlrev_b64 v[96:97], 11, v[96:97]
	v_lshl_add_u64 v[96:97], s[52:53], 0, v[96:97]
	v_lshl_add_u64 v[106:107], v[96:97], 0, v[150:151]
	v_mov_b32_e32 v96, 0
	v_mov_b32_e32 v102, 0
	v_mov_b32_e32 v103, 0
	v_mov_b32_e32 v104, 0
	v_mov_b32_e32 v105, 0
	s_cbranch_vccnz .LBB0_871
	global_load_dwordx4 v[102:105], v[106:107], off
.LBB0_871:
	s_waitcnt vmcnt(0)
	v_lshlrev_b32_e32 v110, 16, v98
	v_and_b32_e32 v111, 0xffff0000, v98
	v_lshlrev_b32_e32 v112, 16, v102
	v_and_b32_e32 v113, 0xffff0000, v102
	v_lshlrev_b32_e32 v98, 16, v99
	v_and_b32_e32 v99, 0xffff0000, v99
	v_lshlrev_b32_e32 v102, 16, v103
	v_and_b32_e32 v103, 0xffff0000, v103
	v_pk_fma_f32 v[92:93], v[92:93], v[110:111], v[112:113]
	v_pk_fma_f32 v[94:95], v[94:95], v[98:99], v[102:103]
	v_cvt_pk_bf16_f32 v92, v92, v93
	v_cvt_pk_bf16_f32 v93, v94, v95
	v_lshlrev_b32_e32 v94, 16, v100
	v_and_b32_e32 v95, 0xffff0000, v100
	v_lshlrev_b32_e32 v98, 16, v104
	v_and_b32_e32 v99, 0xffff0000, v104
	v_pk_fma_f32 v[88:89], v[88:89], v[94:95], v[98:99]
	v_lshlrev_b32_e32 v98, 16, v105
	v_cvt_pk_bf16_f32 v94, v88, v89
	v_lshlrev_b32_e32 v88, 16, v101
	v_and_b32_e32 v89, 0xffff0000, v101
	v_and_b32_e32 v99, 0xffff0000, v105
	v_pk_fma_f32 v[88:89], v[90:91], v[88:89], v[98:99]
	s_and_b64 vcc, exec, s[42:43]
	v_cvt_pk_bf16_f32 v95, v88, v89
	global_store_dwordx4 v[106:107], v[92:95], off sc1
	global_load_dwordx4 v[88:91], v[108:109], off offset:256
	v_mov_b32_e32 v97, 0
	v_mov_b32_e32 v98, 0
	v_mov_b32_e32 v99, 0
	s_cbranch_vccnz .LBB0_873
	global_load_dwordx4 v[96:99], v[106:107], off offset:256
.LBB0_873:
	s_waitcnt vmcnt(0)
	v_lshlrev_b32_e32 v92, 16, v88
	v_and_b32_e32 v93, 0xffff0000, v88
	v_lshlrev_b32_e32 v94, 16, v96
	v_and_b32_e32 v95, 0xffff0000, v96
	v_pk_fma_f32 v[84:85], v[84:85], v[92:93], v[94:95]
	v_lshlrev_b32_e32 v88, 16, v89
	v_and_b32_e32 v89, 0xffff0000, v89
	v_lshlrev_b32_e32 v92, 16, v97
	v_and_b32_e32 v93, 0xffff0000, v97
	v_pk_fma_f32 v[86:87], v[86:87], v[88:89], v[92:93]
	v_cvt_pk_bf16_f32 v84, v84, v85
	v_cvt_pk_bf16_f32 v85, v86, v87
	v_lshlrev_b32_e32 v86, 16, v90
	v_and_b32_e32 v87, 0xffff0000, v90
	v_lshlrev_b32_e32 v88, 16, v98
	v_and_b32_e32 v89, 0xffff0000, v98
	v_pk_fma_f32 v[80:81], v[80:81], v[86:87], v[88:89]
	v_lshlrev_b32_e32 v88, 16, v99
	v_cvt_pk_bf16_f32 v86, v80, v81
	v_lshlrev_b32_e32 v80, 16, v91
	v_and_b32_e32 v81, 0xffff0000, v91
	v_and_b32_e32 v89, 0xffff0000, v99
	v_pk_fma_f32 v[80:81], v[82:83], v[80:81], v[88:89]
	s_and_b64 vcc, exec, s[42:43]
	v_cvt_pk_bf16_f32 v87, v80, v81
	v_or_b32_e32 v80, 48, v148
	v_ashrrev_i32_e32 v81, 31, v80
	v_lshlrev_b64 v[82:83], 12, v[80:81]
	v_lshl_add_u64 v[82:83], s[54:55], 0, v[82:83]
	global_store_dwordx4 v[106:107], v[84:87], off offset:256 sc1
	v_lshl_add_u64 v[92:93], v[82:83], 0, v[150:151]
	global_load_dwordx4 v[82:85], v[92:93], off
	v_lshlrev_b64 v[80:81], 11, v[80:81]
	v_lshl_add_u64 v[80:81], s[52:53], 0, v[80:81]
	v_lshl_add_u64 v[90:91], v[80:81], 0, v[150:151]
	v_mov_b32_e32 v80, 0
	v_mov_b32_e32 v86, 0
	v_mov_b32_e32 v87, 0
	v_mov_b32_e32 v88, 0
	v_mov_b32_e32 v89, 0
	s_cbranch_vccnz .LBB0_875
	global_load_dwordx4 v[86:89], v[90:91], off
.LBB0_875:
	s_waitcnt vmcnt(0)
	v_lshlrev_b32_e32 v94, 16, v82
	v_and_b32_e32 v95, 0xffff0000, v82
	v_lshlrev_b32_e32 v96, 16, v86
	v_and_b32_e32 v97, 0xffff0000, v86
	v_lshlrev_b32_e32 v82, 16, v83
	v_and_b32_e32 v83, 0xffff0000, v83
	v_lshlrev_b32_e32 v86, 16, v87
	v_and_b32_e32 v87, 0xffff0000, v87
	v_pk_fma_f32 v[76:77], v[76:77], v[94:95], v[96:97]
	v_pk_fma_f32 v[78:79], v[78:79], v[82:83], v[86:87]
	v_cvt_pk_bf16_f32 v76, v76, v77
	v_cvt_pk_bf16_f32 v77, v78, v79
	v_lshlrev_b32_e32 v78, 16, v84
	v_and_b32_e32 v79, 0xffff0000, v84
	v_lshlrev_b32_e32 v82, 16, v88
	v_and_b32_e32 v83, 0xffff0000, v88
	v_pk_fma_f32 v[72:73], v[72:73], v[78:79], v[82:83]
	v_lshlrev_b32_e32 v82, 16, v89
	v_cvt_pk_bf16_f32 v78, v72, v73
	v_lshlrev_b32_e32 v72, 16, v85
	v_and_b32_e32 v73, 0xffff0000, v85
	v_and_b32_e32 v83, 0xffff0000, v89
	v_pk_fma_f32 v[72:73], v[74:75], v[72:73], v[82:83]
	s_and_b64 vcc, exec, s[42:43]
	v_cvt_pk_bf16_f32 v79, v72, v73
	global_store_dwordx4 v[90:91], v[76:79], off sc1
	global_load_dwordx4 v[72:75], v[92:93], off offset:256
	v_mov_b32_e32 v81, 0
	v_mov_b32_e32 v82, 0
	v_mov_b32_e32 v83, 0
	s_cbranch_vccnz .LBB0_877
	global_load_dwordx4 v[80:83], v[90:91], off offset:256
.LBB0_877:
	s_waitcnt vmcnt(0)
	v_lshlrev_b32_e32 v76, 16, v72
	v_and_b32_e32 v77, 0xffff0000, v72
	v_lshlrev_b32_e32 v78, 16, v80
	v_and_b32_e32 v79, 0xffff0000, v80
	v_pk_fma_f32 v[68:69], v[68:69], v[76:77], v[78:79]
	v_lshlrev_b32_e32 v72, 16, v73
	v_and_b32_e32 v73, 0xffff0000, v73
	v_lshlrev_b32_e32 v76, 16, v81
	v_and_b32_e32 v77, 0xffff0000, v81
	v_pk_fma_f32 v[70:71], v[70:71], v[72:73], v[76:77]
	v_cvt_pk_bf16_f32 v68, v68, v69
	v_cvt_pk_bf16_f32 v69, v70, v71
	v_lshlrev_b32_e32 v70, 16, v74
	v_and_b32_e32 v71, 0xffff0000, v74
	v_lshlrev_b32_e32 v72, 16, v82
	v_and_b32_e32 v73, 0xffff0000, v82
	v_pk_fma_f32 v[64:65], v[64:65], v[70:71], v[72:73]
	v_lshlrev_b32_e32 v72, 16, v83
	v_cvt_pk_bf16_f32 v70, v64, v65
	v_lshlrev_b32_e32 v64, 16, v75
	v_and_b32_e32 v65, 0xffff0000, v75
	v_and_b32_e32 v73, 0xffff0000, v83
	v_pk_fma_f32 v[64:65], v[66:67], v[64:65], v[72:73]
	s_and_b64 vcc, exec, s[42:43]
	v_cvt_pk_bf16_f32 v71, v64, v65
	v_add_u32_e32 v64, 0x80, v148
	v_ashrrev_i32_e32 v65, 31, v64
	v_lshlrev_b64 v[66:67], 12, v[64:65]
	v_lshl_add_u64 v[66:67], s[54:55], 0, v[66:67]
	global_store_dwordx4 v[90:91], v[68:71], off offset:256 sc1
	v_lshl_add_u64 v[76:77], v[66:67], 0, v[150:151]
	global_load_dwordx4 v[66:69], v[76:77], off
	v_lshlrev_b64 v[64:65], 11, v[64:65]
	v_lshl_add_u64 v[64:65], s[52:53], 0, v[64:65]
	v_lshl_add_u64 v[74:75], v[64:65], 0, v[150:151]
	v_mov_b32_e32 v64, 0
	v_mov_b32_e32 v70, 0
	v_mov_b32_e32 v71, 0
	v_mov_b32_e32 v72, 0
	v_mov_b32_e32 v73, 0
	s_cbranch_vccnz .LBB0_879
	global_load_dwordx4 v[70:73], v[74:75], off
.LBB0_879:
	s_waitcnt vmcnt(0)
	v_lshlrev_b32_e32 v78, 16, v66
	v_and_b32_e32 v79, 0xffff0000, v66
	v_lshlrev_b32_e32 v80, 16, v70
	v_and_b32_e32 v81, 0xffff0000, v70
	v_lshlrev_b32_e32 v66, 16, v67
	v_and_b32_e32 v67, 0xffff0000, v67
	v_lshlrev_b32_e32 v70, 16, v71
	v_and_b32_e32 v71, 0xffff0000, v71
	v_pk_fma_f32 v[60:61], v[60:61], v[78:79], v[80:81]
	v_pk_fma_f32 v[62:63], v[62:63], v[66:67], v[70:71]
	v_cvt_pk_bf16_f32 v60, v60, v61
	v_cvt_pk_bf16_f32 v61, v62, v63
	v_lshlrev_b32_e32 v62, 16, v68
	v_and_b32_e32 v63, 0xffff0000, v68
	v_lshlrev_b32_e32 v66, 16, v72
	v_and_b32_e32 v67, 0xffff0000, v72
	v_pk_fma_f32 v[56:57], v[56:57], v[62:63], v[66:67]
	v_lshlrev_b32_e32 v66, 16, v73
	v_cvt_pk_bf16_f32 v62, v56, v57
	v_lshlrev_b32_e32 v56, 16, v69
	v_and_b32_e32 v57, 0xffff0000, v69
	v_and_b32_e32 v67, 0xffff0000, v73
	v_pk_fma_f32 v[56:57], v[58:59], v[56:57], v[66:67]
	s_and_b64 vcc, exec, s[42:43]
	v_cvt_pk_bf16_f32 v63, v56, v57
	global_store_dwordx4 v[74:75], v[60:63], off sc1
	global_load_dwordx4 v[56:59], v[76:77], off offset:256
	v_mov_b32_e32 v65, 0
	v_mov_b32_e32 v66, 0
	v_mov_b32_e32 v67, 0
	s_cbranch_vccnz .LBB0_881
	global_load_dwordx4 v[64:67], v[74:75], off offset:256
.LBB0_881:
	s_waitcnt vmcnt(0)
	v_lshlrev_b32_e32 v60, 16, v56
	v_and_b32_e32 v61, 0xffff0000, v56
	v_lshlrev_b32_e32 v62, 16, v64
	v_and_b32_e32 v63, 0xffff0000, v64
	v_pk_fma_f32 v[52:53], v[52:53], v[60:61], v[62:63]
	v_lshlrev_b32_e32 v56, 16, v57
	v_and_b32_e32 v57, 0xffff0000, v57
	v_lshlrev_b32_e32 v60, 16, v65
	v_and_b32_e32 v61, 0xffff0000, v65
	v_pk_fma_f32 v[54:55], v[54:55], v[56:57], v[60:61]
	v_cvt_pk_bf16_f32 v52, v52, v53
	v_cvt_pk_bf16_f32 v53, v54, v55
	v_lshlrev_b32_e32 v54, 16, v58
	v_and_b32_e32 v55, 0xffff0000, v58
	v_lshlrev_b32_e32 v56, 16, v66
	v_and_b32_e32 v57, 0xffff0000, v66
	v_pk_fma_f32 v[48:49], v[48:49], v[54:55], v[56:57]
	v_lshlrev_b32_e32 v56, 16, v67
	v_cvt_pk_bf16_f32 v54, v48, v49
	v_lshlrev_b32_e32 v48, 16, v59
	v_and_b32_e32 v49, 0xffff0000, v59
	v_and_b32_e32 v57, 0xffff0000, v67
	v_pk_fma_f32 v[48:49], v[50:51], v[48:49], v[56:57]
	s_and_b64 vcc, exec, s[42:43]
	v_cvt_pk_bf16_f32 v55, v48, v49
	v_add_u32_e32 v48, 0x90, v148
	v_ashrrev_i32_e32 v49, 31, v48
	v_lshlrev_b64 v[50:51], 12, v[48:49]
	v_lshl_add_u64 v[50:51], s[54:55], 0, v[50:51]
	global_store_dwordx4 v[74:75], v[52:55], off offset:256 sc1
	v_lshl_add_u64 v[60:61], v[50:51], 0, v[150:151]
	global_load_dwordx4 v[50:53], v[60:61], off
	v_lshlrev_b64 v[48:49], 11, v[48:49]
	v_lshl_add_u64 v[48:49], s[52:53], 0, v[48:49]
	v_lshl_add_u64 v[58:59], v[48:49], 0, v[150:151]
	v_mov_b32_e32 v48, 0
	v_mov_b32_e32 v54, 0
	v_mov_b32_e32 v55, 0
	v_mov_b32_e32 v56, 0
	v_mov_b32_e32 v57, 0
	s_cbranch_vccnz .LBB0_883
	global_load_dwordx4 v[54:57], v[58:59], off
.LBB0_883:
	s_waitcnt vmcnt(0)
	v_lshlrev_b32_e32 v62, 16, v50
	v_and_b32_e32 v63, 0xffff0000, v50
	v_lshlrev_b32_e32 v64, 16, v54
	v_and_b32_e32 v65, 0xffff0000, v54
	v_lshlrev_b32_e32 v50, 16, v51
	v_and_b32_e32 v51, 0xffff0000, v51
	v_lshlrev_b32_e32 v54, 16, v55
	v_and_b32_e32 v55, 0xffff0000, v55
	v_pk_fma_f32 v[44:45], v[44:45], v[62:63], v[64:65]
	v_pk_fma_f32 v[46:47], v[46:47], v[50:51], v[54:55]
	v_cvt_pk_bf16_f32 v44, v44, v45
	v_cvt_pk_bf16_f32 v45, v46, v47
	v_lshlrev_b32_e32 v46, 16, v52
	v_and_b32_e32 v47, 0xffff0000, v52
	v_lshlrev_b32_e32 v50, 16, v56
	v_and_b32_e32 v51, 0xffff0000, v56
	v_pk_fma_f32 v[40:41], v[40:41], v[46:47], v[50:51]
	v_lshlrev_b32_e32 v50, 16, v57
	v_cvt_pk_bf16_f32 v46, v40, v41
	v_lshlrev_b32_e32 v40, 16, v53
	v_and_b32_e32 v41, 0xffff0000, v53
	v_and_b32_e32 v51, 0xffff0000, v57
	v_pk_fma_f32 v[40:41], v[42:43], v[40:41], v[50:51]
	s_and_b64 vcc, exec, s[42:43]
	v_cvt_pk_bf16_f32 v47, v40, v41
	global_store_dwordx4 v[58:59], v[44:47], off sc1
	global_load_dwordx4 v[40:43], v[60:61], off offset:256
	v_mov_b32_e32 v49, 0
	v_mov_b32_e32 v50, 0
	v_mov_b32_e32 v51, 0
	s_cbranch_vccnz .LBB0_885
	global_load_dwordx4 v[48:51], v[58:59], off offset:256
.LBB0_885:
	s_waitcnt vmcnt(0)
	v_lshlrev_b32_e32 v44, 16, v40
	v_and_b32_e32 v45, 0xffff0000, v40
	v_lshlrev_b32_e32 v46, 16, v48
	v_and_b32_e32 v47, 0xffff0000, v48
	v_pk_fma_f32 v[36:37], v[36:37], v[44:45], v[46:47]
	v_lshlrev_b32_e32 v40, 16, v41
	v_and_b32_e32 v41, 0xffff0000, v41
	v_lshlrev_b32_e32 v44, 16, v49
	v_and_b32_e32 v45, 0xffff0000, v49
	v_pk_fma_f32 v[38:39], v[38:39], v[40:41], v[44:45]
	v_cvt_pk_bf16_f32 v36, v36, v37
	v_cvt_pk_bf16_f32 v37, v38, v39
	v_lshlrev_b32_e32 v38, 16, v42
	v_and_b32_e32 v39, 0xffff0000, v42
	v_lshlrev_b32_e32 v40, 16, v50
	v_and_b32_e32 v41, 0xffff0000, v50
	v_pk_fma_f32 v[32:33], v[32:33], v[38:39], v[40:41]
	v_lshlrev_b32_e32 v40, 16, v51
	v_cvt_pk_bf16_f32 v38, v32, v33
	v_lshlrev_b32_e32 v32, 16, v43
	v_and_b32_e32 v33, 0xffff0000, v43
	v_and_b32_e32 v41, 0xffff0000, v51
	v_pk_fma_f32 v[32:33], v[34:35], v[32:33], v[40:41]
	s_and_b64 vcc, exec, s[42:43]
	v_cvt_pk_bf16_f32 v39, v32, v33
	v_add_u32_e32 v32, 0xa0, v148
	v_ashrrev_i32_e32 v33, 31, v32
	v_lshlrev_b64 v[34:35], 12, v[32:33]
	v_lshl_add_u64 v[34:35], s[54:55], 0, v[34:35]
	global_store_dwordx4 v[58:59], v[36:39], off offset:256 sc1
	v_lshl_add_u64 v[44:45], v[34:35], 0, v[150:151]
	global_load_dwordx4 v[34:37], v[44:45], off
	v_lshlrev_b64 v[32:33], 11, v[32:33]
	v_lshl_add_u64 v[32:33], s[52:53], 0, v[32:33]
	v_lshl_add_u64 v[42:43], v[32:33], 0, v[150:151]
	v_mov_b32_e32 v32, 0
	v_mov_b32_e32 v38, 0
	v_mov_b32_e32 v39, 0
	v_mov_b32_e32 v40, 0
	v_mov_b32_e32 v41, 0
	s_cbranch_vccnz .LBB0_887
	global_load_dwordx4 v[38:41], v[42:43], off
.LBB0_887:
	s_waitcnt vmcnt(0)
	v_lshlrev_b32_e32 v46, 16, v34
	v_and_b32_e32 v47, 0xffff0000, v34
	v_lshlrev_b32_e32 v48, 16, v38
	v_and_b32_e32 v49, 0xffff0000, v38
	v_lshlrev_b32_e32 v34, 16, v35
	v_and_b32_e32 v35, 0xffff0000, v35
	v_lshlrev_b32_e32 v38, 16, v39
	v_and_b32_e32 v39, 0xffff0000, v39
	v_pk_fma_f32 v[28:29], v[28:29], v[46:47], v[48:49]
	v_pk_fma_f32 v[30:31], v[30:31], v[34:35], v[38:39]
	v_cvt_pk_bf16_f32 v28, v28, v29
	v_cvt_pk_bf16_f32 v29, v30, v31
	v_lshlrev_b32_e32 v30, 16, v36
	v_and_b32_e32 v31, 0xffff0000, v36
	v_lshlrev_b32_e32 v34, 16, v40
	v_and_b32_e32 v35, 0xffff0000, v40
	v_pk_fma_f32 v[24:25], v[24:25], v[30:31], v[34:35]
	v_lshlrev_b32_e32 v34, 16, v41
	v_cvt_pk_bf16_f32 v30, v24, v25
	v_lshlrev_b32_e32 v24, 16, v37
	v_and_b32_e32 v25, 0xffff0000, v37
	v_and_b32_e32 v35, 0xffff0000, v41
	v_pk_fma_f32 v[24:25], v[26:27], v[24:25], v[34:35]
	s_and_b64 vcc, exec, s[42:43]
	v_cvt_pk_bf16_f32 v31, v24, v25
	global_store_dwordx4 v[42:43], v[28:31], off sc1
	global_load_dwordx4 v[24:27], v[44:45], off offset:256
	v_mov_b32_e32 v33, 0
	v_mov_b32_e32 v34, 0
	v_mov_b32_e32 v35, 0
	s_cbranch_vccnz .LBB0_889
	global_load_dwordx4 v[32:35], v[42:43], off offset:256
.LBB0_889:
	s_waitcnt vmcnt(0)
	v_lshlrev_b32_e32 v28, 16, v24
	v_and_b32_e32 v29, 0xffff0000, v24
	v_lshlrev_b32_e32 v30, 16, v32
	v_and_b32_e32 v31, 0xffff0000, v32
	v_pk_fma_f32 v[20:21], v[20:21], v[28:29], v[30:31]
	v_lshlrev_b32_e32 v24, 16, v25
	v_and_b32_e32 v25, 0xffff0000, v25
	v_lshlrev_b32_e32 v28, 16, v33
	v_and_b32_e32 v29, 0xffff0000, v33
	v_pk_fma_f32 v[22:23], v[22:23], v[24:25], v[28:29]
	v_cvt_pk_bf16_f32 v20, v20, v21
	v_cvt_pk_bf16_f32 v21, v22, v23
	v_lshlrev_b32_e32 v22, 16, v26
	v_and_b32_e32 v23, 0xffff0000, v26
	v_lshlrev_b32_e32 v24, 16, v34
	v_and_b32_e32 v25, 0xffff0000, v34
	v_pk_fma_f32 v[16:17], v[16:17], v[22:23], v[24:25]
	v_lshlrev_b32_e32 v24, 16, v35
	v_cvt_pk_bf16_f32 v22, v16, v17
	v_lshlrev_b32_e32 v16, 16, v27
	v_and_b32_e32 v17, 0xffff0000, v27
	v_and_b32_e32 v25, 0xffff0000, v35
	v_pk_fma_f32 v[16:17], v[18:19], v[16:17], v[24:25]
	s_and_b64 vcc, exec, s[42:43]
	v_cvt_pk_bf16_f32 v23, v16, v17
	v_add_u32_e32 v16, 0xb0, v148
	v_ashrrev_i32_e32 v17, 31, v16
	v_lshlrev_b64 v[18:19], 12, v[16:17]
	v_lshl_add_u64 v[18:19], s[54:55], 0, v[18:19]
	global_store_dwordx4 v[42:43], v[20:23], off offset:256 sc1
	v_lshl_add_u64 v[28:29], v[18:19], 0, v[150:151]
	global_load_dwordx4 v[18:21], v[28:29], off
	v_lshlrev_b64 v[16:17], 11, v[16:17]
	v_lshl_add_u64 v[16:17], s[52:53], 0, v[16:17]
	v_lshl_add_u64 v[26:27], v[16:17], 0, v[150:151]
	v_mov_b32_e32 v16, 0
	v_mov_b32_e32 v22, 0
	v_mov_b32_e32 v23, 0
	v_mov_b32_e32 v24, 0
	v_mov_b32_e32 v25, 0
	s_cbranch_vccnz .LBB0_891
	global_load_dwordx4 v[22:25], v[26:27], off
.LBB0_891:
	s_waitcnt vmcnt(0)
	v_lshlrev_b32_e32 v30, 16, v18
	v_and_b32_e32 v31, 0xffff0000, v18
	v_lshlrev_b32_e32 v32, 16, v22
	v_and_b32_e32 v33, 0xffff0000, v22
	v_lshlrev_b32_e32 v18, 16, v19
	v_and_b32_e32 v19, 0xffff0000, v19
	v_lshlrev_b32_e32 v22, 16, v23
	v_and_b32_e32 v23, 0xffff0000, v23
	v_pk_fma_f32 v[12:13], v[12:13], v[30:31], v[32:33]
	v_pk_fma_f32 v[14:15], v[14:15], v[18:19], v[22:23]
	v_cvt_pk_bf16_f32 v12, v12, v13
	v_cvt_pk_bf16_f32 v13, v14, v15
	v_lshlrev_b32_e32 v14, 16, v20
	v_and_b32_e32 v15, 0xffff0000, v20
	v_lshlrev_b32_e32 v18, 16, v24
	v_and_b32_e32 v19, 0xffff0000, v24
	v_pk_fma_f32 v[8:9], v[8:9], v[14:15], v[18:19]
	v_lshlrev_b32_e32 v18, 16, v25
	v_cvt_pk_bf16_f32 v14, v8, v9
	v_lshlrev_b32_e32 v8, 16, v21
	v_and_b32_e32 v9, 0xffff0000, v21
	v_and_b32_e32 v19, 0xffff0000, v25
	v_pk_fma_f32 v[8:9], v[10:11], v[8:9], v[18:19]
	s_and_b64 vcc, exec, s[42:43]
	v_cvt_pk_bf16_f32 v15, v8, v9
	global_store_dwordx4 v[26:27], v[12:15], off sc1
	global_load_dwordx4 v[8:11], v[28:29], off offset:256
	v_mov_b32_e32 v17, 0
	v_mov_b32_e32 v18, 0
	v_mov_b32_e32 v19, 0
	s_cbranch_vccnz .LBB0_893
	global_load_dwordx4 v[16:19], v[26:27], off offset:256
.LBB0_893:
	s_waitcnt vmcnt(0)
	v_lshlrev_b32_e32 v12, 16, v8
	v_and_b32_e32 v13, 0xffff0000, v8
	v_lshlrev_b32_e32 v14, 16, v16
	v_and_b32_e32 v15, 0xffff0000, v16
	v_pk_fma_f32 v[4:5], v[4:5], v[12:13], v[14:15]
	v_lshlrev_b32_e32 v8, 16, v9
	v_and_b32_e32 v9, 0xffff0000, v9
	v_lshlrev_b32_e32 v12, 16, v17
	v_and_b32_e32 v13, 0xffff0000, v17
	v_pk_fma_f32 v[6:7], v[6:7], v[8:9], v[12:13]
	v_cvt_pk_bf16_f32 v4, v4, v5
	v_cvt_pk_bf16_f32 v5, v6, v7
	v_lshlrev_b32_e32 v6, 16, v10
	v_and_b32_e32 v7, 0xffff0000, v10
	v_lshlrev_b32_e32 v8, 16, v18
	v_and_b32_e32 v9, 0xffff0000, v18
	v_pk_fma_f32 v[0:1], v[0:1], v[6:7], v[8:9]
	v_lshlrev_b32_e32 v8, 16, v19
	v_cvt_pk_bf16_f32 v6, v0, v1
	v_lshlrev_b32_e32 v0, 16, v11
	v_and_b32_e32 v1, 0xffff0000, v11
	v_and_b32_e32 v9, 0xffff0000, v19
	v_pk_fma_f32 v[0:1], v[2:3], v[0:1], v[8:9]
	s_andn2_b64 vcc, exec, s[44:45]
	v_cvt_pk_bf16_f32 v7, v0, v1
	s_mov_b64 s[6:7], -1
	global_store_dwordx4 v[26:27], v[4:7], off offset:256 sc1
	s_cbranch_vccnz .LBB0_850
	s_andn2_b64 vcc, exec, s[50:51]
	s_cbranch_vccnz .LBB0_849
	s_barrier
	s_branch .LBB0_849

.LBB0_907:
	s_waitcnt lgkmcnt(14)
	v_pk_add_f32 v[40:41], v[40:41], 0 op_sel_hi:[1,0]
	v_pk_add_f32 v[68:69], v[68:69], 0 op_sel_hi:[1,0]
	s_waitcnt lgkmcnt(12)
	v_pk_add_f32 v[36:37], v[40:41], v[36:37]
	v_pk_add_f32 v[64:65], v[68:69], v[64:65]
	s_waitcnt lgkmcnt(10)
	v_pk_add_f32 v[32:33], v[36:37], v[32:33]
	v_pk_add_f32 v[60:61], v[64:65], v[60:61]
	s_waitcnt lgkmcnt(8)
	v_pk_add_f32 v[28:29], v[32:33], v[28:29]
	v_pk_add_f32 v[56:57], v[60:61], v[56:57]
	s_waitcnt lgkmcnt(6)
	v_pk_add_f32 v[24:25], v[28:29], v[24:25]
	v_pk_add_f32 v[52:53], v[56:57], v[52:53]
	s_waitcnt lgkmcnt(4)
	v_pk_add_f32 v[20:21], v[24:25], v[20:21]
	v_pk_add_f32 v[48:49], v[52:53], v[48:49]
	s_waitcnt lgkmcnt(2)
	v_pk_add_f32 v[16:17], v[20:21], v[16:17]
	v_pk_add_f32 v[20:21], v[42:43], 0 op_sel_hi:[1,0]
	v_pk_add_f32 v[44:45], v[48:49], v[44:45]
	v_pk_add_f32 v[20:21], v[20:21], v[38:39]
	v_pk_add_f32 v[48:49], v[70:71], 0 op_sel_hi:[1,0]
	v_pk_add_f32 v[20:21], v[20:21], v[34:35]
	v_pk_add_f32 v[48:49], v[48:49], v[66:67]
	v_pk_add_f32 v[20:21], v[20:21], v[30:31]
	v_pk_add_f32 v[48:49], v[48:49], v[62:63]
	v_pk_add_f32 v[20:21], v[20:21], v[26:27]
	v_pk_add_f32 v[48:49], v[48:49], v[58:59]
	v_pk_add_f32 v[20:21], v[20:21], v[22:23]
	v_pk_add_f32 v[48:49], v[48:49], v[54:55]
	v_pk_add_f32 v[18:19], v[20:21], v[18:19]
	v_pk_add_f32 v[48:49], v[48:49], v[50:51]
	s_waitcnt lgkmcnt(1)
	v_pk_add_f32 v[12:13], v[44:45], v[12:13]
	s_waitcnt lgkmcnt(0)
	v_pk_add_f32 v[8:9], v[16:17], v[8:9]
	v_pk_add_f32 v[10:11], v[18:19], v[10:11]
	s_waitcnt vmcnt(0)
	v_lshlrev_b32_e32 v16, 16, v0
	v_and_b32_e32 v17, 0xffff0000, v0
	v_lshlrev_b32_e32 v18, 16, v4
	v_and_b32_e32 v19, 0xffff0000, v4
	v_pk_add_f32 v[46:47], v[48:49], v[46:47]
	v_pk_fma_f32 v[12:13], v[12:13], v[16:17], v[18:19]
	v_pk_add_f32 v[14:15], v[46:47], v[14:15]
	v_cvt_pk_bf16_f32 v0, v12, v13
	v_lshlrev_b32_e32 v12, 16, v1
	v_and_b32_e32 v13, 0xffff0000, v1
	v_lshlrev_b32_e32 v4, 16, v5
	v_and_b32_e32 v5, 0xffff0000, v5
	v_pk_fma_f32 v[4:5], v[14:15], v[12:13], v[4:5]
	v_lshlrev_b32_e32 v12, 16, v6
	v_cvt_pk_bf16_f32 v1, v4, v5
	v_lshlrev_b32_e32 v4, 16, v2
	v_and_b32_e32 v5, 0xffff0000, v2
	v_and_b32_e32 v13, 0xffff0000, v6
	v_pk_fma_f32 v[4:5], v[8:9], v[4:5], v[12:13]
	v_lshlrev_b32_e32 v6, 16, v7
	v_cvt_pk_bf16_f32 v2, v4, v5
	v_lshlrev_b32_e32 v4, 16, v3
	v_and_b32_e32 v5, 0xffff0000, v3
	v_and_b32_e32 v7, 0xffff0000, v7
	v_pk_fma_f32 v[4:5], v[10:11], v[4:5], v[6:7]
	s_add_i32 s7, s7, s82
	s_add_i32 s6, s6, s39
	v_cvt_pk_bf16_f32 v3, v4, v5
	s_cmp_lt_i32 s7, 16
	global_store_dwordx4 v[88:89], v[0:3], off sc1
	s_barrier
	s_cbranch_scc0 .LBB0_836

.LBB0_978:
	v_and_b32_e32 v142, 64, v215
	v_xor_b32_e32 v141, 16, v215
	v_add_u32_e32 v142, 64, v142
	v_cmp_lt_i32_e32 vcc, v141, v142
	v_lshl_add_u32 v140, s23, 8, v144
	v_lshl_or_b32 v138, s22, 8, v146
	v_cndmask_b32_e32 v141, v215, v141, vcc
	v_lshlrev_b32_e32 v149, 2, v141
	v_xor_b32_e32 v141, 32, v215
	v_cmp_lt_i32_e32 vcc, v141, v142
	v_ashrrev_i32_e32 v139, 31, v138
	s_lshl_b32 s60, s22, 2
	v_cndmask_b32_e32 v141, v215, v141, vcc
	v_lshlrev_b32_e32 v148, 2, v141
	v_ashrrev_i32_e32 v141, 31, v140
	v_lshlrev_b64 v[142:143], 11, v[140:141]
	v_lshl_add_u64 v[142:143], s[46:47], 0, v[142:143]
	v_lshl_add_u64 v[142:143], v[138:139], 1, v[142:143]
	global_load_dwordx4 v[150:153], v[142:143], off
	s_ashr_i32 s61, s60, 31
	s_waitcnt vmcnt(0)
	v_lshlrev_b32_e32 v154, 16, v150
	v_and_b32_e32 v155, 0xffff0000, v150
	v_lshlrev_b32_e32 v150, 16, v151
	v_and_b32_e32 v151, 0xffff0000, v151
	v_lshlrev_b32_e32 v156, 16, v152
	v_and_b32_e32 v157, 0xffff0000, v152
	v_lshlrev_b32_e32 v152, 16, v153
	v_and_b32_e32 v153, 0xffff0000, v153
	v_pk_add_f32 v[126:127], v[126:127], v[150:151]
	v_pk_add_f32 v[124:125], v[124:125], v[154:155]
	v_pk_add_f32 v[150:151], v[122:123], v[152:153]
	v_pk_add_f32 v[152:153], v[120:121], v[156:157]
	v_cvt_pk_bf16_f32 v120, v124, v125
	v_cvt_pk_bf16_f32 v121, v126, v127
	v_cvt_pk_bf16_f32 v122, v152, v153
	v_cvt_pk_bf16_f32 v123, v150, v151
	global_store_dwordx4 v[142:143], v[120:123], off sc1
	s_nop 1
	v_mul_f32_e32 v120, v125, v125
	v_mul_f32_e32 v121, v127, v127
	v_fmac_f32_e32 v120, v124, v124
	v_fmac_f32_e32 v121, v126, v126
	v_add_f32_e32 v120, v120, v121
	v_mul_f32_e32 v121, v153, v153
	v_fmac_f32_e32 v121, v152, v152
	v_add_f32_e32 v120, v121, v120
	v_mul_f32_e32 v121, v151, v151
	v_fmac_f32_e32 v121, v150, v150
	v_add_f32_e32 v150, v121, v120
	global_load_dwordx4 v[120:123], v[142:143], off offset:256
	s_waitcnt vmcnt(0)
	v_lshlrev_b32_e32 v124, 16, v120
	v_and_b32_e32 v125, 0xffff0000, v120
	v_lshlrev_b32_e32 v120, 16, v121
	v_and_b32_e32 v121, 0xffff0000, v121
	v_lshlrev_b32_e32 v126, 16, v122
	v_and_b32_e32 v127, 0xffff0000, v122
	v_lshlrev_b32_e32 v122, 16, v123
	v_and_b32_e32 v123, 0xffff0000, v123
	v_pk_add_f32 v[118:119], v[118:119], v[120:121]
	v_pk_add_f32 v[116:117], v[116:117], v[124:125]
	v_pk_add_f32 v[120:121], v[114:115], v[122:123]
	v_pk_add_f32 v[122:123], v[112:113], v[126:127]
	v_cvt_pk_bf16_f32 v112, v116, v117
	v_cvt_pk_bf16_f32 v113, v118, v119
	v_cvt_pk_bf16_f32 v114, v122, v123
	v_cvt_pk_bf16_f32 v115, v120, v121
	global_store_dwordx4 v[142:143], v[112:115], off offset:256 sc1
	s_nop 1
	v_mul_f32_e32 v112, v117, v117
	v_mul_f32_e32 v113, v119, v119
	v_fmac_f32_e32 v112, v116, v116
	v_fmac_f32_e32 v113, v118, v118
	v_add_f32_e32 v112, v112, v113
	v_mul_f32_e32 v113, v123, v123
	v_fmac_f32_e32 v113, v122, v122
	v_add_f32_e32 v112, v113, v112
	v_mul_f32_e32 v113, v121, v121
	v_fmac_f32_e32 v113, v120, v120
	v_add_f32_e32 v112, v113, v112
	v_add_f32_e32 v112, v150, v112
	ds_bpermute_b32 v113, v149, v112
	s_waitcnt lgkmcnt(0)
	v_add_f32_e32 v112, v112, v113
	ds_bpermute_b32 v113, v148, v112
	s_and_saveexec_b64 s[6:7], s[40:41]
	s_cbranch_execz .LBB0_980
	s_waitcnt lgkmcnt(0)
	v_add_f32_e32 v114, v112, v113
	v_lshlrev_b64 v[112:113], 6, v[140:141]
	v_lshl_add_u64 v[112:113], s[48:49], 0, v[112:113]
	v_lshl_add_u64 v[112:113], s[60:61], 2, v[112:113]
	s_lshl_b32 s92, s73, 2
	v_lshl_add_u64 v[112:113], v[112:113], 0, s[92:93]
	global_store_dword v[112:113], v114, off
.LBB0_980:
	s_or_b64 exec, exec, s[6:7]
	v_or_b32_e32 v112, 16, v140
	s_waitcnt lgkmcnt(0)
	v_ashrrev_i32_e32 v113, 31, v112
	v_lshlrev_b64 v[114:115], 11, v[112:113]
	v_lshl_add_u64 v[114:115], s[46:47], 0, v[114:115]
	v_lshl_add_u64 v[118:119], v[138:139], 1, v[114:115]
	global_load_dwordx4 v[114:117], v[118:119], off
	s_waitcnt vmcnt(0)
	v_lshlrev_b32_e32 v120, 16, v114
	v_and_b32_e32 v121, 0xffff0000, v114
	v_lshlrev_b32_e32 v114, 16, v115
	v_and_b32_e32 v115, 0xffff0000, v115
	v_lshlrev_b32_e32 v122, 16, v116
	v_and_b32_e32 v123, 0xffff0000, v116
	v_lshlrev_b32_e32 v116, 16, v117
	v_and_b32_e32 v117, 0xffff0000, v117
	v_pk_add_f32 v[110:111], v[110:111], v[114:115]
	v_pk_add_f32 v[108:109], v[108:109], v[120:121]
	v_pk_add_f32 v[114:115], v[106:107], v[116:117]
	v_pk_add_f32 v[116:117], v[104:105], v[122:123]
	v_cvt_pk_bf16_f32 v104, v108, v109
	v_cvt_pk_bf16_f32 v105, v110, v111
	v_cvt_pk_bf16_f32 v106, v116, v117
	v_cvt_pk_bf16_f32 v107, v114, v115
	global_store_dwordx4 v[118:119], v[104:107], off sc1
	s_nop 1
	v_mul_f32_e32 v104, v109, v109
	v_mul_f32_e32 v105, v111, v111
	v_fmac_f32_e32 v104, v108, v108
	v_fmac_f32_e32 v105, v110, v110
	v_add_f32_e32 v104, v104, v105
	v_mul_f32_e32 v105, v117, v117
	v_fmac_f32_e32 v105, v116, v116
	v_add_f32_e32 v104, v105, v104
	v_mul_f32_e32 v105, v115, v115
	v_fmac_f32_e32 v105, v114, v114
	v_add_f32_e32 v114, v105, v104
	global_load_dwordx4 v[104:107], v[118:119], off offset:256
	s_waitcnt vmcnt(0)
	v_lshlrev_b32_e32 v108, 16, v104
	v_and_b32_e32 v109, 0xffff0000, v104
	v_lshlrev_b32_e32 v104, 16, v105
	v_and_b32_e32 v105, 0xffff0000, v105
	v_lshlrev_b32_e32 v110, 16, v106
	v_and_b32_e32 v111, 0xffff0000, v106
	v_lshlrev_b32_e32 v106, 16, v107
	v_and_b32_e32 v107, 0xffff0000, v107
	v_pk_add_f32 v[102:103], v[102:103], v[104:105]
	v_pk_add_f32 v[100:101], v[100:101], v[108:109]
	v_pk_add_f32 v[104:105], v[98:99], v[106:107]
	v_pk_add_f32 v[106:107], v[96:97], v[110:111]
	v_cvt_pk_bf16_f32 v96, v100, v101
	v_cvt_pk_bf16_f32 v97, v102, v103
	v_cvt_pk_bf16_f32 v98, v106, v107
	v_cvt_pk_bf16_f32 v99, v104, v105
	global_store_dwordx4 v[118:119], v[96:99], off offset:256 sc1
	s_nop 1
	v_mul_f32_e32 v96, v101, v101
	v_mul_f32_e32 v97, v103, v103
	v_fmac_f32_e32 v96, v100, v100
	v_fmac_f32_e32 v97, v102, v102
	v_add_f32_e32 v96, v96, v97
	v_mul_f32_e32 v97, v107, v107
	v_fmac_f32_e32 v97, v106, v106
	v_add_f32_e32 v96, v97, v96
	v_mul_f32_e32 v97, v105, v105
	v_fmac_f32_e32 v97, v104, v104
	v_add_f32_e32 v96, v97, v96
	v_add_f32_e32 v96, v114, v96
	ds_bpermute_b32 v97, v149, v96
	s_waitcnt lgkmcnt(0)
	v_add_f32_e32 v96, v96, v97
	ds_bpermute_b32 v97, v148, v96
	s_and_saveexec_b64 s[6:7], s[40:41]
	s_cbranch_execz .LBB0_982
	s_waitcnt lgkmcnt(0)
	v_add_f32_e32 v98, v96, v97
	v_lshlrev_b64 v[96:97], 6, v[112:113]
	v_lshl_add_u64 v[96:97], s[48:49], 0, v[96:97]
	v_lshl_add_u64 v[96:97], s[60:61], 2, v[96:97]
	s_lshl_b32 s92, s73, 2
	v_lshl_add_u64 v[96:97], v[96:97], 0, s[92:93]
	global_store_dword v[96:97], v98, off
.LBB0_982:
	s_or_b64 exec, exec, s[6:7]
	v_or_b32_e32 v96, 32, v140
	s_waitcnt lgkmcnt(0)
	v_ashrrev_i32_e32 v97, 31, v96
	v_lshlrev_b64 v[98:99], 11, v[96:97]
	v_lshl_add_u64 v[98:99], s[46:47], 0, v[98:99]
	v_lshl_add_u64 v[102:103], v[138:139], 1, v[98:99]
	global_load_dwordx4 v[98:101], v[102:103], off
	s_waitcnt vmcnt(0)
	v_lshlrev_b32_e32 v104, 16, v98
	v_and_b32_e32 v105, 0xffff0000, v98
	v_lshlrev_b32_e32 v98, 16, v99
	v_and_b32_e32 v99, 0xffff0000, v99
	v_lshlrev_b32_e32 v106, 16, v100
	v_and_b32_e32 v107, 0xffff0000, v100
	v_lshlrev_b32_e32 v100, 16, v101
	v_and_b32_e32 v101, 0xffff0000, v101
	v_pk_add_f32 v[94:95], v[94:95], v[98:99]
	v_pk_add_f32 v[92:93], v[92:93], v[104:105]
	v_pk_add_f32 v[98:99], v[90:91], v[100:101]
	v_pk_add_f32 v[100:101], v[88:89], v[106:107]
	v_cvt_pk_bf16_f32 v88, v92, v93
	v_cvt_pk_bf16_f32 v89, v94, v95
	v_cvt_pk_bf16_f32 v90, v100, v101
	v_cvt_pk_bf16_f32 v91, v98, v99
	global_store_dwordx4 v[102:103], v[88:91], off sc1
	s_nop 1
	v_mul_f32_e32 v88, v93, v93
	v_mul_f32_e32 v89, v95, v95
	v_fmac_f32_e32 v88, v92, v92
	v_fmac_f32_e32 v89, v94, v94
	v_add_f32_e32 v88, v88, v89
	v_mul_f32_e32 v89, v101, v101
	v_fmac_f32_e32 v89, v100, v100
	v_add_f32_e32 v88, v89, v88
	v_mul_f32_e32 v89, v99, v99
	v_fmac_f32_e32 v89, v98, v98
	v_add_f32_e32 v98, v89, v88
	global_load_dwordx4 v[88:91], v[102:103], off offset:256
	s_waitcnt vmcnt(0)
	v_lshlrev_b32_e32 v92, 16, v88
	v_and_b32_e32 v93, 0xffff0000, v88
	v_lshlrev_b32_e32 v88, 16, v89
	v_and_b32_e32 v89, 0xffff0000, v89
	v_lshlrev_b32_e32 v94, 16, v90
	v_and_b32_e32 v95, 0xffff0000, v90
	v_lshlrev_b32_e32 v90, 16, v91
	v_and_b32_e32 v91, 0xffff0000, v91
	v_pk_add_f32 v[86:87], v[86:87], v[88:89]
	v_pk_add_f32 v[84:85], v[84:85], v[92:93]
	v_pk_add_f32 v[88:89], v[82:83], v[90:91]
	v_pk_add_f32 v[90:91], v[80:81], v[94:95]
	v_cvt_pk_bf16_f32 v80, v84, v85
	v_cvt_pk_bf16_f32 v81, v86, v87
	v_cvt_pk_bf16_f32 v82, v90, v91
	v_cvt_pk_bf16_f32 v83, v88, v89
	global_store_dwordx4 v[102:103], v[80:83], off offset:256 sc1
	s_nop 1
	v_mul_f32_e32 v80, v85, v85
	v_mul_f32_e32 v81, v87, v87
	v_fmac_f32_e32 v80, v84, v84
	v_fmac_f32_e32 v81, v86, v86
	v_add_f32_e32 v80, v80, v81
	v_mul_f32_e32 v81, v91, v91
	v_fmac_f32_e32 v81, v90, v90
	v_add_f32_e32 v80, v81, v80
	v_mul_f32_e32 v81, v89, v89
	v_fmac_f32_e32 v81, v88, v88
	v_add_f32_e32 v80, v81, v80
	v_add_f32_e32 v80, v98, v80
	ds_bpermute_b32 v81, v149, v80
	s_waitcnt lgkmcnt(0)
	v_add_f32_e32 v80, v80, v81
	ds_bpermute_b32 v81, v148, v80
	s_and_saveexec_b64 s[6:7], s[40:41]
	s_mov_b64 s[30:31], s[34:35]
	s_cbranch_execz .LBB0_984
	s_waitcnt lgkmcnt(0)
	v_add_f32_e32 v82, v80, v81
	v_lshlrev_b64 v[80:81], 6, v[96:97]
	v_lshl_add_u64 v[80:81], s[48:49], 0, v[80:81]
	v_lshl_add_u64 v[80:81], s[60:61], 2, v[80:81]
	s_lshl_b32 s92, s73, 2
	v_lshl_add_u64 v[80:81], v[80:81], 0, s[92:93]
	global_store_dword v[80:81], v82, off
.LBB0_984:
	s_or_b64 exec, exec, s[6:7]
	v_or_b32_e32 v80, 48, v140
	s_waitcnt lgkmcnt(0)
	v_ashrrev_i32_e32 v81, 31, v80
	v_lshlrev_b64 v[82:83], 11, v[80:81]
	v_lshl_add_u64 v[82:83], s[46:47], 0, v[82:83]
	v_lshl_add_u64 v[86:87], v[138:139], 1, v[82:83]
	global_load_dwordx4 v[82:85], v[86:87], off
	s_waitcnt vmcnt(0)
	v_lshlrev_b32_e32 v88, 16, v82
	v_and_b32_e32 v89, 0xffff0000, v82
	v_lshlrev_b32_e32 v82, 16, v83
	v_and_b32_e32 v83, 0xffff0000, v83
	v_lshlrev_b32_e32 v90, 16, v84
	v_and_b32_e32 v91, 0xffff0000, v84
	v_lshlrev_b32_e32 v84, 16, v85
	v_and_b32_e32 v85, 0xffff0000, v85
	v_pk_add_f32 v[78:79], v[78:79], v[82:83]
	v_pk_add_f32 v[76:77], v[76:77], v[88:89]
	v_pk_add_f32 v[82:83], v[74:75], v[84:85]
	v_pk_add_f32 v[84:85], v[72:73], v[90:91]
	v_cvt_pk_bf16_f32 v72, v76, v77
	v_cvt_pk_bf16_f32 v73, v78, v79
	v_cvt_pk_bf16_f32 v74, v84, v85
	v_cvt_pk_bf16_f32 v75, v82, v83
	global_store_dwordx4 v[86:87], v[72:75], off sc1
	s_nop 1
	v_mul_f32_e32 v72, v77, v77
	v_mul_f32_e32 v73, v79, v79
	v_fmac_f32_e32 v72, v76, v76
	v_fmac_f32_e32 v73, v78, v78
	v_add_f32_e32 v72, v72, v73
	v_mul_f32_e32 v73, v85, v85
	v_fmac_f32_e32 v73, v84, v84
	v_add_f32_e32 v72, v73, v72
	v_mul_f32_e32 v73, v83, v83
	v_fmac_f32_e32 v73, v82, v82
	v_add_f32_e32 v82, v73, v72
	global_load_dwordx4 v[72:75], v[86:87], off offset:256
	s_waitcnt vmcnt(0)
	v_lshlrev_b32_e32 v76, 16, v72
	v_and_b32_e32 v77, 0xffff0000, v72
	v_lshlrev_b32_e32 v72, 16, v73
	v_and_b32_e32 v73, 0xffff0000, v73
	v_lshlrev_b32_e32 v78, 16, v74
	v_and_b32_e32 v79, 0xffff0000, v74
	v_lshlrev_b32_e32 v74, 16, v75
	v_and_b32_e32 v75, 0xffff0000, v75
	v_pk_add_f32 v[70:71], v[70:71], v[72:73]
	v_pk_add_f32 v[68:69], v[68:69], v[76:77]
	v_pk_add_f32 v[72:73], v[66:67], v[74:75]
	v_pk_add_f32 v[74:75], v[64:65], v[78:79]
	v_cvt_pk_bf16_f32 v64, v68, v69
	v_cvt_pk_bf16_f32 v65, v70, v71
	v_cvt_pk_bf16_f32 v66, v74, v75
	v_cvt_pk_bf16_f32 v67, v72, v73
	global_store_dwordx4 v[86:87], v[64:67], off offset:256 sc1
	s_nop 1
	v_mul_f32_e32 v64, v69, v69
	v_mul_f32_e32 v65, v71, v71
	v_fmac_f32_e32 v64, v68, v68
	v_fmac_f32_e32 v65, v70, v70
	v_add_f32_e32 v64, v64, v65
	v_mul_f32_e32 v65, v75, v75
	v_fmac_f32_e32 v65, v74, v74
	v_add_f32_e32 v64, v65, v64
	v_mul_f32_e32 v65, v73, v73
	v_fmac_f32_e32 v65, v72, v72
	v_add_f32_e32 v64, v65, v64
	v_add_f32_e32 v64, v82, v64
	ds_bpermute_b32 v65, v149, v64
	s_waitcnt lgkmcnt(0)
	v_add_f32_e32 v64, v64, v65
	ds_bpermute_b32 v65, v148, v64
	s_and_saveexec_b64 s[6:7], s[40:41]
	s_cbranch_execz .LBB0_986
	s_waitcnt lgkmcnt(0)
	v_add_f32_e32 v66, v64, v65
	v_lshlrev_b64 v[64:65], 6, v[80:81]
	v_lshl_add_u64 v[64:65], s[48:49], 0, v[64:65]
	v_lshl_add_u64 v[64:65], s[60:61], 2, v[64:65]
	s_lshl_b32 s92, s73, 2
	v_lshl_add_u64 v[64:65], v[64:65], 0, s[92:93]
	global_store_dword v[64:65], v66, off
.LBB0_986:
	s_or_b64 exec, exec, s[6:7]
	v_add_u32_e32 v64, 0x80, v140
	s_waitcnt lgkmcnt(0)
	v_ashrrev_i32_e32 v65, 31, v64
	v_lshlrev_b64 v[66:67], 11, v[64:65]
	v_lshl_add_u64 v[66:67], s[46:47], 0, v[66:67]
	v_lshl_add_u64 v[70:71], v[138:139], 1, v[66:67]
	global_load_dwordx4 v[66:69], v[70:71], off
	s_waitcnt vmcnt(0)
	v_lshlrev_b32_e32 v72, 16, v66
	v_and_b32_e32 v73, 0xffff0000, v66
	v_lshlrev_b32_e32 v66, 16, v67
	v_and_b32_e32 v67, 0xffff0000, v67
	v_lshlrev_b32_e32 v74, 16, v68
	v_and_b32_e32 v75, 0xffff0000, v68
	v_lshlrev_b32_e32 v68, 16, v69
	v_and_b32_e32 v69, 0xffff0000, v69
	v_pk_add_f32 v[62:63], v[62:63], v[66:67]
	v_pk_add_f32 v[60:61], v[60:61], v[72:73]
	v_pk_add_f32 v[66:67], v[58:59], v[68:69]
	v_pk_add_f32 v[68:69], v[56:57], v[74:75]
	v_cvt_pk_bf16_f32 v56, v60, v61
	v_cvt_pk_bf16_f32 v57, v62, v63
	v_cvt_pk_bf16_f32 v58, v68, v69
	v_cvt_pk_bf16_f32 v59, v66, v67
	global_store_dwordx4 v[70:71], v[56:59], off sc1
	s_nop 1
	v_mul_f32_e32 v56, v61, v61
	v_mul_f32_e32 v57, v63, v63
	v_fmac_f32_e32 v56, v60, v60
	v_fmac_f32_e32 v57, v62, v62
	v_add_f32_e32 v56, v56, v57
	v_mul_f32_e32 v57, v69, v69
	v_fmac_f32_e32 v57, v68, v68
	v_add_f32_e32 v56, v57, v56
	v_mul_f32_e32 v57, v67, v67
	v_fmac_f32_e32 v57, v66, v66
	v_add_f32_e32 v66, v57, v56
	global_load_dwordx4 v[56:59], v[70:71], off offset:256
	s_waitcnt vmcnt(0)
	v_lshlrev_b32_e32 v60, 16, v56
	v_and_b32_e32 v61, 0xffff0000, v56
	v_lshlrev_b32_e32 v56, 16, v57
	v_and_b32_e32 v57, 0xffff0000, v57
	v_lshlrev_b32_e32 v62, 16, v58
	v_and_b32_e32 v63, 0xffff0000, v58
	v_lshlrev_b32_e32 v58, 16, v59
	v_and_b32_e32 v59, 0xffff0000, v59
	v_pk_add_f32 v[54:55], v[54:55], v[56:57]
	v_pk_add_f32 v[52:53], v[52:53], v[60:61]
	v_pk_add_f32 v[56:57], v[50:51], v[58:59]
	v_pk_add_f32 v[58:59], v[48:49], v[62:63]
	v_cvt_pk_bf16_f32 v48, v52, v53
	v_cvt_pk_bf16_f32 v49, v54, v55
	v_cvt_pk_bf16_f32 v50, v58, v59
	v_cvt_pk_bf16_f32 v51, v56, v57
	global_store_dwordx4 v[70:71], v[48:51], off offset:256 sc1
	s_nop 1
	v_mul_f32_e32 v48, v53, v53
	v_mul_f32_e32 v49, v55, v55
	v_fmac_f32_e32 v48, v52, v52
	v_fmac_f32_e32 v49, v54, v54
	v_add_f32_e32 v48, v48, v49
	v_mul_f32_e32 v49, v59, v59
	v_fmac_f32_e32 v49, v58, v58
	v_add_f32_e32 v48, v49, v48
	v_mul_f32_e32 v49, v57, v57
	v_fmac_f32_e32 v49, v56, v56
	v_add_f32_e32 v48, v49, v48
	v_add_f32_e32 v48, v66, v48
	ds_bpermute_b32 v49, v149, v48
	s_waitcnt lgkmcnt(0)
	v_add_f32_e32 v48, v48, v49
	ds_bpermute_b32 v49, v148, v48
	s_and_saveexec_b64 s[6:7], s[40:41]
	s_cbranch_execz .LBB0_988
	s_waitcnt lgkmcnt(0)
	v_add_f32_e32 v50, v48, v49
	v_lshlrev_b64 v[48:49], 6, v[64:65]
	v_lshl_add_u64 v[48:49], s[48:49], 0, v[48:49]
	v_lshl_add_u64 v[48:49], s[60:61], 2, v[48:49]
	s_lshl_b32 s92, s73, 2
	v_lshl_add_u64 v[48:49], v[48:49], 0, s[92:93]
	global_store_dword v[48:49], v50, off
.LBB0_988:
	s_or_b64 exec, exec, s[6:7]
	v_add_u32_e32 v48, 0x90, v140
	s_waitcnt lgkmcnt(0)
	v_ashrrev_i32_e32 v49, 31, v48
	v_lshlrev_b64 v[50:51], 11, v[48:49]
	v_lshl_add_u64 v[50:51], s[46:47], 0, v[50:51]
	v_lshl_add_u64 v[54:55], v[138:139], 1, v[50:51]
	global_load_dwordx4 v[50:53], v[54:55], off
	s_waitcnt vmcnt(0)
	v_lshlrev_b32_e32 v56, 16, v50
	v_and_b32_e32 v57, 0xffff0000, v50
	v_lshlrev_b32_e32 v50, 16, v51
	v_and_b32_e32 v51, 0xffff0000, v51
	v_lshlrev_b32_e32 v58, 16, v52
	v_and_b32_e32 v59, 0xffff0000, v52
	v_lshlrev_b32_e32 v52, 16, v53
	v_and_b32_e32 v53, 0xffff0000, v53
	v_pk_add_f32 v[46:47], v[46:47], v[50:51]
	v_pk_add_f32 v[44:45], v[44:45], v[56:57]
	v_pk_add_f32 v[50:51], v[42:43], v[52:53]
	v_pk_add_f32 v[52:53], v[40:41], v[58:59]
	v_cvt_pk_bf16_f32 v40, v44, v45
	v_cvt_pk_bf16_f32 v41, v46, v47
	v_cvt_pk_bf16_f32 v42, v52, v53
	v_cvt_pk_bf16_f32 v43, v50, v51
	global_store_dwordx4 v[54:55], v[40:43], off sc1
	s_nop 1
	v_mul_f32_e32 v40, v45, v45
	v_mul_f32_e32 v41, v47, v47
	v_fmac_f32_e32 v40, v44, v44
	v_fmac_f32_e32 v41, v46, v46
	v_add_f32_e32 v40, v40, v41
	v_mul_f32_e32 v41, v53, v53
	v_fmac_f32_e32 v41, v52, v52
	v_add_f32_e32 v40, v41, v40
	v_mul_f32_e32 v41, v51, v51
	v_fmac_f32_e32 v41, v50, v50
	v_add_f32_e32 v50, v41, v40
	global_load_dwordx4 v[40:43], v[54:55], off offset:256
	s_waitcnt vmcnt(0)
	v_lshlrev_b32_e32 v44, 16, v40
	v_and_b32_e32 v45, 0xffff0000, v40
	v_lshlrev_b32_e32 v40, 16, v41
	v_and_b32_e32 v41, 0xffff0000, v41
	v_lshlrev_b32_e32 v46, 16, v42
	v_and_b32_e32 v47, 0xffff0000, v42
	v_lshlrev_b32_e32 v42, 16, v43
	v_and_b32_e32 v43, 0xffff0000, v43
	v_pk_add_f32 v[38:39], v[38:39], v[40:41]
	v_pk_add_f32 v[36:37], v[36:37], v[44:45]
	v_pk_add_f32 v[40:41], v[34:35], v[42:43]
	v_pk_add_f32 v[42:43], v[32:33], v[46:47]
	v_cvt_pk_bf16_f32 v32, v36, v37
	v_cvt_pk_bf16_f32 v33, v38, v39
	v_cvt_pk_bf16_f32 v34, v42, v43
	v_cvt_pk_bf16_f32 v35, v40, v41
	global_store_dwordx4 v[54:55], v[32:35], off offset:256 sc1
	s_nop 1
	v_mul_f32_e32 v32, v37, v37
	v_mul_f32_e32 v33, v39, v39
	v_fmac_f32_e32 v32, v36, v36
	v_fmac_f32_e32 v33, v38, v38
	v_add_f32_e32 v32, v32, v33
	v_mul_f32_e32 v33, v43, v43
	v_fmac_f32_e32 v33, v42, v42
	v_add_f32_e32 v32, v33, v32
	v_mul_f32_e32 v33, v41, v41
	v_fmac_f32_e32 v33, v40, v40
	v_add_f32_e32 v32, v33, v32
	v_add_f32_e32 v32, v50, v32
	ds_bpermute_b32 v33, v149, v32
	s_waitcnt lgkmcnt(0)
	v_add_f32_e32 v32, v32, v33
	ds_bpermute_b32 v33, v148, v32
	s_and_saveexec_b64 s[6:7], s[40:41]
	s_cbranch_execz .LBB0_990
	s_waitcnt lgkmcnt(0)
	v_add_f32_e32 v34, v32, v33
	v_lshlrev_b64 v[32:33], 6, v[48:49]
	v_lshl_add_u64 v[32:33], s[48:49], 0, v[32:33]
	v_lshl_add_u64 v[32:33], s[60:61], 2, v[32:33]
	s_lshl_b32 s92, s73, 2
	v_lshl_add_u64 v[32:33], v[32:33], 0, s[92:93]
	global_store_dword v[32:33], v34, off
.LBB0_990:
	s_or_b64 exec, exec, s[6:7]
	v_add_u32_e32 v32, 0xa0, v140
	s_waitcnt lgkmcnt(0)
	v_ashrrev_i32_e32 v33, 31, v32
	v_lshlrev_b64 v[34:35], 11, v[32:33]
	v_lshl_add_u64 v[34:35], s[46:47], 0, v[34:35]
	v_lshl_add_u64 v[38:39], v[138:139], 1, v[34:35]
	global_load_dwordx4 v[34:37], v[38:39], off
	s_waitcnt vmcnt(0)
	v_lshlrev_b32_e32 v40, 16, v34
	v_and_b32_e32 v41, 0xffff0000, v34
	v_lshlrev_b32_e32 v34, 16, v35
	v_and_b32_e32 v35, 0xffff0000, v35
	v_lshlrev_b32_e32 v42, 16, v36
	v_and_b32_e32 v43, 0xffff0000, v36
	v_lshlrev_b32_e32 v36, 16, v37
	v_and_b32_e32 v37, 0xffff0000, v37
	v_pk_add_f32 v[30:31], v[30:31], v[34:35]
	v_pk_add_f32 v[28:29], v[28:29], v[40:41]
	v_pk_add_f32 v[34:35], v[26:27], v[36:37]
	v_pk_add_f32 v[36:37], v[24:25], v[42:43]
	v_cvt_pk_bf16_f32 v24, v28, v29
	v_cvt_pk_bf16_f32 v25, v30, v31
	v_cvt_pk_bf16_f32 v26, v36, v37
	v_cvt_pk_bf16_f32 v27, v34, v35
	global_store_dwordx4 v[38:39], v[24:27], off sc1
	s_nop 1
	v_mul_f32_e32 v24, v29, v29
	v_mul_f32_e32 v25, v31, v31
	v_fmac_f32_e32 v24, v28, v28
	v_fmac_f32_e32 v25, v30, v30
	v_add_f32_e32 v24, v24, v25
	v_mul_f32_e32 v25, v37, v37
	v_fmac_f32_e32 v25, v36, v36
	v_add_f32_e32 v24, v25, v24
	v_mul_f32_e32 v25, v35, v35
	v_fmac_f32_e32 v25, v34, v34
	v_add_f32_e32 v34, v25, v24
	global_load_dwordx4 v[24:27], v[38:39], off offset:256
	s_waitcnt vmcnt(0)
	v_lshlrev_b32_e32 v28, 16, v24
	v_and_b32_e32 v29, 0xffff0000, v24
	v_lshlrev_b32_e32 v24, 16, v25
	v_and_b32_e32 v25, 0xffff0000, v25
	v_lshlrev_b32_e32 v30, 16, v26
	v_and_b32_e32 v31, 0xffff0000, v26
	v_lshlrev_b32_e32 v26, 16, v27
	v_and_b32_e32 v27, 0xffff0000, v27
	v_pk_add_f32 v[22:23], v[22:23], v[24:25]
	v_pk_add_f32 v[20:21], v[20:21], v[28:29]
	v_pk_add_f32 v[24:25], v[18:19], v[26:27]
	v_pk_add_f32 v[26:27], v[16:17], v[30:31]
	v_cvt_pk_bf16_f32 v16, v20, v21
	v_cvt_pk_bf16_f32 v17, v22, v23
	v_cvt_pk_bf16_f32 v18, v26, v27
	v_cvt_pk_bf16_f32 v19, v24, v25
	global_store_dwordx4 v[38:39], v[16:19], off offset:256 sc1
	s_nop 1
	v_mul_f32_e32 v16, v21, v21
	v_mul_f32_e32 v17, v23, v23
	v_fmac_f32_e32 v16, v20, v20
	v_fmac_f32_e32 v17, v22, v22
	v_add_f32_e32 v16, v16, v17
	v_mul_f32_e32 v17, v27, v27
	v_fmac_f32_e32 v17, v26, v26
	v_add_f32_e32 v16, v17, v16
	v_mul_f32_e32 v17, v25, v25
	v_fmac_f32_e32 v17, v24, v24
	v_add_f32_e32 v16, v17, v16
	v_add_f32_e32 v16, v34, v16
	ds_bpermute_b32 v17, v149, v16
	s_waitcnt lgkmcnt(0)
	v_add_f32_e32 v16, v16, v17
	ds_bpermute_b32 v17, v148, v16
	s_and_saveexec_b64 s[6:7], s[40:41]
	s_cbranch_execz .LBB0_992
	s_waitcnt lgkmcnt(0)
	v_add_f32_e32 v18, v16, v17
	v_lshlrev_b64 v[16:17], 6, v[32:33]
	v_lshl_add_u64 v[16:17], s[48:49], 0, v[16:17]
	v_lshl_add_u64 v[16:17], s[60:61], 2, v[16:17]
	s_lshl_b32 s92, s73, 2
	v_lshl_add_u64 v[16:17], v[16:17], 0, s[92:93]
	global_store_dword v[16:17], v18, off
.LBB0_992:
	s_or_b64 exec, exec, s[6:7]
	v_add_u32_e32 v16, 0xb0, v140
	s_waitcnt lgkmcnt(0)
	v_ashrrev_i32_e32 v17, 31, v16
	v_lshlrev_b64 v[18:19], 11, v[16:17]
	v_lshl_add_u64 v[18:19], s[46:47], 0, v[18:19]
	v_lshl_add_u64 v[22:23], v[138:139], 1, v[18:19]
	global_load_dwordx4 v[18:21], v[22:23], off
	s_waitcnt vmcnt(0)
	v_lshlrev_b32_e32 v24, 16, v18
	v_and_b32_e32 v25, 0xffff0000, v18
	v_lshlrev_b32_e32 v18, 16, v19
	v_and_b32_e32 v19, 0xffff0000, v19
	v_lshlrev_b32_e32 v26, 16, v20
	v_and_b32_e32 v27, 0xffff0000, v20
	v_lshlrev_b32_e32 v20, 16, v21
	v_and_b32_e32 v21, 0xffff0000, v21
	v_pk_add_f32 v[14:15], v[14:15], v[18:19]
	v_pk_add_f32 v[12:13], v[12:13], v[24:25]
	v_pk_add_f32 v[18:19], v[10:11], v[20:21]
	v_pk_add_f32 v[20:21], v[8:9], v[26:27]
	v_cvt_pk_bf16_f32 v8, v12, v13
	v_cvt_pk_bf16_f32 v9, v14, v15
	v_cvt_pk_bf16_f32 v10, v20, v21
	v_cvt_pk_bf16_f32 v11, v18, v19
	global_store_dwordx4 v[22:23], v[8:11], off sc1
	s_nop 1
	v_mul_f32_e32 v8, v13, v13
	v_mul_f32_e32 v9, v15, v15
	v_fmac_f32_e32 v8, v12, v12
	v_fmac_f32_e32 v9, v14, v14
	v_add_f32_e32 v8, v8, v9
	v_mul_f32_e32 v9, v21, v21
	v_fmac_f32_e32 v9, v20, v20
	v_add_f32_e32 v8, v9, v8
	v_mul_f32_e32 v9, v19, v19
	v_fmac_f32_e32 v9, v18, v18
	v_add_f32_e32 v18, v9, v8
	global_load_dwordx4 v[8:11], v[22:23], off offset:256
	s_waitcnt vmcnt(0)
	v_lshlrev_b32_e32 v12, 16, v8
	v_and_b32_e32 v13, 0xffff0000, v8
	v_lshlrev_b32_e32 v8, 16, v9
	v_and_b32_e32 v9, 0xffff0000, v9
	v_lshlrev_b32_e32 v14, 16, v10
	v_and_b32_e32 v15, 0xffff0000, v10
	v_lshlrev_b32_e32 v10, 16, v11
	v_and_b32_e32 v11, 0xffff0000, v11
	v_pk_add_f32 v[6:7], v[6:7], v[8:9]
	v_pk_add_f32 v[4:5], v[4:5], v[12:13]
	v_pk_add_f32 v[8:9], v[2:3], v[10:11]
	v_pk_add_f32 v[10:11], v[0:1], v[14:15]
	v_cvt_pk_bf16_f32 v0, v4, v5
	v_cvt_pk_bf16_f32 v1, v6, v7
	v_cvt_pk_bf16_f32 v2, v10, v11
	v_cvt_pk_bf16_f32 v3, v8, v9
	global_store_dwordx4 v[22:23], v[0:3], off offset:256 sc1
	s_nop 1
	v_mul_f32_e32 v0, v5, v5
	v_mul_f32_e32 v1, v7, v7
	v_fmac_f32_e32 v0, v4, v4
	v_fmac_f32_e32 v1, v6, v6
	v_add_f32_e32 v0, v0, v1
	v_mul_f32_e32 v1, v11, v11
	v_fmac_f32_e32 v1, v10, v10
	v_add_f32_e32 v0, v1, v0
	v_mul_f32_e32 v1, v9, v9
	v_fmac_f32_e32 v1, v8, v8
	v_add_f32_e32 v0, v1, v0
	v_add_f32_e32 v0, v18, v0
	ds_bpermute_b32 v1, v149, v0
	s_waitcnt lgkmcnt(0)
	v_add_f32_e32 v0, v0, v1
	ds_bpermute_b32 v1, v148, v0
	s_and_saveexec_b64 s[6:7], s[40:41]
	s_cbranch_execz .LBB0_994
	s_waitcnt lgkmcnt(0)
	v_add_f32_e32 v2, v0, v1
	v_lshlrev_b64 v[0:1], 6, v[16:17]
	v_lshl_add_u64 v[0:1], s[48:49], 0, v[0:1]
	v_lshl_add_u64 v[0:1], s[60:61], 2, v[0:1]
	s_lshl_b32 s92, s73, 2
	v_lshl_add_u64 v[0:1], v[0:1], 0, s[92:93]
	global_store_dword v[0:1], v2, off

.LBB0_1002:
	v_lshl_add_u64 v[96:97], v[76:77], 0, s[80:81]
	s_mov_b32 s7, 0xe598000
	v_add_co_u32_e64 v108, s[40:41], s7, v96
	s_mov_b32 s7, 0xe5a8000
	s_nop 0
	v_addc_co_u32_e64 v109, s[40:41], 0, v97, s[40:41]
	v_add_co_u32_e64 v110, s[40:41], s7, v96
	v_lshl_add_u64 v[104:105], v[74:75], 0, s[80:81]
	s_nop 0
	v_addc_co_u32_e64 v111, s[40:41], 0, v97, s[40:41]
	s_mov_b32 s7, 0x1108000
	global_load_dwordx4 v[92:95], v[108:109], off offset:2048
	global_load_dwordx4 v[96:99], v[110:111], off offset:2048
	s_waitcnt vmcnt(50)
	v_add_co_u32_e64 v112, s[40:41], s7, v104
	s_mov_b32 s7, 0x1118000
	s_nop 0
	v_addc_co_u32_e64 v113, s[40:41], 0, v105, s[40:41]
	v_add_co_u32_e64 v114, s[40:41], s7, v104
	global_load_dwordx4 v[100:103], v[112:113], off offset:2048
	s_nop 0
	v_addc_co_u32_e64 v115, s[40:41], 0, v105, s[40:41]
	global_load_dwordx4 v[104:107], v[114:115], off offset:2048
	s_add_i32 s6, s6, 64
	v_lshl_add_u64 v[74:75], v[74:75], 0, s[4:5]
	v_lshl_add_u64 v[76:77], v[76:77], 0, s[4:5]
	s_cmpk_gt_u32 s6, 0x6f
	s_waitcnt vmcnt(1)
	v_mfma_f32_32x32x16_bf16 v[48:63], v[92:95], v[100:103], v[48:63]
	s_waitcnt vmcnt(0)
	v_mfma_f32_32x32x16_bf16 v[32:47], v[92:95], v[104:107], v[32:47]
	v_mfma_f32_32x32x16_bf16 v[16:31], v[96:99], v[100:103], v[16:31]
	v_mfma_f32_32x32x16_bf16 v[0:15], v[96:99], v[104:107], v[0:15]
	global_load_dwordx4 v[92:95], v[108:109], off offset:2080
	global_load_dwordx4 v[96:99], v[110:111], off offset:2080
	global_load_dwordx4 v[100:103], v[112:113], off offset:2080
	global_load_dwordx4 v[104:107], v[114:115], off offset:2080
	s_waitcnt vmcnt(1)
	v_mfma_f32_32x32x16_bf16 v[48:63], v[92:95], v[100:103], v[48:63]
	s_waitcnt vmcnt(0)
	v_mfma_f32_32x32x16_bf16 v[32:47], v[92:95], v[104:107], v[32:47]
	v_mfma_f32_32x32x16_bf16 v[16:31], v[96:99], v[100:103], v[16:31]
	v_mfma_f32_32x32x16_bf16 v[0:15], v[96:99], v[104:107], v[0:15]
	global_load_dwordx4 v[92:95], v[108:109], off offset:2112
	global_load_dwordx4 v[96:99], v[110:111], off offset:2112
	global_load_dwordx4 v[100:103], v[112:113], off offset:2112
	global_load_dwordx4 v[104:107], v[114:115], off offset:2112
	s_waitcnt vmcnt(1)
	v_mfma_f32_32x32x16_bf16 v[48:63], v[92:95], v[100:103], v[48:63]
	s_waitcnt vmcnt(0)
	v_mfma_f32_32x32x16_bf16 v[32:47], v[92:95], v[104:107], v[32:47]
	v_mfma_f32_32x32x16_bf16 v[16:31], v[96:99], v[100:103], v[16:31]
	v_mfma_f32_32x32x16_bf16 v[0:15], v[96:99], v[104:107], v[0:15]
	global_load_dwordx4 v[92:95], v[108:109], off offset:2144
	global_load_dwordx4 v[96:99], v[110:111], off offset:2144
	global_load_dwordx4 v[100:103], v[112:113], off offset:2144
	global_load_dwordx4 v[104:107], v[114:115], off offset:2144
	s_waitcnt vmcnt(1)
	v_mfma_f32_32x32x16_bf16 v[48:63], v[92:95], v[100:103], v[48:63]
	s_waitcnt vmcnt(0)
	v_mfma_f32_32x32x16_bf16 v[32:47], v[92:95], v[104:107], v[32:47]
	v_mfma_f32_32x32x16_bf16 v[16:31], v[96:99], v[100:103], v[16:31]
	v_mfma_f32_32x32x16_bf16 v[0:15], v[96:99], v[104:107], v[0:15]
	s_cbranch_scc0 .LBB0_1002
	s_nop 8
	ds_write2_b32 v83, v48, v32 offset1:32
	ds_write2_b32 v83, v49, v33 offset0:64 offset1:96
	ds_write2_b32 v83, v50, v34 offset0:128 offset1:160
	ds_write2_b32 v83, v51, v35 offset0:192 offset1:224
	v_add_u32_e32 v32, 0x800, v83
	ds_write2_b32 v32, v52, v36 offset1:32
	ds_write2_b32 v32, v53, v37 offset0:64 offset1:96
	ds_write2_b32 v32, v54, v38 offset0:128 offset1:160
	ds_write2_b32 v32, v55, v39 offset0:192 offset1:224
	v_add_u32_e32 v32, 0x1000, v83
	ds_write2_b32 v32, v56, v40 offset1:32
	ds_write2_b32 v32, v57, v41 offset0:64 offset1:96
	ds_write2_b32 v32, v58, v42 offset0:128 offset1:160
	ds_write2_b32 v32, v59, v43 offset0:192 offset1:224
	v_add_u32_e32 v32, 0x1800, v83
	ds_write2_b32 v32, v60, v44 offset1:32
	ds_write2_b32 v32, v61, v45 offset0:64 offset1:96
	ds_write2_b32 v32, v62, v46 offset0:128 offset1:160
	ds_write2_b32 v32, v63, v47 offset0:192 offset1:224
	v_add_u32_e32 v32, 0x2000, v83
	ds_write2_b32 v32, v16, v0 offset1:32
	ds_write2_b32 v32, v17, v1 offset0:64 offset1:96
	ds_write2_b32 v32, v18, v2 offset0:128 offset1:160
	ds_write2_b32 v32, v19, v3 offset0:192 offset1:224
	v_add_u32_e32 v0, 0x2800, v83
	ds_write2_b32 v0, v20, v4 offset1:32
	ds_write2_b32 v0, v21, v5 offset0:64 offset1:96
	ds_write2_b32 v0, v22, v6 offset0:128 offset1:160
	ds_write2_b32 v0, v23, v7 offset0:192 offset1:224
	v_add_u32_e32 v0, 0x3000, v83
	ds_write2_b32 v0, v24, v8 offset1:32
	ds_write2_b32 v0, v25, v9 offset0:64 offset1:96
	ds_write2_b32 v0, v26, v10 offset0:128 offset1:160
	ds_write2_b32 v0, v27, v11 offset0:192 offset1:224
	v_add_u32_e32 v0, 0x3800, v83
	ds_write2_b32 v0, v28, v12 offset1:32
	ds_write2_b32 v0, v29, v13 offset0:64 offset1:96
	ds_write2_b32 v0, v30, v14 offset0:128 offset1:160
	ds_write2_b32 v0, v31, v15 offset0:192 offset1:224
	s_waitcnt lgkmcnt(0)
	s_barrier
	ds_read_b128 v[0:3], v78
	ds_read_b128 v[4:7], v78 offset:16
	ds_read_b128 v[8:11], v78 offset:16384
	ds_read_b128 v[12:15], v78 offset:16400
	ds_read_b128 v[16:19], v78 offset:32768
	ds_read_b128 v[20:23], v78 offset:32784
	ds_read_b128 v[24:27], v78 offset:49152
	ds_read_b128 v[28:31], v78 offset:49168
	ds_read_b128 v[32:35], v84
	ds_read_b128 v[36:39], v85
	ds_read_b128 v[40:43], v86
	ds_read_b128 v[44:47], v87
	ds_read_b128 v[48:51], v88
	ds_read_b128 v[52:55], v89
	ds_read_b128 v[56:59], v90
	ds_read_b128 v[60:63], v91
	s_waitcnt lgkmcnt(14)
	v_pk_add_f32 v[0:1], v[0:1], 0 op_sel_hi:[1,0]
	v_pk_add_f32 v[4:5], v[4:5], 0 op_sel_hi:[1,0]
	s_waitcnt lgkmcnt(13)
	v_pk_add_f32 v[0:1], v[0:1], v[8:9]
	v_lshl_or_b32 v8, s42, 6, v79
	v_ashrrev_i32_e32 v9, 31, v8
	v_pk_add_f32 v[2:3], v[2:3], 0 op_sel_hi:[1,0]
	s_waitcnt lgkmcnt(12)
	v_pk_add_f32 v[4:5], v[4:5], v[12:13]
	v_lshl_add_u64 v[12:13], v[8:9], 1, v[64:65]
	v_pk_add_f32 v[2:3], v[2:3], v[10:11]
	global_load_dwordx4 v[8:11], v[12:13], off
	v_pk_add_f32 v[6:7], v[6:7], 0 op_sel_hi:[1,0]
	s_waitcnt lgkmcnt(11)
	v_pk_add_f32 v[2:3], v[2:3], v[18:19]
	v_pk_add_f32 v[6:7], v[6:7], v[14:15]
	v_pk_add_f32 v[0:1], v[0:1], v[16:17]
	s_waitcnt lgkmcnt(10)
	v_pk_add_f32 v[6:7], v[6:7], v[22:23]
	v_pk_add_f32 v[4:5], v[4:5], v[20:21]
	s_waitcnt lgkmcnt(9)
	v_pk_add_f32 v[2:3], v[2:3], v[26:27]
	v_pk_add_f32 v[0:1], v[0:1], v[24:25]
	s_waitcnt lgkmcnt(8)
	v_pk_add_f32 v[6:7], v[6:7], v[30:31]
	v_pk_add_f32 v[4:5], v[4:5], v[28:29]
	s_waitcnt lgkmcnt(7)
	v_pk_add_f32 v[2:3], v[2:3], v[34:35]
	v_pk_add_f32 v[0:1], v[0:1], v[32:33]
	s_waitcnt lgkmcnt(6)
	v_pk_add_f32 v[6:7], v[6:7], v[38:39]
	v_pk_add_f32 v[4:5], v[4:5], v[36:37]
	s_waitcnt lgkmcnt(5)
	v_pk_add_f32 v[2:3], v[2:3], v[42:43]
	v_pk_add_f32 v[0:1], v[0:1], v[40:41]
	s_waitcnt lgkmcnt(4)
	v_pk_add_f32 v[6:7], v[6:7], v[46:47]
	v_pk_add_f32 v[4:5], v[4:5], v[44:45]
	s_waitcnt lgkmcnt(3)
	v_pk_add_f32 v[2:3], v[2:3], v[50:51]
	v_pk_add_f32 v[0:1], v[0:1], v[48:49]
	s_waitcnt lgkmcnt(2)
	v_pk_add_f32 v[6:7], v[6:7], v[54:55]
	v_pk_add_f32 v[4:5], v[4:5], v[52:53]
	s_waitcnt lgkmcnt(1)
	v_pk_add_f32 v[2:3], v[2:3], v[58:59]
	v_pk_add_f32 v[0:1], v[0:1], v[56:57]
	s_waitcnt lgkmcnt(0)
	v_pk_add_f32 v[6:7], v[6:7], v[62:63]
	v_pk_add_f32 v[4:5], v[4:5], v[60:61]
	s_waitcnt vmcnt(0)
	v_lshlrev_b32_e32 v14, 16, v8
	v_and_b32_e32 v15, 0xffff0000, v8
	v_lshlrev_b32_e32 v8, 16, v9
	v_and_b32_e32 v9, 0xffff0000, v9
	v_lshlrev_b32_e32 v16, 16, v10
	v_and_b32_e32 v17, 0xffff0000, v10
	v_lshlrev_b32_e32 v10, 16, v11
	v_and_b32_e32 v11, 0xffff0000, v11
	v_pk_add_f32 v[8:9], v[2:3], v[8:9]
	v_pk_add_f32 v[14:15], v[0:1], v[14:15]
	v_pk_add_f32 v[6:7], v[6:7], v[10:11]
	v_pk_add_f32 v[4:5], v[4:5], v[16:17]
	v_cvt_pk_bf16_f32 v0, v14, v15
	v_cvt_pk_bf16_f32 v1, v8, v9
	v_cvt_pk_bf16_f32 v2, v4, v5
	v_cvt_pk_bf16_f32 v3, v6, v7
	global_store_dwordx4 v[12:13], v[0:3], off sc1
	s_nop 1
	v_mul_f32_e32 v0, v15, v15
	v_mul_f32_e32 v1, v9, v9
	v_fmac_f32_e32 v0, v14, v14
	v_fmac_f32_e32 v1, v8, v8
	v_add_f32_e32 v0, v0, v1
	v_mul_f32_e32 v1, v5, v5
	v_fmac_f32_e32 v1, v4, v4
	v_add_f32_e32 v0, v1, v0
	v_mul_f32_e32 v1, v7, v7
	v_fmac_f32_e32 v1, v6, v6
	v_add_f32_e32 v0, v1, v0
	ds_bpermute_b32 v1, v80, v0
	s_waitcnt lgkmcnt(0)
	v_add_f32_e32 v0, v0, v1
	ds_bpermute_b32 v1, v81, v0
	s_waitcnt lgkmcnt(0)
	v_add_f32_e32 v0, v0, v1
	ds_bpermute_b32 v1, v82, v0
	s_and_saveexec_b64 s[6:7], vcc
	s_cbranch_execz .LBB0_1000
	s_ashr_i32 s43, s42, 31
	s_waitcnt lgkmcnt(0)
	v_add_f32_e32 v2, v0, v1
	v_lshl_add_u64 v[0:1], s[42:43], 2, v[66:67]
	global_store_dword v[0:1], v2, off
	s_branch .LBB0_1000

.LBB0_1082:
	s_waitcnt vmcnt(3)
	v_add_u32_e32 v10, 0x1400, v32
	ds_write2_b32 v10, v14, v15 offset0:40 offset1:106
	ds_write2_b32 v10, v16, v17 offset0:172 offset1:238
	s_waitcnt lgkmcnt(0)
	s_sub_i32 s6, 0, s23
	ds_read2_b32 v[16:17], v30 offset0:33 offset1:41
	ds_read2_b32 v[18:19], v30 offset1:8
	ds_read2_b32 v[20:21], v30 offset0:66 offset1:74
	ds_read2_b32 v[22:23], v30 offset0:99 offset1:107
	ds_read2_b32 v[24:25], v30 offset0:132 offset1:140
	ds_read2_b32 v[26:27], v30 offset0:165 offset1:173
	ds_read2_b32 v[28:29], v30 offset0:198 offset1:206
	ds_read2_b32 v[34:35], v30 offset0:231 offset1:239
	s_add_i32 s6, s6, s8
	v_add_u32_e32 v36, s6, v2
	v_ashrrev_i32_e32 v37, 31, v36
	v_lshl_add_u64 v[14:15], s[60:61], 1, v[8:9]
	v_lshlrev_b64 v[40:41], 11, v[36:37]
	s_waitcnt lgkmcnt(6)
	v_cvt_pk_bf16_f32 v10, v18, v16
	s_waitcnt vmcnt(2) lgkmcnt(4)
	v_cvt_pk_bf16_f32 v11, v20, v22
	s_waitcnt vmcnt(1) lgkmcnt(2)
	v_cvt_pk_bf16_f32 v12, v24, v26
	s_waitcnt vmcnt(0) lgkmcnt(0)
	v_cvt_pk_bf16_f32 v13, v28, v34
	v_lshl_add_u64 v[40:41], v[14:15], 0, v[40:41]
	v_add_u32_e32 v16, 8, v36
	global_store_dwordx4 v[40:41], v[10:13], off sc1
	v_add_u32_e32 v40, 16, v36
	v_ashrrev_i32_e32 v41, 31, v40
	v_cvt_pk_bf16_f32 v10, v19, v17
	v_ashrrev_i32_e32 v17, 31, v16
	v_lshlrev_b64 v[16:17], 11, v[16:17]
	v_cvt_pk_bf16_f32 v11, v21, v23
	v_cvt_pk_bf16_f32 v12, v25, v27
	v_cvt_pk_bf16_f32 v13, v29, v35
	v_lshl_add_u64 v[16:17], v[14:15], 0, v[16:17]
	global_store_dwordx4 v[16:17], v[10:13], off sc1
	ds_read2_b32 v[16:17], v30 offset0:49 offset1:57
	ds_read2_b32 v[18:19], v30 offset0:16 offset1:24
	ds_read2_b32 v[20:21], v30 offset0:82 offset1:90
	ds_read2_b32 v[22:23], v30 offset0:115 offset1:123
	ds_read2_b32 v[24:25], v30 offset0:148 offset1:156
	ds_read2_b32 v[26:27], v30 offset0:181 offset1:189
	ds_read2_b32 v[28:29], v30 offset0:214 offset1:222
	ds_read2_b32 v[34:35], v30 offset0:247 offset1:255
	v_lshlrev_b64 v[40:41], 11, v[40:41]
	s_waitcnt lgkmcnt(6)
	v_cvt_pk_bf16_f32 v10, v18, v16
	s_waitcnt lgkmcnt(4)
	v_cvt_pk_bf16_f32 v11, v20, v22
	s_waitcnt lgkmcnt(2)
	v_cvt_pk_bf16_f32 v12, v24, v26
	s_waitcnt lgkmcnt(0)
	v_cvt_pk_bf16_f32 v13, v28, v34
	v_lshl_add_u64 v[40:41], v[14:15], 0, v[40:41]
	v_add_u32_e32 v16, 24, v36
	global_store_dwordx4 v[40:41], v[10:13], off sc1
	s_add_i32 s22, s22, s38
	s_add_i32 s8, s8, s9
	v_cvt_pk_bf16_f32 v10, v19, v17
	v_ashrrev_i32_e32 v17, 31, v16
	v_lshlrev_b64 v[16:17], 11, v[16:17]
	v_cvt_pk_bf16_f32 v11, v21, v23
	v_cvt_pk_bf16_f32 v12, v25, v27
	v_cvt_pk_bf16_f32 v13, v29, v35
	v_lshl_add_u64 v[14:15], v[14:15], 0, v[16:17]
	global_store_dwordx4 v[14:15], v[10:13], off sc1
	s_waitcnt lgkmcnt(0)
	s_cmpk_lt_i32 s22, 0x200
	s_cbranch_scc0 .LBB0_1098

.LBB0_1101:
	s_waitcnt vmcnt(3)
	v_add_u32_e32 v10, 0x1400, v32
	ds_write2_b32 v10, v14, v15 offset0:40 offset1:106
	ds_write2_b32 v10, v16, v17 offset0:172 offset1:238
	s_waitcnt lgkmcnt(0)
	ds_read2_b32 v[16:17], v30 offset0:33 offset1:41
	ds_read2_b32 v[18:19], v30 offset1:8
	ds_read2_b32 v[20:21], v30 offset0:66 offset1:74
	ds_read2_b32 v[22:23], v30 offset0:99 offset1:107
	ds_read2_b32 v[24:25], v30 offset0:132 offset1:140
	ds_read2_b32 v[26:27], v30 offset0:165 offset1:173
	ds_read2_b32 v[28:29], v30 offset0:198 offset1:206
	ds_read2_b32 v[34:35], v30 offset0:231 offset1:239
	v_add_u32_e32 v33, s60, v2
	v_add_u32_e32 v36, 0x400, v33
	v_ashrrev_i32_e32 v37, 31, v36
	v_lshl_add_u64 v[14:15], s[62:63], 1, v[8:9]
	v_lshlrev_b64 v[36:37], 11, v[36:37]
	s_waitcnt lgkmcnt(6)
	v_cvt_pk_bf16_f32 v10, v18, v16
	s_waitcnt vmcnt(2) lgkmcnt(4)
	v_cvt_pk_bf16_f32 v11, v20, v22
	s_waitcnt vmcnt(1) lgkmcnt(2)
	v_cvt_pk_bf16_f32 v12, v24, v26
	s_waitcnt vmcnt(0) lgkmcnt(0)
	v_cvt_pk_bf16_f32 v13, v28, v34
	v_lshl_add_u64 v[36:37], v[14:15], 0, v[36:37]
	v_add_u32_e32 v16, 0x408, v33
	global_store_dwordx4 v[36:37], v[10:13], off sc1
	v_add_u32_e32 v36, 0x410, v33
	v_ashrrev_i32_e32 v37, 31, v36
	v_cvt_pk_bf16_f32 v10, v19, v17
	v_ashrrev_i32_e32 v17, 31, v16
	v_lshlrev_b64 v[16:17], 11, v[16:17]
	v_cvt_pk_bf16_f32 v11, v21, v23
	v_cvt_pk_bf16_f32 v12, v25, v27
	v_cvt_pk_bf16_f32 v13, v29, v35
	v_lshl_add_u64 v[16:17], v[14:15], 0, v[16:17]
	global_store_dwordx4 v[16:17], v[10:13], off sc1
	ds_read2_b32 v[16:17], v30 offset0:49 offset1:57
	ds_read2_b32 v[18:19], v30 offset0:16 offset1:24
	ds_read2_b32 v[20:21], v30 offset0:82 offset1:90
	ds_read2_b32 v[22:23], v30 offset0:115 offset1:123
	ds_read2_b32 v[24:25], v30 offset0:148 offset1:156
	ds_read2_b32 v[26:27], v30 offset0:181 offset1:189
	ds_read2_b32 v[28:29], v30 offset0:214 offset1:222
	ds_read2_b32 v[34:35], v30 offset0:247 offset1:255
	v_lshlrev_b64 v[36:37], 11, v[36:37]
	s_waitcnt lgkmcnt(6)
	v_cvt_pk_bf16_f32 v10, v18, v16
	s_waitcnt lgkmcnt(4)
	v_cvt_pk_bf16_f32 v11, v20, v22
	s_waitcnt lgkmcnt(2)
	v_cvt_pk_bf16_f32 v12, v24, v26
	s_waitcnt lgkmcnt(0)
	v_cvt_pk_bf16_f32 v13, v28, v34
	v_lshl_add_u64 v[36:37], v[14:15], 0, v[36:37]
	v_add_u32_e32 v16, 0x418, v33
	global_store_dwordx4 v[36:37], v[10:13], off sc1
	s_add_i32 s22, s22, s38
	s_add_i32 s8, s8, s9
	v_cvt_pk_bf16_f32 v10, v19, v17
	v_ashrrev_i32_e32 v17, 31, v16
	v_lshlrev_b64 v[16:17], 11, v[16:17]
	v_cvt_pk_bf16_f32 v11, v21, v23
	v_cvt_pk_bf16_f32 v12, v25, v27
	v_cvt_pk_bf16_f32 v13, v29, v35
	v_lshl_add_u64 v[14:15], v[14:15], 0, v[16:17]
	global_store_dwordx4 v[14:15], v[10:13], off sc1
	s_waitcnt lgkmcnt(0)
	s_cmpk_lt_i32 s22, 0x390
	s_cbranch_scc0 .LBB0_1117

.LBB0_1120:
	s_waitcnt vmcnt(3)
	v_add_u32_e32 v18, 0x1400, v42
	ds_write2_b32 v18, v22, v23 offset0:40 offset1:106
	ds_write2_b32 v18, v24, v25 offset0:172 offset1:238
	s_waitcnt lgkmcnt(0)
	ds_read2_b32 v[24:25], v41 offset0:33 offset1:41
	ds_read2_b32 v[26:27], v41 offset1:8
	ds_read2_b32 v[28:29], v41 offset0:66 offset1:74
	ds_read2_b32 v[30:31], v41 offset0:99 offset1:107
	ds_read2_b32 v[32:33], v41 offset0:132 offset1:140
	ds_read2_b32 v[34:35], v41 offset0:165 offset1:173
	ds_read2_b32 v[36:37], v41 offset0:198 offset1:206
	ds_read2_b32 v[44:45], v41 offset0:231 offset1:239
	v_lshl_add_u64 v[22:23], s[44:45], 1, v[8:9]
	s_waitcnt lgkmcnt(6)
	v_cvt_pk_bf16_f32 v18, v26, v24
	s_waitcnt vmcnt(2) lgkmcnt(4)
	v_cvt_pk_bf16_f32 v19, v28, v30
	s_waitcnt vmcnt(1) lgkmcnt(2)
	v_cvt_pk_bf16_f32 v20, v32, v34
	s_waitcnt vmcnt(0) lgkmcnt(0)
	v_cvt_pk_bf16_f32 v21, v36, v44
	v_lshl_add_u64 v[46:47], v[22:23], 0, v[10:11]
	global_store_dwordx4 v[46:47], v[18:21], off sc1
	v_lshl_add_u64 v[46:47], v[22:23], 0, v[14:15]
	s_add_i32 s8, s8, s38
	v_cvt_pk_bf16_f32 v18, v27, v25
	v_cvt_pk_bf16_f32 v19, v29, v31
	v_cvt_pk_bf16_f32 v20, v33, v35
	v_cvt_pk_bf16_f32 v21, v37, v45
	v_lshl_add_u64 v[24:25], v[22:23], 0, v[12:13]
	global_store_dwordx4 v[24:25], v[18:21], off sc1
	ds_read2_b32 v[24:25], v41 offset0:49 offset1:57
	ds_read2_b32 v[26:27], v41 offset0:16 offset1:24
	ds_read2_b32 v[28:29], v41 offset0:82 offset1:90
	ds_read2_b32 v[30:31], v41 offset0:115 offset1:123
	ds_read2_b32 v[32:33], v41 offset0:148 offset1:156
	ds_read2_b32 v[34:35], v41 offset0:181 offset1:189
	ds_read2_b32 v[36:37], v41 offset0:214 offset1:222
	ds_read2_b32 v[44:45], v41 offset0:247 offset1:255
	v_lshl_add_u64 v[22:23], v[22:23], 0, v[16:17]
	s_waitcnt lgkmcnt(6)
	v_cvt_pk_bf16_f32 v18, v26, v24
	s_waitcnt lgkmcnt(4)
	v_cvt_pk_bf16_f32 v19, v28, v30
	s_waitcnt lgkmcnt(2)
	v_cvt_pk_bf16_f32 v20, v32, v34
	s_waitcnt lgkmcnt(0)
	v_cvt_pk_bf16_f32 v21, v36, v44
	global_store_dwordx4 v[46:47], v[18:21], off sc1
	s_add_i32 s44, s44, s9
	s_cmp_lt_i32 s8, 16
	v_cvt_pk_bf16_f32 v18, v27, v25
	v_cvt_pk_bf16_f32 v19, v29, v31
	v_cvt_pk_bf16_f32 v20, v33, v35
	v_cvt_pk_bf16_f32 v21, v37, v45
	global_store_dwordx4 v[22:23], v[18:21], off sc1
	s_waitcnt lgkmcnt(0)
	s_cbranch_scc0 .LBB0_1136

.LBB0_1138:
	v_lshl_add_u64 v[10:11], v[10:11], 0, s[24:25]
	s_mov_b64 s[8:9], 0x5fff
	v_cmp_lt_u64_e32 vcc, s[8:9], v[10:11]
	global_store_dwordx4 v[8:9], v[224:227], off sc1
	s_or_b64 s[42:43], vcc, s[42:43]
	v_lshl_add_u64 v[8:9], v[8:9], 0, s[30:31]
	s_andn2_b64 exec, exec, s[42:43]
	s_cbranch_execnz .LBB0_1138

.LBB0_1142:
	s_waitcnt vmcnt(3)
	v_add_u32_e32 v12, 0x1400, v33
	ds_write2_b32 v12, v16, v17 offset0:40 offset1:106
	ds_write2_b32 v12, v18, v19 offset0:172 offset1:238
	s_waitcnt lgkmcnt(0)
	s_sub_i32 s6, 0, s23
	ds_read2_b32 v[18:19], v7 offset0:33 offset1:41
	ds_read2_b32 v[20:21], v7 offset1:8
	ds_read2_b32 v[22:23], v7 offset0:66 offset1:74
	ds_read2_b32 v[24:25], v7 offset0:99 offset1:107
	ds_read2_b32 v[26:27], v7 offset0:132 offset1:140
	ds_read2_b32 v[28:29], v7 offset0:165 offset1:173
	ds_read2_b32 v[30:31], v7 offset0:198 offset1:206
	ds_read2_b32 v[34:35], v7 offset0:231 offset1:239
	s_add_i32 s6, s6, s8
	v_add_u32_e32 v36, s6, v2
	v_ashrrev_i32_e32 v37, 31, v36
	v_lshl_add_u64 v[16:17], s[60:61], 1, v[10:11]
	v_lshlrev_b64 v[40:41], 11, v[36:37]
	s_waitcnt lgkmcnt(6)
	v_cvt_pk_bf16_f32 v12, v20, v18
	s_waitcnt vmcnt(2) lgkmcnt(4)
	v_cvt_pk_bf16_f32 v13, v22, v24
	s_waitcnt vmcnt(1) lgkmcnt(2)
	v_cvt_pk_bf16_f32 v14, v26, v28
	s_waitcnt vmcnt(0) lgkmcnt(0)
	v_cvt_pk_bf16_f32 v15, v30, v34
	v_lshl_add_u64 v[40:41], v[16:17], 0, v[40:41]
	v_add_u32_e32 v18, 8, v36
	global_store_dwordx4 v[40:41], v[12:15], off sc1
	v_add_u32_e32 v40, 16, v36
	v_ashrrev_i32_e32 v41, 31, v40
	v_cvt_pk_bf16_f32 v12, v21, v19
	v_ashrrev_i32_e32 v19, 31, v18
	v_lshlrev_b64 v[18:19], 11, v[18:19]
	v_cvt_pk_bf16_f32 v13, v23, v25
	v_cvt_pk_bf16_f32 v14, v27, v29
	v_cvt_pk_bf16_f32 v15, v31, v35
	v_lshl_add_u64 v[18:19], v[16:17], 0, v[18:19]
	global_store_dwordx4 v[18:19], v[12:15], off sc1
	ds_read2_b32 v[18:19], v7 offset0:49 offset1:57
	ds_read2_b32 v[20:21], v7 offset0:16 offset1:24
	ds_read2_b32 v[22:23], v7 offset0:82 offset1:90
	ds_read2_b32 v[24:25], v7 offset0:115 offset1:123
	ds_read2_b32 v[26:27], v7 offset0:148 offset1:156
	ds_read2_b32 v[28:29], v7 offset0:181 offset1:189
	ds_read2_b32 v[30:31], v7 offset0:214 offset1:222
	ds_read2_b32 v[34:35], v7 offset0:247 offset1:255
	v_lshlrev_b64 v[40:41], 11, v[40:41]
	s_waitcnt lgkmcnt(6)
	v_cvt_pk_bf16_f32 v12, v20, v18
	s_waitcnt lgkmcnt(4)
	v_cvt_pk_bf16_f32 v13, v22, v24
	s_waitcnt lgkmcnt(2)
	v_cvt_pk_bf16_f32 v14, v26, v28
	s_waitcnt lgkmcnt(0)
	v_cvt_pk_bf16_f32 v15, v30, v34
	v_lshl_add_u64 v[40:41], v[16:17], 0, v[40:41]
	v_add_u32_e32 v18, 24, v36
	global_store_dwordx4 v[40:41], v[12:15], off sc1
	s_add_i32 s22, s22, s38
	s_add_i32 s8, s8, s9
	v_cvt_pk_bf16_f32 v12, v21, v19
	v_ashrrev_i32_e32 v19, 31, v18
	v_lshlrev_b64 v[18:19], 11, v[18:19]
	v_cvt_pk_bf16_f32 v13, v23, v25
	v_cvt_pk_bf16_f32 v14, v27, v29
	v_cvt_pk_bf16_f32 v15, v31, v35
	v_lshl_add_u64 v[16:17], v[16:17], 0, v[18:19]
	global_store_dwordx4 v[16:17], v[12:15], off sc1
	s_waitcnt lgkmcnt(0)
	s_cmpk_lt_i32 s22, 0x100
	s_cbranch_scc0 .LBB0_1158

.LBB0_1161:
	s_waitcnt vmcnt(3)
	v_add_u32_e32 v12, 0x1400, v33
	ds_write2_b32 v12, v16, v17 offset0:40 offset1:106
	ds_write2_b32 v12, v18, v19 offset0:172 offset1:238
	s_waitcnt lgkmcnt(0)
	s_sub_i32 s6, 0, s23
	ds_read2_b32 v[18:19], v7 offset0:33 offset1:41
	ds_read2_b32 v[20:21], v7 offset1:8
	ds_read2_b32 v[22:23], v7 offset0:66 offset1:74
	ds_read2_b32 v[24:25], v7 offset0:99 offset1:107
	ds_read2_b32 v[26:27], v7 offset0:132 offset1:140
	ds_read2_b32 v[28:29], v7 offset0:165 offset1:173
	ds_read2_b32 v[30:31], v7 offset0:198 offset1:206
	ds_read2_b32 v[34:35], v7 offset0:231 offset1:239
	s_add_i32 s6, s6, s8
	v_add_u32_e32 v36, s6, v2
	v_ashrrev_i32_e32 v37, 31, v36
	v_lshl_add_u64 v[16:17], s[56:57], 1, v[10:11]
	v_lshlrev_b64 v[40:41], 11, v[36:37]
	s_waitcnt lgkmcnt(6)
	v_cvt_pk_bf16_f32 v12, v20, v18
	s_waitcnt vmcnt(2) lgkmcnt(4)
	v_cvt_pk_bf16_f32 v13, v22, v24
	s_waitcnt vmcnt(1) lgkmcnt(2)
	v_cvt_pk_bf16_f32 v14, v26, v28
	s_waitcnt vmcnt(0) lgkmcnt(0)
	v_cvt_pk_bf16_f32 v15, v30, v34
	v_lshl_add_u64 v[40:41], v[16:17], 0, v[40:41]
	v_add_u32_e32 v18, 8, v36
	global_store_dwordx4 v[40:41], v[12:15], off sc1
	v_add_u32_e32 v40, 16, v36
	v_ashrrev_i32_e32 v41, 31, v40
	v_cvt_pk_bf16_f32 v12, v21, v19
	v_ashrrev_i32_e32 v19, 31, v18
	v_lshlrev_b64 v[18:19], 11, v[18:19]
	v_cvt_pk_bf16_f32 v13, v23, v25
	v_cvt_pk_bf16_f32 v14, v27, v29
	v_cvt_pk_bf16_f32 v15, v31, v35
	v_lshl_add_u64 v[18:19], v[16:17], 0, v[18:19]
	global_store_dwordx4 v[18:19], v[12:15], off sc1
	ds_read2_b32 v[18:19], v7 offset0:49 offset1:57
	ds_read2_b32 v[20:21], v7 offset0:16 offset1:24
	ds_read2_b32 v[22:23], v7 offset0:82 offset1:90
	ds_read2_b32 v[24:25], v7 offset0:115 offset1:123
	ds_read2_b32 v[26:27], v7 offset0:148 offset1:156
	ds_read2_b32 v[28:29], v7 offset0:181 offset1:189
	ds_read2_b32 v[30:31], v7 offset0:214 offset1:222
	ds_read2_b32 v[34:35], v7 offset0:247 offset1:255
	v_lshlrev_b64 v[40:41], 11, v[40:41]
	s_waitcnt lgkmcnt(6)
	v_cvt_pk_bf16_f32 v12, v20, v18
	s_waitcnt lgkmcnt(4)
	v_cvt_pk_bf16_f32 v13, v22, v24
	s_waitcnt lgkmcnt(2)
	v_cvt_pk_bf16_f32 v14, v26, v28
	s_waitcnt lgkmcnt(0)
	v_cvt_pk_bf16_f32 v15, v30, v34
	v_lshl_add_u64 v[40:41], v[16:17], 0, v[40:41]
	v_add_u32_e32 v18, 24, v36
	global_store_dwordx4 v[40:41], v[12:15], off sc1
	s_add_i32 s22, s22, s38
	s_add_i32 s8, s8, s9
	v_cvt_pk_bf16_f32 v12, v21, v19
	v_ashrrev_i32_e32 v19, 31, v18
	v_lshlrev_b64 v[18:19], 11, v[18:19]
	v_cvt_pk_bf16_f32 v13, v23, v25
	v_cvt_pk_bf16_f32 v14, v27, v29
	v_cvt_pk_bf16_f32 v15, v31, v35
	v_lshl_add_u64 v[16:17], v[16:17], 0, v[18:19]
	global_store_dwordx4 v[16:17], v[12:15], off sc1
	s_waitcnt lgkmcnt(0)
	s_cmpk_lt_i32 s22, 0x400
	s_cbranch_scc0 .LBB0_1177

.LBB0_1179:
	s_ashr_i32 s22, s9, 31
	s_lshr_b32 s22, s22, 27
	s_add_i32 s22, s9, s22
	s_ashr_i32 s22, s22, 5
	s_lshl_b32 s52, s22, 6
	s_lshl_b32 s22, s22, 10
	s_sub_i32 s44, s8, s22
	v_add_u32_e32 v16, s52, v0
	s_ashr_i32 s45, s44, 31
	v_ashrrev_i32_e32 v17, 31, v16
	v_lshl_add_u64 v[14:15], s[44:45], 2, v[10:11]
	v_lshlrev_b64 v[18:19], 12, v[16:17]
	v_lshl_add_u64 v[18:19], v[14:15], 0, v[18:19]
	global_load_dword v5, v[18:19], off
	v_add_u32_e32 v18, 2, v16
	v_ashrrev_i32_e32 v19, 31, v18
	v_lshlrev_b64 v[18:19], 12, v[18:19]
	v_lshl_add_u64 v[18:19], v[14:15], 0, v[18:19]
	global_load_dword v7, v[18:19], off
	v_add_u32_e32 v18, 4, v16
	v_ashrrev_i32_e32 v19, 31, v18
	v_lshlrev_b64 v[18:19], 12, v[18:19]
	v_lshl_add_u64 v[18:19], v[14:15], 0, v[18:19]
	global_load_dword v9, v[18:19], off
	v_add_u32_e32 v18, 6, v16
	v_add_u32_e32 v20, 8, v16
	v_ashrrev_i32_e32 v19, 31, v18
	v_ashrrev_i32_e32 v21, 31, v20
	v_lshlrev_b64 v[18:19], 12, v[18:19]
	v_lshlrev_b64 v[20:21], 12, v[20:21]
	v_lshl_add_u64 v[18:19], v[14:15], 0, v[18:19]
	v_lshl_add_u64 v[20:21], v[14:15], 0, v[20:21]
	global_load_dword v18, v[18:19], off
	v_add_u32_e32 v22, 12, v16
	global_load_dword v19, v[20:21], off
	v_add_u32_e32 v20, 10, v16
	v_ashrrev_i32_e32 v21, 31, v20
	v_ashrrev_i32_e32 v23, 31, v22
	v_lshlrev_b64 v[20:21], 12, v[20:21]
	v_lshlrev_b64 v[22:23], 12, v[22:23]
	v_lshl_add_u64 v[20:21], v[14:15], 0, v[20:21]
	v_lshl_add_u64 v[22:23], v[14:15], 0, v[22:23]
	global_load_dword v20, v[20:21], off
	v_add_u32_e32 v24, 16, v16
	global_load_dword v21, v[22:23], off
	v_add_u32_e32 v22, 14, v16
	v_ashrrev_i32_e32 v23, 31, v22
	v_ashrrev_i32_e32 v25, 31, v24
	v_lshlrev_b64 v[22:23], 12, v[22:23]
	v_lshlrev_b64 v[24:25], 12, v[24:25]
	v_lshl_add_u64 v[22:23], v[14:15], 0, v[22:23]
	v_lshl_add_u64 v[24:25], v[14:15], 0, v[24:25]
	global_load_dword v22, v[22:23], off
	v_add_u32_e32 v26, 20, v16
	global_load_dword v23, v[24:25], off
	v_add_u32_e32 v24, 18, v16
	v_ashrrev_i32_e32 v25, 31, v24
	v_ashrrev_i32_e32 v27, 31, v26
	v_lshlrev_b64 v[24:25], 12, v[24:25]
	v_lshlrev_b64 v[26:27], 12, v[26:27]
	v_lshl_add_u64 v[24:25], v[14:15], 0, v[24:25]
	v_lshl_add_u64 v[26:27], v[14:15], 0, v[26:27]
	global_load_dword v24, v[24:25], off
	v_add_u32_e32 v28, 24, v16
	global_load_dword v25, v[26:27], off
	v_add_u32_e32 v26, 22, v16
	v_ashrrev_i32_e32 v27, 31, v26
	v_ashrrev_i32_e32 v29, 31, v28
	v_lshlrev_b64 v[26:27], 12, v[26:27]
	v_lshlrev_b64 v[28:29], 12, v[28:29]
	v_lshl_add_u64 v[26:27], v[14:15], 0, v[26:27]
	v_lshl_add_u64 v[28:29], v[14:15], 0, v[28:29]
	global_load_dword v26, v[26:27], off
	v_add_u32_e32 v30, 28, v16
	global_load_dword v27, v[28:29], off
	v_add_u32_e32 v28, 26, v16
	v_ashrrev_i32_e32 v29, 31, v28
	v_ashrrev_i32_e32 v31, 31, v30
	v_lshlrev_b64 v[28:29], 12, v[28:29]
	v_lshlrev_b64 v[30:31], 12, v[30:31]
	v_lshl_add_u64 v[28:29], v[14:15], 0, v[28:29]
	v_lshl_add_u64 v[30:31], v[14:15], 0, v[30:31]
	global_load_dword v28, v[28:29], off
	v_add_u32_e32 v32, 32, v16
	global_load_dword v29, v[30:31], off
	v_add_u32_e32 v30, 30, v16
	v_ashrrev_i32_e32 v31, 31, v30
	v_ashrrev_i32_e32 v33, 31, v32
	v_lshlrev_b64 v[30:31], 12, v[30:31]
	v_lshlrev_b64 v[32:33], 12, v[32:33]
	v_lshl_add_u64 v[30:31], v[14:15], 0, v[30:31]
	v_lshl_add_u64 v[32:33], v[14:15], 0, v[32:33]
	global_load_dword v30, v[30:31], off
	v_add_u32_e32 v34, 36, v16
	global_load_dword v31, v[32:33], off
	v_add_u32_e32 v32, 34, v16
	v_ashrrev_i32_e32 v33, 31, v32
	v_ashrrev_i32_e32 v35, 31, v34
	v_lshlrev_b64 v[32:33], 12, v[32:33]
	v_lshlrev_b64 v[34:35], 12, v[34:35]
	v_lshl_add_u64 v[32:33], v[14:15], 0, v[32:33]
	v_lshl_add_u64 v[34:35], v[14:15], 0, v[34:35]
	global_load_dword v32, v[32:33], off
	v_add_u32_e32 v36, 40, v16
	global_load_dword v33, v[34:35], off
	v_add_u32_e32 v34, 38, v16
	v_ashrrev_i32_e32 v35, 31, v34
	v_ashrrev_i32_e32 v37, 31, v36
	v_lshlrev_b64 v[34:35], 12, v[34:35]
	v_lshlrev_b64 v[36:37], 12, v[36:37]
	v_lshl_add_u64 v[34:35], v[14:15], 0, v[34:35]
	v_lshl_add_u64 v[36:37], v[14:15], 0, v[36:37]
	global_load_dword v34, v[34:35], off
	v_add_u32_e32 v40, 44, v16
	global_load_dword v35, v[36:37], off
	v_add_u32_e32 v36, 42, v16
	v_ashrrev_i32_e32 v37, 31, v36
	v_ashrrev_i32_e32 v41, 31, v40
	v_lshlrev_b64 v[36:37], 12, v[36:37]
	v_lshlrev_b64 v[40:41], 12, v[40:41]
	v_lshl_add_u64 v[36:37], v[14:15], 0, v[36:37]
	v_lshl_add_u64 v[40:41], v[14:15], 0, v[40:41]
	global_load_dword v36, v[36:37], off
	v_add_u32_e32 v42, 48, v16
	global_load_dword v37, v[40:41], off
	v_add_u32_e32 v40, 46, v16
	v_ashrrev_i32_e32 v41, 31, v40
	v_ashrrev_i32_e32 v43, 31, v42
	v_lshlrev_b64 v[40:41], 12, v[40:41]
	v_lshlrev_b64 v[42:43], 12, v[42:43]
	v_lshl_add_u64 v[40:41], v[14:15], 0, v[40:41]
	v_lshl_add_u64 v[42:43], v[14:15], 0, v[42:43]
	global_load_dword v40, v[40:41], off
	v_add_u32_e32 v44, 52, v16
	global_load_dword v41, v[42:43], off
	v_add_u32_e32 v42, 50, v16
	v_ashrrev_i32_e32 v43, 31, v42
	v_ashrrev_i32_e32 v45, 31, v44
	v_lshlrev_b64 v[42:43], 12, v[42:43]
	v_lshlrev_b64 v[44:45], 12, v[44:45]
	v_lshl_add_u64 v[42:43], v[14:15], 0, v[42:43]
	v_lshl_add_u64 v[44:45], v[14:15], 0, v[44:45]
	global_load_dword v42, v[42:43], off
	v_add_u32_e32 v46, 56, v16
	global_load_dword v43, v[44:45], off
	v_add_u32_e32 v44, 54, v16
	v_ashrrev_i32_e32 v45, 31, v44
	v_ashrrev_i32_e32 v47, 31, v46
	v_lshlrev_b64 v[44:45], 12, v[44:45]
	v_lshlrev_b64 v[46:47], 12, v[46:47]
	v_lshl_add_u64 v[44:45], v[14:15], 0, v[44:45]
	v_lshl_add_u64 v[46:47], v[14:15], 0, v[46:47]
	global_load_dword v44, v[44:45], off
	v_add_u32_e32 v48, 60, v16
	global_load_dword v45, v[46:47], off
	v_add_u32_e32 v46, 58, v16
	v_ashrrev_i32_e32 v47, 31, v46
	v_add_u32_e32 v16, 62, v16
	v_lshlrev_b64 v[46:47], 12, v[46:47]
	v_ashrrev_i32_e32 v49, 31, v48
	v_ashrrev_i32_e32 v17, 31, v16
	v_lshl_add_u64 v[46:47], v[14:15], 0, v[46:47]
	v_lshlrev_b64 v[48:49], 12, v[48:49]
	v_lshlrev_b64 v[16:17], 12, v[16:17]
	global_load_dword v46, v[46:47], off
	v_lshl_add_u64 v[48:49], v[14:15], 0, v[48:49]
	v_lshl_add_u64 v[14:15], v[14:15], 0, v[16:17]
	global_load_dword v14, v[14:15], off
	v_add_u32_e32 v16, 0xc00, v3
	global_load_dword v47, v[48:49], off
	s_waitcnt vmcnt(30)
	ds_write2_b32 v3, v5, v7 offset1:66
	s_waitcnt vmcnt(28)
	ds_write2_b32 v3, v9, v18 offset0:132 offset1:198
	v_add_u32_e32 v5, 0x400, v3
	s_waitcnt vmcnt(26)
	ds_write2_b32 v5, v19, v20 offset0:8 offset1:74
	s_waitcnt vmcnt(24)
	ds_write2_b32 v5, v21, v22 offset0:140 offset1:206
	v_add_u32_e32 v7, 0x800, v3
	v_add_u32_e32 v17, 0x1000, v3
	v_add_u32_e32 v18, 0x1400, v3
	v_add_u32_e32 v19, 0x1800, v3
	v_add_u32_e32 v20, 0x1c00, v3
	s_waitcnt vmcnt(22)
	ds_write2_b32 v7, v23, v24 offset0:16 offset1:82
	s_waitcnt vmcnt(20)
	ds_write2_b32 v7, v25, v26 offset0:148 offset1:214
	s_waitcnt vmcnt(18)
	ds_write2_b32 v16, v27, v28 offset0:24 offset1:90
	s_waitcnt vmcnt(16)
	ds_write2_b32 v16, v29, v30 offset0:156 offset1:222
	s_waitcnt vmcnt(14)
	ds_write2_b32 v17, v31, v32 offset0:32 offset1:98
	s_waitcnt vmcnt(12)
	ds_write2_b32 v17, v33, v34 offset0:164 offset1:230
	s_waitcnt vmcnt(10)
	ds_write2_b32 v18, v35, v36 offset0:40 offset1:106
	s_waitcnt vmcnt(8)
	ds_write2_b32 v18, v37, v40 offset0:172 offset1:238
	s_waitcnt vmcnt(6)
	ds_write2_b32 v19, v41, v42 offset0:48 offset1:114
	s_waitcnt vmcnt(4)
	ds_write2_b32 v19, v43, v44 offset0:180 offset1:246
	s_waitcnt vmcnt(2)
	ds_write2_b32 v20, v45, v46 offset0:56 offset1:122
	s_waitcnt vmcnt(0)
	ds_write2_b32 v20, v47, v14 offset0:188 offset1:254
	s_waitcnt lgkmcnt(0)
	ds_read2_b32 v[26:27], v1 offset0:33 offset1:41
	ds_read2_b32 v[28:29], v1 offset1:8
	ds_read2_b32 v[30:31], v1 offset0:66 offset1:74
	ds_read2_b32 v[32:33], v1 offset0:99 offset1:107
	ds_read2_b32 v[34:35], v1 offset0:132 offset1:140
	ds_read2_b32 v[36:37], v1 offset0:165 offset1:173
	ds_read2_b32 v[40:41], v1 offset0:198 offset1:206
	ds_read2_b32 v[42:43], v1 offset0:231 offset1:239
	v_add_u32_e32 v44, s44, v2
	s_ashr_i32 s53, s52, 31
	v_ashrrev_i32_e32 v45, 31, v44
	v_lshl_add_u64 v[14:15], s[52:53], 1, v[12:13]
	v_lshlrev_b64 v[46:47], 10, v[44:45]
	s_waitcnt lgkmcnt(6)
	v_cvt_pk_bf16_f32 v22, v28, v26
	s_waitcnt lgkmcnt(4)
	v_cvt_pk_bf16_f32 v23, v30, v32
	s_waitcnt lgkmcnt(2)
	v_cvt_pk_bf16_f32 v24, v34, v36
	s_waitcnt lgkmcnt(0)
	v_cvt_pk_bf16_f32 v25, v40, v42
	v_lshl_add_u64 v[46:47], v[14:15], 0, v[46:47]
	v_add_u32_e32 v26, 8, v44
	global_store_dwordx4 v[46:47], v[22:25], off sc1
	v_add_u32_e32 v46, 16, v44
	v_ashrrev_i32_e32 v47, 31, v46
	v_cvt_pk_bf16_f32 v22, v29, v27
	v_ashrrev_i32_e32 v27, 31, v26
	v_lshlrev_b64 v[26:27], 10, v[26:27]
	v_cvt_pk_bf16_f32 v23, v31, v33
	v_cvt_pk_bf16_f32 v24, v35, v37
	v_cvt_pk_bf16_f32 v25, v41, v43
	v_lshl_add_u64 v[26:27], v[14:15], 0, v[26:27]
	global_store_dwordx4 v[26:27], v[22:25], off sc1
	ds_read2_b32 v[26:27], v1 offset0:49 offset1:57
	ds_read2_b32 v[28:29], v1 offset0:16 offset1:24
	ds_read2_b32 v[30:31], v1 offset0:82 offset1:90
	ds_read2_b32 v[32:33], v1 offset0:115 offset1:123
	ds_read2_b32 v[34:35], v1 offset0:148 offset1:156
	ds_read2_b32 v[36:37], v1 offset0:181 offset1:189
	ds_read2_b32 v[40:41], v1 offset0:214 offset1:222
	ds_read2_b32 v[42:43], v1 offset0:247 offset1:255
	v_lshlrev_b64 v[46:47], 10, v[46:47]
	s_waitcnt lgkmcnt(6)
	v_cvt_pk_bf16_f32 v22, v28, v26
	s_waitcnt lgkmcnt(4)
	v_cvt_pk_bf16_f32 v23, v30, v32
	s_waitcnt lgkmcnt(2)
	v_cvt_pk_bf16_f32 v24, v34, v36
	s_waitcnt lgkmcnt(0)
	v_cvt_pk_bf16_f32 v25, v40, v42
	v_lshl_add_u64 v[46:47], v[14:15], 0, v[46:47]
	v_add_u32_e32 v26, 24, v44
	global_store_dwordx4 v[46:47], v[22:25], off sc1
	s_add_i32 s9, s9, s38
	s_add_i32 s8, s8, s7
	v_cvt_pk_bf16_f32 v22, v29, v27
	v_ashrrev_i32_e32 v27, 31, v26
	v_lshlrev_b64 v[26:27], 10, v[26:27]
	v_cvt_pk_bf16_f32 v23, v31, v33
	v_cvt_pk_bf16_f32 v24, v35, v37
	v_cvt_pk_bf16_f32 v25, v41, v43
	v_lshl_add_u64 v[14:15], v[14:15], 0, v[26:27]
	global_store_dwordx4 v[14:15], v[22:25], off sc1
	s_waitcnt lgkmcnt(0)
	s_cmpk_lt_i32 s9, 0x100
	s_cbranch_scc1 .LBB0_1179
	s_load_dwordx2 s[8:9], s[50:51], 0xb0
	s_lshl_b64 s[22:23], s[42:43], 2
	v_lshlrev_b32_e32 v8, 2, v8
	v_mov_b32_e32 v9, v163
	v_lshlrev_b32_e32 v10, 1, v4
	s_waitcnt lgkmcnt(0)
	s_add_u32 s8, s8, s22
	s_addc_u32 s9, s9, s23
	v_mov_b32_e32 v11, v163
	v_lshl_add_u64 v[8:9], s[8:9], 0, v[8:9]
	v_lshl_add_u64 v[10:11], s[48:49], 0, v[10:11]
	s_mov_b64 s[8:9], 0x1008800
	v_lshl_add_u64 v[10:11], v[10:11], 0, s[8:9]
	v_readlane_b32 s8, v254, 6
.LBB0_1181:
	s_ashr_i32 s9, s8, 31
	s_lshr_b32 s9, s9, 27
	s_add_i32 s9, s8, s9
	s_ashr_i32 s9, s9, 5
	s_lshl_b32 s44, s9, 6
	s_lshl_b32 s9, s9, 10
	s_sub_i32 s42, s6, s9
	v_add_u32_e32 v14, s44, v0
	s_ashr_i32 s43, s42, 31
	v_ashrrev_i32_e32 v15, 31, v14
	v_lshl_add_u64 v[12:13], s[42:43], 2, v[8:9]
	v_lshlrev_b64 v[22:23], 12, v[14:15]
	v_lshl_add_u64 v[22:23], v[12:13], 0, v[22:23]
	global_load_dword v21, v[22:23], off
	v_add_u32_e32 v22, 2, v14
	v_add_u32_e32 v24, 4, v14
	v_ashrrev_i32_e32 v23, 31, v22
	v_ashrrev_i32_e32 v25, 31, v24
	v_lshlrev_b64 v[22:23], 12, v[22:23]
	v_lshlrev_b64 v[24:25], 12, v[24:25]
	v_lshl_add_u64 v[22:23], v[12:13], 0, v[22:23]
	v_lshl_add_u64 v[24:25], v[12:13], 0, v[24:25]
	global_load_dword v22, v[22:23], off
	v_add_u32_e32 v26, 8, v14
	global_load_dword v23, v[24:25], off
	v_add_u32_e32 v24, 6, v14
	v_ashrrev_i32_e32 v25, 31, v24
	v_ashrrev_i32_e32 v27, 31, v26
	v_lshlrev_b64 v[24:25], 12, v[24:25]
	v_lshlrev_b64 v[26:27], 12, v[26:27]
	v_lshl_add_u64 v[24:25], v[12:13], 0, v[24:25]
	v_lshl_add_u64 v[26:27], v[12:13], 0, v[26:27]
	global_load_dword v24, v[24:25], off
	v_add_u32_e32 v28, 12, v14
	global_load_dword v25, v[26:27], off
	v_add_u32_e32 v26, 10, v14
	v_ashrrev_i32_e32 v27, 31, v26
	v_ashrrev_i32_e32 v29, 31, v28
	v_lshlrev_b64 v[26:27], 12, v[26:27]
	v_lshlrev_b64 v[28:29], 12, v[28:29]
	v_lshl_add_u64 v[26:27], v[12:13], 0, v[26:27]
	v_lshl_add_u64 v[28:29], v[12:13], 0, v[28:29]
	global_load_dword v26, v[26:27], off
	v_add_u32_e32 v30, 16, v14
	global_load_dword v27, v[28:29], off
	v_add_u32_e32 v28, 14, v14
	v_ashrrev_i32_e32 v29, 31, v28
	v_ashrrev_i32_e32 v31, 31, v30
	v_lshlrev_b64 v[28:29], 12, v[28:29]
	v_lshlrev_b64 v[30:31], 12, v[30:31]
	v_lshl_add_u64 v[28:29], v[12:13], 0, v[28:29]
	v_lshl_add_u64 v[30:31], v[12:13], 0, v[30:31]
	global_load_dword v28, v[28:29], off
	v_add_u32_e32 v32, 20, v14
	global_load_dword v29, v[30:31], off
	v_add_u32_e32 v30, 18, v14
	v_ashrrev_i32_e32 v31, 31, v30
	v_ashrrev_i32_e32 v33, 31, v32
	v_lshlrev_b64 v[30:31], 12, v[30:31]
	v_lshlrev_b64 v[32:33], 12, v[32:33]
	v_lshl_add_u64 v[30:31], v[12:13], 0, v[30:31]
	v_lshl_add_u64 v[32:33], v[12:13], 0, v[32:33]
	global_load_dword v30, v[30:31], off
	v_add_u32_e32 v34, 24, v14
	global_load_dword v31, v[32:33], off
	v_add_u32_e32 v32, 22, v14
	v_ashrrev_i32_e32 v33, 31, v32
	v_ashrrev_i32_e32 v35, 31, v34
	v_lshlrev_b64 v[32:33], 12, v[32:33]
	v_lshlrev_b64 v[34:35], 12, v[34:35]
	v_lshl_add_u64 v[32:33], v[12:13], 0, v[32:33]
	v_lshl_add_u64 v[34:35], v[12:13], 0, v[34:35]
	global_load_dword v32, v[32:33], off
	v_add_u32_e32 v36, 28, v14
	global_load_dword v33, v[34:35], off
	v_add_u32_e32 v34, 26, v14
	v_ashrrev_i32_e32 v35, 31, v34
	v_ashrrev_i32_e32 v37, 31, v36
	v_lshlrev_b64 v[34:35], 12, v[34:35]
	v_lshlrev_b64 v[36:37], 12, v[36:37]
	v_lshl_add_u64 v[34:35], v[12:13], 0, v[34:35]
	v_lshl_add_u64 v[36:37], v[12:13], 0, v[36:37]
	global_load_dword v34, v[34:35], off
	v_add_u32_e32 v40, 32, v14
	global_load_dword v35, v[36:37], off
	v_add_u32_e32 v36, 30, v14
	v_ashrrev_i32_e32 v37, 31, v36
	v_ashrrev_i32_e32 v41, 31, v40
	v_lshlrev_b64 v[36:37], 12, v[36:37]
	v_lshlrev_b64 v[40:41], 12, v[40:41]
	v_lshl_add_u64 v[36:37], v[12:13], 0, v[36:37]
	v_lshl_add_u64 v[40:41], v[12:13], 0, v[40:41]
	global_load_dword v36, v[36:37], off
	v_add_u32_e32 v42, 36, v14
	global_load_dword v37, v[40:41], off
	v_add_u32_e32 v40, 34, v14
	v_ashrrev_i32_e32 v41, 31, v40
	v_ashrrev_i32_e32 v43, 31, v42
	v_lshlrev_b64 v[40:41], 12, v[40:41]
	v_lshlrev_b64 v[42:43], 12, v[42:43]
	v_lshl_add_u64 v[40:41], v[12:13], 0, v[40:41]
	v_lshl_add_u64 v[42:43], v[12:13], 0, v[42:43]
	global_load_dword v40, v[40:41], off
	v_add_u32_e32 v44, 40, v14
	global_load_dword v41, v[42:43], off
	v_add_u32_e32 v42, 38, v14
	v_ashrrev_i32_e32 v43, 31, v42
	v_ashrrev_i32_e32 v45, 31, v44
	v_lshlrev_b64 v[42:43], 12, v[42:43]
	v_lshlrev_b64 v[44:45], 12, v[44:45]
	v_lshl_add_u64 v[42:43], v[12:13], 0, v[42:43]
	v_lshl_add_u64 v[44:45], v[12:13], 0, v[44:45]
	global_load_dword v42, v[42:43], off
	v_add_u32_e32 v46, 44, v14
	global_load_dword v43, v[44:45], off
	v_add_u32_e32 v44, 42, v14
	v_ashrrev_i32_e32 v45, 31, v44
	v_ashrrev_i32_e32 v47, 31, v46
	v_lshlrev_b64 v[44:45], 12, v[44:45]
	v_lshlrev_b64 v[46:47], 12, v[46:47]
	v_lshl_add_u64 v[44:45], v[12:13], 0, v[44:45]
	v_lshl_add_u64 v[46:47], v[12:13], 0, v[46:47]
	global_load_dword v44, v[44:45], off
	v_add_u32_e32 v48, 48, v14
	global_load_dword v45, v[46:47], off
	v_add_u32_e32 v46, 46, v14
	v_ashrrev_i32_e32 v47, 31, v46
	v_ashrrev_i32_e32 v49, 31, v48
	v_lshlrev_b64 v[46:47], 12, v[46:47]
	v_lshlrev_b64 v[48:49], 12, v[48:49]
	v_lshl_add_u64 v[46:47], v[12:13], 0, v[46:47]
	v_lshl_add_u64 v[48:49], v[12:13], 0, v[48:49]
	global_load_dword v46, v[46:47], off
	v_add_u32_e32 v50, 52, v14
	global_load_dword v47, v[48:49], off
	v_add_u32_e32 v48, 50, v14
	v_ashrrev_i32_e32 v49, 31, v48
	v_ashrrev_i32_e32 v51, 31, v50
	v_lshlrev_b64 v[48:49], 12, v[48:49]
	v_lshlrev_b64 v[50:51], 12, v[50:51]
	v_lshl_add_u64 v[48:49], v[12:13], 0, v[48:49]
	v_lshl_add_u64 v[50:51], v[12:13], 0, v[50:51]
	global_load_dword v48, v[48:49], off
	v_add_u32_e32 v52, 56, v14
	global_load_dword v49, v[50:51], off
	v_add_u32_e32 v50, 54, v14
	v_ashrrev_i32_e32 v51, 31, v50
	v_ashrrev_i32_e32 v53, 31, v52
	v_lshlrev_b64 v[50:51], 12, v[50:51]
	v_lshlrev_b64 v[52:53], 12, v[52:53]
	v_lshl_add_u64 v[50:51], v[12:13], 0, v[50:51]
	v_lshl_add_u64 v[52:53], v[12:13], 0, v[52:53]
	global_load_dword v50, v[50:51], off
	v_add_u32_e32 v54, 60, v14
	global_load_dword v51, v[52:53], off
	v_add_u32_e32 v52, 58, v14
	v_ashrrev_i32_e32 v53, 31, v52
	v_add_u32_e32 v14, 62, v14
	v_lshlrev_b64 v[52:53], 12, v[52:53]
	v_ashrrev_i32_e32 v55, 31, v54
	v_ashrrev_i32_e32 v15, 31, v14
	v_lshl_add_u64 v[52:53], v[12:13], 0, v[52:53]
	v_lshlrev_b64 v[54:55], 12, v[54:55]
	v_lshlrev_b64 v[14:15], 12, v[14:15]
	global_load_dword v52, v[52:53], off
	v_lshl_add_u64 v[54:55], v[12:13], 0, v[54:55]
	v_lshl_add_u64 v[12:13], v[12:13], 0, v[14:15]
	global_load_dword v12, v[12:13], off
	s_ashr_i32 s45, s44, 31
	global_load_dword v53, v[54:55], off
	s_waitcnt vmcnt(30)
	ds_write2_b32 v3, v21, v22 offset1:66
	s_waitcnt vmcnt(28)
	ds_write2_b32 v3, v23, v24 offset0:132 offset1:198
	s_waitcnt vmcnt(26)
	ds_write2_b32 v5, v25, v26 offset0:8 offset1:74
	s_waitcnt vmcnt(24)
	ds_write2_b32 v5, v27, v28 offset0:140 offset1:206
	s_waitcnt vmcnt(22)
	ds_write2_b32 v7, v29, v30 offset0:16 offset1:82
	s_waitcnt vmcnt(20)
	ds_write2_b32 v7, v31, v32 offset0:148 offset1:214
	s_waitcnt vmcnt(18)
	ds_write2_b32 v16, v33, v34 offset0:24 offset1:90
	s_waitcnt vmcnt(16)
	ds_write2_b32 v16, v35, v36 offset0:156 offset1:222
	s_waitcnt vmcnt(14)
	ds_write2_b32 v17, v37, v40 offset0:32 offset1:98
	s_waitcnt vmcnt(12)
	ds_write2_b32 v17, v41, v42 offset0:164 offset1:230
	s_waitcnt vmcnt(10)
	ds_write2_b32 v18, v43, v44 offset0:40 offset1:106
	s_waitcnt vmcnt(8)
	ds_write2_b32 v18, v45, v46 offset0:172 offset1:238
	s_waitcnt vmcnt(6)
	ds_write2_b32 v19, v47, v48 offset0:48 offset1:114
	s_waitcnt vmcnt(4)
	ds_write2_b32 v19, v49, v50 offset0:180 offset1:246
	s_waitcnt vmcnt(2)
	ds_write2_b32 v20, v51, v52 offset0:56 offset1:122
	s_waitcnt vmcnt(0)
	ds_write2_b32 v20, v53, v12 offset0:188 offset1:254
	s_waitcnt lgkmcnt(0)
	ds_read2_b32 v[24:25], v1 offset0:33 offset1:41
	ds_read2_b32 v[26:27], v1 offset1:8
	ds_read2_b32 v[28:29], v1 offset0:66 offset1:74
	ds_read2_b32 v[30:31], v1 offset0:99 offset1:107
	ds_read2_b32 v[32:33], v1 offset0:132 offset1:140
	ds_read2_b32 v[34:35], v1 offset0:165 offset1:173
	ds_read2_b32 v[36:37], v1 offset0:198 offset1:206
	ds_read2_b32 v[40:41], v1 offset0:231 offset1:239
	v_add_u32_e32 v42, s42, v2
	v_ashrrev_i32_e32 v43, 31, v42
	v_lshl_add_u64 v[22:23], s[44:45], 1, v[10:11]
	v_lshlrev_b64 v[44:45], 10, v[42:43]
	s_waitcnt lgkmcnt(6)
	v_cvt_pk_bf16_f32 v12, v26, v24
	s_waitcnt lgkmcnt(4)
	v_cvt_pk_bf16_f32 v13, v28, v30
	s_waitcnt lgkmcnt(2)
	v_cvt_pk_bf16_f32 v14, v32, v34
	s_waitcnt lgkmcnt(0)
	v_cvt_pk_bf16_f32 v15, v36, v40
	v_lshl_add_u64 v[44:45], v[22:23], 0, v[44:45]
	v_add_u32_e32 v24, 8, v42
	global_store_dwordx4 v[44:45], v[12:15], off sc1
	v_add_u32_e32 v44, 16, v42
	v_ashrrev_i32_e32 v45, 31, v44
	v_cvt_pk_bf16_f32 v12, v27, v25
	v_ashrrev_i32_e32 v25, 31, v24
	v_lshlrev_b64 v[24:25], 10, v[24:25]
	v_cvt_pk_bf16_f32 v13, v29, v31
	v_cvt_pk_bf16_f32 v14, v33, v35
	v_cvt_pk_bf16_f32 v15, v37, v41
	v_lshl_add_u64 v[24:25], v[22:23], 0, v[24:25]
	global_store_dwordx4 v[24:25], v[12:15], off sc1
	ds_read2_b32 v[24:25], v1 offset0:49 offset1:57
	ds_read2_b32 v[26:27], v1 offset0:16 offset1:24
	ds_read2_b32 v[28:29], v1 offset0:82 offset1:90
	ds_read2_b32 v[30:31], v1 offset0:115 offset1:123
	ds_read2_b32 v[32:33], v1 offset0:148 offset1:156
	ds_read2_b32 v[34:35], v1 offset0:181 offset1:189
	ds_read2_b32 v[36:37], v1 offset0:214 offset1:222
	ds_read2_b32 v[40:41], v1 offset0:247 offset1:255
	v_lshlrev_b64 v[44:45], 10, v[44:45]
	s_waitcnt lgkmcnt(6)
	v_cvt_pk_bf16_f32 v12, v26, v24
	s_waitcnt lgkmcnt(4)
	v_cvt_pk_bf16_f32 v13, v28, v30
	s_waitcnt lgkmcnt(2)
	v_cvt_pk_bf16_f32 v14, v32, v34
	s_waitcnt lgkmcnt(0)
	v_cvt_pk_bf16_f32 v15, v36, v40
	v_lshl_add_u64 v[44:45], v[22:23], 0, v[44:45]
	v_add_u32_e32 v24, 24, v42
	global_store_dwordx4 v[44:45], v[12:15], off sc1
	s_add_i32 s8, s8, s38
	s_add_i32 s6, s6, s7
	v_cvt_pk_bf16_f32 v12, v27, v25
	v_ashrrev_i32_e32 v25, 31, v24
	v_lshlrev_b64 v[24:25], 10, v[24:25]
	v_cvt_pk_bf16_f32 v13, v29, v31
	v_cvt_pk_bf16_f32 v14, v33, v35
	v_cvt_pk_bf16_f32 v15, v37, v41
	v_lshl_add_u64 v[22:23], v[22:23], 0, v[24:25]
	global_store_dwordx4 v[22:23], v[12:15], off sc1
	s_waitcnt lgkmcnt(0)
	s_cmpk_lt_i32 s8, 0x100
	s_cbranch_scc1 .LBB0_1181

.LBB0_1184:
	s_ashr_i32 s9, s8, 31
	s_lshr_b32 s9, s9, 27
	s_add_i32 s9, s8, s9
	s_ashr_i32 s9, s9, 5
	s_lshl_b32 s42, s9, 6
	s_lshl_b32 s9, s9, 10
	s_sub_i32 s40, s6, s9
	v_add_u32_e32 v12, s42, v0
	s_ashr_i32 s41, s40, 31
	v_ashrrev_i32_e32 v13, 31, v12
	v_lshl_add_u64 v[10:11], s[40:41], 2, v[8:9]
	v_lshlrev_b64 v[14:15], 12, v[12:13]
	v_lshl_add_u64 v[14:15], v[10:11], 0, v[14:15]
	global_load_dword v7, v[14:15], off
	v_add_u32_e32 v14, 2, v12
	v_add_u32_e32 v16, 4, v12
	v_ashrrev_i32_e32 v15, 31, v14
	v_ashrrev_i32_e32 v17, 31, v16
	v_lshlrev_b64 v[14:15], 12, v[14:15]
	v_lshlrev_b64 v[16:17], 12, v[16:17]
	v_lshl_add_u64 v[14:15], v[10:11], 0, v[14:15]
	v_lshl_add_u64 v[16:17], v[10:11], 0, v[16:17]
	global_load_dword v14, v[14:15], off
	v_add_u32_e32 v18, 8, v12
	global_load_dword v15, v[16:17], off
	v_add_u32_e32 v16, 6, v12
	v_ashrrev_i32_e32 v17, 31, v16
	v_ashrrev_i32_e32 v19, 31, v18
	v_lshlrev_b64 v[16:17], 12, v[16:17]
	v_lshlrev_b64 v[18:19], 12, v[18:19]
	v_lshl_add_u64 v[16:17], v[10:11], 0, v[16:17]
	v_lshl_add_u64 v[18:19], v[10:11], 0, v[18:19]
	global_load_dword v16, v[16:17], off
	v_add_u32_e32 v20, 12, v12
	global_load_dword v17, v[18:19], off
	v_add_u32_e32 v18, 10, v12
	v_ashrrev_i32_e32 v19, 31, v18
	v_ashrrev_i32_e32 v21, 31, v20
	v_lshlrev_b64 v[18:19], 12, v[18:19]
	v_lshlrev_b64 v[20:21], 12, v[20:21]
	v_lshl_add_u64 v[18:19], v[10:11], 0, v[18:19]
	v_lshl_add_u64 v[20:21], v[10:11], 0, v[20:21]
	global_load_dword v18, v[18:19], off
	v_add_u32_e32 v22, 16, v12
	global_load_dword v19, v[20:21], off
	v_add_u32_e32 v20, 14, v12
	v_ashrrev_i32_e32 v21, 31, v20
	v_ashrrev_i32_e32 v23, 31, v22
	v_lshlrev_b64 v[20:21], 12, v[20:21]
	v_lshlrev_b64 v[22:23], 12, v[22:23]
	v_lshl_add_u64 v[20:21], v[10:11], 0, v[20:21]
	v_lshl_add_u64 v[22:23], v[10:11], 0, v[22:23]
	global_load_dword v20, v[20:21], off
	v_add_u32_e32 v24, 20, v12
	global_load_dword v21, v[22:23], off
	v_add_u32_e32 v22, 18, v12
	v_ashrrev_i32_e32 v23, 31, v22
	v_ashrrev_i32_e32 v25, 31, v24
	v_lshlrev_b64 v[22:23], 12, v[22:23]
	v_lshlrev_b64 v[24:25], 12, v[24:25]
	v_lshl_add_u64 v[22:23], v[10:11], 0, v[22:23]
	v_lshl_add_u64 v[24:25], v[10:11], 0, v[24:25]
	global_load_dword v22, v[22:23], off
	v_add_u32_e32 v26, 24, v12
	global_load_dword v23, v[24:25], off
	v_add_u32_e32 v24, 22, v12
	v_ashrrev_i32_e32 v25, 31, v24
	v_ashrrev_i32_e32 v27, 31, v26
	v_lshlrev_b64 v[24:25], 12, v[24:25]
	v_lshlrev_b64 v[26:27], 12, v[26:27]
	v_lshl_add_u64 v[24:25], v[10:11], 0, v[24:25]
	v_lshl_add_u64 v[26:27], v[10:11], 0, v[26:27]
	global_load_dword v24, v[24:25], off
	v_add_u32_e32 v28, 28, v12
	global_load_dword v25, v[26:27], off
	v_add_u32_e32 v26, 26, v12
	v_ashrrev_i32_e32 v27, 31, v26
	v_ashrrev_i32_e32 v29, 31, v28
	v_lshlrev_b64 v[26:27], 12, v[26:27]
	v_lshlrev_b64 v[28:29], 12, v[28:29]
	v_lshl_add_u64 v[26:27], v[10:11], 0, v[26:27]
	v_lshl_add_u64 v[28:29], v[10:11], 0, v[28:29]
	global_load_dword v26, v[26:27], off
	v_add_u32_e32 v30, 32, v12
	global_load_dword v27, v[28:29], off
	v_add_u32_e32 v28, 30, v12
	v_ashrrev_i32_e32 v29, 31, v28
	v_ashrrev_i32_e32 v31, 31, v30
	v_lshlrev_b64 v[28:29], 12, v[28:29]
	v_lshlrev_b64 v[30:31], 12, v[30:31]
	v_lshl_add_u64 v[28:29], v[10:11], 0, v[28:29]
	v_lshl_add_u64 v[30:31], v[10:11], 0, v[30:31]
	global_load_dword v28, v[28:29], off
	v_add_u32_e32 v32, 36, v12
	global_load_dword v29, v[30:31], off
	v_add_u32_e32 v30, 34, v12
	v_ashrrev_i32_e32 v31, 31, v30
	v_ashrrev_i32_e32 v33, 31, v32
	v_lshlrev_b64 v[30:31], 12, v[30:31]
	v_lshlrev_b64 v[32:33], 12, v[32:33]
	v_lshl_add_u64 v[30:31], v[10:11], 0, v[30:31]
	v_lshl_add_u64 v[32:33], v[10:11], 0, v[32:33]
	global_load_dword v30, v[30:31], off
	v_add_u32_e32 v34, 40, v12
	global_load_dword v31, v[32:33], off
	v_add_u32_e32 v32, 38, v12
	v_ashrrev_i32_e32 v33, 31, v32
	v_ashrrev_i32_e32 v35, 31, v34
	v_lshlrev_b64 v[32:33], 12, v[32:33]
	v_lshlrev_b64 v[34:35], 12, v[34:35]
	v_lshl_add_u64 v[32:33], v[10:11], 0, v[32:33]
	v_lshl_add_u64 v[34:35], v[10:11], 0, v[34:35]
	global_load_dword v32, v[32:33], off
	v_add_u32_e32 v36, 44, v12
	global_load_dword v33, v[34:35], off
	v_add_u32_e32 v34, 42, v12
	v_ashrrev_i32_e32 v35, 31, v34
	v_ashrrev_i32_e32 v37, 31, v36
	v_lshlrev_b64 v[34:35], 12, v[34:35]
	v_lshlrev_b64 v[36:37], 12, v[36:37]
	v_lshl_add_u64 v[34:35], v[10:11], 0, v[34:35]
	v_lshl_add_u64 v[36:37], v[10:11], 0, v[36:37]
	global_load_dword v34, v[34:35], off
	v_add_u32_e32 v38, 48, v12
	global_load_dword v35, v[36:37], off
	v_add_u32_e32 v36, 46, v12
	v_ashrrev_i32_e32 v37, 31, v36
	v_ashrrev_i32_e32 v39, 31, v38
	v_lshlrev_b64 v[36:37], 12, v[36:37]
	v_lshlrev_b64 v[38:39], 12, v[38:39]
	v_lshl_add_u64 v[36:37], v[10:11], 0, v[36:37]
	v_lshl_add_u64 v[38:39], v[10:11], 0, v[38:39]
	global_load_dword v36, v[36:37], off
	v_add_u32_e32 v40, 52, v12
	global_load_dword v37, v[38:39], off
	v_add_u32_e32 v38, 50, v12
	v_ashrrev_i32_e32 v39, 31, v38
	v_ashrrev_i32_e32 v41, 31, v40
	v_lshlrev_b64 v[38:39], 12, v[38:39]
	v_lshlrev_b64 v[40:41], 12, v[40:41]
	v_lshl_add_u64 v[38:39], v[10:11], 0, v[38:39]
	v_lshl_add_u64 v[40:41], v[10:11], 0, v[40:41]
	global_load_dword v38, v[38:39], off
	v_add_u32_e32 v42, 56, v12
	global_load_dword v39, v[40:41], off
	v_add_u32_e32 v40, 54, v12
	v_ashrrev_i32_e32 v41, 31, v40
	v_ashrrev_i32_e32 v43, 31, v42
	v_lshlrev_b64 v[40:41], 12, v[40:41]
	v_lshlrev_b64 v[42:43], 12, v[42:43]
	v_lshl_add_u64 v[40:41], v[10:11], 0, v[40:41]
	v_lshl_add_u64 v[42:43], v[10:11], 0, v[42:43]
	global_load_dword v40, v[40:41], off
	v_add_u32_e32 v44, 60, v12
	global_load_dword v41, v[42:43], off
	v_add_u32_e32 v42, 58, v12
	v_ashrrev_i32_e32 v43, 31, v42
	v_add_u32_e32 v12, 62, v12
	v_lshlrev_b64 v[42:43], 12, v[42:43]
	v_ashrrev_i32_e32 v45, 31, v44
	v_ashrrev_i32_e32 v13, 31, v12
	v_lshl_add_u64 v[42:43], v[10:11], 0, v[42:43]
	v_lshlrev_b64 v[44:45], 12, v[44:45]
	v_lshlrev_b64 v[12:13], 12, v[12:13]
	global_load_dword v42, v[42:43], off
	v_lshl_add_u64 v[44:45], v[10:11], 0, v[44:45]
	v_lshl_add_u64 v[10:11], v[10:11], 0, v[12:13]
	global_load_dword v10, v[10:11], off
	s_ashr_i32 s43, s42, 31
	global_load_dword v43, v[44:45], off
	s_waitcnt vmcnt(30)
	ds_write2_b32 v3, v7, v14 offset1:66
	s_waitcnt vmcnt(28)
	ds_write2_b32 v3, v15, v16 offset0:132 offset1:198
	v_add_u32_e32 v7, 0x400, v3
	s_waitcnt vmcnt(26)
	ds_write2_b32 v7, v17, v18 offset0:8 offset1:74
	s_waitcnt vmcnt(24)
	ds_write2_b32 v7, v19, v20 offset0:140 offset1:206
	v_add_u32_e32 v7, 0x800, v3
	s_waitcnt vmcnt(22)
	ds_write2_b32 v7, v21, v22 offset0:16 offset1:82
	s_waitcnt vmcnt(20)
	ds_write2_b32 v7, v23, v24 offset0:148 offset1:214
	v_add_u32_e32 v7, 0xc00, v3
	s_waitcnt vmcnt(18)
	ds_write2_b32 v7, v25, v26 offset0:24 offset1:90
	s_waitcnt vmcnt(16)
	ds_write2_b32 v7, v27, v28 offset0:156 offset1:222
	v_add_u32_e32 v7, 0x1000, v3
	s_waitcnt vmcnt(14)
	ds_write2_b32 v7, v29, v30 offset0:32 offset1:98
	s_waitcnt vmcnt(12)
	ds_write2_b32 v7, v31, v32 offset0:164 offset1:230
	v_add_u32_e32 v7, 0x1400, v3
	s_waitcnt vmcnt(10)
	ds_write2_b32 v7, v33, v34 offset0:40 offset1:106
	s_waitcnt vmcnt(8)
	ds_write2_b32 v7, v35, v36 offset0:172 offset1:238
	v_add_u32_e32 v7, 0x1800, v3
	s_waitcnt vmcnt(6)
	ds_write2_b32 v7, v37, v38 offset0:48 offset1:114
	s_waitcnt vmcnt(4)
	ds_write2_b32 v7, v39, v40 offset0:180 offset1:246
	v_add_u32_e32 v7, 0x1c00, v3
	s_waitcnt vmcnt(2)
	ds_write2_b32 v7, v41, v42 offset0:56 offset1:122
	s_waitcnt vmcnt(0)
	ds_write2_b32 v7, v43, v10 offset0:188 offset1:254
	s_waitcnt lgkmcnt(0)
	ds_read2_b32 v[16:17], v1 offset0:33 offset1:41
	ds_read2_b32 v[18:19], v1 offset1:8
	ds_read2_b32 v[20:21], v1 offset0:66 offset1:74
	ds_read2_b32 v[22:23], v1 offset0:99 offset1:107
	ds_read2_b32 v[24:25], v1 offset0:132 offset1:140
	ds_read2_b32 v[26:27], v1 offset0:165 offset1:173
	ds_read2_b32 v[28:29], v1 offset0:198 offset1:206
	ds_read2_b32 v[30:31], v1 offset0:231 offset1:239
	v_add_u32_e32 v32, s40, v2
	v_ashrrev_i32_e32 v33, 31, v32
	v_lshl_add_u64 v[14:15], s[42:43], 1, v[4:5]
	v_lshlrev_b64 v[34:35], 11, v[32:33]
	s_waitcnt lgkmcnt(6)
	v_cvt_pk_bf16_f32 v10, v18, v16
	s_waitcnt lgkmcnt(4)
	v_cvt_pk_bf16_f32 v11, v20, v22
	s_waitcnt lgkmcnt(2)
	v_cvt_pk_bf16_f32 v12, v24, v26
	s_waitcnt lgkmcnt(0)
	v_cvt_pk_bf16_f32 v13, v28, v30
	v_lshl_add_u64 v[34:35], v[14:15], 0, v[34:35]
	v_add_u32_e32 v16, 8, v32
	global_store_dwordx4 v[34:35], v[10:13], off sc1
	v_add_u32_e32 v34, 16, v32
	v_ashrrev_i32_e32 v35, 31, v34
	v_cvt_pk_bf16_f32 v10, v19, v17
	v_ashrrev_i32_e32 v17, 31, v16
	v_lshlrev_b64 v[16:17], 11, v[16:17]
	v_cvt_pk_bf16_f32 v11, v21, v23
	v_cvt_pk_bf16_f32 v12, v25, v27
	v_cvt_pk_bf16_f32 v13, v29, v31
	v_lshl_add_u64 v[16:17], v[14:15], 0, v[16:17]
	global_store_dwordx4 v[16:17], v[10:13], off sc1
	ds_read2_b32 v[16:17], v1 offset0:49 offset1:57
	ds_read2_b32 v[18:19], v1 offset0:16 offset1:24
	ds_read2_b32 v[20:21], v1 offset0:82 offset1:90
	ds_read2_b32 v[22:23], v1 offset0:115 offset1:123
	ds_read2_b32 v[24:25], v1 offset0:148 offset1:156
	ds_read2_b32 v[26:27], v1 offset0:181 offset1:189
	ds_read2_b32 v[28:29], v1 offset0:214 offset1:222
	ds_read2_b32 v[30:31], v1 offset0:247 offset1:255
	v_lshlrev_b64 v[34:35], 11, v[34:35]
	s_waitcnt lgkmcnt(6)
	v_cvt_pk_bf16_f32 v10, v18, v16
	s_waitcnt lgkmcnt(4)
	v_cvt_pk_bf16_f32 v11, v20, v22
	s_waitcnt lgkmcnt(2)
	v_cvt_pk_bf16_f32 v12, v24, v26
	s_waitcnt lgkmcnt(0)
	v_cvt_pk_bf16_f32 v13, v28, v30
	v_lshl_add_u64 v[34:35], v[14:15], 0, v[34:35]
	v_add_u32_e32 v16, 24, v32
	global_store_dwordx4 v[34:35], v[10:13], off sc1
	s_add_i32 s8, s8, s38
	s_add_i32 s6, s6, s7
	v_cvt_pk_bf16_f32 v10, v19, v17
	v_ashrrev_i32_e32 v17, 31, v16
	v_lshlrev_b64 v[16:17], 11, v[16:17]
	v_cvt_pk_bf16_f32 v11, v21, v23
	v_cvt_pk_bf16_f32 v12, v25, v27
	v_cvt_pk_bf16_f32 v13, v29, v31
	v_lshl_add_u64 v[14:15], v[14:15], 0, v[16:17]
	global_store_dwordx4 v[14:15], v[10:13], off sc1
	s_waitcnt lgkmcnt(0)
	s_cmpk_lt_i32 s8, 0x200
	s_cbranch_scc1 .LBB0_1184

.LBB0_1283:
	v_and_b32_e32 v142, 64, v215
	v_xor_b32_e32 v141, 16, v215
	v_add_u32_e32 v142, 64, v142
	v_cmp_lt_i32_e32 vcc, v141, v142
	v_lshl_add_u32 v140, s23, 8, v144
	v_lshl_or_b32 v138, s22, 8, v146
	v_cndmask_b32_e32 v141, v215, v141, vcc
	v_lshlrev_b32_e32 v149, 2, v141
	v_xor_b32_e32 v141, 32, v215
	v_cmp_lt_i32_e32 vcc, v141, v142
	v_ashrrev_i32_e32 v139, 31, v138
	s_lshl_b32 s58, s22, 2
	v_cndmask_b32_e32 v141, v215, v141, vcc
	v_lshlrev_b32_e32 v148, 2, v141
	v_ashrrev_i32_e32 v141, 31, v140
	v_lshlrev_b64 v[142:143], 11, v[140:141]
	v_lshl_add_u64 v[142:143], s[52:53], 0, v[142:143]
	v_lshl_add_u64 v[142:143], v[138:139], 1, v[142:143]
	global_load_dwordx4 v[150:153], v[142:143], off
	s_ashr_i32 s59, s58, 31
	s_waitcnt vmcnt(0)
	v_lshlrev_b32_e32 v154, 16, v150
	v_and_b32_e32 v155, 0xffff0000, v150
	v_lshlrev_b32_e32 v150, 16, v151
	v_and_b32_e32 v151, 0xffff0000, v151
	v_lshlrev_b32_e32 v156, 16, v152
	v_and_b32_e32 v157, 0xffff0000, v152
	v_lshlrev_b32_e32 v152, 16, v153
	v_and_b32_e32 v153, 0xffff0000, v153
	v_pk_add_f32 v[126:127], v[126:127], v[150:151]
	v_pk_add_f32 v[124:125], v[124:125], v[154:155]
	v_pk_add_f32 v[150:151], v[122:123], v[152:153]
	v_pk_add_f32 v[152:153], v[120:121], v[156:157]
	v_cvt_pk_bf16_f32 v120, v124, v125
	v_cvt_pk_bf16_f32 v121, v126, v127
	v_cvt_pk_bf16_f32 v122, v152, v153
	v_cvt_pk_bf16_f32 v123, v150, v151
	global_store_dwordx4 v[142:143], v[120:123], off sc1
	s_nop 1
	v_mul_f32_e32 v120, v125, v125
	v_mul_f32_e32 v121, v127, v127
	v_fmac_f32_e32 v120, v124, v124
	v_fmac_f32_e32 v121, v126, v126
	v_add_f32_e32 v120, v120, v121
	v_mul_f32_e32 v121, v153, v153
	v_fmac_f32_e32 v121, v152, v152
	v_add_f32_e32 v120, v121, v120
	v_mul_f32_e32 v121, v151, v151
	v_fmac_f32_e32 v121, v150, v150
	v_add_f32_e32 v150, v121, v120
	global_load_dwordx4 v[120:123], v[142:143], off offset:256
	s_waitcnt vmcnt(0)
	v_lshlrev_b32_e32 v124, 16, v120
	v_and_b32_e32 v125, 0xffff0000, v120
	v_lshlrev_b32_e32 v120, 16, v121
	v_and_b32_e32 v121, 0xffff0000, v121
	v_lshlrev_b32_e32 v126, 16, v122
	v_and_b32_e32 v127, 0xffff0000, v122
	v_lshlrev_b32_e32 v122, 16, v123
	v_and_b32_e32 v123, 0xffff0000, v123
	v_pk_add_f32 v[118:119], v[118:119], v[120:121]
	v_pk_add_f32 v[116:117], v[116:117], v[124:125]
	v_pk_add_f32 v[120:121], v[114:115], v[122:123]
	v_pk_add_f32 v[122:123], v[112:113], v[126:127]
	v_cvt_pk_bf16_f32 v112, v116, v117
	v_cvt_pk_bf16_f32 v113, v118, v119
	v_cvt_pk_bf16_f32 v114, v122, v123
	v_cvt_pk_bf16_f32 v115, v120, v121
	global_store_dwordx4 v[142:143], v[112:115], off offset:256 sc1
	s_nop 1
	v_mul_f32_e32 v112, v117, v117
	v_mul_f32_e32 v113, v119, v119
	v_fmac_f32_e32 v112, v116, v116
	v_fmac_f32_e32 v113, v118, v118
	v_add_f32_e32 v112, v112, v113
	v_mul_f32_e32 v113, v123, v123
	v_fmac_f32_e32 v113, v122, v122
	v_add_f32_e32 v112, v113, v112
	v_mul_f32_e32 v113, v121, v121
	v_fmac_f32_e32 v113, v120, v120
	v_add_f32_e32 v112, v113, v112
	v_add_f32_e32 v112, v150, v112
	ds_bpermute_b32 v113, v149, v112
	s_waitcnt lgkmcnt(0)
	v_add_f32_e32 v112, v112, v113
	ds_bpermute_b32 v113, v148, v112
	s_and_saveexec_b64 s[6:7], s[40:41]
	s_cbranch_execz .LBB0_1285
	s_waitcnt lgkmcnt(0)
	v_add_f32_e32 v114, v112, v113
	v_lshlrev_b64 v[112:113], 6, v[140:141]
	v_lshl_add_u64 v[112:113], s[48:49], 0, v[112:113]
	v_lshl_add_u64 v[112:113], s[58:59], 2, v[112:113]
	s_lshl_b32 s92, s72, 2
	v_lshl_add_u64 v[112:113], v[112:113], 0, s[92:93]
	global_store_dword v[112:113], v114, off
.LBB0_1285:
	s_or_b64 exec, exec, s[6:7]
	v_or_b32_e32 v112, 16, v140
	s_waitcnt lgkmcnt(0)
	v_ashrrev_i32_e32 v113, 31, v112
	v_lshlrev_b64 v[114:115], 11, v[112:113]
	v_lshl_add_u64 v[114:115], s[52:53], 0, v[114:115]
	v_lshl_add_u64 v[118:119], v[138:139], 1, v[114:115]
	global_load_dwordx4 v[114:117], v[118:119], off
	s_waitcnt vmcnt(0)
	v_lshlrev_b32_e32 v120, 16, v114
	v_and_b32_e32 v121, 0xffff0000, v114
	v_lshlrev_b32_e32 v114, 16, v115
	v_and_b32_e32 v115, 0xffff0000, v115
	v_lshlrev_b32_e32 v122, 16, v116
	v_and_b32_e32 v123, 0xffff0000, v116
	v_lshlrev_b32_e32 v116, 16, v117
	v_and_b32_e32 v117, 0xffff0000, v117
	v_pk_add_f32 v[110:111], v[110:111], v[114:115]
	v_pk_add_f32 v[108:109], v[108:109], v[120:121]
	v_pk_add_f32 v[114:115], v[106:107], v[116:117]
	v_pk_add_f32 v[116:117], v[104:105], v[122:123]
	v_cvt_pk_bf16_f32 v104, v108, v109
	v_cvt_pk_bf16_f32 v105, v110, v111
	v_cvt_pk_bf16_f32 v106, v116, v117
	v_cvt_pk_bf16_f32 v107, v114, v115
	global_store_dwordx4 v[118:119], v[104:107], off sc1
	s_nop 1
	v_mul_f32_e32 v104, v109, v109
	v_mul_f32_e32 v105, v111, v111
	v_fmac_f32_e32 v104, v108, v108
	v_fmac_f32_e32 v105, v110, v110
	v_add_f32_e32 v104, v104, v105
	v_mul_f32_e32 v105, v117, v117
	v_fmac_f32_e32 v105, v116, v116
	v_add_f32_e32 v104, v105, v104
	v_mul_f32_e32 v105, v115, v115
	v_fmac_f32_e32 v105, v114, v114
	v_add_f32_e32 v114, v105, v104
	global_load_dwordx4 v[104:107], v[118:119], off offset:256
	s_waitcnt vmcnt(0)
	v_lshlrev_b32_e32 v108, 16, v104
	v_and_b32_e32 v109, 0xffff0000, v104
	v_lshlrev_b32_e32 v104, 16, v105
	v_and_b32_e32 v105, 0xffff0000, v105
	v_lshlrev_b32_e32 v110, 16, v106
	v_and_b32_e32 v111, 0xffff0000, v106
	v_lshlrev_b32_e32 v106, 16, v107
	v_and_b32_e32 v107, 0xffff0000, v107
	v_pk_add_f32 v[102:103], v[102:103], v[104:105]
	v_pk_add_f32 v[100:101], v[100:101], v[108:109]
	v_pk_add_f32 v[104:105], v[98:99], v[106:107]
	v_pk_add_f32 v[106:107], v[96:97], v[110:111]
	v_cvt_pk_bf16_f32 v96, v100, v101
	v_cvt_pk_bf16_f32 v97, v102, v103
	v_cvt_pk_bf16_f32 v98, v106, v107
	v_cvt_pk_bf16_f32 v99, v104, v105
	global_store_dwordx4 v[118:119], v[96:99], off offset:256 sc1
	s_nop 1
	v_mul_f32_e32 v96, v101, v101
	v_mul_f32_e32 v97, v103, v103
	v_fmac_f32_e32 v96, v100, v100
	v_fmac_f32_e32 v97, v102, v102
	v_add_f32_e32 v96, v96, v97
	v_mul_f32_e32 v97, v107, v107
	v_fmac_f32_e32 v97, v106, v106
	v_add_f32_e32 v96, v97, v96
	v_mul_f32_e32 v97, v105, v105
	v_fmac_f32_e32 v97, v104, v104
	v_add_f32_e32 v96, v97, v96
	v_add_f32_e32 v96, v114, v96
	ds_bpermute_b32 v97, v149, v96
	s_waitcnt lgkmcnt(0)
	v_add_f32_e32 v96, v96, v97
	ds_bpermute_b32 v97, v148, v96
	s_and_saveexec_b64 s[6:7], s[40:41]
	s_cbranch_execz .LBB0_1287
	s_waitcnt lgkmcnt(0)
	v_add_f32_e32 v98, v96, v97
	v_lshlrev_b64 v[96:97], 6, v[112:113]
	v_lshl_add_u64 v[96:97], s[48:49], 0, v[96:97]
	v_lshl_add_u64 v[96:97], s[58:59], 2, v[96:97]
	s_lshl_b32 s92, s72, 2
	v_lshl_add_u64 v[96:97], v[96:97], 0, s[92:93]
	global_store_dword v[96:97], v98, off
.LBB0_1287:
	s_or_b64 exec, exec, s[6:7]
	v_or_b32_e32 v96, 32, v140
	s_waitcnt lgkmcnt(0)
	v_ashrrev_i32_e32 v97, 31, v96
	v_lshlrev_b64 v[98:99], 11, v[96:97]
	v_lshl_add_u64 v[98:99], s[52:53], 0, v[98:99]
	v_lshl_add_u64 v[102:103], v[138:139], 1, v[98:99]
	global_load_dwordx4 v[98:101], v[102:103], off
	s_waitcnt vmcnt(0)
	v_lshlrev_b32_e32 v104, 16, v98
	v_and_b32_e32 v105, 0xffff0000, v98
	v_lshlrev_b32_e32 v98, 16, v99
	v_and_b32_e32 v99, 0xffff0000, v99
	v_lshlrev_b32_e32 v106, 16, v100
	v_and_b32_e32 v107, 0xffff0000, v100
	v_lshlrev_b32_e32 v100, 16, v101
	v_and_b32_e32 v101, 0xffff0000, v101
	v_pk_add_f32 v[94:95], v[94:95], v[98:99]
	v_pk_add_f32 v[92:93], v[92:93], v[104:105]
	v_pk_add_f32 v[98:99], v[90:91], v[100:101]
	v_pk_add_f32 v[100:101], v[88:89], v[106:107]
	v_cvt_pk_bf16_f32 v88, v92, v93
	v_cvt_pk_bf16_f32 v89, v94, v95
	v_cvt_pk_bf16_f32 v90, v100, v101
	v_cvt_pk_bf16_f32 v91, v98, v99
	global_store_dwordx4 v[102:103], v[88:91], off sc1
	s_nop 1
	v_mul_f32_e32 v88, v93, v93
	v_mul_f32_e32 v89, v95, v95
	v_fmac_f32_e32 v88, v92, v92
	v_fmac_f32_e32 v89, v94, v94
	v_add_f32_e32 v88, v88, v89
	v_mul_f32_e32 v89, v101, v101
	v_fmac_f32_e32 v89, v100, v100
	v_add_f32_e32 v88, v89, v88
	v_mul_f32_e32 v89, v99, v99
	v_fmac_f32_e32 v89, v98, v98
	v_add_f32_e32 v98, v89, v88
	global_load_dwordx4 v[88:91], v[102:103], off offset:256
	s_waitcnt vmcnt(0)
	v_lshlrev_b32_e32 v92, 16, v88
	v_and_b32_e32 v93, 0xffff0000, v88
	v_lshlrev_b32_e32 v88, 16, v89
	v_and_b32_e32 v89, 0xffff0000, v89
	v_lshlrev_b32_e32 v94, 16, v90
	v_and_b32_e32 v95, 0xffff0000, v90
	v_lshlrev_b32_e32 v90, 16, v91
	v_and_b32_e32 v91, 0xffff0000, v91
	v_pk_add_f32 v[86:87], v[86:87], v[88:89]
	v_pk_add_f32 v[84:85], v[84:85], v[92:93]
	v_pk_add_f32 v[88:89], v[82:83], v[90:91]
	v_pk_add_f32 v[90:91], v[80:81], v[94:95]
	v_cvt_pk_bf16_f32 v80, v84, v85
	v_cvt_pk_bf16_f32 v81, v86, v87
	v_cvt_pk_bf16_f32 v82, v90, v91
	v_cvt_pk_bf16_f32 v83, v88, v89
	global_store_dwordx4 v[102:103], v[80:83], off offset:256 sc1
	s_nop 1
	v_mul_f32_e32 v80, v85, v85
	v_mul_f32_e32 v81, v87, v87
	v_fmac_f32_e32 v80, v84, v84
	v_fmac_f32_e32 v81, v86, v86
	v_add_f32_e32 v80, v80, v81
	v_mul_f32_e32 v81, v91, v91
	v_fmac_f32_e32 v81, v90, v90
	v_add_f32_e32 v80, v81, v80
	v_mul_f32_e32 v81, v89, v89
	v_fmac_f32_e32 v81, v88, v88
	v_add_f32_e32 v80, v81, v80
	v_add_f32_e32 v80, v98, v80
	ds_bpermute_b32 v81, v149, v80
	s_waitcnt lgkmcnt(0)
	v_add_f32_e32 v80, v80, v81
	ds_bpermute_b32 v81, v148, v80
	s_and_saveexec_b64 s[6:7], s[40:41]
	s_cbranch_execz .LBB0_1289
	s_waitcnt lgkmcnt(0)
	v_add_f32_e32 v82, v80, v81
	v_lshlrev_b64 v[80:81], 6, v[96:97]
	v_lshl_add_u64 v[80:81], s[48:49], 0, v[80:81]
	v_lshl_add_u64 v[80:81], s[58:59], 2, v[80:81]
	s_lshl_b32 s92, s72, 2
	v_lshl_add_u64 v[80:81], v[80:81], 0, s[92:93]
	global_store_dword v[80:81], v82, off
.LBB0_1289:
	s_or_b64 exec, exec, s[6:7]
	v_or_b32_e32 v80, 48, v140
	s_waitcnt lgkmcnt(0)
	v_ashrrev_i32_e32 v81, 31, v80
	v_lshlrev_b64 v[82:83], 11, v[80:81]
	v_lshl_add_u64 v[82:83], s[52:53], 0, v[82:83]
	v_lshl_add_u64 v[86:87], v[138:139], 1, v[82:83]
	global_load_dwordx4 v[82:85], v[86:87], off
	s_waitcnt vmcnt(0)
	v_lshlrev_b32_e32 v88, 16, v82
	v_and_b32_e32 v89, 0xffff0000, v82
	v_lshlrev_b32_e32 v82, 16, v83
	v_and_b32_e32 v83, 0xffff0000, v83
	v_lshlrev_b32_e32 v90, 16, v84
	v_and_b32_e32 v91, 0xffff0000, v84
	v_lshlrev_b32_e32 v84, 16, v85
	v_and_b32_e32 v85, 0xffff0000, v85
	v_pk_add_f32 v[78:79], v[78:79], v[82:83]
	v_pk_add_f32 v[76:77], v[76:77], v[88:89]
	v_pk_add_f32 v[82:83], v[74:75], v[84:85]
	v_pk_add_f32 v[84:85], v[72:73], v[90:91]
	v_cvt_pk_bf16_f32 v72, v76, v77
	v_cvt_pk_bf16_f32 v73, v78, v79
	v_cvt_pk_bf16_f32 v74, v84, v85
	v_cvt_pk_bf16_f32 v75, v82, v83
	global_store_dwordx4 v[86:87], v[72:75], off sc1
	s_nop 1
	v_mul_f32_e32 v72, v77, v77
	v_mul_f32_e32 v73, v79, v79
	v_fmac_f32_e32 v72, v76, v76
	v_fmac_f32_e32 v73, v78, v78
	v_add_f32_e32 v72, v72, v73
	v_mul_f32_e32 v73, v85, v85
	v_fmac_f32_e32 v73, v84, v84
	v_add_f32_e32 v72, v73, v72
	v_mul_f32_e32 v73, v83, v83
	v_fmac_f32_e32 v73, v82, v82
	v_add_f32_e32 v82, v73, v72
	global_load_dwordx4 v[72:75], v[86:87], off offset:256
	s_waitcnt vmcnt(0)
	v_lshlrev_b32_e32 v76, 16, v72
	v_and_b32_e32 v77, 0xffff0000, v72
	v_lshlrev_b32_e32 v72, 16, v73
	v_and_b32_e32 v73, 0xffff0000, v73
	v_lshlrev_b32_e32 v78, 16, v74
	v_and_b32_e32 v79, 0xffff0000, v74
	v_lshlrev_b32_e32 v74, 16, v75
	v_and_b32_e32 v75, 0xffff0000, v75
	v_pk_add_f32 v[70:71], v[70:71], v[72:73]
	v_pk_add_f32 v[68:69], v[68:69], v[76:77]
	v_pk_add_f32 v[72:73], v[66:67], v[74:75]
	v_pk_add_f32 v[74:75], v[64:65], v[78:79]
	v_cvt_pk_bf16_f32 v64, v68, v69
	v_cvt_pk_bf16_f32 v65, v70, v71
	v_cvt_pk_bf16_f32 v66, v74, v75
	v_cvt_pk_bf16_f32 v67, v72, v73
	global_store_dwordx4 v[86:87], v[64:67], off offset:256 sc1
	s_nop 1
	v_mul_f32_e32 v64, v69, v69
	v_mul_f32_e32 v65, v71, v71
	v_fmac_f32_e32 v64, v68, v68
	v_fmac_f32_e32 v65, v70, v70
	v_add_f32_e32 v64, v64, v65
	v_mul_f32_e32 v65, v75, v75
	v_fmac_f32_e32 v65, v74, v74
	v_add_f32_e32 v64, v65, v64
	v_mul_f32_e32 v65, v73, v73
	v_fmac_f32_e32 v65, v72, v72
	v_add_f32_e32 v64, v65, v64
	v_add_f32_e32 v64, v82, v64
	ds_bpermute_b32 v65, v149, v64
	s_waitcnt lgkmcnt(0)
	v_add_f32_e32 v64, v64, v65
	ds_bpermute_b32 v65, v148, v64
	s_and_saveexec_b64 s[6:7], s[40:41]
	s_cbranch_execz .LBB0_1291
	s_waitcnt lgkmcnt(0)
	v_add_f32_e32 v66, v64, v65
	v_lshlrev_b64 v[64:65], 6, v[80:81]
	v_lshl_add_u64 v[64:65], s[48:49], 0, v[64:65]
	v_lshl_add_u64 v[64:65], s[58:59], 2, v[64:65]
	s_lshl_b32 s92, s72, 2
	v_lshl_add_u64 v[64:65], v[64:65], 0, s[92:93]
	global_store_dword v[64:65], v66, off
.LBB0_1291:
	s_or_b64 exec, exec, s[6:7]
	v_add_u32_e32 v64, 0x80, v140
	s_waitcnt lgkmcnt(0)
	v_ashrrev_i32_e32 v65, 31, v64
	v_lshlrev_b64 v[66:67], 11, v[64:65]
	v_lshl_add_u64 v[66:67], s[52:53], 0, v[66:67]
	v_lshl_add_u64 v[70:71], v[138:139], 1, v[66:67]
	global_load_dwordx4 v[66:69], v[70:71], off
	s_waitcnt vmcnt(0)
	v_lshlrev_b32_e32 v72, 16, v66
	v_and_b32_e32 v73, 0xffff0000, v66
	v_lshlrev_b32_e32 v66, 16, v67
	v_and_b32_e32 v67, 0xffff0000, v67
	v_lshlrev_b32_e32 v74, 16, v68
	v_and_b32_e32 v75, 0xffff0000, v68
	v_lshlrev_b32_e32 v68, 16, v69
	v_and_b32_e32 v69, 0xffff0000, v69
	v_pk_add_f32 v[62:63], v[62:63], v[66:67]
	v_pk_add_f32 v[60:61], v[60:61], v[72:73]
	v_pk_add_f32 v[66:67], v[58:59], v[68:69]
	v_pk_add_f32 v[68:69], v[56:57], v[74:75]
	v_cvt_pk_bf16_f32 v56, v60, v61
	v_cvt_pk_bf16_f32 v57, v62, v63
	v_cvt_pk_bf16_f32 v58, v68, v69
	v_cvt_pk_bf16_f32 v59, v66, v67
	global_store_dwordx4 v[70:71], v[56:59], off sc1
	s_nop 1
	v_mul_f32_e32 v56, v61, v61
	v_mul_f32_e32 v57, v63, v63
	v_fmac_f32_e32 v56, v60, v60
	v_fmac_f32_e32 v57, v62, v62
	v_add_f32_e32 v56, v56, v57
	v_mul_f32_e32 v57, v69, v69
	v_fmac_f32_e32 v57, v68, v68
	v_add_f32_e32 v56, v57, v56
	v_mul_f32_e32 v57, v67, v67
	v_fmac_f32_e32 v57, v66, v66
	v_add_f32_e32 v66, v57, v56
	global_load_dwordx4 v[56:59], v[70:71], off offset:256
	s_waitcnt vmcnt(0)
	v_lshlrev_b32_e32 v60, 16, v56
	v_and_b32_e32 v61, 0xffff0000, v56
	v_lshlrev_b32_e32 v56, 16, v57
	v_and_b32_e32 v57, 0xffff0000, v57
	v_lshlrev_b32_e32 v62, 16, v58
	v_and_b32_e32 v63, 0xffff0000, v58
	v_lshlrev_b32_e32 v58, 16, v59
	v_and_b32_e32 v59, 0xffff0000, v59
	v_pk_add_f32 v[54:55], v[54:55], v[56:57]
	v_pk_add_f32 v[52:53], v[52:53], v[60:61]
	v_pk_add_f32 v[56:57], v[50:51], v[58:59]
	v_pk_add_f32 v[58:59], v[48:49], v[62:63]
	v_cvt_pk_bf16_f32 v48, v52, v53
	v_cvt_pk_bf16_f32 v49, v54, v55
	v_cvt_pk_bf16_f32 v50, v58, v59
	v_cvt_pk_bf16_f32 v51, v56, v57
	global_store_dwordx4 v[70:71], v[48:51], off offset:256 sc1
	s_nop 1
	v_mul_f32_e32 v48, v53, v53
	v_mul_f32_e32 v49, v55, v55
	v_fmac_f32_e32 v48, v52, v52
	v_fmac_f32_e32 v49, v54, v54
	v_add_f32_e32 v48, v48, v49
	v_mul_f32_e32 v49, v59, v59
	v_fmac_f32_e32 v49, v58, v58
	v_add_f32_e32 v48, v49, v48
	v_mul_f32_e32 v49, v57, v57
	v_fmac_f32_e32 v49, v56, v56
	v_add_f32_e32 v48, v49, v48
	v_add_f32_e32 v48, v66, v48
	ds_bpermute_b32 v49, v149, v48
	s_waitcnt lgkmcnt(0)
	v_add_f32_e32 v48, v48, v49
	ds_bpermute_b32 v49, v148, v48
	s_and_saveexec_b64 s[6:7], s[40:41]
	s_cbranch_execz .LBB0_1293
	s_waitcnt lgkmcnt(0)
	v_add_f32_e32 v50, v48, v49
	v_lshlrev_b64 v[48:49], 6, v[64:65]
	v_lshl_add_u64 v[48:49], s[48:49], 0, v[48:49]
	v_lshl_add_u64 v[48:49], s[58:59], 2, v[48:49]
	s_lshl_b32 s92, s72, 2
	v_lshl_add_u64 v[48:49], v[48:49], 0, s[92:93]
	global_store_dword v[48:49], v50, off
.LBB0_1293:
	s_or_b64 exec, exec, s[6:7]
	v_add_u32_e32 v48, 0x90, v140
	s_waitcnt lgkmcnt(0)
	v_ashrrev_i32_e32 v49, 31, v48
	v_lshlrev_b64 v[50:51], 11, v[48:49]
	v_lshl_add_u64 v[50:51], s[52:53], 0, v[50:51]
	v_lshl_add_u64 v[54:55], v[138:139], 1, v[50:51]
	global_load_dwordx4 v[50:53], v[54:55], off
	s_waitcnt vmcnt(0)
	v_lshlrev_b32_e32 v56, 16, v50
	v_and_b32_e32 v57, 0xffff0000, v50
	v_lshlrev_b32_e32 v50, 16, v51
	v_and_b32_e32 v51, 0xffff0000, v51
	v_lshlrev_b32_e32 v58, 16, v52
	v_and_b32_e32 v59, 0xffff0000, v52
	v_lshlrev_b32_e32 v52, 16, v53
	v_and_b32_e32 v53, 0xffff0000, v53
	v_pk_add_f32 v[46:47], v[46:47], v[50:51]
	v_pk_add_f32 v[44:45], v[44:45], v[56:57]
	v_pk_add_f32 v[50:51], v[42:43], v[52:53]
	v_pk_add_f32 v[52:53], v[40:41], v[58:59]
	v_cvt_pk_bf16_f32 v40, v44, v45
	v_cvt_pk_bf16_f32 v41, v46, v47
	v_cvt_pk_bf16_f32 v42, v52, v53
	v_cvt_pk_bf16_f32 v43, v50, v51
	global_store_dwordx4 v[54:55], v[40:43], off sc1
	s_nop 1
	v_mul_f32_e32 v40, v45, v45
	v_mul_f32_e32 v41, v47, v47
	v_fmac_f32_e32 v40, v44, v44
	v_fmac_f32_e32 v41, v46, v46
	v_add_f32_e32 v40, v40, v41
	v_mul_f32_e32 v41, v53, v53
	v_fmac_f32_e32 v41, v52, v52
	v_add_f32_e32 v40, v41, v40
	v_mul_f32_e32 v41, v51, v51
	v_fmac_f32_e32 v41, v50, v50
	v_add_f32_e32 v50, v41, v40
	global_load_dwordx4 v[40:43], v[54:55], off offset:256
	s_waitcnt vmcnt(0)
	v_lshlrev_b32_e32 v44, 16, v40
	v_and_b32_e32 v45, 0xffff0000, v40
	v_lshlrev_b32_e32 v40, 16, v41
	v_and_b32_e32 v41, 0xffff0000, v41
	v_lshlrev_b32_e32 v46, 16, v42
	v_and_b32_e32 v47, 0xffff0000, v42
	v_lshlrev_b32_e32 v42, 16, v43
	v_and_b32_e32 v43, 0xffff0000, v43
	v_pk_add_f32 v[38:39], v[38:39], v[40:41]
	v_pk_add_f32 v[36:37], v[36:37], v[44:45]
	v_pk_add_f32 v[40:41], v[34:35], v[42:43]
	v_pk_add_f32 v[42:43], v[32:33], v[46:47]
	v_cvt_pk_bf16_f32 v32, v36, v37
	v_cvt_pk_bf16_f32 v33, v38, v39
	v_cvt_pk_bf16_f32 v34, v42, v43
	v_cvt_pk_bf16_f32 v35, v40, v41
	global_store_dwordx4 v[54:55], v[32:35], off offset:256 sc1
	s_nop 1
	v_mul_f32_e32 v32, v37, v37
	v_mul_f32_e32 v33, v39, v39
	v_fmac_f32_e32 v32, v36, v36
	v_fmac_f32_e32 v33, v38, v38
	v_add_f32_e32 v32, v32, v33
	v_mul_f32_e32 v33, v43, v43
	v_fmac_f32_e32 v33, v42, v42
	v_add_f32_e32 v32, v33, v32
	v_mul_f32_e32 v33, v41, v41
	v_fmac_f32_e32 v33, v40, v40
	v_add_f32_e32 v32, v33, v32
	v_add_f32_e32 v32, v50, v32
	ds_bpermute_b32 v33, v149, v32
	s_waitcnt lgkmcnt(0)
	v_add_f32_e32 v32, v32, v33
	ds_bpermute_b32 v33, v148, v32
	s_and_saveexec_b64 s[6:7], s[40:41]
	s_cbranch_execz .LBB0_1295
	s_waitcnt lgkmcnt(0)
	v_add_f32_e32 v34, v32, v33
	v_lshlrev_b64 v[32:33], 6, v[48:49]
	v_lshl_add_u64 v[32:33], s[48:49], 0, v[32:33]
	v_lshl_add_u64 v[32:33], s[58:59], 2, v[32:33]
	s_lshl_b32 s92, s72, 2
	v_lshl_add_u64 v[32:33], v[32:33], 0, s[92:93]
	global_store_dword v[32:33], v34, off
.LBB0_1295:
	s_or_b64 exec, exec, s[6:7]
	v_add_u32_e32 v32, 0xa0, v140
	s_waitcnt lgkmcnt(0)
	v_ashrrev_i32_e32 v33, 31, v32
	v_lshlrev_b64 v[34:35], 11, v[32:33]
	v_lshl_add_u64 v[34:35], s[52:53], 0, v[34:35]
	v_lshl_add_u64 v[38:39], v[138:139], 1, v[34:35]
	global_load_dwordx4 v[34:37], v[38:39], off
	s_waitcnt vmcnt(0)
	v_lshlrev_b32_e32 v40, 16, v34
	v_and_b32_e32 v41, 0xffff0000, v34
	v_lshlrev_b32_e32 v34, 16, v35
	v_and_b32_e32 v35, 0xffff0000, v35
	v_lshlrev_b32_e32 v42, 16, v36
	v_and_b32_e32 v43, 0xffff0000, v36
	v_lshlrev_b32_e32 v36, 16, v37
	v_and_b32_e32 v37, 0xffff0000, v37
	v_pk_add_f32 v[30:31], v[30:31], v[34:35]
	v_pk_add_f32 v[28:29], v[28:29], v[40:41]
	v_pk_add_f32 v[34:35], v[26:27], v[36:37]
	v_pk_add_f32 v[36:37], v[24:25], v[42:43]
	v_cvt_pk_bf16_f32 v24, v28, v29
	v_cvt_pk_bf16_f32 v25, v30, v31
	v_cvt_pk_bf16_f32 v26, v36, v37
	v_cvt_pk_bf16_f32 v27, v34, v35
	global_store_dwordx4 v[38:39], v[24:27], off sc1
	s_nop 1
	v_mul_f32_e32 v24, v29, v29
	v_mul_f32_e32 v25, v31, v31
	v_fmac_f32_e32 v24, v28, v28
	v_fmac_f32_e32 v25, v30, v30
	v_add_f32_e32 v24, v24, v25
	v_mul_f32_e32 v25, v37, v37
	v_fmac_f32_e32 v25, v36, v36
	v_add_f32_e32 v24, v25, v24
	v_mul_f32_e32 v25, v35, v35
	v_fmac_f32_e32 v25, v34, v34
	v_add_f32_e32 v34, v25, v24
	global_load_dwordx4 v[24:27], v[38:39], off offset:256
	s_waitcnt vmcnt(0)
	v_lshlrev_b32_e32 v28, 16, v24
	v_and_b32_e32 v29, 0xffff0000, v24
	v_lshlrev_b32_e32 v24, 16, v25
	v_and_b32_e32 v25, 0xffff0000, v25
	v_lshlrev_b32_e32 v30, 16, v26
	v_and_b32_e32 v31, 0xffff0000, v26
	v_lshlrev_b32_e32 v26, 16, v27
	v_and_b32_e32 v27, 0xffff0000, v27
	v_pk_add_f32 v[22:23], v[22:23], v[24:25]
	v_pk_add_f32 v[20:21], v[20:21], v[28:29]
	v_pk_add_f32 v[24:25], v[18:19], v[26:27]
	v_pk_add_f32 v[26:27], v[16:17], v[30:31]
	v_cvt_pk_bf16_f32 v16, v20, v21
	v_cvt_pk_bf16_f32 v17, v22, v23
	v_cvt_pk_bf16_f32 v18, v26, v27
	v_cvt_pk_bf16_f32 v19, v24, v25
	global_store_dwordx4 v[38:39], v[16:19], off offset:256 sc1
	s_nop 1
	v_mul_f32_e32 v16, v21, v21
	v_mul_f32_e32 v17, v23, v23
	v_fmac_f32_e32 v16, v20, v20
	v_fmac_f32_e32 v17, v22, v22
	v_add_f32_e32 v16, v16, v17
	v_mul_f32_e32 v17, v27, v27
	v_fmac_f32_e32 v17, v26, v26
	v_add_f32_e32 v16, v17, v16
	v_mul_f32_e32 v17, v25, v25
	v_fmac_f32_e32 v17, v24, v24
	v_add_f32_e32 v16, v17, v16
	v_add_f32_e32 v16, v34, v16
	ds_bpermute_b32 v17, v149, v16
	s_waitcnt lgkmcnt(0)
	v_add_f32_e32 v16, v16, v17
	ds_bpermute_b32 v17, v148, v16
	s_and_saveexec_b64 s[6:7], s[40:41]
	s_cbranch_execz .LBB0_1297
	s_waitcnt lgkmcnt(0)
	v_add_f32_e32 v18, v16, v17
	v_lshlrev_b64 v[16:17], 6, v[32:33]
	v_lshl_add_u64 v[16:17], s[48:49], 0, v[16:17]
	v_lshl_add_u64 v[16:17], s[58:59], 2, v[16:17]
	s_lshl_b32 s92, s72, 2
	v_lshl_add_u64 v[16:17], v[16:17], 0, s[92:93]
	global_store_dword v[16:17], v18, off
.LBB0_1297:
	s_or_b64 exec, exec, s[6:7]
	v_add_u32_e32 v16, 0xb0, v140
	s_waitcnt lgkmcnt(0)
	v_ashrrev_i32_e32 v17, 31, v16
	v_lshlrev_b64 v[18:19], 11, v[16:17]
	v_lshl_add_u64 v[18:19], s[52:53], 0, v[18:19]
	v_lshl_add_u64 v[22:23], v[138:139], 1, v[18:19]
	global_load_dwordx4 v[18:21], v[22:23], off
	s_waitcnt vmcnt(0)
	v_lshlrev_b32_e32 v24, 16, v18
	v_and_b32_e32 v25, 0xffff0000, v18
	v_lshlrev_b32_e32 v18, 16, v19
	v_and_b32_e32 v19, 0xffff0000, v19
	v_lshlrev_b32_e32 v26, 16, v20
	v_and_b32_e32 v27, 0xffff0000, v20
	v_lshlrev_b32_e32 v20, 16, v21
	v_and_b32_e32 v21, 0xffff0000, v21
	v_pk_add_f32 v[14:15], v[14:15], v[18:19]
	v_pk_add_f32 v[12:13], v[12:13], v[24:25]
	v_pk_add_f32 v[18:19], v[10:11], v[20:21]
	v_pk_add_f32 v[20:21], v[8:9], v[26:27]
	v_cvt_pk_bf16_f32 v8, v12, v13
	v_cvt_pk_bf16_f32 v9, v14, v15
	v_cvt_pk_bf16_f32 v10, v20, v21
	v_cvt_pk_bf16_f32 v11, v18, v19
	global_store_dwordx4 v[22:23], v[8:11], off sc1
	s_nop 1
	v_mul_f32_e32 v8, v13, v13
	v_mul_f32_e32 v9, v15, v15
	v_fmac_f32_e32 v8, v12, v12
	v_fmac_f32_e32 v9, v14, v14
	v_add_f32_e32 v8, v8, v9
	v_mul_f32_e32 v9, v21, v21
	v_fmac_f32_e32 v9, v20, v20
	v_add_f32_e32 v8, v9, v8
	v_mul_f32_e32 v9, v19, v19
	v_fmac_f32_e32 v9, v18, v18
	v_add_f32_e32 v18, v9, v8
	global_load_dwordx4 v[8:11], v[22:23], off offset:256
	s_waitcnt vmcnt(0)
	v_lshlrev_b32_e32 v12, 16, v8
	v_and_b32_e32 v13, 0xffff0000, v8
	v_lshlrev_b32_e32 v8, 16, v9
	v_and_b32_e32 v9, 0xffff0000, v9
	v_lshlrev_b32_e32 v14, 16, v10
	v_and_b32_e32 v15, 0xffff0000, v10
	v_lshlrev_b32_e32 v10, 16, v11
	v_and_b32_e32 v11, 0xffff0000, v11
	v_pk_add_f32 v[6:7], v[6:7], v[8:9]
	v_pk_add_f32 v[4:5], v[4:5], v[12:13]
	v_pk_add_f32 v[8:9], v[2:3], v[10:11]
	v_pk_add_f32 v[10:11], v[0:1], v[14:15]
	v_cvt_pk_bf16_f32 v0, v4, v5
	v_cvt_pk_bf16_f32 v1, v6, v7
	v_cvt_pk_bf16_f32 v2, v10, v11
	v_cvt_pk_bf16_f32 v3, v8, v9
	global_store_dwordx4 v[22:23], v[0:3], off offset:256 sc1
	s_nop 1
	v_mul_f32_e32 v0, v5, v5
	v_mul_f32_e32 v1, v7, v7
	v_fmac_f32_e32 v0, v4, v4
	v_fmac_f32_e32 v1, v6, v6
	v_add_f32_e32 v0, v0, v1
	v_mul_f32_e32 v1, v11, v11
	v_fmac_f32_e32 v1, v10, v10
	v_add_f32_e32 v0, v1, v0
	v_mul_f32_e32 v1, v9, v9
	v_fmac_f32_e32 v1, v8, v8
	v_add_f32_e32 v0, v1, v0
	v_add_f32_e32 v0, v18, v0
	ds_bpermute_b32 v1, v149, v0
	s_waitcnt lgkmcnt(0)
	v_add_f32_e32 v0, v0, v1
	ds_bpermute_b32 v1, v148, v0
	s_and_saveexec_b64 s[6:7], s[40:41]
	s_cbranch_execz .LBB0_1299
	s_waitcnt lgkmcnt(0)
	v_add_f32_e32 v2, v0, v1
	v_lshlrev_b64 v[0:1], 6, v[16:17]
	v_lshl_add_u64 v[0:1], s[48:49], 0, v[0:1]
	v_lshl_add_u64 v[0:1], s[58:59], 2, v[0:1]
	s_lshl_b32 s92, s72, 2
	v_lshl_add_u64 v[0:1], v[0:1], 0, s[92:93]
	global_store_dword v[0:1], v2, off

.LBB0_1306:
	v_add_u32_e32 v0, s8, v120
	v_mad_i64_i32 v[116:117], s[6:7], v0, s16, v[66:67]
	v_add_co_u32_e32 v118, vcc, 0x2c000, v116
	global_load_dwordx4 v[0:3], v[64:65], off
	global_load_dwordx4 v[16:19], v[68:69], off
	global_load_dwordx4 v[4:7], v[116:117], off
	v_addc_co_u32_e32 v119, vcc, 0, v117, vcc
	global_load_dwordx4 v[20:23], v[118:119], off
	global_load_dwordx4 v[136:139], v[64:65], off offset:32
	global_load_dwordx4 v[140:143], v[74:75], off
	global_load_dwordx4 v[144:147], v[116:117], off offset:32
	global_load_dwordx4 v[148:151], v[118:119], off offset:32
	s_waitcnt vmcnt(5)
	v_mfma_f32_32x32x16_bf16 v[32:47], v[0:3], v[4:7], 0
	s_waitcnt vmcnt(4)
	v_mfma_f32_32x32x16_bf16 v[48:63], v[0:3], v[20:23], 0
	v_mfma_f32_32x32x16_bf16 v[0:15], v[16:19], v[4:7], 0
	v_mfma_f32_32x32x16_bf16 v[16:31], v[16:19], v[20:23], 0
	s_waitcnt vmcnt(1)
	v_mfma_f32_32x32x16_bf16 v[32:47], v[136:139], v[144:147], v[32:47]
	s_waitcnt vmcnt(0)
	v_mfma_f32_32x32x16_bf16 v[48:63], v[136:139], v[148:151], v[48:63]
	v_mfma_f32_32x32x16_bf16 v[0:15], v[140:143], v[144:147], v[0:15]
	v_mfma_f32_32x32x16_bf16 v[16:31], v[140:143], v[148:151], v[16:31]
	global_load_dwordx4 v[136:139], v[64:65], off offset:64
	global_load_dwordx4 v[140:143], v[76:77], off
	global_load_dwordx4 v[144:147], v[116:117], off offset:64
	global_load_dwordx4 v[148:151], v[118:119], off offset:64
	s_waitcnt vmcnt(1)
	v_mfma_f32_32x32x16_bf16 v[32:47], v[136:139], v[144:147], v[32:47]
	s_waitcnt vmcnt(0)
	v_mfma_f32_32x32x16_bf16 v[48:63], v[136:139], v[148:151], v[48:63]
	v_mfma_f32_32x32x16_bf16 v[0:15], v[140:143], v[144:147], v[0:15]
	v_mfma_f32_32x32x16_bf16 v[16:31], v[140:143], v[148:151], v[16:31]
	global_load_dwordx4 v[136:139], v[64:65], off offset:96
	global_load_dwordx4 v[140:143], v[78:79], off
	global_load_dwordx4 v[144:147], v[116:117], off offset:96
	global_load_dwordx4 v[148:151], v[118:119], off offset:96
	s_waitcnt vmcnt(1)
	v_mfma_f32_32x32x16_bf16 v[32:47], v[136:139], v[144:147], v[32:47]
	s_waitcnt vmcnt(0)
	v_mfma_f32_32x32x16_bf16 v[48:63], v[136:139], v[148:151], v[48:63]
	v_mfma_f32_32x32x16_bf16 v[0:15], v[140:143], v[144:147], v[0:15]
	v_mfma_f32_32x32x16_bf16 v[16:31], v[140:143], v[148:151], v[16:31]
	global_load_dwordx4 v[136:139], v[64:65], off offset:128
	global_load_dwordx4 v[140:143], v[80:81], off
	global_load_dwordx4 v[144:147], v[116:117], off offset:128
	global_load_dwordx4 v[148:151], v[118:119], off offset:128
	s_waitcnt vmcnt(1)
	v_mfma_f32_32x32x16_bf16 v[32:47], v[136:139], v[144:147], v[32:47]
	s_waitcnt vmcnt(0)
	v_mfma_f32_32x32x16_bf16 v[48:63], v[136:139], v[148:151], v[48:63]
	v_mfma_f32_32x32x16_bf16 v[0:15], v[140:143], v[144:147], v[0:15]
	v_mfma_f32_32x32x16_bf16 v[16:31], v[140:143], v[148:151], v[16:31]
	global_load_dwordx4 v[136:139], v[64:65], off offset:160
	global_load_dwordx4 v[140:143], v[82:83], off
	global_load_dwordx4 v[144:147], v[116:117], off offset:160
	global_load_dwordx4 v[148:151], v[118:119], off offset:160
	s_waitcnt vmcnt(1)
	v_mfma_f32_32x32x16_bf16 v[32:47], v[136:139], v[144:147], v[32:47]
	s_waitcnt vmcnt(0)
	v_mfma_f32_32x32x16_bf16 v[48:63], v[136:139], v[148:151], v[48:63]
	v_mfma_f32_32x32x16_bf16 v[0:15], v[140:143], v[144:147], v[0:15]
	v_mfma_f32_32x32x16_bf16 v[16:31], v[140:143], v[148:151], v[16:31]
	global_load_dwordx4 v[136:139], v[64:65], off offset:192
	global_load_dwordx4 v[140:143], v[84:85], off
	global_load_dwordx4 v[144:147], v[116:117], off offset:192
	global_load_dwordx4 v[148:151], v[118:119], off offset:192
	s_waitcnt vmcnt(1)
	v_mfma_f32_32x32x16_bf16 v[32:47], v[136:139], v[144:147], v[32:47]
	s_waitcnt vmcnt(0)
	v_mfma_f32_32x32x16_bf16 v[48:63], v[136:139], v[148:151], v[48:63]
	v_mfma_f32_32x32x16_bf16 v[0:15], v[140:143], v[144:147], v[0:15]
	v_mfma_f32_32x32x16_bf16 v[16:31], v[140:143], v[148:151], v[16:31]
	global_load_dwordx4 v[136:139], v[64:65], off offset:224
	global_load_dwordx4 v[140:143], v[86:87], off
	global_load_dwordx4 v[144:147], v[116:117], off offset:224
	global_load_dwordx4 v[148:151], v[118:119], off offset:224
	s_waitcnt vmcnt(1)
	v_mfma_f32_32x32x16_bf16 v[32:47], v[136:139], v[144:147], v[32:47]
	s_waitcnt vmcnt(0)
	v_mfma_f32_32x32x16_bf16 v[48:63], v[136:139], v[148:151], v[48:63]
	v_mfma_f32_32x32x16_bf16 v[0:15], v[140:143], v[144:147], v[0:15]
	v_mfma_f32_32x32x16_bf16 v[16:31], v[140:143], v[148:151], v[16:31]
	global_load_dwordx4 v[136:139], v[64:65], off offset:256
	global_load_dwordx4 v[140:143], v[88:89], off
	global_load_dwordx4 v[144:147], v[116:117], off offset:256
	global_load_dwordx4 v[148:151], v[118:119], off offset:256
	s_waitcnt vmcnt(1)
	v_mfma_f32_32x32x16_bf16 v[32:47], v[136:139], v[144:147], v[32:47]
	s_waitcnt vmcnt(0)
	v_mfma_f32_32x32x16_bf16 v[48:63], v[136:139], v[148:151], v[48:63]
	v_mfma_f32_32x32x16_bf16 v[0:15], v[140:143], v[144:147], v[0:15]
	v_mfma_f32_32x32x16_bf16 v[16:31], v[140:143], v[148:151], v[16:31]
	global_load_dwordx4 v[136:139], v[64:65], off offset:288
	global_load_dwordx4 v[140:143], v[90:91], off
	global_load_dwordx4 v[144:147], v[116:117], off offset:288
	global_load_dwordx4 v[148:151], v[118:119], off offset:288
	s_waitcnt vmcnt(1)
	v_mfma_f32_32x32x16_bf16 v[32:47], v[136:139], v[144:147], v[32:47]
	s_waitcnt vmcnt(0)
	v_mfma_f32_32x32x16_bf16 v[48:63], v[136:139], v[148:151], v[48:63]
	v_mfma_f32_32x32x16_bf16 v[0:15], v[140:143], v[144:147], v[0:15]
	v_mfma_f32_32x32x16_bf16 v[16:31], v[140:143], v[148:151], v[16:31]
	global_load_dwordx4 v[136:139], v[64:65], off offset:320
	global_load_dwordx4 v[140:143], v[92:93], off
	global_load_dwordx4 v[144:147], v[116:117], off offset:320
	global_load_dwordx4 v[148:151], v[118:119], off offset:320
	s_waitcnt vmcnt(1)
	v_mfma_f32_32x32x16_bf16 v[32:47], v[136:139], v[144:147], v[32:47]
	s_waitcnt vmcnt(0)
	v_mfma_f32_32x32x16_bf16 v[48:63], v[136:139], v[148:151], v[48:63]
	v_mfma_f32_32x32x16_bf16 v[0:15], v[140:143], v[144:147], v[0:15]
	v_mfma_f32_32x32x16_bf16 v[16:31], v[140:143], v[148:151], v[16:31]
	global_load_dwordx4 v[136:139], v[64:65], off offset:352
	global_load_dwordx4 v[140:143], v[94:95], off
	global_load_dwordx4 v[144:147], v[116:117], off offset:352
	global_load_dwordx4 v[148:151], v[118:119], off offset:352
	s_waitcnt vmcnt(1)
	v_mfma_f32_32x32x16_bf16 v[32:47], v[136:139], v[144:147], v[32:47]
	s_waitcnt vmcnt(0)
	v_mfma_f32_32x32x16_bf16 v[48:63], v[136:139], v[148:151], v[48:63]
	v_mfma_f32_32x32x16_bf16 v[0:15], v[140:143], v[144:147], v[0:15]
	v_mfma_f32_32x32x16_bf16 v[16:31], v[140:143], v[148:151], v[16:31]
	global_load_dwordx4 v[136:139], v[64:65], off offset:384
	global_load_dwordx4 v[140:143], v[96:97], off
	global_load_dwordx4 v[144:147], v[116:117], off offset:384
	global_load_dwordx4 v[148:151], v[118:119], off offset:384
	s_waitcnt vmcnt(1)
	v_mfma_f32_32x32x16_bf16 v[32:47], v[136:139], v[144:147], v[32:47]
	s_waitcnt vmcnt(0)
	v_mfma_f32_32x32x16_bf16 v[48:63], v[136:139], v[148:151], v[48:63]
	v_mfma_f32_32x32x16_bf16 v[0:15], v[140:143], v[144:147], v[0:15]
	v_mfma_f32_32x32x16_bf16 v[16:31], v[140:143], v[148:151], v[16:31]
	global_load_dwordx4 v[136:139], v[64:65], off offset:416
	global_load_dwordx4 v[140:143], v[98:99], off
	global_load_dwordx4 v[144:147], v[116:117], off offset:416
	global_load_dwordx4 v[148:151], v[118:119], off offset:416
	s_waitcnt vmcnt(1)
	v_mfma_f32_32x32x16_bf16 v[32:47], v[136:139], v[144:147], v[32:47]
	s_waitcnt vmcnt(0)
	v_mfma_f32_32x32x16_bf16 v[48:63], v[136:139], v[148:151], v[48:63]
	v_mfma_f32_32x32x16_bf16 v[0:15], v[140:143], v[144:147], v[0:15]
	v_mfma_f32_32x32x16_bf16 v[16:31], v[140:143], v[148:151], v[16:31]
	global_load_dwordx4 v[136:139], v[64:65], off offset:448
	global_load_dwordx4 v[140:143], v[100:101], off
	global_load_dwordx4 v[144:147], v[116:117], off offset:448
	global_load_dwordx4 v[148:151], v[118:119], off offset:448
	s_waitcnt vmcnt(1)
	v_mfma_f32_32x32x16_bf16 v[32:47], v[136:139], v[144:147], v[32:47]
	s_waitcnt vmcnt(0)
	v_mfma_f32_32x32x16_bf16 v[48:63], v[136:139], v[148:151], v[48:63]
	v_mfma_f32_32x32x16_bf16 v[0:15], v[140:143], v[144:147], v[0:15]
	v_mfma_f32_32x32x16_bf16 v[16:31], v[140:143], v[148:151], v[16:31]
	global_load_dwordx4 v[136:139], v[64:65], off offset:480
	global_load_dwordx4 v[140:143], v[102:103], off
	global_load_dwordx4 v[144:147], v[116:117], off offset:480
	global_load_dwordx4 v[148:151], v[118:119], off offset:480
	s_waitcnt vmcnt(1)
	v_mfma_f32_32x32x16_bf16 v[32:47], v[136:139], v[144:147], v[32:47]
	s_waitcnt vmcnt(0)
	v_mfma_f32_32x32x16_bf16 v[48:63], v[136:139], v[148:151], v[48:63]
	v_mfma_f32_32x32x16_bf16 v[0:15], v[140:143], v[144:147], v[0:15]
	v_mfma_f32_32x32x16_bf16 v[16:31], v[140:143], v[148:151], v[16:31]
	global_load_dwordx4 v[136:139], v[64:65], off offset:512
	global_load_dwordx4 v[140:143], v[104:105], off
	global_load_dwordx4 v[144:147], v[116:117], off offset:512
	global_load_dwordx4 v[148:151], v[118:119], off offset:512
	s_waitcnt vmcnt(1)
	v_mfma_f32_32x32x16_bf16 v[32:47], v[136:139], v[144:147], v[32:47]
	s_waitcnt vmcnt(0)
	v_mfma_f32_32x32x16_bf16 v[48:63], v[136:139], v[148:151], v[48:63]
	v_mfma_f32_32x32x16_bf16 v[0:15], v[140:143], v[144:147], v[0:15]
	v_mfma_f32_32x32x16_bf16 v[16:31], v[140:143], v[148:151], v[16:31]
	global_load_dwordx4 v[136:139], v[64:65], off offset:544
	global_load_dwordx4 v[140:143], v[106:107], off
	global_load_dwordx4 v[144:147], v[116:117], off offset:544
	global_load_dwordx4 v[148:151], v[118:119], off offset:544
	s_waitcnt vmcnt(1)
	v_mfma_f32_32x32x16_bf16 v[32:47], v[136:139], v[144:147], v[32:47]
	s_waitcnt vmcnt(0)
	v_mfma_f32_32x32x16_bf16 v[48:63], v[136:139], v[148:151], v[48:63]
	v_mfma_f32_32x32x16_bf16 v[0:15], v[140:143], v[144:147], v[0:15]
	v_mfma_f32_32x32x16_bf16 v[16:31], v[140:143], v[148:151], v[16:31]
	global_load_dwordx4 v[136:139], v[64:65], off offset:576
	global_load_dwordx4 v[140:143], v[108:109], off
	global_load_dwordx4 v[144:147], v[116:117], off offset:576
	global_load_dwordx4 v[148:151], v[118:119], off offset:576
	s_waitcnt vmcnt(1)
	v_mfma_f32_32x32x16_bf16 v[32:47], v[136:139], v[144:147], v[32:47]
	s_waitcnt vmcnt(0)
	v_mfma_f32_32x32x16_bf16 v[48:63], v[136:139], v[148:151], v[48:63]
	v_mfma_f32_32x32x16_bf16 v[0:15], v[140:143], v[144:147], v[0:15]
	v_mfma_f32_32x32x16_bf16 v[16:31], v[140:143], v[148:151], v[16:31]
	global_load_dwordx4 v[136:139], v[64:65], off offset:608
	global_load_dwordx4 v[140:143], v[110:111], off
	global_load_dwordx4 v[144:147], v[116:117], off offset:608
	global_load_dwordx4 v[148:151], v[118:119], off offset:608
	s_waitcnt vmcnt(1)
	v_mfma_f32_32x32x16_bf16 v[32:47], v[136:139], v[144:147], v[32:47]
	s_waitcnt vmcnt(0)
	v_mfma_f32_32x32x16_bf16 v[48:63], v[136:139], v[148:151], v[48:63]
	v_mfma_f32_32x32x16_bf16 v[0:15], v[140:143], v[144:147], v[0:15]
	v_mfma_f32_32x32x16_bf16 v[16:31], v[140:143], v[148:151], v[16:31]
	global_load_dwordx4 v[136:139], v[64:65], off offset:640
	global_load_dwordx4 v[140:143], v[112:113], off
	global_load_dwordx4 v[144:147], v[116:117], off offset:640
	global_load_dwordx4 v[148:151], v[118:119], off offset:640
	s_waitcnt vmcnt(1)
	v_mfma_f32_32x32x16_bf16 v[32:47], v[136:139], v[144:147], v[32:47]
	s_waitcnt vmcnt(0)
	v_mfma_f32_32x32x16_bf16 v[48:63], v[136:139], v[148:151], v[48:63]
	v_mfma_f32_32x32x16_bf16 v[0:15], v[140:143], v[144:147], v[0:15]
	v_mfma_f32_32x32x16_bf16 v[16:31], v[140:143], v[148:151], v[16:31]
	global_load_dwordx4 v[136:139], v[64:65], off offset:672
	global_load_dwordx4 v[140:143], v[114:115], off
	global_load_dwordx4 v[144:147], v[116:117], off offset:672
	s_nop 0
	global_load_dwordx4 v[116:119], v[118:119], off offset:672
	s_waitcnt vmcnt(1)
	v_mfma_f32_32x32x16_bf16 v[32:47], v[136:139], v[144:147], v[32:47]
	s_waitcnt vmcnt(0)
	v_mfma_f32_32x32x16_bf16 v[48:63], v[136:139], v[116:119], v[48:63]
	s_nop 11
	ds_write2_b32 v126, v32, v48 offset1:32
	ds_write2_b32 v126, v33, v49 offset0:64 offset1:96
	ds_write2_b32 v126, v34, v50 offset0:128 offset1:160
	ds_write2_b32 v126, v35, v51 offset0:192 offset1:224
	v_mfma_f32_32x32x16_bf16 v[0:15], v[140:143], v[144:147], v[0:15]
	v_add_u32_e32 v32, 0x800, v126
	ds_write2_b32 v32, v36, v52 offset1:32
	ds_write2_b32 v32, v37, v53 offset0:64 offset1:96
	ds_write2_b32 v32, v38, v54 offset0:128 offset1:160
	ds_write2_b32 v32, v39, v55 offset0:192 offset1:224
	v_add_u32_e32 v32, 0x1000, v126
	ds_write2_b32 v32, v40, v56 offset1:32
	ds_write2_b32 v32, v41, v57 offset0:64 offset1:96
	ds_write2_b32 v32, v42, v58 offset0:128 offset1:160
	ds_write2_b32 v32, v43, v59 offset0:192 offset1:224
	v_add_u32_e32 v32, 0x1800, v126
	ds_write2_b32 v32, v44, v60 offset1:32
	ds_write2_b32 v32, v45, v61 offset0:64 offset1:96
	ds_write2_b32 v32, v46, v62 offset0:128 offset1:160
	ds_write2_b32 v32, v47, v63 offset0:192 offset1:224
	v_add_u32_e32 v32, 0x2000, v126
	v_mfma_f32_32x32x16_bf16 v[16:31], v[140:143], v[116:119], v[16:31]
	s_nop 11
	ds_write2_b32 v32, v0, v16 offset1:32
	ds_write2_b32 v32, v1, v17 offset0:64 offset1:96
	ds_write2_b32 v32, v2, v18 offset0:128 offset1:160
	ds_write2_b32 v32, v3, v19 offset0:192 offset1:224
	v_add_u32_e32 v0, 0x2800, v126
	ds_write2_b32 v0, v4, v20 offset1:32
	ds_write2_b32 v0, v5, v21 offset0:64 offset1:96
	ds_write2_b32 v0, v6, v22 offset0:128 offset1:160
	ds_write2_b32 v0, v7, v23 offset0:192 offset1:224
	v_add_u32_e32 v0, 0x3000, v126
	ds_write2_b32 v0, v8, v24 offset1:32
	ds_write2_b32 v0, v9, v25 offset0:64 offset1:96
	ds_write2_b32 v0, v10, v26 offset0:128 offset1:160
	ds_write2_b32 v0, v11, v27 offset0:192 offset1:224
	v_add_u32_e32 v0, 0x3800, v126
	ds_write2_b32 v0, v12, v28 offset1:32
	ds_write2_b32 v0, v13, v29 offset0:64 offset1:96
	ds_write2_b32 v0, v14, v30 offset0:128 offset1:160
	ds_write2_b32 v0, v15, v31 offset0:192 offset1:224
	s_waitcnt lgkmcnt(0)
	s_barrier
	ds_read_b128 v[0:3], v121
	ds_read_b128 v[4:7], v121 offset:16
	ds_read_b128 v[8:11], v121 offset:16384
	ds_read_b128 v[12:15], v121 offset:16400
	ds_read_b128 v[16:19], v121 offset:32768
	ds_read_b128 v[20:23], v121 offset:32784
	ds_read_b128 v[24:27], v121 offset:49152
	ds_read_b128 v[28:31], v121 offset:49168
	ds_read_b128 v[32:35], v127
	ds_read_b128 v[36:39], v128
	ds_read_b128 v[40:43], v129
	ds_read_b128 v[44:47], v130
	ds_read_b128 v[48:51], v131
	ds_read_b128 v[52:55], v132
	ds_read_b128 v[56:59], v133
	ds_read_b128 v[60:63], v134
	s_waitcnt lgkmcnt(14)
	v_pk_add_f32 v[0:1], v[0:1], 0 op_sel_hi:[1,0]
	v_pk_add_f32 v[4:5], v[4:5], 0 op_sel_hi:[1,0]
	s_waitcnt lgkmcnt(13)
	v_pk_add_f32 v[0:1], v[0:1], v[8:9]
	v_add_u32_e32 v8, s8, v122
	v_ashrrev_i32_e32 v9, 31, v8
	v_pk_add_f32 v[2:3], v[2:3], 0 op_sel_hi:[1,0]
	s_waitcnt lgkmcnt(12)
	v_pk_add_f32 v[4:5], v[4:5], v[12:13]
	v_lshl_add_u64 v[12:13], v[8:9], 1, v[70:71]
	v_pk_add_f32 v[2:3], v[2:3], v[10:11]
	global_load_dwordx4 v[8:11], v[12:13], off
	v_pk_add_f32 v[6:7], v[6:7], 0 op_sel_hi:[1,0]
	s_waitcnt lgkmcnt(11)
	v_pk_add_f32 v[2:3], v[2:3], v[18:19]
	v_pk_add_f32 v[6:7], v[6:7], v[14:15]
	v_pk_add_f32 v[0:1], v[0:1], v[16:17]
	s_waitcnt lgkmcnt(10)
	v_pk_add_f32 v[6:7], v[6:7], v[22:23]
	v_pk_add_f32 v[4:5], v[4:5], v[20:21]
	s_waitcnt lgkmcnt(9)
	v_pk_add_f32 v[2:3], v[2:3], v[26:27]
	v_pk_add_f32 v[0:1], v[0:1], v[24:25]
	s_waitcnt lgkmcnt(8)
	v_pk_add_f32 v[6:7], v[6:7], v[30:31]
	v_pk_add_f32 v[4:5], v[4:5], v[28:29]
	s_waitcnt lgkmcnt(7)
	v_pk_add_f32 v[2:3], v[2:3], v[34:35]
	v_pk_add_f32 v[0:1], v[0:1], v[32:33]
	s_waitcnt lgkmcnt(6)
	v_pk_add_f32 v[6:7], v[6:7], v[38:39]
	v_pk_add_f32 v[4:5], v[4:5], v[36:37]
	s_waitcnt lgkmcnt(5)
	v_pk_add_f32 v[2:3], v[2:3], v[42:43]
	v_pk_add_f32 v[0:1], v[0:1], v[40:41]
	s_waitcnt lgkmcnt(4)
	v_pk_add_f32 v[6:7], v[6:7], v[46:47]
	v_pk_add_f32 v[4:5], v[4:5], v[44:45]
	s_waitcnt lgkmcnt(3)
	v_pk_add_f32 v[2:3], v[2:3], v[50:51]
	v_pk_add_f32 v[0:1], v[0:1], v[48:49]
	s_waitcnt lgkmcnt(2)
	v_pk_add_f32 v[6:7], v[6:7], v[54:55]
	v_pk_add_f32 v[4:5], v[4:5], v[52:53]
	s_waitcnt lgkmcnt(1)
	v_pk_add_f32 v[2:3], v[2:3], v[58:59]
	v_pk_add_f32 v[0:1], v[0:1], v[56:57]
	s_waitcnt lgkmcnt(0)
	v_pk_add_f32 v[6:7], v[6:7], v[62:63]
	v_pk_add_f32 v[4:5], v[4:5], v[60:61]
	s_waitcnt vmcnt(0)
	v_lshlrev_b32_e32 v14, 16, v8
	v_and_b32_e32 v15, 0xffff0000, v8
	v_lshlrev_b32_e32 v8, 16, v9
	v_and_b32_e32 v9, 0xffff0000, v9
	v_lshlrev_b32_e32 v16, 16, v10
	v_and_b32_e32 v17, 0xffff0000, v10
	v_lshlrev_b32_e32 v10, 16, v11
	v_and_b32_e32 v11, 0xffff0000, v11
	v_pk_add_f32 v[8:9], v[2:3], v[8:9]
	v_pk_add_f32 v[14:15], v[0:1], v[14:15]
	v_pk_add_f32 v[6:7], v[6:7], v[10:11]
	v_pk_add_f32 v[4:5], v[4:5], v[16:17]
	v_cvt_pk_bf16_f32 v0, v14, v15
	v_cvt_pk_bf16_f32 v1, v8, v9
	v_cvt_pk_bf16_f32 v2, v4, v5
	v_cvt_pk_bf16_f32 v3, v6, v7
	global_store_dwordx4 v[12:13], v[0:3], off sc1
	s_nop 1
	v_mul_f32_e32 v0, v15, v15
	v_mul_f32_e32 v1, v9, v9
	v_fmac_f32_e32 v0, v14, v14
	v_fmac_f32_e32 v1, v8, v8
	v_add_f32_e32 v0, v0, v1
	v_mul_f32_e32 v1, v5, v5
	v_fmac_f32_e32 v1, v4, v4
	v_add_f32_e32 v0, v1, v0
	v_mul_f32_e32 v1, v7, v7
	v_fmac_f32_e32 v1, v6, v6
	v_add_f32_e32 v0, v1, v0
	ds_bpermute_b32 v1, v123, v0
	s_waitcnt lgkmcnt(0)
	v_add_f32_e32 v0, v0, v1
	ds_bpermute_b32 v1, v124, v0
	s_waitcnt lgkmcnt(0)
	v_add_f32_e32 v0, v0, v1
	ds_bpermute_b32 v1, v125, v0
	s_and_saveexec_b64 s[6:7], s[40:41]
	s_cbranch_execz .LBB0_1305
	s_ashr_i32 s43, s42, 31
	s_waitcnt lgkmcnt(0)
	v_add_f32_e32 v2, v0, v1
	v_lshl_add_u64 v[0:1], s[42:43], 2, v[72:73]
	global_store_dword v[0:1], v2, off
	s_branch .LBB0_1305

.LBB0_1363:
	s_add_i32 s9, s78, s88
	s_min_i32 s0, s9, 0x3fff
	s_ashr_i32 s1, s0, 31
	s_lshr_b32 s1, s1, 20
	s_add_i32 s1, s0, s1
	s_ashr_i32 s8, s1, 12
	s_mulk_i32 s8, 0x1010
	s_add_i32 s0, s0, s8
	s_and_b32 s1, s1, 0xfffff000
	s_sub_i32 s0, s0, s1
	s_add_i32 s0, s0, 16
	s_ashr_i32 s1, s0, 31
	s_lshl_b64 s[10:11], s[0:1], 6
	s_add_u32 s12, s6, s10
	s_addc_u32 s13, s7, s11
	s_lshl_b64 s[16:17], s[0:1], 11
	v_readlane_b32 s0, v254, 53
	s_add_i32 s10, s0, s88
	s_min_i32 s0, s10, 0x3fff
	s_ashr_i32 s1, s0, 31
	s_lshr_b32 s1, s1, 20
	s_add_i32 s1, s0, s1
	s_ashr_i32 s8, s1, 12
	s_mulk_i32 s8, 0x1010
	s_add_i32 s0, s0, s8
	s_and_b32 s1, s1, 0xfffff000
	s_sub_i32 s0, s0, s1
	s_add_i32 s14, s0, 16
	s_ashr_i32 s15, s14, 31
	s_lshl_b64 s[0:1], s[14:15], 6
	s_add_u32 s0, s6, s0
	s_addc_u32 s1, s7, s1
	s_add_i32 s8, s86, s88
	s_min_i32 s11, s8, 0x3fff
	s_ashr_i32 s18, s11, 31
	s_lshr_b32 s18, s18, 20
	s_add_i32 s18, s11, s18
	s_ashr_i32 s19, s18, 12
	s_mulk_i32 s19, 0x1010
	s_add_i32 s11, s11, s19
	s_and_b32 s18, s18, 0xfffff000
	s_sub_i32 s11, s11, s18
	s_add_i32 s18, s11, 16
	s_ashr_i32 s19, s18, 31
	s_lshl_b64 s[14:15], s[14:15], 11
	s_lshl_b64 s[20:21], s[18:19], 6
	s_add_u32 s20, s6, s20
	s_addc_u32 s21, s7, s21
	s_ashr_i32 s11, s88, 31
	s_lshr_b32 s11, s11, 20
	s_add_i32 s11, s88, s11
	s_ashr_i32 s11, s11, 12
	s_lshl_b32 s11, s11, 4
	s_add_i32 s11, s88, s11
	global_load_dwordx4 v[82:85], v53, s[20:21]
	global_load_dwordx4 v[86:89], v53, s[20:21] offset:32
	global_load_dwordx4 v[90:93], v53, s[20:21] offset:16
	global_load_dwordx4 v[94:97], v53, s[20:21] offset:48
	s_add_i32 s20, s11, 16
	s_ashr_i32 s21, s20, 31
	s_lshl_b64 s[18:19], s[18:19], 11
	s_lshl_b64 s[22:23], s[20:21], 6
	s_add_u32 s22, s6, s22
	s_addc_u32 s23, s7, s23
	global_load_dwordx4 v[98:101], v53, s[22:23]
	global_load_dwordx4 v[102:105], v53, s[22:23] offset:32
	global_load_dwordx4 v[106:109], v53, s[22:23] offset:16
	global_load_dwordx4 v[110:113], v53, s[22:23] offset:48
	s_lshl_b64 s[20:21], s[20:21], 11
	s_waitcnt vmcnt(23)
	v_lshl_add_u64 v[16:17], v[48:49], 0, s[20:21]
	global_load_dwordx2 v[114:115], v[16:17], off
	global_load_dwordx4 v[32:35], v53, s[12:13] offset:48
	global_load_dwordx4 v[40:43], v53, s[12:13] offset:32
	global_load_dwordx4 v[36:39], v53, s[12:13] offset:16
	global_load_dwordx4 v[44:47], v53, s[12:13]
	global_load_dwordx2 v[116:117], v[16:17], off offset:1536
	global_load_dwordx2 v[118:119], v[16:17], off offset:1024
	global_load_dwordx2 v[120:121], v[16:17], off offset:512
	s_waitcnt vmcnt(29)
	v_lshl_add_u64 v[24:25], v[48:49], 0, s[16:17]
	global_load_dwordx2 v[80:81], v[24:25], off
	global_load_dwordx2 v[78:79], v[24:25], off offset:512
	global_load_dwordx2 v[76:77], v[24:25], off offset:1024
	global_load_dwordx2 v[74:75], v[24:25], off offset:1536
	global_load_dwordx4 v[16:19], v53, s[0:1] offset:48
	global_load_dwordx4 v[20:23], v53, s[0:1] offset:32
	s_waitcnt vmcnt(26)
	v_lshl_add_u64 v[56:57], v[48:49], 0, s[14:15]
	global_load_dwordx4 v[24:27], v53, s[0:1] offset:16
	global_load_dwordx4 v[28:31], v53, s[0:1]
	global_load_dwordx2 v[72:73], v[56:57], off
	global_load_dwordx2 v[70:71], v[56:57], off offset:512
	global_load_dwordx2 v[66:67], v[56:57], off offset:1024
	global_load_dwordx2 v[64:65], v[56:57], off offset:1536
	v_lshl_add_u64 v[68:69], v[48:49], 0, s[18:19]
	global_load_dwordx2 v[62:63], v[68:69], off
	global_load_dwordx2 v[60:61], v[68:69], off offset:512
	global_load_dwordx2 v[58:59], v[68:69], off offset:1024
	global_load_dwordx2 v[56:57], v[68:69], off offset:1536
	v_readlane_b32 s0, v253, 49
	v_readlane_b32 s1, v253, 50
	s_cmpk_gt_i32 s9, 0x3fff
	s_waitcnt vmcnt(31)
	v_mov_b32_e32 v68, v82
	s_waitcnt vmcnt(30)
	v_mov_b32_e32 v69, v86
	v_mov_b32_e32 v86, v83
	v_mov_b32_e32 v82, v84
	v_mov_b32_e32 v83, v88
	v_mov_b32_e32 v88, v85
	s_waitcnt vmcnt(29)
	v_mov_b32_e32 v84, v90
	s_waitcnt vmcnt(28)
	v_mov_b32_e32 v85, v94
	v_mov_b32_e32 v94, v91
	v_mov_b32_e32 v90, v92
	v_mov_b32_e32 v91, v96
	v_mov_b32_e32 v96, v93
	v_pk_add_f32 v[68:69], v[68:69], v[86:87]
	v_pk_add_f32 v[82:83], v[82:83], v[88:89]
	v_pk_add_f32 v[84:85], v[84:85], v[94:95]
	v_pk_add_f32 v[86:87], v[90:91], v[96:97]
	v_pk_add_f32 v[68:69], v[68:69], v[82:83]
	v_pk_add_f32 v[82:83], v[84:85], v[86:87]
	s_waitcnt vmcnt(27)
	v_mov_b32_e32 v84, v98
	s_waitcnt vmcnt(26)
	v_mov_b32_e32 v85, v102
	v_mov_b32_e32 v102, v99
	v_mov_b32_e32 v86, v100
	v_mov_b32_e32 v87, v104
	v_mov_b32_e32 v104, v101
	s_waitcnt vmcnt(25)
	v_mov_b32_e32 v88, v106
	s_waitcnt vmcnt(24)
	v_mov_b32_e32 v89, v110
	v_mov_b32_e32 v110, v107
	v_mov_b32_e32 v90, v108
	v_mov_b32_e32 v91, v112
	v_mov_b32_e32 v112, v109
	v_pk_add_f32 v[84:85], v[84:85], v[102:103]
	v_pk_add_f32 v[86:87], v[86:87], v[104:105]
	v_pk_add_f32 v[88:89], v[88:89], v[110:111]
	v_pk_add_f32 v[90:91], v[90:91], v[112:113]
	v_pk_add_f32 v[84:85], v[84:85], v[86:87]
	v_pk_add_f32 v[86:87], v[88:89], v[90:91]
	v_pk_add_f32 v[68:69], v[68:69], v[82:83]
	v_pk_add_f32 v[84:85], v[84:85], v[86:87]
	v_mov_b32_e32 v83, v68
	v_mov_b32_e32 v82, v84
	v_mov_b32_e32 v68, v85
	v_pk_add_f32 v[68:69], v[82:83], v[68:69]
	s_waitcnt vmcnt(23)
	v_lshlrev_b32_e32 v84, 16, v115
	v_pk_fma_f32 v[68:69], v[68:69], s[4:5], v[52:53] op_sel_hi:[1,0,0]
	v_and_b32_e32 v85, 0xffff0000, v115
	v_mul_f32_e32 v82, 0x4b800000, v68
	v_cmp_gt_f32_e32 vcc, s5, v68
	v_lshl_add_u64 v[86:87], v[54:55], 0, s[0:1]
	s_nop 0
	v_cndmask_b32_e32 v68, v68, v82, vcc
	v_rsq_f32_e32 v68, v68
	v_lshlrev_b32_e32 v82, 16, v114
	v_mul_f32_e32 v83, 0x45800000, v68
	v_cndmask_b32_e32 v68, v68, v83, vcc
	v_and_b32_e32 v83, 0xffff0000, v114
	v_pk_mul_f32 v[82:83], v[68:69], v[82:83] op_sel_hi:[0,1]
	v_pk_mul_f32 v[84:85], v[68:69], v[84:85] op_sel_hi:[0,1]
	v_pk_mul_f32 v[84:85], v[2:3], v[84:85]
	v_pk_mul_f32 v[82:83], v[0:1], v[82:83]
	global_store_dwordx4 v[86:87], v[82:85], off sc1
	v_cmp_gt_f32_e32 vcc, s5, v69
	s_waitcnt vmcnt(17)
	v_lshlrev_b32_e32 v82, 16, v120
	v_and_b32_e32 v83, 0xffff0000, v120
	v_lshlrev_b32_e32 v84, 16, v121
	v_and_b32_e32 v85, 0xffff0000, v121
	v_pk_mul_f32 v[82:83], v[68:69], v[82:83] op_sel_hi:[0,1]
	v_pk_mul_f32 v[84:85], v[68:69], v[84:85] op_sel_hi:[0,1]
	v_pk_mul_f32 v[84:85], v[6:7], v[84:85]
	v_pk_mul_f32 v[82:83], v[4:5], v[82:83]
	global_store_dwordx4 v[86:87], v[82:85], off offset:1024 sc1
	s_nop 1
	v_lshlrev_b32_e32 v82, 16, v118
	v_and_b32_e32 v83, 0xffff0000, v118
	v_lshlrev_b32_e32 v84, 16, v119
	v_and_b32_e32 v85, 0xffff0000, v119
	v_pk_mul_f32 v[82:83], v[68:69], v[82:83] op_sel_hi:[0,1]
	v_pk_mul_f32 v[84:85], v[68:69], v[84:85] op_sel_hi:[0,1]
	v_pk_mul_f32 v[84:85], v[10:11], v[84:85]
	v_pk_mul_f32 v[82:83], v[8:9], v[82:83]
	global_store_dwordx4 v[86:87], v[82:85], off offset:2048 sc1
	s_nop 1
	v_lshlrev_b32_e32 v82, 16, v116
	v_and_b32_e32 v83, 0xffff0000, v116
	v_lshlrev_b32_e32 v84, 16, v117
	v_and_b32_e32 v85, 0xffff0000, v117
	v_pk_mul_f32 v[82:83], v[68:69], v[82:83] op_sel_hi:[0,1]
	v_pk_mul_f32 v[84:85], v[68:69], v[84:85] op_sel_hi:[0,1]
	v_pk_mul_f32 v[84:85], v[14:15], v[84:85]
	v_pk_mul_f32 v[82:83], v[12:13], v[82:83]
	global_store_dwordx4 v[86:87], v[82:85], off offset:3072 sc1
	s_cbranch_scc1 .LBB0_1366
	s_nop 0
	v_mov_b32_e32 v82, v44
	v_mov_b32_e32 v83, v40
	v_mov_b32_e32 v40, v45
	v_mov_b32_e32 v44, v46
	v_mov_b32_e32 v45, v42
	v_mov_b32_e32 v42, v47
	v_pk_add_f32 v[40:41], v[82:83], v[40:41]
	v_pk_add_f32 v[42:43], v[44:45], v[42:43]
	s_nop 0
	v_pk_add_f32 v[40:41], v[40:41], v[42:43]
	v_mov_b32_e32 v42, v36
	v_mov_b32_e32 v43, v32
	v_mov_b32_e32 v32, v37
	v_mov_b32_e32 v36, v38
	v_mov_b32_e32 v37, v34
	v_mov_b32_e32 v34, v39
	v_pk_add_f32 v[32:33], v[42:43], v[32:33]
	v_pk_add_f32 v[34:35], v[36:37], v[34:35]
	v_lshl_add_u64 v[38:39], v[54:55], 0, s[2:3]
	v_pk_add_f32 v[32:33], v[32:33], v[34:35]
	s_waitcnt vmcnt(19)
	v_lshlrev_b32_e32 v34, 16, v81
	v_pk_add_f32 v[32:33], v[40:41], v[32:33]
	v_and_b32_e32 v35, 0xffff0000, v81
	v_add_f32_e32 v32, v32, v33
	v_fmamk_f32 v32, v32, 0x3a800000, v52
	v_mul_f32_e32 v33, 0x4b800000, v32
	v_cmp_gt_f32_e64 s[0:1], s5, v32
	s_nop 1
	v_cndmask_b32_e64 v32, v32, v33, s[0:1]
	v_rsq_f32_e32 v32, v32
	s_nop 0
	v_mul_f32_e32 v33, 0x45800000, v32
	v_cndmask_b32_e64 v36, v32, v33, s[0:1]
	v_lshlrev_b32_e32 v32, 16, v80
	v_and_b32_e32 v33, 0xffff0000, v80
	v_pk_mul_f32 v[32:33], v[36:37], v[32:33] op_sel_hi:[0,1]
	v_pk_mul_f32 v[34:35], v[36:37], v[34:35] op_sel_hi:[0,1]
	v_pk_mul_f32 v[34:35], v[2:3], v[34:35]
	v_pk_mul_f32 v[32:33], v[0:1], v[32:33]
	global_store_dwordx4 v[38:39], v[32:35], off sc1
	s_waitcnt vmcnt(19)
	s_nop 0
	v_lshlrev_b32_e32 v32, 16, v78
	v_and_b32_e32 v33, 0xffff0000, v78
	v_lshlrev_b32_e32 v34, 16, v79
	v_and_b32_e32 v35, 0xffff0000, v79
	v_pk_mul_f32 v[32:33], v[36:37], v[32:33] op_sel_hi:[0,1]
	v_pk_mul_f32 v[34:35], v[36:37], v[34:35] op_sel_hi:[0,1]
	v_pk_mul_f32 v[34:35], v[6:7], v[34:35]
	v_pk_mul_f32 v[32:33], v[4:5], v[32:33]
	global_store_dwordx4 v[38:39], v[32:35], off offset:1024 sc1
	s_waitcnt vmcnt(19)
	s_nop 0
	v_lshlrev_b32_e32 v32, 16, v76
	v_and_b32_e32 v33, 0xffff0000, v76
	v_lshlrev_b32_e32 v34, 16, v77
	v_and_b32_e32 v35, 0xffff0000, v77
	v_pk_mul_f32 v[32:33], v[36:37], v[32:33] op_sel_hi:[0,1]
	v_pk_mul_f32 v[34:35], v[36:37], v[34:35] op_sel_hi:[0,1]
	v_pk_mul_f32 v[34:35], v[10:11], v[34:35]
	v_pk_mul_f32 v[32:33], v[8:9], v[32:33]
	global_store_dwordx4 v[38:39], v[32:35], off offset:2048 sc1
	s_waitcnt vmcnt(19)
	s_nop 0
	v_lshlrev_b32_e32 v32, 16, v74
	v_and_b32_e32 v33, 0xffff0000, v74
	v_lshlrev_b32_e32 v34, 16, v75
	v_and_b32_e32 v35, 0xffff0000, v75
	v_pk_mul_f32 v[32:33], v[36:37], v[32:33] op_sel_hi:[0,1]
	v_pk_mul_f32 v[34:35], v[36:37], v[34:35] op_sel_hi:[0,1]
	v_pk_mul_f32 v[34:35], v[14:15], v[34:35]
	v_pk_mul_f32 v[32:33], v[12:13], v[32:33]
	global_store_dwordx4 v[38:39], v[32:35], off offset:3072 sc1
	s_add_i32 s9, s78, s9
	s_cmpk_gt_i32 s9, 0x3fff
	s_cbranch_scc0 .LBB0_1367

.LBB0_1367:
	s_waitcnt vmcnt(12)
	v_mov_b32_e32 v32, v28
	v_mov_b32_e32 v33, v20
	v_mov_b32_e32 v20, v29
	v_mov_b32_e32 v28, v30
	v_mov_b32_e32 v29, v22
	v_mov_b32_e32 v22, v31
	v_pk_add_f32 v[20:21], v[32:33], v[20:21]
	v_pk_add_f32 v[22:23], v[28:29], v[22:23]
	s_ashr_i32 s11, s10, 31
	v_pk_add_f32 v[20:21], v[20:21], v[22:23]
	v_mov_b32_e32 v22, v24
	v_mov_b32_e32 v23, v16
	v_mov_b32_e32 v16, v25
	v_pk_add_f32 v[16:17], v[22:23], v[16:17]
	v_mov_b32_e32 v22, v26
	v_mov_b32_e32 v23, v18
	v_mov_b32_e32 v18, v27
	v_pk_add_f32 v[18:19], v[22:23], v[18:19]
	s_nop 0
	v_pk_add_f32 v[16:17], v[16:17], v[18:19]
	s_waitcnt vmcnt(11)
	v_lshlrev_b32_e32 v18, 16, v73
	v_pk_add_f32 v[16:17], v[20:21], v[16:17]
	v_and_b32_e32 v19, 0xffff0000, v73
	v_add_f32_e32 v16, v16, v17
	v_fmamk_f32 v16, v16, 0x3a800000, v52
	v_mul_f32_e32 v17, 0x4b800000, v16
	v_cmp_gt_f32_e64 s[0:1], s5, v16
	s_nop 1
	v_cndmask_b32_e64 v16, v16, v17, s[0:1]
	v_rsq_f32_e32 v16, v16
	s_nop 0
	v_mul_f32_e32 v17, 0x45800000, v16
	v_cndmask_b32_e64 v20, v16, v17, s[0:1]
	v_lshlrev_b32_e32 v16, 16, v72
	v_and_b32_e32 v17, 0xffff0000, v72
	s_lshl_b64 s[0:1], s[10:11], 12
	v_pk_mul_f32 v[16:17], v[20:21], v[16:17] op_sel_hi:[0,1]
	v_pk_mul_f32 v[18:19], v[20:21], v[18:19] op_sel_hi:[0,1]
	v_lshl_add_u64 v[22:23], v[50:51], 0, s[0:1]
	v_pk_mul_f32 v[18:19], v[2:3], v[18:19]
	v_pk_mul_f32 v[16:17], v[0:1], v[16:17]
	global_store_dwordx4 v[22:23], v[16:19], off sc1
	s_waitcnt vmcnt(11)
	s_nop 0
	v_lshlrev_b32_e32 v16, 16, v70
	v_and_b32_e32 v17, 0xffff0000, v70
	v_lshlrev_b32_e32 v18, 16, v71
	v_and_b32_e32 v19, 0xffff0000, v71
	v_pk_mul_f32 v[16:17], v[20:21], v[16:17] op_sel_hi:[0,1]
	v_pk_mul_f32 v[18:19], v[20:21], v[18:19] op_sel_hi:[0,1]
	v_pk_mul_f32 v[18:19], v[6:7], v[18:19]
	v_pk_mul_f32 v[16:17], v[4:5], v[16:17]
	global_store_dwordx4 v[22:23], v[16:19], off offset:1024 sc1
	s_waitcnt vmcnt(11)
	s_nop 0
	v_lshlrev_b32_e32 v16, 16, v66
	v_and_b32_e32 v17, 0xffff0000, v66
	v_lshlrev_b32_e32 v18, 16, v67
	v_and_b32_e32 v19, 0xffff0000, v67
	v_pk_mul_f32 v[16:17], v[20:21], v[16:17] op_sel_hi:[0,1]
	v_pk_mul_f32 v[18:19], v[20:21], v[18:19] op_sel_hi:[0,1]
	v_pk_mul_f32 v[18:19], v[10:11], v[18:19]
	v_pk_mul_f32 v[16:17], v[8:9], v[16:17]
	global_store_dwordx4 v[22:23], v[16:19], off offset:2048 sc1
	s_waitcnt vmcnt(11)
	s_nop 0
	v_lshlrev_b32_e32 v16, 16, v64
	v_and_b32_e32 v17, 0xffff0000, v64
	v_lshlrev_b32_e32 v18, 16, v65
	v_and_b32_e32 v19, 0xffff0000, v65
	v_pk_mul_f32 v[16:17], v[20:21], v[16:17] op_sel_hi:[0,1]
	v_pk_mul_f32 v[18:19], v[20:21], v[18:19] op_sel_hi:[0,1]
	v_pk_mul_f32 v[18:19], v[14:15], v[18:19]
	v_pk_mul_f32 v[16:17], v[12:13], v[16:17]
	global_store_dwordx4 v[22:23], v[16:19], off offset:3072 sc1
	s_add_i32 s0, s78, s9
	s_cmpk_gt_i32 s0, 0x3fff
	s_cbranch_scc1 .LBB0_1362
.LBB0_1368:
	s_waitcnt vmcnt(15)
	v_mul_f32_e32 v16, 0x4b800000, v69
	v_cndmask_b32_e32 v16, v69, v16, vcc
	v_rsq_f32_e32 v16, v16
	s_ashr_i32 s9, s8, 31
	s_waitcnt vmcnt(7)
	v_lshlrev_b32_e32 v18, 16, v63
	v_and_b32_e32 v19, 0xffff0000, v63
	v_mul_f32_e32 v17, 0x45800000, v16
	v_cndmask_b32_e32 v22, v16, v17, vcc
	v_lshlrev_b32_e32 v16, 16, v62
	v_and_b32_e32 v17, 0xffff0000, v62
	s_lshl_b64 s[8:9], s[8:9], 12
	v_pk_mul_f32 v[16:17], v[22:23], v[16:17] op_sel_hi:[0,1]
	v_pk_mul_f32 v[18:19], v[22:23], v[18:19] op_sel_hi:[0,1]
	v_lshl_add_u64 v[20:21], v[50:51], 0, s[8:9]
	v_pk_mul_f32 v[18:19], v[2:3], v[18:19]
	v_pk_mul_f32 v[16:17], v[0:1], v[16:17]
	global_store_dwordx4 v[20:21], v[16:19], off sc1
	s_waitcnt vmcnt(7)
	s_nop 0
	v_lshlrev_b32_e32 v16, 16, v60
	v_and_b32_e32 v17, 0xffff0000, v60
	v_lshlrev_b32_e32 v18, 16, v61
	v_and_b32_e32 v19, 0xffff0000, v61
	v_pk_mul_f32 v[16:17], v[22:23], v[16:17] op_sel_hi:[0,1]
	v_pk_mul_f32 v[18:19], v[22:23], v[18:19] op_sel_hi:[0,1]
	v_pk_mul_f32 v[18:19], v[6:7], v[18:19]
	v_pk_mul_f32 v[16:17], v[4:5], v[16:17]
	global_store_dwordx4 v[20:21], v[16:19], off offset:1024 sc1
	s_waitcnt vmcnt(7)
	s_nop 0
	v_lshlrev_b32_e32 v16, 16, v58
	v_and_b32_e32 v17, 0xffff0000, v58
	v_lshlrev_b32_e32 v18, 16, v59
	v_and_b32_e32 v19, 0xffff0000, v59
	v_pk_mul_f32 v[16:17], v[22:23], v[16:17] op_sel_hi:[0,1]
	v_pk_mul_f32 v[18:19], v[22:23], v[18:19] op_sel_hi:[0,1]
	v_pk_mul_f32 v[18:19], v[10:11], v[18:19]
	v_pk_mul_f32 v[16:17], v[8:9], v[16:17]
	global_store_dwordx4 v[20:21], v[16:19], off offset:2048 sc1
	s_waitcnt vmcnt(7)
	s_nop 0
	v_lshlrev_b32_e32 v16, 16, v56
	v_and_b32_e32 v17, 0xffff0000, v56
	v_lshlrev_b32_e32 v18, 16, v57
	v_and_b32_e32 v19, 0xffff0000, v57
	v_pk_mul_f32 v[16:17], v[22:23], v[16:17] op_sel_hi:[0,1]
	v_pk_mul_f32 v[18:19], v[22:23], v[18:19] op_sel_hi:[0,1]
	v_pk_mul_f32 v[18:19], v[14:15], v[18:19]
	v_pk_mul_f32 v[16:17], v[12:13], v[16:17]
	global_store_dwordx4 v[20:21], v[16:19], off offset:3072 sc1
	s_branch .LBB0_1362
